# GEMM phases: 32 MFMAs contiguous (mid-phase setprio pair dropped), 16 accumulator chains on a boustrophedon path so every chain boundary shares one operand register
# speedup vs baseline: 1.0186x; 1.0032x over previous
; #define PG8_STAGE(bufoff, gbase, voff) do { _Pragma("unroll") for (int _i = 0; _i < 2; ++_i) \
;         __builtin_amdgcn_global_load_lds((const unsigned*)((const char*)(gbase) + (voff)[_i]), (PG8_LAS unsigned*)(lds + (bufoff) + ldsw + _i * 8192), 16, 0, 0); } while (0)
; #define PG8_LDA(dst, b, h) do { _Pragma("unroll") for (int m = 0; m < 4; ++m) _Pragma("unroll") for (int k = 0; k < 2; ++k) dst[m][k] = *(const PG8_LAS bf16x8*)(lds + PG8_SA(b, h) + aoff + m * 2048 + k * 1024); } while (0)
; #define PG8_LDB(dst, b, h) do { _Pragma("unroll") for (int n = 0; n < 2; ++n) _Pragma("unroll") for (int k = 0; k < 2; ++k) dst[n][k] = *(const PG8_LAS bf16x8*)(lds + PG8_SB(b, h) + boff + n * 2048 + k * 1024); } while (0)
; #define PG8_WAIT_V(n) asm volatile("s_waitcnt vmcnt(" #n ")" ::: "memory")
; #define PG8_WAIT_L(n) asm volatile("s_waitcnt lgkmcnt(" #n ")" ::: "memory")
; #define PG8_BAR __builtin_amdgcn_s_barrier()
; #define PG8_SCHED __builtin_amdgcn_sched_barrier(0)
; template <class Epi, class Sched, bool ALIGN_EPI = false, bool SP2 = false, bool I8 = false>
; __device__ __forceinline__ void gemm_phase(PG8_LAS unsigned char* lds, const Gemm g, const Sched& S, const Epi& E) {
;     ...
;         const bool has_next = S.next(ui + 1, nxt);
;         const char* nA = has_next ? (const char*)g.A + (size_t)nxt.pm * tstep : cA; const char* nB = has_next ? (const char*)g.Bt + (size_t)nxt.pn * tstep : cB;
;         for (int t = 0; t < nt; t += 2) {
;             const bool last = (t == nt - 2);
;             const char* a1 = cA + (size_t)(t + 1) * kstep;
;             const char* a2 = last ? nA : cA + (size_t)(t + 2) * kstep; const char* b2 = last ? nB : cB + (size_t)(t + 2) * kstep;
;             const char* a3 = a2 + kstep; const char* b3 = b2 + kstep;
;             if (last && has_next) S.a_ready(nxt);
;             if constexpr (SP2) {
;             PG8_LDB(B0, 0, 0); PG8_LDB(B1, 0, 1); PG8_SCHED; PG8_LDA(At, 0, 0); PG8_STAGE(PG8_SA(1, 1), a1 + hstep, voffA);
;             PG8_WAIT_V(8); PG8_WAIT_L(0); PG8_BAR; PG8_MMA(0, 0, At, B0); PG8_MMA(0, 1, At, B1); PG8_BAR; PG8_SCHED;
;             PG8_LDA(At, 0, 1); PG8_STAGE(PG8_SB(0, 0), b2, voffB); PG8_STAGE(PG8_SB(0, 1), b2 + hstep, voffB); PG8_STAGE(PG8_SA(0, 0), a2, voffA);
;             PG8_WAIT_V(8); PG8_WAIT_L(0); PG8_BAR; PG8_MMA(1, 0, At, B0); PG8_MMA(1, 1, At, B1); PG8_BAR; PG8_SCHED;
.LBB0_207:
	s_ashr_i32 s19, s18, 31
	s_lshl_b64 s[22:23], s[18:19], 20
	s_add_u32 s22, s28, s22
	s_addc_u32 s23, s34, s23
	s_and_b64 s[24:25], s[6:7], exec
	s_cselect_b32 s19, s23, s27
	s_cselect_b32 s64, s22, s26
	s_ashr_i32 s17, s16, 31
	s_lshl_b64 s[24:25], s[16:17], 20
	s_add_u32 s24, s35, s24
	s_addc_u32 s25, s42, s25
	s_and_b64 s[40:41], s[6:7], exec
	s_cselect_b32 s17, s25, s37
	s_cselect_b32 s65, s24, s36
	s_add_u32 s26, s26, 0x80080
	s_addc_u32 s27, s27, 0
	s_add_u32 s72, s36, 0x100
	s_addc_u32 s73, s37, 0
	s_mov_b32 s76, -2
	s_add_u32 s36, s26, 0xfff80080
	s_addc_u32 s37, s27, -1
	s_add_i32 s50, 0, 0x10000
	s_cmp_eq_u32 s76, 28
	s_cselect_b32 s41, s19, s37
	s_cselect_b32 s40, s64, s36
	s_cselect_b32 s37, s17, s73
	s_cselect_b32 s36, s65, s72
	s_add_i32 s56, 0, 0x14000
	v_add_u32_e32 v136, s50, v175
	v_add_u32_e32 v172, s56, v175
	ds_read_b128 v[116:119], v136
	ds_read_b128 v[124:127], v136 offset:1024
	ds_read_b128 v[132:135], v136 offset:2048
	ds_read_b128 v[136:139], v136 offset:3072
	ds_read_b128 v[160:163], v172
	ds_read_b128 v[164:167], v172 offset:1024
	ds_read_b128 v[168:171], v172 offset:2048
	ds_read_b128 v[178:181], v172 offset:3072
	v_lshl_add_u64 v[172:173], s[26:27], 0, v[156:157]
	s_add_i32 m0, s44, 0xc000
	ds_read_b128 v[182:185], v177
	ds_read_b128 v[186:189], v177 offset:1024
	ds_read_b128 v[204:207], v177 offset:2048
	ds_read_b128 v[208:211], v177 offset:3072
	ds_read_b128 v[212:215], v177 offset:4096
	ds_read_b128 v[216:219], v177 offset:5120
	ds_read_b128 v[220:223], v177 offset:6144
	ds_read_b128 v[224:227], v177 offset:7168
	global_load_lds_dwordx4 v[172:173], off
	v_lshl_add_u64 v[172:173], s[26:27], 0, v[158:159]
	s_add_i32 m0, s44, 0xe000
	s_nop 0
	global_load_lds_dwordx4 v[172:173], off
	s_waitcnt vmcnt(8)
	s_waitcnt lgkmcnt(0)
	s_barrier
	s_setprio 1
	s_waitcnt lgkmcnt(0)
	v_mfma_i32_16x16x64_i8 v[144:147], v[116:119], v[182:185], 0
	v_mfma_i32_16x16x64_i8 v[144:147], v[124:127], v[186:189], v[144:147]
	v_mfma_i32_16x16x64_i8 v[112:115], v[124:127], v[208:211], 0
	v_mfma_i32_16x16x64_i8 v[112:115], v[116:119], v[204:207], v[112:115]
	v_mfma_i32_16x16x64_i8 v[96:99], v[116:119], v[212:215], 0
	v_mfma_i32_16x16x64_i8 v[96:99], v[124:127], v[216:219], v[96:99]
	v_mfma_i32_16x16x64_i8 v[80:83], v[124:127], v[224:227], 0
	v_mfma_i32_16x16x64_i8 v[80:83], v[116:119], v[220:223], v[80:83]
	v_mfma_i32_16x16x64_i8 v[76:79], v[132:135], v[220:223], 0
	v_mfma_i32_16x16x64_i8 v[76:79], v[136:139], v[224:227], v[76:79]
	v_mfma_i32_16x16x64_i8 v[92:95], v[136:139], v[216:219], 0
	v_mfma_i32_16x16x64_i8 v[92:95], v[132:135], v[212:215], v[92:95]
	v_mfma_i32_16x16x64_i8 v[108:111], v[132:135], v[204:207], 0
	v_mfma_i32_16x16x64_i8 v[108:111], v[136:139], v[208:211], v[108:111]
	v_mfma_i32_16x16x64_i8 v[140:143], v[136:139], v[186:189], 0
	v_mfma_i32_16x16x64_i8 v[140:143], v[132:135], v[182:185], v[140:143]
	v_mfma_i32_16x16x64_i8 v[128:131], v[160:163], v[182:185], 0
	v_mfma_i32_16x16x64_i8 v[128:131], v[164:167], v[186:189], v[128:131]
	v_mfma_i32_16x16x64_i8 v[104:107], v[164:167], v[208:211], 0
	v_mfma_i32_16x16x64_i8 v[104:107], v[160:163], v[204:207], v[104:107]
	v_mfma_i32_16x16x64_i8 v[88:91], v[160:163], v[212:215], 0
	v_mfma_i32_16x16x64_i8 v[88:91], v[164:167], v[216:219], v[88:91]
	v_mfma_i32_16x16x64_i8 v[72:75], v[164:167], v[224:227], 0
	v_mfma_i32_16x16x64_i8 v[72:75], v[160:163], v[220:223], v[72:75]
	v_mfma_i32_16x16x64_i8 v[68:71], v[168:171], v[220:223], 0
	v_mfma_i32_16x16x64_i8 v[68:71], v[178:181], v[224:227], v[68:71]
	v_mfma_i32_16x16x64_i8 v[84:87], v[178:181], v[216:219], 0
	v_mfma_i32_16x16x64_i8 v[84:87], v[168:171], v[212:215], v[84:87]
	v_mfma_i32_16x16x64_i8 v[100:103], v[168:171], v[204:207], 0
	v_mfma_i32_16x16x64_i8 v[100:103], v[178:181], v[208:211], v[100:103]
	v_mfma_i32_16x16x64_i8 v[120:123], v[178:181], v[186:189], 0
	v_mfma_i32_16x16x64_i8 v[120:123], v[168:171], v[182:185], v[120:123]
	s_setprio 0
	s_barrier
	s_add_i32 s50, s50, s43
	v_lshl_add_u64 v[172:173], s[36:37], 0, v[2:3]
	s_mov_b32 m0, s50
	ds_read_b128 v[182:185], v177 offset:16384
	ds_read_b128 v[186:189], v177 offset:17408
	ds_read_b128 v[204:207], v177 offset:18432
	ds_read_b128 v[208:211], v177 offset:19456
	ds_read_b128 v[212:215], v177 offset:20480
	ds_read_b128 v[216:219], v177 offset:21504
	ds_read_b128 v[220:223], v177 offset:22528
	ds_read_b128 v[224:227], v177 offset:23552
	global_load_lds_dwordx4 v[172:173], off
	s_add_i32 m0, s50, 0x2000
	s_add_u32 s50, s36, 0x80000
	v_lshl_add_u64 v[190:191], s[36:37], 0, v[148:149]
	s_addc_u32 s51, s37, 0
	s_add_i32 s56, s56, s43
	global_load_lds_dwordx4 v[190:191], off
	v_lshl_add_u64 v[228:229], s[50:51], 0, v[2:3]
	s_mov_b32 m0, s56
	v_lshl_add_u64 v[240:241], s[40:41], 0, v[150:151]
	global_load_lds_dwordx4 v[228:229], off
	v_lshl_add_u64 v[228:229], s[50:51], 0, v[148:149]
	s_add_i32 m0, s56, 0x2000
	s_nop 0
	global_load_lds_dwordx4 v[228:229], off
	v_lshl_add_u64 v[228:229], s[40:41], 0, v[152:153]
	s_mov_b32 m0, s44
	s_nop 0
	global_load_lds_dwordx4 v[228:229], off
	s_mov_b32 m0, s45
	s_nop 0
	global_load_lds_dwordx4 v[240:241], off
	s_waitcnt vmcnt(8)
	s_waitcnt lgkmcnt(0)
	s_barrier
; #define PG8_STAGE(bufoff, gbase, voff) do { _Pragma("unroll") for (int _i = 0; _i < 2; ++_i) \
;         __builtin_amdgcn_global_load_lds((const unsigned*)((const char*)(gbase) + (voff)[_i]), (PG8_LAS unsigned*)(lds + (bufoff) + ldsw + _i * 8192), 16, 0, 0); } while (0)
; #define PG8_LDA(dst, b, h) do { _Pragma("unroll") for (int m = 0; m < 4; ++m) _Pragma("unroll") for (int k = 0; k < 2; ++k) dst[m][k] = *(const PG8_LAS bf16x8*)(lds + PG8_SA(b, h) + aoff + m * 2048 + k * 1024); } while (0)
; #define PG8_LDB(dst, b, h) do { _Pragma("unroll") for (int n = 0; n < 2; ++n) _Pragma("unroll") for (int k = 0; k < 2; ++k) dst[n][k] = *(const PG8_LAS bf16x8*)(lds + PG8_SB(b, h) + boff + n * 2048 + k * 1024); } while (0)
; #define PG8_WAIT_V(n) asm volatile("s_waitcnt vmcnt(" #n ")" ::: "memory")
; #define PG8_WAIT_L(n) asm volatile("s_waitcnt lgkmcnt(" #n ")" ::: "memory")
; #define PG8_BAR __builtin_amdgcn_s_barrier()
; #define PG8_SCHED __builtin_amdgcn_sched_barrier(0)
; template <class Epi, class Sched, bool ALIGN_EPI = false, bool SP2 = false, bool I8 = false>
; __device__ __forceinline__ void gemm_phase(PG8_LAS unsigned char* lds, const Gemm g, const Sched& S, const Epi& E) {
;     ...
;             PG8_WAIT_V(8); PG8_WAIT_L(0); PG8_BAR; PG8_MMA(1, 0, At, B0); PG8_MMA(1, 1, At, B1); PG8_BAR; PG8_SCHED;
;             PG8_LDB(B0, 1, 0); PG8_LDB(B1, 1, 1); PG8_SCHED; PG8_LDA(At, 1, 0); PG8_STAGE(PG8_SA(0, 1), a2 + hstep, voffA);
;             PG8_WAIT_V(8); PG8_WAIT_L(0); PG8_BAR; PG8_MMA(0, 0, At, B0); PG8_MMA(0, 1, At, B1); PG8_BAR; PG8_SCHED;
	s_setprio 1
	s_waitcnt lgkmcnt(0)
	v_mfma_i32_16x16x64_i8 v[64:67], v[116:119], v[182:185], 0
	v_mfma_i32_16x16x64_i8 v[64:67], v[124:127], v[186:189], v[64:67]
	v_mfma_i32_16x16x64_i8 v[48:51], v[124:127], v[208:211], 0
	v_mfma_i32_16x16x64_i8 v[48:51], v[116:119], v[204:207], v[48:51]
	v_mfma_i32_16x16x64_i8 v[32:35], v[116:119], v[212:215], 0
	v_mfma_i32_16x16x64_i8 v[32:35], v[124:127], v[216:219], v[32:35]
	v_mfma_i32_16x16x64_i8 v[16:19], v[124:127], v[224:227], 0
	v_mfma_i32_16x16x64_i8 v[16:19], v[116:119], v[220:223], v[16:19]
	v_mfma_i32_16x16x64_i8 v[12:15], v[132:135], v[220:223], 0
	v_mfma_i32_16x16x64_i8 v[12:15], v[136:139], v[224:227], v[12:15]
	v_mfma_i32_16x16x64_i8 v[28:31], v[136:139], v[216:219], 0
	v_mfma_i32_16x16x64_i8 v[28:31], v[132:135], v[212:215], v[28:31]
	v_mfma_i32_16x16x64_i8 v[44:47], v[132:135], v[204:207], 0
	v_mfma_i32_16x16x64_i8 v[44:47], v[136:139], v[208:211], v[44:47]
	v_mfma_i32_16x16x64_i8 v[60:63], v[136:139], v[186:189], 0
	v_mfma_i32_16x16x64_i8 v[60:63], v[132:135], v[182:185], v[60:63]
	v_mfma_i32_16x16x64_i8 v[56:59], v[160:163], v[182:185], 0
	v_mfma_i32_16x16x64_i8 v[56:59], v[164:167], v[186:189], v[56:59]
	v_mfma_i32_16x16x64_i8 v[40:43], v[164:167], v[208:211], 0
	v_mfma_i32_16x16x64_i8 v[40:43], v[160:163], v[204:207], v[40:43]
	v_mfma_i32_16x16x64_i8 v[24:27], v[160:163], v[212:215], 0
	v_mfma_i32_16x16x64_i8 v[24:27], v[164:167], v[216:219], v[24:27]
	v_mfma_i32_16x16x64_i8 v[8:11], v[164:167], v[224:227], 0
	v_mfma_i32_16x16x64_i8 v[8:11], v[160:163], v[220:223], v[8:11]
	v_mfma_i32_16x16x64_i8 v[4:7], v[168:171], v[220:223], 0
	v_mfma_i32_16x16x64_i8 v[4:7], v[178:181], v[224:227], v[4:7]
	v_mfma_i32_16x16x64_i8 v[20:23], v[178:181], v[216:219], 0
	v_mfma_i32_16x16x64_i8 v[20:23], v[168:171], v[212:215], v[20:23]
	v_mfma_i32_16x16x64_i8 v[36:39], v[168:171], v[204:207], 0
	v_mfma_i32_16x16x64_i8 v[36:39], v[178:181], v[208:211], v[36:39]
	v_mfma_i32_16x16x64_i8 v[52:55], v[178:181], v[186:189], 0
	v_mfma_i32_16x16x64_i8 v[52:55], v[168:171], v[182:185], v[52:55]
	s_setprio 0
	s_barrier
	s_add_i32 s50, 0, 0x18000
	s_add_i32 s51, 0, 0x1c000
	v_add_u32_e32 v136, s50, v175
	v_add_u32_e32 v178, s51, v175
	ds_read_b128 v[116:119], v136
	ds_read_b128 v[124:127], v136 offset:1024
	ds_read_b128 v[132:135], v136 offset:2048
	ds_read_b128 v[136:139], v136 offset:3072
	ds_read_b128 v[160:163], v178
	ds_read_b128 v[164:167], v178 offset:1024
	ds_read_b128 v[168:171], v178 offset:2048
	ds_read_b128 v[178:181], v178 offset:3072
	s_add_u32 s40, s40, 0x80000
	s_addc_u32 s41, s41, 0
	s_mov_b32 m0, s46
	v_lshl_add_u64 v[242:243], s[40:41], 0, v[152:153]
	ds_read_b128 v[182:185], v177 offset:32768
	ds_read_b128 v[186:189], v177 offset:33792
	ds_read_b128 v[204:207], v177 offset:34816
	ds_read_b128 v[208:211], v177 offset:35840
	ds_read_b128 v[212:215], v177 offset:36864
	ds_read_b128 v[216:219], v177 offset:37888
	ds_read_b128 v[220:223], v177 offset:38912
	ds_read_b128 v[224:227], v177 offset:39936
	global_load_lds_dwordx4 v[242:243], off
	v_lshl_add_u64 v[242:243], s[40:41], 0, v[150:151]
	s_mov_b32 m0, s47
	s_nop 0
	global_load_lds_dwordx4 v[242:243], off
	s_waitcnt vmcnt(8)
	s_waitcnt lgkmcnt(0)
	s_barrier
	s_setprio 1
	s_waitcnt lgkmcnt(0)
	v_mfma_i32_16x16x64_i8 v[144:147], v[116:119], v[182:185], v[144:147]
	v_mfma_i32_16x16x64_i8 v[144:147], v[124:127], v[186:189], v[144:147]
	v_mfma_i32_16x16x64_i8 v[112:115], v[124:127], v[208:211], v[112:115]
	v_mfma_i32_16x16x64_i8 v[112:115], v[116:119], v[204:207], v[112:115]
	v_mfma_i32_16x16x64_i8 v[96:99], v[116:119], v[212:215], v[96:99]
	v_mfma_i32_16x16x64_i8 v[96:99], v[124:127], v[216:219], v[96:99]
	v_mfma_i32_16x16x64_i8 v[80:83], v[124:127], v[224:227], v[80:83]
	v_mfma_i32_16x16x64_i8 v[80:83], v[116:119], v[220:223], v[80:83]
	v_mfma_i32_16x16x64_i8 v[76:79], v[132:135], v[220:223], v[76:79]
	v_mfma_i32_16x16x64_i8 v[76:79], v[136:139], v[224:227], v[76:79]
	v_mfma_i32_16x16x64_i8 v[92:95], v[136:139], v[216:219], v[92:95]
	v_mfma_i32_16x16x64_i8 v[92:95], v[132:135], v[212:215], v[92:95]
	v_mfma_i32_16x16x64_i8 v[108:111], v[132:135], v[204:207], v[108:111]
	v_mfma_i32_16x16x64_i8 v[108:111], v[136:139], v[208:211], v[108:111]
	v_mfma_i32_16x16x64_i8 v[140:143], v[136:139], v[186:189], v[140:143]
	v_mfma_i32_16x16x64_i8 v[140:143], v[132:135], v[182:185], v[140:143]
	v_mfma_i32_16x16x64_i8 v[128:131], v[160:163], v[182:185], v[128:131]
	v_mfma_i32_16x16x64_i8 v[128:131], v[164:167], v[186:189], v[128:131]
	v_mfma_i32_16x16x64_i8 v[104:107], v[164:167], v[208:211], v[104:107]
	v_mfma_i32_16x16x64_i8 v[104:107], v[160:163], v[204:207], v[104:107]
	v_mfma_i32_16x16x64_i8 v[88:91], v[160:163], v[212:215], v[88:91]
	v_mfma_i32_16x16x64_i8 v[88:91], v[164:167], v[216:219], v[88:91]
	v_mfma_i32_16x16x64_i8 v[72:75], v[164:167], v[224:227], v[72:75]
	v_mfma_i32_16x16x64_i8 v[72:75], v[160:163], v[220:223], v[72:75]
	v_mfma_i32_16x16x64_i8 v[68:71], v[168:171], v[220:223], v[68:71]
	v_mfma_i32_16x16x64_i8 v[68:71], v[178:181], v[224:227], v[68:71]
	v_mfma_i32_16x16x64_i8 v[84:87], v[178:181], v[216:219], v[84:87]
	v_mfma_i32_16x16x64_i8 v[84:87], v[168:171], v[212:215], v[84:87]
	v_mfma_i32_16x16x64_i8 v[100:103], v[168:171], v[204:207], v[100:103]
	v_mfma_i32_16x16x64_i8 v[100:103], v[178:181], v[208:211], v[100:103]
	v_mfma_i32_16x16x64_i8 v[120:123], v[178:181], v[186:189], v[120:123]
	v_mfma_i32_16x16x64_i8 v[120:123], v[168:171], v[182:185], v[120:123]
	s_setprio 0
	s_barrier
; #define PG8_STAGE(bufoff, gbase, voff) do { _Pragma("unroll") for (int _i = 0; _i < 2; ++_i) \
;         __builtin_amdgcn_global_load_lds((const unsigned*)((const char*)(gbase) + (voff)[_i]), (PG8_LAS unsigned*)(lds + (bufoff) + ldsw + _i * 8192), 16, 0, 0); } while (0)
; #define PG8_LDA(dst, b, h) do { _Pragma("unroll") for (int m = 0; m < 4; ++m) _Pragma("unroll") for (int k = 0; k < 2; ++k) dst[m][k] = *(const PG8_LAS bf16x8*)(lds + PG8_SA(b, h) + aoff + m * 2048 + k * 1024); } while (0)
; #define PG8_LDB(dst, b, h) do { _Pragma("unroll") for (int n = 0; n < 2; ++n) _Pragma("unroll") for (int k = 0; k < 2; ++k) dst[n][k] = *(const PG8_LAS bf16x8*)(lds + PG8_SB(b, h) + boff + n * 2048 + k * 1024); } while (0)
; #define PG8_WAIT_V(n) asm volatile("s_waitcnt vmcnt(" #n ")" ::: "memory")
; template <class Epi, class Sched, bool ALIGN_EPI = false, bool SP2 = false, bool I8 = false>
; __device__ __forceinline__ void gemm_phase(PG8_LAS unsigned char* lds, const Gemm g, const Sched& S, const Epi& E) {
;     ...
;             const char* a1 = cA + (size_t)(t + 1) * kstep;
;             const char* a2 = last ? nA : cA + (size_t)(t + 2) * kstep; const char* b2 = last ? nB : cB + (size_t)(t + 2) * kstep;
;             const char* a3 = a2 + kstep; const char* b3 = b2 + kstep;
;             if (last && has_next) S.a_ready(nxt);
;             if constexpr (SP2) {
;             PG8_LDB(B0, 0, 0); PG8_LDB(B1, 0, 1); PG8_SCHED; PG8_LDA(At, 0, 0); PG8_STAGE(PG8_SA(1, 1), a1 + hstep, voffA);
;             PG8_WAIT_V(8); PG8_WAIT_L(0); PG8_BAR; PG8_MMA(0, 0, At, B0); PG8_MMA(0, 1, At, B1); PG8_BAR; PG8_SCHED;
;             PG8_LDA(At, 0, 1); PG8_STAGE(PG8_SB(0, 0), b2, voffB); PG8_STAGE(PG8_SB(0, 1), b2 + hstep, voffB); PG8_STAGE(PG8_SA(0, 0), a2, voffA);
;             PG8_WAIT_V(8); PG8_WAIT_L(0); PG8_BAR; PG8_MMA(1, 0, At, B0); PG8_MMA(1, 1, At, B1); PG8_BAR; PG8_SCHED;
;             PG8_LDB(B0, 1, 0); PG8_LDB(B1, 1, 1); PG8_SCHED; PG8_LDA(At, 1, 0); PG8_STAGE(PG8_SA(0, 1), a2 + hstep, voffA);
;             PG8_WAIT_V(8); PG8_WAIT_L(0); PG8_BAR; PG8_MMA(0, 0, At, B0); PG8_MMA(0, 1, At, B1); PG8_BAR; PG8_SCHED;
;             PG8_LDA(At, 1, 1); PG8_STAGE(PG8_SB(1, 0), b3, voffB); PG8_STAGE(PG8_SB(1, 1), b3 + hstep, voffB); PG8_STAGE(PG8_SA(1, 0), a3, voffA);
;             PG8_WAIT_V(8); PG8_WAIT_L(0); PG8_BAR; PG8_MMA(1, 0, At, B0); PG8_MMA(1, 1, At, B1); PG8_BAR; PG8_SCHED;
	s_add_i32 s40, s50, s43
	v_lshl_add_u64 v[172:173], v[172:173], 0, s[84:85]
	s_mov_b32 m0, s40
	ds_read_b128 v[182:185], v177 offset:49152
	ds_read_b128 v[186:189], v177 offset:50176
	ds_read_b128 v[204:207], v177 offset:51200
	ds_read_b128 v[208:211], v177 offset:52224
	ds_read_b128 v[212:215], v177 offset:53248
	ds_read_b128 v[216:219], v177 offset:54272
	ds_read_b128 v[220:223], v177 offset:55296
	ds_read_b128 v[224:227], v177 offset:56320
	global_load_lds_dwordx4 v[172:173], off
	s_add_i32 m0, s40, 0x2000
	s_add_u32 s36, s36, 0x80080
	v_lshl_add_u64 v[172:173], v[190:191], 0, s[84:85]
	s_addc_u32 s37, s37, 0
	s_add_i32 s40, s51, s43
	global_load_lds_dwordx4 v[172:173], off
	v_lshl_add_u64 v[172:173], s[36:37], 0, v[2:3]
	s_mov_b32 m0, s40
	s_nop 0
	global_load_lds_dwordx4 v[172:173], off
	v_lshl_add_u64 v[172:173], s[36:37], 0, v[148:149]
	s_add_i32 m0, s40, 0x2000
	s_nop 0
	global_load_lds_dwordx4 v[172:173], off
	v_lshl_add_u64 v[172:173], v[228:229], 0, s[84:85]
	s_mov_b32 m0, s52
	s_nop 0
	global_load_lds_dwordx4 v[172:173], off
	v_lshl_add_u64 v[172:173], v[240:241], 0, s[84:85]
	s_mov_b32 m0, s53
	s_nop 0
	global_load_lds_dwordx4 v[172:173], off
	s_waitcnt vmcnt(8)
	s_waitcnt lgkmcnt(0)
	s_barrier
	s_setprio 1
	s_waitcnt lgkmcnt(0)
	v_mfma_i32_16x16x64_i8 v[64:67], v[116:119], v[182:185], v[64:67]
	v_mfma_i32_16x16x64_i8 v[64:67], v[124:127], v[186:189], v[64:67]
	v_mfma_i32_16x16x64_i8 v[48:51], v[124:127], v[208:211], v[48:51]
	v_mfma_i32_16x16x64_i8 v[48:51], v[116:119], v[204:207], v[48:51]
	v_mfma_i32_16x16x64_i8 v[32:35], v[116:119], v[212:215], v[32:35]
	v_mfma_i32_16x16x64_i8 v[32:35], v[124:127], v[216:219], v[32:35]
	v_mfma_i32_16x16x64_i8 v[16:19], v[124:127], v[224:227], v[16:19]
	v_mfma_i32_16x16x64_i8 v[16:19], v[116:119], v[220:223], v[16:19]
	v_mfma_i32_16x16x64_i8 v[12:15], v[132:135], v[220:223], v[12:15]
	v_mfma_i32_16x16x64_i8 v[12:15], v[136:139], v[224:227], v[12:15]
	v_mfma_i32_16x16x64_i8 v[28:31], v[136:139], v[216:219], v[28:31]
	v_mfma_i32_16x16x64_i8 v[28:31], v[132:135], v[212:215], v[28:31]
	v_mfma_i32_16x16x64_i8 v[44:47], v[132:135], v[204:207], v[44:47]
	v_mfma_i32_16x16x64_i8 v[44:47], v[136:139], v[208:211], v[44:47]
	v_mfma_i32_16x16x64_i8 v[60:63], v[136:139], v[186:189], v[60:63]
	v_mfma_i32_16x16x64_i8 v[60:63], v[132:135], v[182:185], v[60:63]
	v_mfma_i32_16x16x64_i8 v[56:59], v[160:163], v[182:185], v[56:59]
	v_mfma_i32_16x16x64_i8 v[56:59], v[164:167], v[186:189], v[56:59]
	v_mfma_i32_16x16x64_i8 v[40:43], v[164:167], v[208:211], v[40:43]
	v_mfma_i32_16x16x64_i8 v[40:43], v[160:163], v[204:207], v[40:43]
	v_mfma_i32_16x16x64_i8 v[24:27], v[160:163], v[212:215], v[24:27]
	v_mfma_i32_16x16x64_i8 v[24:27], v[164:167], v[216:219], v[24:27]
	v_mfma_i32_16x16x64_i8 v[8:11], v[164:167], v[224:227], v[8:11]
	v_mfma_i32_16x16x64_i8 v[8:11], v[160:163], v[220:223], v[8:11]
	v_mfma_i32_16x16x64_i8 v[4:7], v[168:171], v[220:223], v[4:7]
	v_mfma_i32_16x16x64_i8 v[4:7], v[178:181], v[224:227], v[4:7]
	v_mfma_i32_16x16x64_i8 v[20:23], v[178:181], v[216:219], v[20:23]
	v_mfma_i32_16x16x64_i8 v[20:23], v[168:171], v[212:215], v[20:23]
	v_mfma_i32_16x16x64_i8 v[36:39], v[168:171], v[204:207], v[36:39]
	v_mfma_i32_16x16x64_i8 v[36:39], v[178:181], v[208:211], v[36:39]
	v_mfma_i32_16x16x64_i8 v[52:55], v[178:181], v[186:189], v[52:55]
	v_mfma_i32_16x16x64_i8 v[52:55], v[168:171], v[182:185], v[52:55]
	s_setprio 0
	s_barrier
	s_add_i32 s76, s76, 2
	s_add_u32 s26, s26, 0x100
	s_addc_u32 s27, s27, 0
	s_add_u32 s72, s72, 0x100
	s_addc_u32 s73, s73, 0
	s_cmp_gt_u32 s76, 29
	s_cbranch_scc1 .Lkloop_exit_0
.LBB0_208:
	s_add_u32 s36, s26, 0xfff80080
	s_addc_u32 s37, s27, -1
	s_add_i32 s50, 0, 0x10000
	s_cmp_eq_u32 s76, 28
	s_cselect_b32 s41, s19, s37
	s_cselect_b32 s40, s64, s36
	s_cselect_b32 s37, s17, s73
	s_cselect_b32 s36, s65, s72
	s_add_i32 s56, 0, 0x14000
	v_add_u32_e32 v136, s50, v175
	v_add_u32_e32 v172, s56, v175
	ds_read_b128 v[116:119], v136
	ds_read_b128 v[124:127], v136 offset:1024
	ds_read_b128 v[132:135], v136 offset:2048
	ds_read_b128 v[136:139], v136 offset:3072
	ds_read_b128 v[160:163], v172
	ds_read_b128 v[164:167], v172 offset:1024
	ds_read_b128 v[168:171], v172 offset:2048
	ds_read_b128 v[178:181], v172 offset:3072
	v_lshl_add_u64 v[172:173], s[26:27], 0, v[156:157]
	s_add_i32 m0, s44, 0xc000
	ds_read_b128 v[182:185], v177
	ds_read_b128 v[186:189], v177 offset:1024
	ds_read_b128 v[204:207], v177 offset:2048
	ds_read_b128 v[208:211], v177 offset:3072
	ds_read_b128 v[212:215], v177 offset:4096
	ds_read_b128 v[216:219], v177 offset:5120
	ds_read_b128 v[220:223], v177 offset:6144
	ds_read_b128 v[224:227], v177 offset:7168
	global_load_lds_dwordx4 v[172:173], off
	v_lshl_add_u64 v[172:173], s[26:27], 0, v[158:159]
	s_add_i32 m0, s44, 0xe000
	s_nop 0
	global_load_lds_dwordx4 v[172:173], off
	s_waitcnt vmcnt(8)
	s_waitcnt lgkmcnt(0)
	s_barrier
; #define PG8_STAGE(bufoff, gbase, voff) do { _Pragma("unroll") for (int _i = 0; _i < 2; ++_i) \
;         __builtin_amdgcn_global_load_lds((const unsigned*)((const char*)(gbase) + (voff)[_i]), (PG8_LAS unsigned*)(lds + (bufoff) + ldsw + _i * 8192), 16, 0, 0); } while (0)
; #define PG8_LDA(dst, b, h) do { _Pragma("unroll") for (int m = 0; m < 4; ++m) _Pragma("unroll") for (int k = 0; k < 2; ++k) dst[m][k] = *(const PG8_LAS bf16x8*)(lds + PG8_SA(b, h) + aoff + m * 2048 + k * 1024); } while (0)
; #define PG8_WAIT_V(n) asm volatile("s_waitcnt vmcnt(" #n ")" ::: "memory")
; #define PG8_WAIT_L(n) asm volatile("s_waitcnt lgkmcnt(" #n ")" ::: "memory")
; #define PG8_BAR __builtin_amdgcn_s_barrier()
; #define PG8_SCHED __builtin_amdgcn_sched_barrier(0)
; template <class Epi, class Sched, bool ALIGN_EPI = false, bool SP2 = false, bool I8 = false>
; __device__ __forceinline__ void gemm_phase(PG8_LAS unsigned char* lds, const Gemm g, const Sched& S, const Epi& E) {
;     ...
;             PG8_WAIT_V(8); PG8_WAIT_L(0); PG8_BAR; PG8_MMA(0, 0, At, B0); PG8_MMA(0, 1, At, B1); PG8_BAR; PG8_SCHED;
;             PG8_LDA(At, 0, 1); PG8_STAGE(PG8_SB(0, 0), b2, voffB); PG8_STAGE(PG8_SB(0, 1), b2 + hstep, voffB); PG8_STAGE(PG8_SA(0, 0), a2, voffA);
;             PG8_WAIT_V(8); PG8_WAIT_L(0); PG8_BAR; PG8_MMA(1, 0, At, B0); PG8_MMA(1, 1, At, B1); PG8_BAR; PG8_SCHED;
	s_setprio 1
	s_waitcnt lgkmcnt(0)
	v_mfma_i32_16x16x64_i8 v[144:147], v[116:119], v[182:185], v[144:147]
	v_mfma_i32_16x16x64_i8 v[144:147], v[124:127], v[186:189], v[144:147]
	v_mfma_i32_16x16x64_i8 v[112:115], v[124:127], v[208:211], v[112:115]
	v_mfma_i32_16x16x64_i8 v[112:115], v[116:119], v[204:207], v[112:115]
	v_mfma_i32_16x16x64_i8 v[96:99], v[116:119], v[212:215], v[96:99]
	v_mfma_i32_16x16x64_i8 v[96:99], v[124:127], v[216:219], v[96:99]
	v_mfma_i32_16x16x64_i8 v[80:83], v[124:127], v[224:227], v[80:83]
	v_mfma_i32_16x16x64_i8 v[80:83], v[116:119], v[220:223], v[80:83]
	v_mfma_i32_16x16x64_i8 v[76:79], v[132:135], v[220:223], v[76:79]
	v_mfma_i32_16x16x64_i8 v[76:79], v[136:139], v[224:227], v[76:79]
	v_mfma_i32_16x16x64_i8 v[92:95], v[136:139], v[216:219], v[92:95]
	v_mfma_i32_16x16x64_i8 v[92:95], v[132:135], v[212:215], v[92:95]
	v_mfma_i32_16x16x64_i8 v[108:111], v[132:135], v[204:207], v[108:111]
	v_mfma_i32_16x16x64_i8 v[108:111], v[136:139], v[208:211], v[108:111]
	v_mfma_i32_16x16x64_i8 v[140:143], v[136:139], v[186:189], v[140:143]
	v_mfma_i32_16x16x64_i8 v[140:143], v[132:135], v[182:185], v[140:143]
	v_mfma_i32_16x16x64_i8 v[128:131], v[160:163], v[182:185], v[128:131]
	v_mfma_i32_16x16x64_i8 v[128:131], v[164:167], v[186:189], v[128:131]
	v_mfma_i32_16x16x64_i8 v[104:107], v[164:167], v[208:211], v[104:107]
	v_mfma_i32_16x16x64_i8 v[104:107], v[160:163], v[204:207], v[104:107]
	v_mfma_i32_16x16x64_i8 v[88:91], v[160:163], v[212:215], v[88:91]
	v_mfma_i32_16x16x64_i8 v[88:91], v[164:167], v[216:219], v[88:91]
	v_mfma_i32_16x16x64_i8 v[72:75], v[164:167], v[224:227], v[72:75]
	v_mfma_i32_16x16x64_i8 v[72:75], v[160:163], v[220:223], v[72:75]
	v_mfma_i32_16x16x64_i8 v[68:71], v[168:171], v[220:223], v[68:71]
	v_mfma_i32_16x16x64_i8 v[68:71], v[178:181], v[224:227], v[68:71]
	v_mfma_i32_16x16x64_i8 v[84:87], v[178:181], v[216:219], v[84:87]
	v_mfma_i32_16x16x64_i8 v[84:87], v[168:171], v[212:215], v[84:87]
	v_mfma_i32_16x16x64_i8 v[100:103], v[168:171], v[204:207], v[100:103]
	v_mfma_i32_16x16x64_i8 v[100:103], v[178:181], v[208:211], v[100:103]
	v_mfma_i32_16x16x64_i8 v[120:123], v[178:181], v[186:189], v[120:123]
	v_mfma_i32_16x16x64_i8 v[120:123], v[168:171], v[182:185], v[120:123]
	s_setprio 0
	s_barrier
	s_add_i32 s50, s50, s43
	v_lshl_add_u64 v[172:173], s[36:37], 0, v[2:3]
	s_mov_b32 m0, s50
	ds_read_b128 v[182:185], v177 offset:16384
	ds_read_b128 v[186:189], v177 offset:17408
	ds_read_b128 v[204:207], v177 offset:18432
	ds_read_b128 v[208:211], v177 offset:19456
	ds_read_b128 v[212:215], v177 offset:20480
	ds_read_b128 v[216:219], v177 offset:21504
	ds_read_b128 v[220:223], v177 offset:22528
	ds_read_b128 v[224:227], v177 offset:23552
	global_load_lds_dwordx4 v[172:173], off
	s_add_i32 m0, s50, 0x2000
	s_add_u32 s50, s36, 0x80000
	v_lshl_add_u64 v[190:191], s[36:37], 0, v[148:149]
	s_addc_u32 s51, s37, 0
	s_add_i32 s56, s56, s43
	global_load_lds_dwordx4 v[190:191], off
	v_lshl_add_u64 v[228:229], s[50:51], 0, v[2:3]
	s_mov_b32 m0, s56
	v_lshl_add_u64 v[240:241], s[40:41], 0, v[150:151]
	global_load_lds_dwordx4 v[228:229], off
	v_lshl_add_u64 v[228:229], s[50:51], 0, v[148:149]
	s_add_i32 m0, s56, 0x2000
	s_nop 0
	global_load_lds_dwordx4 v[228:229], off
	v_lshl_add_u64 v[228:229], s[40:41], 0, v[152:153]
	s_mov_b32 m0, s44
	s_nop 0
	global_load_lds_dwordx4 v[228:229], off
	s_mov_b32 m0, s45
	s_nop 0
	global_load_lds_dwordx4 v[240:241], off
	s_waitcnt vmcnt(8)
	s_waitcnt lgkmcnt(0)
	s_barrier
	s_setprio 1
	s_waitcnt lgkmcnt(0)
	v_mfma_i32_16x16x64_i8 v[64:67], v[116:119], v[182:185], v[64:67]
	v_mfma_i32_16x16x64_i8 v[64:67], v[124:127], v[186:189], v[64:67]
	v_mfma_i32_16x16x64_i8 v[48:51], v[124:127], v[208:211], v[48:51]
	v_mfma_i32_16x16x64_i8 v[48:51], v[116:119], v[204:207], v[48:51]
	v_mfma_i32_16x16x64_i8 v[32:35], v[116:119], v[212:215], v[32:35]
	v_mfma_i32_16x16x64_i8 v[32:35], v[124:127], v[216:219], v[32:35]
	v_mfma_i32_16x16x64_i8 v[16:19], v[124:127], v[224:227], v[16:19]
	v_mfma_i32_16x16x64_i8 v[16:19], v[116:119], v[220:223], v[16:19]
	v_mfma_i32_16x16x64_i8 v[12:15], v[132:135], v[220:223], v[12:15]
	v_mfma_i32_16x16x64_i8 v[12:15], v[136:139], v[224:227], v[12:15]
	v_mfma_i32_16x16x64_i8 v[28:31], v[136:139], v[216:219], v[28:31]
	v_mfma_i32_16x16x64_i8 v[28:31], v[132:135], v[212:215], v[28:31]
	v_mfma_i32_16x16x64_i8 v[44:47], v[132:135], v[204:207], v[44:47]
	v_mfma_i32_16x16x64_i8 v[44:47], v[136:139], v[208:211], v[44:47]
	v_mfma_i32_16x16x64_i8 v[60:63], v[136:139], v[186:189], v[60:63]
	v_mfma_i32_16x16x64_i8 v[60:63], v[132:135], v[182:185], v[60:63]
	v_mfma_i32_16x16x64_i8 v[56:59], v[160:163], v[182:185], v[56:59]
	v_mfma_i32_16x16x64_i8 v[56:59], v[164:167], v[186:189], v[56:59]
	v_mfma_i32_16x16x64_i8 v[40:43], v[164:167], v[208:211], v[40:43]
	v_mfma_i32_16x16x64_i8 v[40:43], v[160:163], v[204:207], v[40:43]
	v_mfma_i32_16x16x64_i8 v[24:27], v[160:163], v[212:215], v[24:27]
	v_mfma_i32_16x16x64_i8 v[24:27], v[164:167], v[216:219], v[24:27]
	v_mfma_i32_16x16x64_i8 v[8:11], v[164:167], v[224:227], v[8:11]
	v_mfma_i32_16x16x64_i8 v[8:11], v[160:163], v[220:223], v[8:11]
	v_mfma_i32_16x16x64_i8 v[4:7], v[168:171], v[220:223], v[4:7]
	v_mfma_i32_16x16x64_i8 v[4:7], v[178:181], v[224:227], v[4:7]
	v_mfma_i32_16x16x64_i8 v[20:23], v[178:181], v[216:219], v[20:23]
	v_mfma_i32_16x16x64_i8 v[20:23], v[168:171], v[212:215], v[20:23]
	v_mfma_i32_16x16x64_i8 v[36:39], v[168:171], v[204:207], v[36:39]
	v_mfma_i32_16x16x64_i8 v[36:39], v[178:181], v[208:211], v[36:39]
	v_mfma_i32_16x16x64_i8 v[52:55], v[178:181], v[186:189], v[52:55]
	v_mfma_i32_16x16x64_i8 v[52:55], v[168:171], v[182:185], v[52:55]
	s_setprio 0
	s_barrier
; #define PG8_STAGE(bufoff, gbase, voff) do { _Pragma("unroll") for (int _i = 0; _i < 2; ++_i) \
;         __builtin_amdgcn_global_load_lds((const unsigned*)((const char*)(gbase) + (voff)[_i]), (PG8_LAS unsigned*)(lds + (bufoff) + ldsw + _i * 8192), 16, 0, 0); } while (0)
; #define PG8_LDA(dst, b, h) do { _Pragma("unroll") for (int m = 0; m < 4; ++m) _Pragma("unroll") for (int k = 0; k < 2; ++k) dst[m][k] = *(const PG8_LAS bf16x8*)(lds + PG8_SA(b, h) + aoff + m * 2048 + k * 1024); } while (0)
; #define PG8_LDB(dst, b, h) do { _Pragma("unroll") for (int n = 0; n < 2; ++n) _Pragma("unroll") for (int k = 0; k < 2; ++k) dst[n][k] = *(const PG8_LAS bf16x8*)(lds + PG8_SB(b, h) + boff + n * 2048 + k * 1024); } while (0)
; #define PG8_WAIT_V(n) asm volatile("s_waitcnt vmcnt(" #n ")" ::: "memory")
; #define PG8_WAIT_L(n) asm volatile("s_waitcnt lgkmcnt(" #n ")" ::: "memory")
; #define PG8_BAR __builtin_amdgcn_s_barrier()
; #define PG8_SCHED __builtin_amdgcn_sched_barrier(0)
; template <class Epi, class Sched, bool ALIGN_EPI = false, bool SP2 = false, bool I8 = false>
; __device__ __forceinline__ void gemm_phase(PG8_LAS unsigned char* lds, const Gemm g, const Sched& S, const Epi& E) {
;     ...
;             PG8_LDB(B0, 1, 0); PG8_LDB(B1, 1, 1); PG8_SCHED; PG8_LDA(At, 1, 0); PG8_STAGE(PG8_SA(0, 1), a2 + hstep, voffA);
;             PG8_WAIT_V(8); PG8_WAIT_L(0); PG8_BAR; PG8_MMA(0, 0, At, B0); PG8_MMA(0, 1, At, B1); PG8_BAR; PG8_SCHED;
;             PG8_LDA(At, 1, 1); PG8_STAGE(PG8_SB(1, 0), b3, voffB); PG8_STAGE(PG8_SB(1, 1), b3 + hstep, voffB); PG8_STAGE(PG8_SA(1, 0), a3, voffA);
;             PG8_WAIT_V(8); PG8_WAIT_L(0); PG8_BAR; PG8_MMA(1, 0, At, B0); PG8_MMA(1, 1, At, B1); PG8_BAR; PG8_SCHED;
	s_add_i32 s50, 0, 0x18000
	s_add_i32 s51, 0, 0x1c000
	v_add_u32_e32 v136, s50, v175
	v_add_u32_e32 v178, s51, v175
	ds_read_b128 v[116:119], v136
	ds_read_b128 v[124:127], v136 offset:1024
	ds_read_b128 v[132:135], v136 offset:2048
	ds_read_b128 v[136:139], v136 offset:3072
	ds_read_b128 v[160:163], v178
	ds_read_b128 v[164:167], v178 offset:1024
	ds_read_b128 v[168:171], v178 offset:2048
	ds_read_b128 v[178:181], v178 offset:3072
	s_add_u32 s40, s40, 0x80000
	s_addc_u32 s41, s41, 0
	s_mov_b32 m0, s46
	v_lshl_add_u64 v[242:243], s[40:41], 0, v[152:153]
	ds_read_b128 v[182:185], v177 offset:32768
	ds_read_b128 v[186:189], v177 offset:33792
	ds_read_b128 v[204:207], v177 offset:34816
	ds_read_b128 v[208:211], v177 offset:35840
	ds_read_b128 v[212:215], v177 offset:36864
	ds_read_b128 v[216:219], v177 offset:37888
	ds_read_b128 v[220:223], v177 offset:38912
	ds_read_b128 v[224:227], v177 offset:39936
	global_load_lds_dwordx4 v[242:243], off
	v_lshl_add_u64 v[242:243], s[40:41], 0, v[150:151]
	s_mov_b32 m0, s47
	s_nop 0
	global_load_lds_dwordx4 v[242:243], off
	s_waitcnt vmcnt(8)
	s_waitcnt lgkmcnt(0)
	s_barrier
	s_setprio 1
	s_waitcnt lgkmcnt(0)
	v_mfma_i32_16x16x64_i8 v[144:147], v[116:119], v[182:185], v[144:147]
	v_mfma_i32_16x16x64_i8 v[144:147], v[124:127], v[186:189], v[144:147]
	v_mfma_i32_16x16x64_i8 v[112:115], v[124:127], v[208:211], v[112:115]
	v_mfma_i32_16x16x64_i8 v[112:115], v[116:119], v[204:207], v[112:115]
	v_mfma_i32_16x16x64_i8 v[96:99], v[116:119], v[212:215], v[96:99]
	v_mfma_i32_16x16x64_i8 v[96:99], v[124:127], v[216:219], v[96:99]
	v_mfma_i32_16x16x64_i8 v[80:83], v[124:127], v[224:227], v[80:83]
	v_mfma_i32_16x16x64_i8 v[80:83], v[116:119], v[220:223], v[80:83]
	v_mfma_i32_16x16x64_i8 v[76:79], v[132:135], v[220:223], v[76:79]
	v_mfma_i32_16x16x64_i8 v[76:79], v[136:139], v[224:227], v[76:79]
	v_mfma_i32_16x16x64_i8 v[92:95], v[136:139], v[216:219], v[92:95]
	v_mfma_i32_16x16x64_i8 v[92:95], v[132:135], v[212:215], v[92:95]
	v_mfma_i32_16x16x64_i8 v[108:111], v[132:135], v[204:207], v[108:111]
	v_mfma_i32_16x16x64_i8 v[108:111], v[136:139], v[208:211], v[108:111]
	v_mfma_i32_16x16x64_i8 v[140:143], v[136:139], v[186:189], v[140:143]
	v_mfma_i32_16x16x64_i8 v[140:143], v[132:135], v[182:185], v[140:143]
	v_mfma_i32_16x16x64_i8 v[128:131], v[160:163], v[182:185], v[128:131]
	v_mfma_i32_16x16x64_i8 v[128:131], v[164:167], v[186:189], v[128:131]
	v_mfma_i32_16x16x64_i8 v[104:107], v[164:167], v[208:211], v[104:107]
	v_mfma_i32_16x16x64_i8 v[104:107], v[160:163], v[204:207], v[104:107]
	v_mfma_i32_16x16x64_i8 v[88:91], v[160:163], v[212:215], v[88:91]
	v_mfma_i32_16x16x64_i8 v[88:91], v[164:167], v[216:219], v[88:91]
	v_mfma_i32_16x16x64_i8 v[72:75], v[164:167], v[224:227], v[72:75]
	v_mfma_i32_16x16x64_i8 v[72:75], v[160:163], v[220:223], v[72:75]
	v_mfma_i32_16x16x64_i8 v[68:71], v[168:171], v[220:223], v[68:71]
	v_mfma_i32_16x16x64_i8 v[68:71], v[178:181], v[224:227], v[68:71]
	v_mfma_i32_16x16x64_i8 v[84:87], v[178:181], v[216:219], v[84:87]
	v_mfma_i32_16x16x64_i8 v[84:87], v[168:171], v[212:215], v[84:87]
	v_mfma_i32_16x16x64_i8 v[100:103], v[168:171], v[204:207], v[100:103]
	v_mfma_i32_16x16x64_i8 v[100:103], v[178:181], v[208:211], v[100:103]
	v_mfma_i32_16x16x64_i8 v[120:123], v[178:181], v[186:189], v[120:123]
	v_mfma_i32_16x16x64_i8 v[120:123], v[168:171], v[182:185], v[120:123]
	s_setprio 0
	s_barrier
	s_add_i32 s40, s50, s43
	v_lshl_add_u64 v[172:173], v[172:173], 0, s[84:85]
	s_mov_b32 m0, s40
	ds_read_b128 v[182:185], v177 offset:49152
	ds_read_b128 v[186:189], v177 offset:50176
	ds_read_b128 v[204:207], v177 offset:51200
	ds_read_b128 v[208:211], v177 offset:52224
	ds_read_b128 v[212:215], v177 offset:53248
	ds_read_b128 v[216:219], v177 offset:54272
	ds_read_b128 v[220:223], v177 offset:55296
	ds_read_b128 v[224:227], v177 offset:56320
	global_load_lds_dwordx4 v[172:173], off
	s_add_i32 m0, s40, 0x2000
	s_add_u32 s36, s36, 0x80080
	v_lshl_add_u64 v[172:173], v[190:191], 0, s[84:85]
	s_addc_u32 s37, s37, 0
	s_add_i32 s40, s51, s43
	global_load_lds_dwordx4 v[172:173], off
	v_lshl_add_u64 v[172:173], s[36:37], 0, v[2:3]
	s_mov_b32 m0, s40
	s_nop 0
	global_load_lds_dwordx4 v[172:173], off
	v_lshl_add_u64 v[172:173], s[36:37], 0, v[148:149]
	s_add_i32 m0, s40, 0x2000
	s_nop 0
	global_load_lds_dwordx4 v[172:173], off
	v_lshl_add_u64 v[172:173], v[228:229], 0, s[84:85]
	s_mov_b32 m0, s52
	s_nop 0
	global_load_lds_dwordx4 v[172:173], off
	v_lshl_add_u64 v[172:173], v[240:241], 0, s[84:85]
	s_mov_b32 m0, s53
	s_nop 0
	global_load_lds_dwordx4 v[172:173], off
	s_waitcnt vmcnt(8)
	s_waitcnt lgkmcnt(0)
	s_barrier
	s_setprio 1
	s_waitcnt lgkmcnt(0)
	v_mfma_i32_16x16x64_i8 v[64:67], v[116:119], v[182:185], v[64:67]
	v_mfma_i32_16x16x64_i8 v[64:67], v[124:127], v[186:189], v[64:67]
	v_mfma_i32_16x16x64_i8 v[48:51], v[124:127], v[208:211], v[48:51]
	v_mfma_i32_16x16x64_i8 v[48:51], v[116:119], v[204:207], v[48:51]
	v_mfma_i32_16x16x64_i8 v[32:35], v[116:119], v[212:215], v[32:35]
	v_mfma_i32_16x16x64_i8 v[32:35], v[124:127], v[216:219], v[32:35]
	v_mfma_i32_16x16x64_i8 v[16:19], v[124:127], v[224:227], v[16:19]
	v_mfma_i32_16x16x64_i8 v[16:19], v[116:119], v[220:223], v[16:19]
	v_mfma_i32_16x16x64_i8 v[12:15], v[132:135], v[220:223], v[12:15]
	v_mfma_i32_16x16x64_i8 v[12:15], v[136:139], v[224:227], v[12:15]
	v_mfma_i32_16x16x64_i8 v[28:31], v[136:139], v[216:219], v[28:31]
	v_mfma_i32_16x16x64_i8 v[28:31], v[132:135], v[212:215], v[28:31]
	v_mfma_i32_16x16x64_i8 v[44:47], v[132:135], v[204:207], v[44:47]
	v_mfma_i32_16x16x64_i8 v[44:47], v[136:139], v[208:211], v[44:47]
	v_mfma_i32_16x16x64_i8 v[60:63], v[136:139], v[186:189], v[60:63]
	v_mfma_i32_16x16x64_i8 v[60:63], v[132:135], v[182:185], v[60:63]
	v_mfma_i32_16x16x64_i8 v[56:59], v[160:163], v[182:185], v[56:59]
	v_mfma_i32_16x16x64_i8 v[56:59], v[164:167], v[186:189], v[56:59]
	v_mfma_i32_16x16x64_i8 v[40:43], v[164:167], v[208:211], v[40:43]
	v_mfma_i32_16x16x64_i8 v[40:43], v[160:163], v[204:207], v[40:43]
	v_mfma_i32_16x16x64_i8 v[24:27], v[160:163], v[212:215], v[24:27]
	v_mfma_i32_16x16x64_i8 v[24:27], v[164:167], v[216:219], v[24:27]
	v_mfma_i32_16x16x64_i8 v[8:11], v[164:167], v[224:227], v[8:11]
	v_mfma_i32_16x16x64_i8 v[8:11], v[160:163], v[220:223], v[8:11]
	v_mfma_i32_16x16x64_i8 v[4:7], v[168:171], v[220:223], v[4:7]
	v_mfma_i32_16x16x64_i8 v[4:7], v[178:181], v[224:227], v[4:7]
	v_mfma_i32_16x16x64_i8 v[20:23], v[178:181], v[216:219], v[20:23]
	v_mfma_i32_16x16x64_i8 v[20:23], v[168:171], v[212:215], v[20:23]
	v_mfma_i32_16x16x64_i8 v[36:39], v[168:171], v[204:207], v[36:39]
	v_mfma_i32_16x16x64_i8 v[36:39], v[178:181], v[208:211], v[36:39]
	v_mfma_i32_16x16x64_i8 v[52:55], v[178:181], v[186:189], v[52:55]
	v_mfma_i32_16x16x64_i8 v[52:55], v[168:171], v[182:185], v[52:55]
	s_setprio 0
	s_barrier
	s_add_i32 s76, s76, 2
	s_add_u32 s26, s26, 0x100
	s_addc_u32 s27, s27, 0
	s_add_u32 s72, s72, 0x100
	s_addc_u32 s73, s73, 0
	s_cmp_gt_u32 s76, 29
	s_cbranch_scc0 .LBB0_208

; #define PG8_STAGE(bufoff, gbase, voff) do { _Pragma("unroll") for (int _i = 0; _i < 2; ++_i) \
;         __builtin_amdgcn_global_load_lds((const unsigned*)((const char*)(gbase) + (voff)[_i]), (PG8_LAS unsigned*)(lds + (bufoff) + ldsw + _i * 8192), 16, 0, 0); } while (0)
; #define PG8_LDA(dst, b, h) do { _Pragma("unroll") for (int m = 0; m < 4; ++m) _Pragma("unroll") for (int k = 0; k < 2; ++k) dst[m][k] = *(const PG8_LAS bf16x8*)(lds + PG8_SA(b, h) + aoff + m * 2048 + k * 1024); } while (0)
; #define PG8_LDB(dst, b, h) do { _Pragma("unroll") for (int n = 0; n < 2; ++n) _Pragma("unroll") for (int k = 0; k < 2; ++k) dst[n][k] = *(const PG8_LAS bf16x8*)(lds + PG8_SB(b, h) + boff + n * 2048 + k * 1024); } while (0)
; #define PG8_WAIT_V(n) asm volatile("s_waitcnt vmcnt(" #n ")" ::: "memory")
; #define PG8_WAIT_L(n) asm volatile("s_waitcnt lgkmcnt(" #n ")" ::: "memory")
; #define PG8_BAR __builtin_amdgcn_s_barrier()
; #define PG8_SCHED __builtin_amdgcn_sched_barrier(0)
; template <class Epi, class Sched, bool ALIGN_EPI = false, bool SP2 = false, bool I8 = false>
; __device__ __forceinline__ void gemm_phase(PG8_LAS unsigned char* lds, const Gemm g, const Sched& S, const Epi& E) {
;     ...
;         const bool has_next = S.next(ui + 1, nxt);
;         const char* nA = has_next ? (const char*)g.A + (size_t)nxt.pm * tstep : cA; const char* nB = has_next ? (const char*)g.Bt + (size_t)nxt.pn * tstep : cB;
;         for (int t = 0; t < nt; t += 2) {
;             const bool last = (t == nt - 2);
;             const char* a1 = cA + (size_t)(t + 1) * kstep;
;             const char* a2 = last ? nA : cA + (size_t)(t + 2) * kstep; const char* b2 = last ? nB : cB + (size_t)(t + 2) * kstep;
;             const char* a3 = a2 + kstep; const char* b3 = b2 + kstep;
;             if (last && has_next) S.a_ready(nxt);
;             if constexpr (SP2) {
;             PG8_LDB(B0, 0, 0); PG8_LDB(B1, 0, 1); PG8_SCHED; PG8_LDA(At, 0, 0); PG8_STAGE(PG8_SA(1, 1), a1 + hstep, voffA);
;             PG8_WAIT_V(8); PG8_WAIT_L(0); PG8_BAR; PG8_MMA(0, 0, At, B0); PG8_MMA(0, 1, At, B1); PG8_BAR; PG8_SCHED;
;             PG8_LDA(At, 0, 1); PG8_STAGE(PG8_SB(0, 0), b2, voffB); PG8_STAGE(PG8_SB(0, 1), b2 + hstep, voffB); PG8_STAGE(PG8_SA(0, 0), a2, voffA);
;             PG8_WAIT_V(8); PG8_WAIT_L(0); PG8_BAR; PG8_MMA(1, 0, At, B0); PG8_MMA(1, 1, At, B1); PG8_BAR; PG8_SCHED;
.LBB0_229:
	s_ashr_i32 s37, s36, 31
	s_lshl_b64 s[34:35], s[36:37], 21
	s_add_u32 s40, s42, s34
	s_addc_u32 s41, s43, s35
	s_and_b64 s[34:35], s[8:9], exec
	s_cselect_b32 s11, s41, s13
	s_cselect_b32 s34, s40, s12
	s_ashr_i32 s27, s26, 31
	s_lshl_b64 s[50:51], s[26:27], 21
	s_add_u32 s54, s44, s50
	s_addc_u32 s55, s45, s51
	s_and_b64 s[50:51], s[8:9], exec
	s_cselect_b32 s27, s55, s73
	s_cselect_b32 s35, s54, s72
	s_add_u32 s12, s12, 0x100080
	s_addc_u32 s13, s13, 0
	s_add_u32 s37, s72, 0x100
	s_addc_u32 s61, s73, 0
	s_mov_b32 s97, -2
	s_add_u32 s50, s12, 0xfff00080
	s_addc_u32 s51, s13, -1
	s_add_i32 s56, 0, 0x10000
	s_cmp_eq_u32 s97, 60
	s_cselect_b32 s77, s11, s51
	s_cselect_b32 s76, s34, s50
	s_cselect_b32 s73, s27, s61
	s_cselect_b32 s72, s35, s37
	s_add_i32 s57, 0, 0x14000
	v_add_u32_e32 v156, s56, v171
	v_add_u32_e32 v168, s57, v171
	s_waitcnt vmcnt(0)
	ds_read_b128 v[112:115], v156
	ds_read_b128 v[120:123], v156 offset:1024
	ds_read_b128 v[152:155], v156 offset:2048
	ds_read_b128 v[156:159], v156 offset:3072
	ds_read_b128 v[160:163], v168
	ds_read_b128 v[164:167], v168 offset:1024
	s_waitcnt lgkmcnt(0)
	ds_read_b128 v[176:179], v168 offset:2048
	ds_read_b128 v[180:183], v168 offset:3072
	v_lshl_add_u64 v[168:169], s[12:13], 0, v[148:149]
	s_add_i32 m0, s47, 0xc000
	ds_read_b128 v[184:187], v173
	ds_read_b128 v[188:191], v173 offset:1024
	ds_read_b128 v[204:207], v173 offset:2048
	ds_read_b128 v[208:211], v173 offset:3072
	ds_read_b128 v[212:215], v173 offset:4096
	ds_read_b128 v[216:219], v173 offset:5120
	ds_read_b128 v[220:223], v173 offset:6144
	ds_read_b128 v[224:227], v173 offset:7168
	global_load_lds_dwordx4 v[168:169], off
	v_lshl_add_u64 v[168:169], s[12:13], 0, v[150:151]
	s_add_i32 m0, s47, 0xe000
	s_nop 0
	global_load_lds_dwordx4 v[168:169], off
	s_waitcnt vmcnt(8)
	s_waitcnt lgkmcnt(0)
	s_barrier
	s_setprio 1
	s_waitcnt lgkmcnt(0)
	v_mfma_f32_16x16x32_bf16 v[136:139], v[112:115], v[184:187], 0
	v_mfma_f32_16x16x32_bf16 v[136:139], v[120:123], v[188:191], v[136:139]
	v_mfma_f32_16x16x32_bf16 v[116:119], v[120:123], v[208:211], 0
	v_mfma_f32_16x16x32_bf16 v[116:119], v[112:115], v[204:207], v[116:119]
	v_mfma_f32_16x16x32_bf16 v[96:99], v[112:115], v[212:215], 0
	v_mfma_f32_16x16x32_bf16 v[96:99], v[120:123], v[216:219], v[96:99]
	v_mfma_f32_16x16x32_bf16 v[80:83], v[120:123], v[224:227], 0
	v_mfma_f32_16x16x32_bf16 v[80:83], v[112:115], v[220:223], v[80:83]
	v_mfma_f32_16x16x32_bf16 v[76:79], v[152:155], v[220:223], 0
	v_mfma_f32_16x16x32_bf16 v[76:79], v[156:159], v[224:227], v[76:79]
	v_mfma_f32_16x16x32_bf16 v[92:95], v[156:159], v[216:219], 0
	v_mfma_f32_16x16x32_bf16 v[92:95], v[152:155], v[212:215], v[92:95]
	v_mfma_f32_16x16x32_bf16 v[108:111], v[152:155], v[204:207], 0
	v_mfma_f32_16x16x32_bf16 v[108:111], v[156:159], v[208:211], v[108:111]
	v_mfma_f32_16x16x32_bf16 v[132:135], v[156:159], v[188:191], 0
	v_mfma_f32_16x16x32_bf16 v[132:135], v[152:155], v[184:187], v[132:135]
	v_mfma_f32_16x16x32_bf16 v[128:131], v[160:163], v[184:187], 0
	v_mfma_f32_16x16x32_bf16 v[128:131], v[164:167], v[188:191], v[128:131]
	v_mfma_f32_16x16x32_bf16 v[104:107], v[164:167], v[208:211], 0
	v_mfma_f32_16x16x32_bf16 v[104:107], v[160:163], v[204:207], v[104:107]
	v_mfma_f32_16x16x32_bf16 v[88:91], v[160:163], v[212:215], 0
	v_mfma_f32_16x16x32_bf16 v[88:91], v[164:167], v[216:219], v[88:91]
	v_mfma_f32_16x16x32_bf16 v[72:75], v[164:167], v[224:227], 0
	v_mfma_f32_16x16x32_bf16 v[72:75], v[160:163], v[220:223], v[72:75]
	v_mfma_f32_16x16x32_bf16 v[68:71], v[176:179], v[220:223], 0
	v_mfma_f32_16x16x32_bf16 v[68:71], v[180:183], v[224:227], v[68:71]
	v_mfma_f32_16x16x32_bf16 v[84:87], v[180:183], v[216:219], 0
	v_mfma_f32_16x16x32_bf16 v[84:87], v[176:179], v[212:215], v[84:87]
	v_mfma_f32_16x16x32_bf16 v[100:103], v[176:179], v[204:207], 0
	v_mfma_f32_16x16x32_bf16 v[100:103], v[180:183], v[208:211], v[100:103]
	v_mfma_f32_16x16x32_bf16 v[124:127], v[180:183], v[188:191], 0
	v_mfma_f32_16x16x32_bf16 v[124:127], v[176:179], v[184:187], v[124:127]
	s_setprio 0
	s_barrier
	s_add_i32 s50, s56, s46
	v_lshl_add_u64 v[168:169], s[72:73], 0, v[2:3]
	s_mov_b32 m0, s50
	ds_read_b128 v[184:187], v173 offset:16384
	ds_read_b128 v[188:191], v173 offset:17408
	ds_read_b128 v[204:207], v173 offset:18432
	ds_read_b128 v[208:211], v173 offset:19456
	ds_read_b128 v[212:215], v173 offset:20480
	ds_read_b128 v[216:219], v173 offset:21504
	ds_read_b128 v[220:223], v173 offset:22528
	ds_read_b128 v[224:227], v173 offset:23552
	global_load_lds_dwordx4 v[168:169], off
	s_add_i32 m0, s50, 0x2000
	s_add_u32 s50, s72, 0x100000
	v_lshl_add_u64 v[228:229], s[72:73], 0, v[144:145]
	s_addc_u32 s51, s73, 0
	s_add_i32 s56, s57, s46
	global_load_lds_dwordx4 v[228:229], off
	v_lshl_add_u64 v[240:241], s[50:51], 0, v[2:3]
	s_mov_b32 m0, s56
	v_lshl_add_u64 v[242:243], s[76:77], 0, v[142:143]
	global_load_lds_dwordx4 v[240:241], off
	v_lshl_add_u64 v[240:241], s[50:51], 0, v[144:145]
	s_add_i32 m0, s56, 0x2000
	s_nop 0
	global_load_lds_dwordx4 v[240:241], off
	v_lshl_add_u64 v[240:241], s[76:77], 0, v[140:141]
	s_mov_b32 m0, s47
	s_nop 0
	global_load_lds_dwordx4 v[240:241], off
	s_mov_b32 m0, s52
	s_nop 0
	global_load_lds_dwordx4 v[242:243], off
	s_waitcnt vmcnt(8)
	s_waitcnt lgkmcnt(0)
	s_barrier
; #define PG8_STAGE(bufoff, gbase, voff) do { _Pragma("unroll") for (int _i = 0; _i < 2; ++_i) \
;         __builtin_amdgcn_global_load_lds((const unsigned*)((const char*)(gbase) + (voff)[_i]), (PG8_LAS unsigned*)(lds + (bufoff) + ldsw + _i * 8192), 16, 0, 0); } while (0)
; #define PG8_LDA(dst, b, h) do { _Pragma("unroll") for (int m = 0; m < 4; ++m) _Pragma("unroll") for (int k = 0; k < 2; ++k) dst[m][k] = *(const PG8_LAS bf16x8*)(lds + PG8_SA(b, h) + aoff + m * 2048 + k * 1024); } while (0)
; #define PG8_LDB(dst, b, h) do { _Pragma("unroll") for (int n = 0; n < 2; ++n) _Pragma("unroll") for (int k = 0; k < 2; ++k) dst[n][k] = *(const PG8_LAS bf16x8*)(lds + PG8_SB(b, h) + boff + n * 2048 + k * 1024); } while (0)
; #define PG8_WAIT_V(n) asm volatile("s_waitcnt vmcnt(" #n ")" ::: "memory")
; #define PG8_WAIT_L(n) asm volatile("s_waitcnt lgkmcnt(" #n ")" ::: "memory")
; #define PG8_BAR __builtin_amdgcn_s_barrier()
; #define PG8_SCHED __builtin_amdgcn_sched_barrier(0)
; template <class Epi, class Sched, bool ALIGN_EPI = false, bool SP2 = false, bool I8 = false>
; __device__ __forceinline__ void gemm_phase(PG8_LAS unsigned char* lds, const Gemm g, const Sched& S, const Epi& E) {
;     ...
;             PG8_WAIT_V(8); PG8_WAIT_L(0); PG8_BAR; PG8_MMA(1, 0, At, B0); PG8_MMA(1, 1, At, B1); PG8_BAR; PG8_SCHED;
;             PG8_LDB(B0, 1, 0); PG8_LDB(B1, 1, 1); PG8_SCHED; PG8_LDA(At, 1, 0); PG8_STAGE(PG8_SA(0, 1), a2 + hstep, voffA);
;             PG8_WAIT_V(8); PG8_WAIT_L(0); PG8_BAR; PG8_MMA(0, 0, At, B0); PG8_MMA(0, 1, At, B1); PG8_BAR; PG8_SCHED;
	s_setprio 1
	s_waitcnt lgkmcnt(0)
	v_mfma_f32_16x16x32_bf16 v[64:67], v[112:115], v[184:187], 0
	v_mfma_f32_16x16x32_bf16 v[64:67], v[120:123], v[188:191], v[64:67]
	v_mfma_f32_16x16x32_bf16 v[48:51], v[120:123], v[208:211], 0
	v_mfma_f32_16x16x32_bf16 v[48:51], v[112:115], v[204:207], v[48:51]
	v_mfma_f32_16x16x32_bf16 v[32:35], v[112:115], v[212:215], 0
	v_mfma_f32_16x16x32_bf16 v[32:35], v[120:123], v[216:219], v[32:35]
	v_mfma_f32_16x16x32_bf16 v[16:19], v[120:123], v[224:227], 0
	v_mfma_f32_16x16x32_bf16 v[16:19], v[112:115], v[220:223], v[16:19]
	v_mfma_f32_16x16x32_bf16 v[12:15], v[152:155], v[220:223], 0
	v_mfma_f32_16x16x32_bf16 v[12:15], v[156:159], v[224:227], v[12:15]
	v_mfma_f32_16x16x32_bf16 v[28:31], v[156:159], v[216:219], 0
	v_mfma_f32_16x16x32_bf16 v[28:31], v[152:155], v[212:215], v[28:31]
	v_mfma_f32_16x16x32_bf16 v[44:47], v[152:155], v[204:207], 0
	v_mfma_f32_16x16x32_bf16 v[44:47], v[156:159], v[208:211], v[44:47]
	v_mfma_f32_16x16x32_bf16 v[60:63], v[156:159], v[188:191], 0
	v_mfma_f32_16x16x32_bf16 v[60:63], v[152:155], v[184:187], v[60:63]
	v_mfma_f32_16x16x32_bf16 v[56:59], v[160:163], v[184:187], 0
	v_mfma_f32_16x16x32_bf16 v[56:59], v[164:167], v[188:191], v[56:59]
	v_mfma_f32_16x16x32_bf16 v[40:43], v[164:167], v[208:211], 0
	v_mfma_f32_16x16x32_bf16 v[40:43], v[160:163], v[204:207], v[40:43]
	v_mfma_f32_16x16x32_bf16 v[24:27], v[160:163], v[212:215], 0
	v_mfma_f32_16x16x32_bf16 v[24:27], v[164:167], v[216:219], v[24:27]
	v_mfma_f32_16x16x32_bf16 v[8:11], v[164:167], v[224:227], 0
	v_mfma_f32_16x16x32_bf16 v[8:11], v[160:163], v[220:223], v[8:11]
	v_mfma_f32_16x16x32_bf16 v[4:7], v[176:179], v[220:223], 0
	v_mfma_f32_16x16x32_bf16 v[4:7], v[180:183], v[224:227], v[4:7]
	v_mfma_f32_16x16x32_bf16 v[20:23], v[180:183], v[216:219], 0
	v_mfma_f32_16x16x32_bf16 v[20:23], v[176:179], v[212:215], v[20:23]
	v_mfma_f32_16x16x32_bf16 v[36:39], v[176:179], v[204:207], 0
	v_mfma_f32_16x16x32_bf16 v[36:39], v[180:183], v[208:211], v[36:39]
	v_mfma_f32_16x16x32_bf16 v[52:55], v[180:183], v[188:191], 0
	v_mfma_f32_16x16x32_bf16 v[52:55], v[176:179], v[184:187], v[52:55]
	s_setprio 0
	s_barrier
	s_add_i32 s56, 0, 0x18000
	s_add_i32 s57, 0, 0x1c000
	v_add_u32_e32 v156, s56, v171
	v_add_u32_e32 v175, s57, v171
	ds_read_b128 v[112:115], v156
	ds_read_b128 v[120:123], v156 offset:1024
	ds_read_b128 v[152:155], v156 offset:2048
	ds_read_b128 v[156:159], v156 offset:3072
	ds_read_b128 v[160:163], v175
	ds_read_b128 v[164:167], v175 offset:1024
	ds_read_b128 v[176:179], v175 offset:2048
	ds_read_b128 v[180:183], v175 offset:3072
	s_add_u32 s50, s76, 0x100000
	s_addc_u32 s51, s77, 0
	s_mov_b32 m0, s53
	v_lshl_add_u64 v[244:245], s[50:51], 0, v[140:141]
	ds_read_b128 v[184:187], v173 offset:32768
	ds_read_b128 v[188:191], v173 offset:33792
	ds_read_b128 v[204:207], v173 offset:34816
	ds_read_b128 v[208:211], v173 offset:35840
	ds_read_b128 v[212:215], v173 offset:36864
	ds_read_b128 v[216:219], v173 offset:37888
	ds_read_b128 v[220:223], v173 offset:38912
	ds_read_b128 v[224:227], v173 offset:39936
	global_load_lds_dwordx4 v[244:245], off
	v_lshl_add_u64 v[244:245], s[50:51], 0, v[142:143]
	s_mov_b32 m0, s64
	s_nop 0
	global_load_lds_dwordx4 v[244:245], off
	s_waitcnt vmcnt(8)
	s_waitcnt lgkmcnt(0)
	s_barrier
	s_setprio 1
	s_waitcnt lgkmcnt(0)
	v_mfma_f32_16x16x32_bf16 v[136:139], v[112:115], v[184:187], v[136:139]
	v_mfma_f32_16x16x32_bf16 v[136:139], v[120:123], v[188:191], v[136:139]
	v_mfma_f32_16x16x32_bf16 v[116:119], v[120:123], v[208:211], v[116:119]
	v_mfma_f32_16x16x32_bf16 v[116:119], v[112:115], v[204:207], v[116:119]
	v_mfma_f32_16x16x32_bf16 v[96:99], v[112:115], v[212:215], v[96:99]
	v_mfma_f32_16x16x32_bf16 v[96:99], v[120:123], v[216:219], v[96:99]
	v_mfma_f32_16x16x32_bf16 v[80:83], v[120:123], v[224:227], v[80:83]
	v_mfma_f32_16x16x32_bf16 v[80:83], v[112:115], v[220:223], v[80:83]
	v_mfma_f32_16x16x32_bf16 v[76:79], v[152:155], v[220:223], v[76:79]
	v_mfma_f32_16x16x32_bf16 v[76:79], v[156:159], v[224:227], v[76:79]
	v_mfma_f32_16x16x32_bf16 v[92:95], v[156:159], v[216:219], v[92:95]
	v_mfma_f32_16x16x32_bf16 v[92:95], v[152:155], v[212:215], v[92:95]
	v_mfma_f32_16x16x32_bf16 v[108:111], v[152:155], v[204:207], v[108:111]
	v_mfma_f32_16x16x32_bf16 v[108:111], v[156:159], v[208:211], v[108:111]
	v_mfma_f32_16x16x32_bf16 v[132:135], v[156:159], v[188:191], v[132:135]
	v_mfma_f32_16x16x32_bf16 v[132:135], v[152:155], v[184:187], v[132:135]
	v_mfma_f32_16x16x32_bf16 v[128:131], v[160:163], v[184:187], v[128:131]
	v_mfma_f32_16x16x32_bf16 v[128:131], v[164:167], v[188:191], v[128:131]
	v_mfma_f32_16x16x32_bf16 v[104:107], v[164:167], v[208:211], v[104:107]
	v_mfma_f32_16x16x32_bf16 v[104:107], v[160:163], v[204:207], v[104:107]
	v_mfma_f32_16x16x32_bf16 v[88:91], v[160:163], v[212:215], v[88:91]
	v_mfma_f32_16x16x32_bf16 v[88:91], v[164:167], v[216:219], v[88:91]
	v_mfma_f32_16x16x32_bf16 v[72:75], v[164:167], v[224:227], v[72:75]
	v_mfma_f32_16x16x32_bf16 v[72:75], v[160:163], v[220:223], v[72:75]
	v_mfma_f32_16x16x32_bf16 v[68:71], v[176:179], v[220:223], v[68:71]
	v_mfma_f32_16x16x32_bf16 v[68:71], v[180:183], v[224:227], v[68:71]
	v_mfma_f32_16x16x32_bf16 v[84:87], v[180:183], v[216:219], v[84:87]
	v_mfma_f32_16x16x32_bf16 v[84:87], v[176:179], v[212:215], v[84:87]
	v_mfma_f32_16x16x32_bf16 v[100:103], v[176:179], v[204:207], v[100:103]
	v_mfma_f32_16x16x32_bf16 v[100:103], v[180:183], v[208:211], v[100:103]
	v_mfma_f32_16x16x32_bf16 v[124:127], v[180:183], v[188:191], v[124:127]
	v_mfma_f32_16x16x32_bf16 v[124:127], v[176:179], v[184:187], v[124:127]
	s_setprio 0
	s_barrier
; #define PG8_STAGE(bufoff, gbase, voff) do { _Pragma("unroll") for (int _i = 0; _i < 2; ++_i) \
;         __builtin_amdgcn_global_load_lds((const unsigned*)((const char*)(gbase) + (voff)[_i]), (PG8_LAS unsigned*)(lds + (bufoff) + ldsw + _i * 8192), 16, 0, 0); } while (0)
; #define PG8_LDA(dst, b, h) do { _Pragma("unroll") for (int m = 0; m < 4; ++m) _Pragma("unroll") for (int k = 0; k < 2; ++k) dst[m][k] = *(const PG8_LAS bf16x8*)(lds + PG8_SA(b, h) + aoff + m * 2048 + k * 1024); } while (0)
; #define PG8_LDB(dst, b, h) do { _Pragma("unroll") for (int n = 0; n < 2; ++n) _Pragma("unroll") for (int k = 0; k < 2; ++k) dst[n][k] = *(const PG8_LAS bf16x8*)(lds + PG8_SB(b, h) + boff + n * 2048 + k * 1024); } while (0)
; #define PG8_WAIT_V(n) asm volatile("s_waitcnt vmcnt(" #n ")" ::: "memory")
; template <class Epi, class Sched, bool ALIGN_EPI = false, bool SP2 = false, bool I8 = false>
; __device__ __forceinline__ void gemm_phase(PG8_LAS unsigned char* lds, const Gemm g, const Sched& S, const Epi& E) {
;     ...
;             const char* a1 = cA + (size_t)(t + 1) * kstep;
;             const char* a2 = last ? nA : cA + (size_t)(t + 2) * kstep; const char* b2 = last ? nB : cB + (size_t)(t + 2) * kstep;
;             const char* a3 = a2 + kstep; const char* b3 = b2 + kstep;
;             if (last && has_next) S.a_ready(nxt);
;             if constexpr (SP2) {
;             PG8_LDB(B0, 0, 0); PG8_LDB(B1, 0, 1); PG8_SCHED; PG8_LDA(At, 0, 0); PG8_STAGE(PG8_SA(1, 1), a1 + hstep, voffA);
;             PG8_WAIT_V(8); PG8_WAIT_L(0); PG8_BAR; PG8_MMA(0, 0, At, B0); PG8_MMA(0, 1, At, B1); PG8_BAR; PG8_SCHED;
;             PG8_LDA(At, 0, 1); PG8_STAGE(PG8_SB(0, 0), b2, voffB); PG8_STAGE(PG8_SB(0, 1), b2 + hstep, voffB); PG8_STAGE(PG8_SA(0, 0), a2, voffA);
;             PG8_WAIT_V(8); PG8_WAIT_L(0); PG8_BAR; PG8_MMA(1, 0, At, B0); PG8_MMA(1, 1, At, B1); PG8_BAR; PG8_SCHED;
;             PG8_LDB(B0, 1, 0); PG8_LDB(B1, 1, 1); PG8_SCHED; PG8_LDA(At, 1, 0); PG8_STAGE(PG8_SA(0, 1), a2 + hstep, voffA);
;             PG8_WAIT_V(8); PG8_WAIT_L(0); PG8_BAR; PG8_MMA(0, 0, At, B0); PG8_MMA(0, 1, At, B1); PG8_BAR; PG8_SCHED;
;             PG8_LDA(At, 1, 1); PG8_STAGE(PG8_SB(1, 0), b3, voffB); PG8_STAGE(PG8_SB(1, 1), b3 + hstep, voffB); PG8_STAGE(PG8_SA(1, 0), a3, voffA);
;             PG8_WAIT_V(8); PG8_WAIT_L(0); PG8_BAR; PG8_MMA(1, 0, At, B0); PG8_MMA(1, 1, At, B1); PG8_BAR; PG8_SCHED;
	s_add_i32 s50, s56, s46
	v_lshl_add_u64 v[168:169], v[168:169], 0, s[84:85]
	s_mov_b32 m0, s50
	ds_read_b128 v[184:187], v173 offset:49152
	ds_read_b128 v[188:191], v173 offset:50176
	ds_read_b128 v[204:207], v173 offset:51200
	ds_read_b128 v[208:211], v173 offset:52224
	ds_read_b128 v[212:215], v173 offset:53248
	ds_read_b128 v[216:219], v173 offset:54272
	ds_read_b128 v[220:223], v173 offset:55296
	ds_read_b128 v[224:227], v173 offset:56320
	global_load_lds_dwordx4 v[168:169], off
	s_add_i32 m0, s50, 0x2000
	s_add_u32 s50, s72, 0x100080
	v_lshl_add_u64 v[168:169], v[228:229], 0, s[84:85]
	s_addc_u32 s51, s73, 0
	s_add_i32 s56, s57, s46
	global_load_lds_dwordx4 v[168:169], off
	v_lshl_add_u64 v[168:169], s[50:51], 0, v[2:3]
	s_mov_b32 m0, s56
	s_nop 0
	global_load_lds_dwordx4 v[168:169], off
	v_lshl_add_u64 v[168:169], s[50:51], 0, v[144:145]
	s_add_i32 m0, s56, 0x2000
	s_nop 0
	global_load_lds_dwordx4 v[168:169], off
	v_lshl_add_u64 v[168:169], v[240:241], 0, s[84:85]
	s_mov_b32 m0, s28
	s_nop 0
	global_load_lds_dwordx4 v[168:169], off
	v_lshl_add_u64 v[168:169], v[242:243], 0, s[84:85]
	s_mov_b32 m0, s65
	s_nop 0
	global_load_lds_dwordx4 v[168:169], off
	s_waitcnt vmcnt(8)
	s_waitcnt lgkmcnt(0)
	s_barrier
	s_setprio 1
	s_waitcnt lgkmcnt(0)
	v_mfma_f32_16x16x32_bf16 v[64:67], v[112:115], v[184:187], v[64:67]
	v_mfma_f32_16x16x32_bf16 v[64:67], v[120:123], v[188:191], v[64:67]
	v_mfma_f32_16x16x32_bf16 v[48:51], v[120:123], v[208:211], v[48:51]
	v_mfma_f32_16x16x32_bf16 v[48:51], v[112:115], v[204:207], v[48:51]
	v_mfma_f32_16x16x32_bf16 v[32:35], v[112:115], v[212:215], v[32:35]
	v_mfma_f32_16x16x32_bf16 v[32:35], v[120:123], v[216:219], v[32:35]
	v_mfma_f32_16x16x32_bf16 v[16:19], v[120:123], v[224:227], v[16:19]
	v_mfma_f32_16x16x32_bf16 v[16:19], v[112:115], v[220:223], v[16:19]
	v_mfma_f32_16x16x32_bf16 v[12:15], v[152:155], v[220:223], v[12:15]
	v_mfma_f32_16x16x32_bf16 v[12:15], v[156:159], v[224:227], v[12:15]
	v_mfma_f32_16x16x32_bf16 v[28:31], v[156:159], v[216:219], v[28:31]
	v_mfma_f32_16x16x32_bf16 v[28:31], v[152:155], v[212:215], v[28:31]
	v_mfma_f32_16x16x32_bf16 v[44:47], v[152:155], v[204:207], v[44:47]
	v_mfma_f32_16x16x32_bf16 v[44:47], v[156:159], v[208:211], v[44:47]
	v_mfma_f32_16x16x32_bf16 v[60:63], v[156:159], v[188:191], v[60:63]
	v_mfma_f32_16x16x32_bf16 v[60:63], v[152:155], v[184:187], v[60:63]
	v_mfma_f32_16x16x32_bf16 v[56:59], v[160:163], v[184:187], v[56:59]
	v_mfma_f32_16x16x32_bf16 v[56:59], v[164:167], v[188:191], v[56:59]
	v_mfma_f32_16x16x32_bf16 v[40:43], v[164:167], v[208:211], v[40:43]
	v_mfma_f32_16x16x32_bf16 v[40:43], v[160:163], v[204:207], v[40:43]
	v_mfma_f32_16x16x32_bf16 v[24:27], v[160:163], v[212:215], v[24:27]
	v_mfma_f32_16x16x32_bf16 v[24:27], v[164:167], v[216:219], v[24:27]
	v_mfma_f32_16x16x32_bf16 v[8:11], v[164:167], v[224:227], v[8:11]
	v_mfma_f32_16x16x32_bf16 v[8:11], v[160:163], v[220:223], v[8:11]
	v_mfma_f32_16x16x32_bf16 v[4:7], v[176:179], v[220:223], v[4:7]
	v_mfma_f32_16x16x32_bf16 v[4:7], v[180:183], v[224:227], v[4:7]
	v_mfma_f32_16x16x32_bf16 v[20:23], v[180:183], v[216:219], v[20:23]
	v_mfma_f32_16x16x32_bf16 v[20:23], v[176:179], v[212:215], v[20:23]
	v_mfma_f32_16x16x32_bf16 v[36:39], v[176:179], v[204:207], v[36:39]
	v_mfma_f32_16x16x32_bf16 v[36:39], v[180:183], v[208:211], v[36:39]
	v_mfma_f32_16x16x32_bf16 v[52:55], v[180:183], v[188:191], v[52:55]
	v_mfma_f32_16x16x32_bf16 v[52:55], v[176:179], v[184:187], v[52:55]
	s_setprio 0
	s_barrier
	s_add_i32 s97, s97, 2
	s_add_u32 s12, s12, 0x100
	s_addc_u32 s13, s13, 0
	s_add_u32 s37, s37, 0x100
	s_addc_u32 s61, s61, 0
	s_cmp_gt_u32 s97, 61
	s_cbranch_scc1 .Lkloop_exit_1
.LBB0_230:
	s_add_u32 s50, s12, 0xfff00080
	s_addc_u32 s51, s13, -1
	s_add_i32 s56, 0, 0x10000
	s_cmp_eq_u32 s97, 60
	s_cselect_b32 s77, s11, s51
	s_cselect_b32 s76, s34, s50
	s_cselect_b32 s73, s27, s61
	s_cselect_b32 s72, s35, s37
	s_add_i32 s57, 0, 0x14000
	v_add_u32_e32 v156, s56, v171
	v_add_u32_e32 v168, s57, v171
	s_waitcnt vmcnt(0)
	ds_read_b128 v[112:115], v156
	ds_read_b128 v[120:123], v156 offset:1024
	ds_read_b128 v[152:155], v156 offset:2048
	ds_read_b128 v[156:159], v156 offset:3072
	ds_read_b128 v[160:163], v168
	ds_read_b128 v[164:167], v168 offset:1024
	s_waitcnt lgkmcnt(0)
	ds_read_b128 v[176:179], v168 offset:2048
	ds_read_b128 v[180:183], v168 offset:3072
	v_lshl_add_u64 v[168:169], s[12:13], 0, v[148:149]
	s_add_i32 m0, s47, 0xc000
	ds_read_b128 v[184:187], v173
	ds_read_b128 v[188:191], v173 offset:1024
	ds_read_b128 v[204:207], v173 offset:2048
	ds_read_b128 v[208:211], v173 offset:3072
	ds_read_b128 v[212:215], v173 offset:4096
	ds_read_b128 v[216:219], v173 offset:5120
	ds_read_b128 v[220:223], v173 offset:6144
	ds_read_b128 v[224:227], v173 offset:7168
	global_load_lds_dwordx4 v[168:169], off
	v_lshl_add_u64 v[168:169], s[12:13], 0, v[150:151]
	s_add_i32 m0, s47, 0xe000
	s_nop 0
	global_load_lds_dwordx4 v[168:169], off
	s_waitcnt vmcnt(8)
	s_waitcnt lgkmcnt(0)
	s_barrier
; #define PG8_STAGE(bufoff, gbase, voff) do { _Pragma("unroll") for (int _i = 0; _i < 2; ++_i) \
;         __builtin_amdgcn_global_load_lds((const unsigned*)((const char*)(gbase) + (voff)[_i]), (PG8_LAS unsigned*)(lds + (bufoff) + ldsw + _i * 8192), 16, 0, 0); } while (0)
; #define PG8_LDA(dst, b, h) do { _Pragma("unroll") for (int m = 0; m < 4; ++m) _Pragma("unroll") for (int k = 0; k < 2; ++k) dst[m][k] = *(const PG8_LAS bf16x8*)(lds + PG8_SA(b, h) + aoff + m * 2048 + k * 1024); } while (0)
; #define PG8_WAIT_V(n) asm volatile("s_waitcnt vmcnt(" #n ")" ::: "memory")
; #define PG8_WAIT_L(n) asm volatile("s_waitcnt lgkmcnt(" #n ")" ::: "memory")
; #define PG8_BAR __builtin_amdgcn_s_barrier()
; #define PG8_SCHED __builtin_amdgcn_sched_barrier(0)
; template <class Epi, class Sched, bool ALIGN_EPI = false, bool SP2 = false, bool I8 = false>
; __device__ __forceinline__ void gemm_phase(PG8_LAS unsigned char* lds, const Gemm g, const Sched& S, const Epi& E) {
;     ...
;             PG8_WAIT_V(8); PG8_WAIT_L(0); PG8_BAR; PG8_MMA(0, 0, At, B0); PG8_MMA(0, 1, At, B1); PG8_BAR; PG8_SCHED;
;             PG8_LDA(At, 0, 1); PG8_STAGE(PG8_SB(0, 0), b2, voffB); PG8_STAGE(PG8_SB(0, 1), b2 + hstep, voffB); PG8_STAGE(PG8_SA(0, 0), a2, voffA);
;             PG8_WAIT_V(8); PG8_WAIT_L(0); PG8_BAR; PG8_MMA(1, 0, At, B0); PG8_MMA(1, 1, At, B1); PG8_BAR; PG8_SCHED;
	s_setprio 1
	s_waitcnt lgkmcnt(0)
	v_mfma_f32_16x16x32_bf16 v[136:139], v[112:115], v[184:187], v[136:139]
	v_mfma_f32_16x16x32_bf16 v[136:139], v[120:123], v[188:191], v[136:139]
	v_mfma_f32_16x16x32_bf16 v[116:119], v[120:123], v[208:211], v[116:119]
	v_mfma_f32_16x16x32_bf16 v[116:119], v[112:115], v[204:207], v[116:119]
	v_mfma_f32_16x16x32_bf16 v[96:99], v[112:115], v[212:215], v[96:99]
	v_mfma_f32_16x16x32_bf16 v[96:99], v[120:123], v[216:219], v[96:99]
	v_mfma_f32_16x16x32_bf16 v[80:83], v[120:123], v[224:227], v[80:83]
	v_mfma_f32_16x16x32_bf16 v[80:83], v[112:115], v[220:223], v[80:83]
	v_mfma_f32_16x16x32_bf16 v[76:79], v[152:155], v[220:223], v[76:79]
	v_mfma_f32_16x16x32_bf16 v[76:79], v[156:159], v[224:227], v[76:79]
	v_mfma_f32_16x16x32_bf16 v[92:95], v[156:159], v[216:219], v[92:95]
	v_mfma_f32_16x16x32_bf16 v[92:95], v[152:155], v[212:215], v[92:95]
	v_mfma_f32_16x16x32_bf16 v[108:111], v[152:155], v[204:207], v[108:111]
	v_mfma_f32_16x16x32_bf16 v[108:111], v[156:159], v[208:211], v[108:111]
	v_mfma_f32_16x16x32_bf16 v[132:135], v[156:159], v[188:191], v[132:135]
	v_mfma_f32_16x16x32_bf16 v[132:135], v[152:155], v[184:187], v[132:135]
	v_mfma_f32_16x16x32_bf16 v[128:131], v[160:163], v[184:187], v[128:131]
	v_mfma_f32_16x16x32_bf16 v[128:131], v[164:167], v[188:191], v[128:131]
	v_mfma_f32_16x16x32_bf16 v[104:107], v[164:167], v[208:211], v[104:107]
	v_mfma_f32_16x16x32_bf16 v[104:107], v[160:163], v[204:207], v[104:107]
	v_mfma_f32_16x16x32_bf16 v[88:91], v[160:163], v[212:215], v[88:91]
	v_mfma_f32_16x16x32_bf16 v[88:91], v[164:167], v[216:219], v[88:91]
	v_mfma_f32_16x16x32_bf16 v[72:75], v[164:167], v[224:227], v[72:75]
	v_mfma_f32_16x16x32_bf16 v[72:75], v[160:163], v[220:223], v[72:75]
	v_mfma_f32_16x16x32_bf16 v[68:71], v[176:179], v[220:223], v[68:71]
	v_mfma_f32_16x16x32_bf16 v[68:71], v[180:183], v[224:227], v[68:71]
	v_mfma_f32_16x16x32_bf16 v[84:87], v[180:183], v[216:219], v[84:87]
	v_mfma_f32_16x16x32_bf16 v[84:87], v[176:179], v[212:215], v[84:87]
	v_mfma_f32_16x16x32_bf16 v[100:103], v[176:179], v[204:207], v[100:103]
	v_mfma_f32_16x16x32_bf16 v[100:103], v[180:183], v[208:211], v[100:103]
	v_mfma_f32_16x16x32_bf16 v[124:127], v[180:183], v[188:191], v[124:127]
	v_mfma_f32_16x16x32_bf16 v[124:127], v[176:179], v[184:187], v[124:127]
	s_setprio 0
	s_barrier
	s_add_i32 s50, s56, s46
	v_lshl_add_u64 v[168:169], s[72:73], 0, v[2:3]
	s_mov_b32 m0, s50
	ds_read_b128 v[184:187], v173 offset:16384
	ds_read_b128 v[188:191], v173 offset:17408
	ds_read_b128 v[204:207], v173 offset:18432
	ds_read_b128 v[208:211], v173 offset:19456
	ds_read_b128 v[212:215], v173 offset:20480
	ds_read_b128 v[216:219], v173 offset:21504
	ds_read_b128 v[220:223], v173 offset:22528
	ds_read_b128 v[224:227], v173 offset:23552
	global_load_lds_dwordx4 v[168:169], off
	s_add_i32 m0, s50, 0x2000
	s_add_u32 s50, s72, 0x100000
	v_lshl_add_u64 v[228:229], s[72:73], 0, v[144:145]
	s_addc_u32 s51, s73, 0
	s_add_i32 s56, s57, s46
	global_load_lds_dwordx4 v[228:229], off
	v_lshl_add_u64 v[240:241], s[50:51], 0, v[2:3]
	s_mov_b32 m0, s56
	v_lshl_add_u64 v[242:243], s[76:77], 0, v[142:143]
	global_load_lds_dwordx4 v[240:241], off
	v_lshl_add_u64 v[240:241], s[50:51], 0, v[144:145]
	s_add_i32 m0, s56, 0x2000
	s_nop 0
	global_load_lds_dwordx4 v[240:241], off
	v_lshl_add_u64 v[240:241], s[76:77], 0, v[140:141]
	s_mov_b32 m0, s47
	s_nop 0
	global_load_lds_dwordx4 v[240:241], off
	s_mov_b32 m0, s52
	s_nop 0
	global_load_lds_dwordx4 v[242:243], off
	s_waitcnt vmcnt(8)
	s_waitcnt lgkmcnt(0)
	s_barrier
	s_setprio 1
	s_waitcnt lgkmcnt(0)
	v_mfma_f32_16x16x32_bf16 v[64:67], v[112:115], v[184:187], v[64:67]
	v_mfma_f32_16x16x32_bf16 v[64:67], v[120:123], v[188:191], v[64:67]
	v_mfma_f32_16x16x32_bf16 v[48:51], v[120:123], v[208:211], v[48:51]
	v_mfma_f32_16x16x32_bf16 v[48:51], v[112:115], v[204:207], v[48:51]
	v_mfma_f32_16x16x32_bf16 v[32:35], v[112:115], v[212:215], v[32:35]
	v_mfma_f32_16x16x32_bf16 v[32:35], v[120:123], v[216:219], v[32:35]
	v_mfma_f32_16x16x32_bf16 v[16:19], v[120:123], v[224:227], v[16:19]
	v_mfma_f32_16x16x32_bf16 v[16:19], v[112:115], v[220:223], v[16:19]
	v_mfma_f32_16x16x32_bf16 v[12:15], v[152:155], v[220:223], v[12:15]
	v_mfma_f32_16x16x32_bf16 v[12:15], v[156:159], v[224:227], v[12:15]
	v_mfma_f32_16x16x32_bf16 v[28:31], v[156:159], v[216:219], v[28:31]
	v_mfma_f32_16x16x32_bf16 v[28:31], v[152:155], v[212:215], v[28:31]
	v_mfma_f32_16x16x32_bf16 v[44:47], v[152:155], v[204:207], v[44:47]
	v_mfma_f32_16x16x32_bf16 v[44:47], v[156:159], v[208:211], v[44:47]
	v_mfma_f32_16x16x32_bf16 v[60:63], v[156:159], v[188:191], v[60:63]
	v_mfma_f32_16x16x32_bf16 v[60:63], v[152:155], v[184:187], v[60:63]
	v_mfma_f32_16x16x32_bf16 v[56:59], v[160:163], v[184:187], v[56:59]
	v_mfma_f32_16x16x32_bf16 v[56:59], v[164:167], v[188:191], v[56:59]
	v_mfma_f32_16x16x32_bf16 v[40:43], v[164:167], v[208:211], v[40:43]
	v_mfma_f32_16x16x32_bf16 v[40:43], v[160:163], v[204:207], v[40:43]
	v_mfma_f32_16x16x32_bf16 v[24:27], v[160:163], v[212:215], v[24:27]
	v_mfma_f32_16x16x32_bf16 v[24:27], v[164:167], v[216:219], v[24:27]
	v_mfma_f32_16x16x32_bf16 v[8:11], v[164:167], v[224:227], v[8:11]
	v_mfma_f32_16x16x32_bf16 v[8:11], v[160:163], v[220:223], v[8:11]
	v_mfma_f32_16x16x32_bf16 v[4:7], v[176:179], v[220:223], v[4:7]
	v_mfma_f32_16x16x32_bf16 v[4:7], v[180:183], v[224:227], v[4:7]
	v_mfma_f32_16x16x32_bf16 v[20:23], v[180:183], v[216:219], v[20:23]
	v_mfma_f32_16x16x32_bf16 v[20:23], v[176:179], v[212:215], v[20:23]
	v_mfma_f32_16x16x32_bf16 v[36:39], v[176:179], v[204:207], v[36:39]
	v_mfma_f32_16x16x32_bf16 v[36:39], v[180:183], v[208:211], v[36:39]
	v_mfma_f32_16x16x32_bf16 v[52:55], v[180:183], v[188:191], v[52:55]
	v_mfma_f32_16x16x32_bf16 v[52:55], v[176:179], v[184:187], v[52:55]
	s_setprio 0
	s_barrier
; #define PG8_STAGE(bufoff, gbase, voff) do { _Pragma("unroll") for (int _i = 0; _i < 2; ++_i) \
;         __builtin_amdgcn_global_load_lds((const unsigned*)((const char*)(gbase) + (voff)[_i]), (PG8_LAS unsigned*)(lds + (bufoff) + ldsw + _i * 8192), 16, 0, 0); } while (0)
; #define PG8_LDA(dst, b, h) do { _Pragma("unroll") for (int m = 0; m < 4; ++m) _Pragma("unroll") for (int k = 0; k < 2; ++k) dst[m][k] = *(const PG8_LAS bf16x8*)(lds + PG8_SA(b, h) + aoff + m * 2048 + k * 1024); } while (0)
; #define PG8_LDB(dst, b, h) do { _Pragma("unroll") for (int n = 0; n < 2; ++n) _Pragma("unroll") for (int k = 0; k < 2; ++k) dst[n][k] = *(const PG8_LAS bf16x8*)(lds + PG8_SB(b, h) + boff + n * 2048 + k * 1024); } while (0)
; #define PG8_WAIT_V(n) asm volatile("s_waitcnt vmcnt(" #n ")" ::: "memory")
; #define PG8_WAIT_L(n) asm volatile("s_waitcnt lgkmcnt(" #n ")" ::: "memory")
; #define PG8_BAR __builtin_amdgcn_s_barrier()
; #define PG8_SCHED __builtin_amdgcn_sched_barrier(0)
; template <class Epi, class Sched, bool ALIGN_EPI = false, bool SP2 = false, bool I8 = false>
; __device__ __forceinline__ void gemm_phase(PG8_LAS unsigned char* lds, const Gemm g, const Sched& S, const Epi& E) {
;     ...
;             PG8_LDB(B0, 1, 0); PG8_LDB(B1, 1, 1); PG8_SCHED; PG8_LDA(At, 1, 0); PG8_STAGE(PG8_SA(0, 1), a2 + hstep, voffA);
;             PG8_WAIT_V(8); PG8_WAIT_L(0); PG8_BAR; PG8_MMA(0, 0, At, B0); PG8_MMA(0, 1, At, B1); PG8_BAR; PG8_SCHED;
	s_add_i32 s56, 0, 0x18000
	s_add_i32 s57, 0, 0x1c000
	v_add_u32_e32 v156, s56, v171
	v_add_u32_e32 v175, s57, v171
	ds_read_b128 v[112:115], v156
	ds_read_b128 v[120:123], v156 offset:1024
	ds_read_b128 v[152:155], v156 offset:2048
	ds_read_b128 v[156:159], v156 offset:3072
	ds_read_b128 v[160:163], v175
	ds_read_b128 v[164:167], v175 offset:1024
	ds_read_b128 v[176:179], v175 offset:2048
	ds_read_b128 v[180:183], v175 offset:3072
	s_add_u32 s50, s76, 0x100000
	s_addc_u32 s51, s77, 0
	s_mov_b32 m0, s53
	v_lshl_add_u64 v[244:245], s[50:51], 0, v[140:141]
	ds_read_b128 v[184:187], v173 offset:32768
	ds_read_b128 v[188:191], v173 offset:33792
	ds_read_b128 v[204:207], v173 offset:34816
	ds_read_b128 v[208:211], v173 offset:35840
	ds_read_b128 v[212:215], v173 offset:36864
	ds_read_b128 v[216:219], v173 offset:37888
	ds_read_b128 v[220:223], v173 offset:38912
	ds_read_b128 v[224:227], v173 offset:39936
	global_load_lds_dwordx4 v[244:245], off
	v_lshl_add_u64 v[244:245], s[50:51], 0, v[142:143]
	s_mov_b32 m0, s64
	s_nop 0
	global_load_lds_dwordx4 v[244:245], off
	s_waitcnt vmcnt(8)
	s_waitcnt lgkmcnt(0)
	s_barrier
	s_setprio 1
	s_waitcnt lgkmcnt(0)
	v_mfma_f32_16x16x32_bf16 v[136:139], v[112:115], v[184:187], v[136:139]
	v_mfma_f32_16x16x32_bf16 v[136:139], v[120:123], v[188:191], v[136:139]
	v_mfma_f32_16x16x32_bf16 v[116:119], v[120:123], v[208:211], v[116:119]
	v_mfma_f32_16x16x32_bf16 v[116:119], v[112:115], v[204:207], v[116:119]
	v_mfma_f32_16x16x32_bf16 v[96:99], v[112:115], v[212:215], v[96:99]
	v_mfma_f32_16x16x32_bf16 v[96:99], v[120:123], v[216:219], v[96:99]
	v_mfma_f32_16x16x32_bf16 v[80:83], v[120:123], v[224:227], v[80:83]
	v_mfma_f32_16x16x32_bf16 v[80:83], v[112:115], v[220:223], v[80:83]
	v_mfma_f32_16x16x32_bf16 v[76:79], v[152:155], v[220:223], v[76:79]
	v_mfma_f32_16x16x32_bf16 v[76:79], v[156:159], v[224:227], v[76:79]
	v_mfma_f32_16x16x32_bf16 v[92:95], v[156:159], v[216:219], v[92:95]
	v_mfma_f32_16x16x32_bf16 v[92:95], v[152:155], v[212:215], v[92:95]
	v_mfma_f32_16x16x32_bf16 v[108:111], v[152:155], v[204:207], v[108:111]
	v_mfma_f32_16x16x32_bf16 v[108:111], v[156:159], v[208:211], v[108:111]
	v_mfma_f32_16x16x32_bf16 v[132:135], v[156:159], v[188:191], v[132:135]
	v_mfma_f32_16x16x32_bf16 v[132:135], v[152:155], v[184:187], v[132:135]
	v_mfma_f32_16x16x32_bf16 v[128:131], v[160:163], v[184:187], v[128:131]
	v_mfma_f32_16x16x32_bf16 v[128:131], v[164:167], v[188:191], v[128:131]
	v_mfma_f32_16x16x32_bf16 v[104:107], v[164:167], v[208:211], v[104:107]
	v_mfma_f32_16x16x32_bf16 v[104:107], v[160:163], v[204:207], v[104:107]
	v_mfma_f32_16x16x32_bf16 v[88:91], v[160:163], v[212:215], v[88:91]
	v_mfma_f32_16x16x32_bf16 v[88:91], v[164:167], v[216:219], v[88:91]
	v_mfma_f32_16x16x32_bf16 v[72:75], v[164:167], v[224:227], v[72:75]
	v_mfma_f32_16x16x32_bf16 v[72:75], v[160:163], v[220:223], v[72:75]
	v_mfma_f32_16x16x32_bf16 v[68:71], v[176:179], v[220:223], v[68:71]
	v_mfma_f32_16x16x32_bf16 v[68:71], v[180:183], v[224:227], v[68:71]
	v_mfma_f32_16x16x32_bf16 v[84:87], v[180:183], v[216:219], v[84:87]
	v_mfma_f32_16x16x32_bf16 v[84:87], v[176:179], v[212:215], v[84:87]
	v_mfma_f32_16x16x32_bf16 v[100:103], v[176:179], v[204:207], v[100:103]
	v_mfma_f32_16x16x32_bf16 v[100:103], v[180:183], v[208:211], v[100:103]
	v_mfma_f32_16x16x32_bf16 v[124:127], v[180:183], v[188:191], v[124:127]
	v_mfma_f32_16x16x32_bf16 v[124:127], v[176:179], v[184:187], v[124:127]
	s_setprio 0
	s_barrier
; #define PG8_STAGE(bufoff, gbase, voff) do { _Pragma("unroll") for (int _i = 0; _i < 2; ++_i) \
;         __builtin_amdgcn_global_load_lds((const unsigned*)((const char*)(gbase) + (voff)[_i]), (PG8_LAS unsigned*)(lds + (bufoff) + ldsw + _i * 8192), 16, 0, 0); } while (0)
; #define PG8_LDA(dst, b, h) do { _Pragma("unroll") for (int m = 0; m < 4; ++m) _Pragma("unroll") for (int k = 0; k < 2; ++k) dst[m][k] = *(const PG8_LAS bf16x8*)(lds + PG8_SA(b, h) + aoff + m * 2048 + k * 1024); } while (0)
; #define PG8_WAIT_V(n) asm volatile("s_waitcnt vmcnt(" #n ")" ::: "memory")
; #define PG8_WAIT_L(n) asm volatile("s_waitcnt lgkmcnt(" #n ")" ::: "memory")
; #define PG8_BAR __builtin_amdgcn_s_barrier()
; #define PG8_SCHED __builtin_amdgcn_sched_barrier(0)
; template <class Epi, class Sched, bool ALIGN_EPI = false, bool SP2 = false, bool I8 = false>
; __device__ __forceinline__ void gemm_phase(PG8_LAS unsigned char* lds, const Gemm g, const Sched& S, const Epi& E) {
;     ...
;             PG8_LDA(At, 1, 1); PG8_STAGE(PG8_SB(1, 0), b3, voffB); PG8_STAGE(PG8_SB(1, 1), b3 + hstep, voffB); PG8_STAGE(PG8_SA(1, 0), a3, voffA);
;             PG8_WAIT_V(8); PG8_WAIT_L(0); PG8_BAR; PG8_MMA(1, 0, At, B0); PG8_MMA(1, 1, At, B1); PG8_BAR; PG8_SCHED;
	s_add_i32 s50, s56, s46
	v_lshl_add_u64 v[168:169], v[168:169], 0, s[84:85]
	s_mov_b32 m0, s50
	ds_read_b128 v[184:187], v173 offset:49152
	ds_read_b128 v[188:191], v173 offset:50176
	ds_read_b128 v[204:207], v173 offset:51200
	ds_read_b128 v[208:211], v173 offset:52224
	ds_read_b128 v[212:215], v173 offset:53248
	ds_read_b128 v[216:219], v173 offset:54272
	ds_read_b128 v[220:223], v173 offset:55296
	ds_read_b128 v[224:227], v173 offset:56320
	global_load_lds_dwordx4 v[168:169], off
	s_add_i32 m0, s50, 0x2000
	s_add_u32 s50, s72, 0x100080
	v_lshl_add_u64 v[168:169], v[228:229], 0, s[84:85]
	s_addc_u32 s51, s73, 0
	s_add_i32 s56, s57, s46
	global_load_lds_dwordx4 v[168:169], off
	v_lshl_add_u64 v[168:169], s[50:51], 0, v[2:3]
	s_mov_b32 m0, s56
	s_nop 0
	global_load_lds_dwordx4 v[168:169], off
	v_lshl_add_u64 v[168:169], s[50:51], 0, v[144:145]
	s_add_i32 m0, s56, 0x2000
	s_nop 0
	global_load_lds_dwordx4 v[168:169], off
	v_lshl_add_u64 v[168:169], v[240:241], 0, s[84:85]
	s_mov_b32 m0, s28
	s_nop 0
	global_load_lds_dwordx4 v[168:169], off
	v_lshl_add_u64 v[168:169], v[242:243], 0, s[84:85]
	s_mov_b32 m0, s65
	s_nop 0
	global_load_lds_dwordx4 v[168:169], off
	s_waitcnt vmcnt(8)
	s_waitcnt lgkmcnt(0)
	s_barrier
	s_setprio 1
	s_waitcnt lgkmcnt(0)
	v_mfma_f32_16x16x32_bf16 v[64:67], v[112:115], v[184:187], v[64:67]
	v_mfma_f32_16x16x32_bf16 v[64:67], v[120:123], v[188:191], v[64:67]
	v_mfma_f32_16x16x32_bf16 v[48:51], v[120:123], v[208:211], v[48:51]
	v_mfma_f32_16x16x32_bf16 v[48:51], v[112:115], v[204:207], v[48:51]
	v_mfma_f32_16x16x32_bf16 v[32:35], v[112:115], v[212:215], v[32:35]
	v_mfma_f32_16x16x32_bf16 v[32:35], v[120:123], v[216:219], v[32:35]
	v_mfma_f32_16x16x32_bf16 v[16:19], v[120:123], v[224:227], v[16:19]
	v_mfma_f32_16x16x32_bf16 v[16:19], v[112:115], v[220:223], v[16:19]
	v_mfma_f32_16x16x32_bf16 v[12:15], v[152:155], v[220:223], v[12:15]
	v_mfma_f32_16x16x32_bf16 v[12:15], v[156:159], v[224:227], v[12:15]
	v_mfma_f32_16x16x32_bf16 v[28:31], v[156:159], v[216:219], v[28:31]
	v_mfma_f32_16x16x32_bf16 v[28:31], v[152:155], v[212:215], v[28:31]
	v_mfma_f32_16x16x32_bf16 v[44:47], v[152:155], v[204:207], v[44:47]
	v_mfma_f32_16x16x32_bf16 v[44:47], v[156:159], v[208:211], v[44:47]
	v_mfma_f32_16x16x32_bf16 v[60:63], v[156:159], v[188:191], v[60:63]
	v_mfma_f32_16x16x32_bf16 v[60:63], v[152:155], v[184:187], v[60:63]
	v_mfma_f32_16x16x32_bf16 v[56:59], v[160:163], v[184:187], v[56:59]
	v_mfma_f32_16x16x32_bf16 v[56:59], v[164:167], v[188:191], v[56:59]
	v_mfma_f32_16x16x32_bf16 v[40:43], v[164:167], v[208:211], v[40:43]
	v_mfma_f32_16x16x32_bf16 v[40:43], v[160:163], v[204:207], v[40:43]
	v_mfma_f32_16x16x32_bf16 v[24:27], v[160:163], v[212:215], v[24:27]
	v_mfma_f32_16x16x32_bf16 v[24:27], v[164:167], v[216:219], v[24:27]
	v_mfma_f32_16x16x32_bf16 v[8:11], v[164:167], v[224:227], v[8:11]
	v_mfma_f32_16x16x32_bf16 v[8:11], v[160:163], v[220:223], v[8:11]
	v_mfma_f32_16x16x32_bf16 v[4:7], v[176:179], v[220:223], v[4:7]
	v_mfma_f32_16x16x32_bf16 v[4:7], v[180:183], v[224:227], v[4:7]
	v_mfma_f32_16x16x32_bf16 v[20:23], v[180:183], v[216:219], v[20:23]
	v_mfma_f32_16x16x32_bf16 v[20:23], v[176:179], v[212:215], v[20:23]
	v_mfma_f32_16x16x32_bf16 v[36:39], v[176:179], v[204:207], v[36:39]
	v_mfma_f32_16x16x32_bf16 v[36:39], v[180:183], v[208:211], v[36:39]
	v_mfma_f32_16x16x32_bf16 v[52:55], v[180:183], v[188:191], v[52:55]
	v_mfma_f32_16x16x32_bf16 v[52:55], v[176:179], v[184:187], v[52:55]
	s_setprio 0
	s_barrier
	s_add_i32 s97, s97, 2
	s_add_u32 s12, s12, 0x100
	s_addc_u32 s13, s13, 0
	s_add_u32 s37, s37, 0x100
	s_addc_u32 s61, s61, 0
	s_cmp_gt_u32 s97, 61
	s_cbranch_scc0 .LBB0_230

; #define PG8_STAGE(bufoff, gbase, voff) do { _Pragma("unroll") for (int _i = 0; _i < 2; ++_i) \
;         __builtin_amdgcn_global_load_lds((const unsigned*)((const char*)(gbase) + (voff)[_i]), (PG8_LAS unsigned*)(lds + (bufoff) + ldsw + _i * 8192), 16, 0, 0); } while (0)
; #define PG8_LDA(dst, b, h) do { _Pragma("unroll") for (int m = 0; m < 4; ++m) _Pragma("unroll") for (int k = 0; k < 2; ++k) dst[m][k] = *(const PG8_LAS bf16x8*)(lds + PG8_SA(b, h) + aoff + m * 2048 + k * 1024); } while (0)
; #define PG8_LDB(dst, b, h) do { _Pragma("unroll") for (int n = 0; n < 2; ++n) _Pragma("unroll") for (int k = 0; k < 2; ++k) dst[n][k] = *(const PG8_LAS bf16x8*)(lds + PG8_SB(b, h) + boff + n * 2048 + k * 1024); } while (0)
; #define PG8_WAIT_V(n) asm volatile("s_waitcnt vmcnt(" #n ")" ::: "memory")
; #define PG8_WAIT_L(n) asm volatile("s_waitcnt lgkmcnt(" #n ")" ::: "memory")
; #define PG8_BAR __builtin_amdgcn_s_barrier()
; #define PG8_SCHED __builtin_amdgcn_sched_barrier(0)
; template <class Epi, class Sched, bool ALIGN_EPI = false, bool SP2 = false, bool I8 = false>
; __device__ __forceinline__ void gemm_phase(PG8_LAS unsigned char* lds, const Gemm g, const Sched& S, const Epi& E) {
;     ...
;         const bool has_next = S.next(ui + 1, nxt);
;         const char* nA = has_next ? (const char*)g.A + (size_t)nxt.pm * tstep : cA; const char* nB = has_next ? (const char*)g.Bt + (size_t)nxt.pn * tstep : cB;
;         for (int t = 0; t < nt; t += 2) {
;             const bool last = (t == nt - 2);
;             const char* a1 = cA + (size_t)(t + 1) * kstep;
;             const char* a2 = last ? nA : cA + (size_t)(t + 2) * kstep; const char* b2 = last ? nB : cB + (size_t)(t + 2) * kstep;
;             const char* a3 = a2 + kstep; const char* b3 = b2 + kstep;
;             if (last && has_next) S.a_ready(nxt);
;             if constexpr (SP2) {
;             PG8_LDB(B0, 0, 0); PG8_LDB(B1, 0, 1); PG8_SCHED; PG8_LDA(At, 0, 0); PG8_STAGE(PG8_SA(1, 1), a1 + hstep, voffA);
;             PG8_WAIT_V(8); PG8_WAIT_L(0); PG8_BAR; PG8_MMA(0, 0, At, B0); PG8_MMA(0, 1, At, B1); PG8_BAR; PG8_SCHED;
;             PG8_LDA(At, 0, 1); PG8_STAGE(PG8_SB(0, 0), b2, voffB); PG8_STAGE(PG8_SB(0, 1), b2 + hstep, voffB); PG8_STAGE(PG8_SA(0, 0), a2, voffA);
;             PG8_WAIT_V(8); PG8_WAIT_L(0); PG8_BAR; PG8_MMA(1, 0, At, B0); PG8_MMA(1, 1, At, B1); PG8_BAR; PG8_SCHED;
.LBB0_1455:
	s_ashr_i32 s17, s16, 31
	s_lshl_b64 s[20:21], s[16:17], 21
	s_add_u32 s20, s28, s20
	s_addc_u32 s21, s34, s21
	s_and_b64 s[22:23], s[8:9], exec
	s_cselect_b32 s17, s21, s25
	s_cselect_b32 s51, s20, s24
	s_ashr_i32 s19, s18, 31
	s_lshl_b64 s[22:23], s[18:19], 21
	s_add_u32 s22, s35, s22
	s_addc_u32 s23, s39, s23
	s_and_b64 s[36:37], s[8:9], exec
	s_cselect_b32 s19, s23, s27
	s_cselect_b32 s52, s22, s26
	s_add_u32 s24, s24, 0x100080
	s_addc_u32 s25, s25, 0
	s_add_u32 s53, s26, 0x100
	s_addc_u32 s54, s27, 0
	s_mov_b32 s55, -2
	s_waitcnt vmcnt(0)
	s_add_u32 s26, s24, 0xfff00080
	s_addc_u32 s27, s25, -1
	s_add_i32 s56, 0, 0x10000
	s_cmp_eq_u32 s55, 60
	s_cselect_b32 s37, s17, s27
	s_cselect_b32 s36, s51, s26
	s_cselect_b32 s27, s19, s54
	s_cselect_b32 s26, s52, s53
	s_add_i32 s58, 0, 0x14000
	v_add_u32_e32 v144, s56, v240
	v_add_u32_e32 v160, s58, v240
	ds_read_b128 v[124:127], v144
	ds_read_b128 v[128:131], v144 offset:1024
	ds_read_b128 v[132:135], v144 offset:2048
	ds_read_b128 v[144:147], v144 offset:3072
	ds_read_b128 v[148:151], v160
	ds_read_b128 v[152:155], v160 offset:1024
	ds_read_b128 v[156:159], v160 offset:2048
	ds_read_b128 v[160:163], v160 offset:3072
	v_lshl_add_u64 v[218:219], s[24:25], 0, v[210:211]
	s_add_i32 m0, s41, 0xc000
	ds_read_b128 v[164:167], v242
	ds_read_b128 v[168:171], v242 offset:1024
	ds_read_b128 v[172:175], v242 offset:2048
	ds_read_b128 v[176:179], v242 offset:3072
	ds_read_b128 v[180:183], v242 offset:4096
	ds_read_b128 v[184:187], v242 offset:5120
	ds_read_b128 v[188:191], v242 offset:6144
	ds_read_b128 v[214:217], v242 offset:7168
	global_load_lds_dwordx4 v[218:219], off
	v_lshl_add_u64 v[218:219], s[24:25], 0, v[212:213]
	s_add_i32 m0, s41, 0xe000
	s_nop 0
	global_load_lds_dwordx4 v[218:219], off
	s_waitcnt vmcnt(8)
	s_waitcnt lgkmcnt(0)
	s_barrier
	s_setprio 1
	s_waitcnt lgkmcnt(0)
	v_mfma_f32_16x16x32_bf16 v[140:143], v[124:127], v[164:167], 0
	v_mfma_f32_16x16x32_bf16 v[140:143], v[128:131], v[168:171], v[140:143]
	v_mfma_f32_16x16x32_bf16 v[112:115], v[128:131], v[176:179], 0
	v_mfma_f32_16x16x32_bf16 v[112:115], v[124:127], v[172:175], v[112:115]
	v_mfma_f32_16x16x32_bf16 v[96:99], v[124:127], v[180:183], 0
	v_mfma_f32_16x16x32_bf16 v[96:99], v[128:131], v[184:187], v[96:99]
	v_mfma_f32_16x16x32_bf16 v[80:83], v[128:131], v[214:217], 0
	v_mfma_f32_16x16x32_bf16 v[80:83], v[124:127], v[188:191], v[80:83]
	v_mfma_f32_16x16x32_bf16 v[76:79], v[132:135], v[188:191], 0
	v_mfma_f32_16x16x32_bf16 v[76:79], v[144:147], v[214:217], v[76:79]
	v_mfma_f32_16x16x32_bf16 v[92:95], v[144:147], v[184:187], 0
	v_mfma_f32_16x16x32_bf16 v[92:95], v[132:135], v[180:183], v[92:95]
	v_mfma_f32_16x16x32_bf16 v[108:111], v[132:135], v[172:175], 0
	v_mfma_f32_16x16x32_bf16 v[108:111], v[144:147], v[176:179], v[108:111]
	v_mfma_f32_16x16x32_bf16 v[136:139], v[144:147], v[168:171], 0
	v_mfma_f32_16x16x32_bf16 v[136:139], v[132:135], v[164:167], v[136:139]
	v_mfma_f32_16x16x32_bf16 v[120:123], v[148:151], v[164:167], 0
	v_mfma_f32_16x16x32_bf16 v[120:123], v[152:155], v[168:171], v[120:123]
	v_mfma_f32_16x16x32_bf16 v[104:107], v[152:155], v[176:179], 0
	v_mfma_f32_16x16x32_bf16 v[104:107], v[148:151], v[172:175], v[104:107]
	v_mfma_f32_16x16x32_bf16 v[88:91], v[148:151], v[180:183], 0
	v_mfma_f32_16x16x32_bf16 v[88:91], v[152:155], v[184:187], v[88:91]
	v_mfma_f32_16x16x32_bf16 v[72:75], v[152:155], v[214:217], 0
	v_mfma_f32_16x16x32_bf16 v[72:75], v[148:151], v[188:191], v[72:75]
	v_mfma_f32_16x16x32_bf16 v[68:71], v[156:159], v[188:191], 0
	v_mfma_f32_16x16x32_bf16 v[68:71], v[160:163], v[214:217], v[68:71]
	v_mfma_f32_16x16x32_bf16 v[84:87], v[160:163], v[184:187], 0
	v_mfma_f32_16x16x32_bf16 v[84:87], v[156:159], v[180:183], v[84:87]
	v_mfma_f32_16x16x32_bf16 v[100:103], v[156:159], v[172:175], 0
	v_mfma_f32_16x16x32_bf16 v[100:103], v[160:163], v[176:179], v[100:103]
	v_mfma_f32_16x16x32_bf16 v[116:119], v[160:163], v[168:171], 0
	v_mfma_f32_16x16x32_bf16 v[116:119], v[156:159], v[164:167], v[116:119]
	s_setprio 0
	s_barrier
	s_add_i32 s56, s56, s40
	v_lshl_add_u64 v[218:219], s[26:27], 0, v[2:3]
	s_mov_b32 m0, s56
	ds_read_b128 v[164:167], v242 offset:16384
	ds_read_b128 v[168:171], v242 offset:17408
	ds_read_b128 v[172:175], v242 offset:18432
	ds_read_b128 v[176:179], v242 offset:19456
	ds_read_b128 v[180:183], v242 offset:20480
	ds_read_b128 v[184:187], v242 offset:21504
	ds_read_b128 v[188:191], v242 offset:22528
	ds_read_b128 v[214:217], v242 offset:23552
	global_load_lds_dwordx4 v[218:219], off
	s_add_i32 m0, s56, 0x2000
	s_add_u32 s56, s26, 0x100000
	v_lshl_add_u64 v[220:221], s[26:27], 0, v[204:205]
	s_addc_u32 s57, s27, 0
	s_add_i32 s58, s58, s40
	global_load_lds_dwordx4 v[220:221], off
	v_lshl_add_u64 v[222:223], s[56:57], 0, v[2:3]
	s_mov_b32 m0, s58
	v_lshl_add_u64 v[224:225], s[36:37], 0, v[206:207]
	global_load_lds_dwordx4 v[222:223], off
	v_lshl_add_u64 v[222:223], s[56:57], 0, v[204:205]
	s_add_i32 m0, s58, 0x2000
	s_nop 0
	global_load_lds_dwordx4 v[222:223], off
	v_lshl_add_u64 v[222:223], s[36:37], 0, v[208:209]
	s_mov_b32 m0, s41
	s_nop 0
	global_load_lds_dwordx4 v[222:223], off
	s_mov_b32 m0, s42
	s_nop 0
	global_load_lds_dwordx4 v[224:225], off
	s_waitcnt vmcnt(8)
	s_waitcnt lgkmcnt(0)
	s_barrier
; #define PG8_STAGE(bufoff, gbase, voff) do { _Pragma("unroll") for (int _i = 0; _i < 2; ++_i) \
;         __builtin_amdgcn_global_load_lds((const unsigned*)((const char*)(gbase) + (voff)[_i]), (PG8_LAS unsigned*)(lds + (bufoff) + ldsw + _i * 8192), 16, 0, 0); } while (0)
; #define PG8_LDA(dst, b, h) do { _Pragma("unroll") for (int m = 0; m < 4; ++m) _Pragma("unroll") for (int k = 0; k < 2; ++k) dst[m][k] = *(const PG8_LAS bf16x8*)(lds + PG8_SA(b, h) + aoff + m * 2048 + k * 1024); } while (0)
; #define PG8_LDB(dst, b, h) do { _Pragma("unroll") for (int n = 0; n < 2; ++n) _Pragma("unroll") for (int k = 0; k < 2; ++k) dst[n][k] = *(const PG8_LAS bf16x8*)(lds + PG8_SB(b, h) + boff + n * 2048 + k * 1024); } while (0)
; #define PG8_WAIT_V(n) asm volatile("s_waitcnt vmcnt(" #n ")" ::: "memory")
; #define PG8_WAIT_L(n) asm volatile("s_waitcnt lgkmcnt(" #n ")" ::: "memory")
; #define PG8_BAR __builtin_amdgcn_s_barrier()
; #define PG8_SCHED __builtin_amdgcn_sched_barrier(0)
; template <class Epi, class Sched, bool ALIGN_EPI = false, bool SP2 = false, bool I8 = false>
; __device__ __forceinline__ void gemm_phase(PG8_LAS unsigned char* lds, const Gemm g, const Sched& S, const Epi& E) {
;     ...
;             PG8_WAIT_V(8); PG8_WAIT_L(0); PG8_BAR; PG8_MMA(1, 0, At, B0); PG8_MMA(1, 1, At, B1); PG8_BAR; PG8_SCHED;
;             PG8_LDB(B0, 1, 0); PG8_LDB(B1, 1, 1); PG8_SCHED; PG8_LDA(At, 1, 0); PG8_STAGE(PG8_SA(0, 1), a2 + hstep, voffA);
;             PG8_WAIT_V(8); PG8_WAIT_L(0); PG8_BAR; PG8_MMA(0, 0, At, B0); PG8_MMA(0, 1, At, B1); PG8_BAR; PG8_SCHED;
	s_setprio 1
	s_waitcnt lgkmcnt(0)
	v_mfma_f32_16x16x32_bf16 v[64:67], v[124:127], v[164:167], 0
	v_mfma_f32_16x16x32_bf16 v[64:67], v[128:131], v[168:171], v[64:67]
	v_mfma_f32_16x16x32_bf16 v[48:51], v[128:131], v[176:179], 0
	v_mfma_f32_16x16x32_bf16 v[48:51], v[124:127], v[172:175], v[48:51]
	v_mfma_f32_16x16x32_bf16 v[32:35], v[124:127], v[180:183], 0
	v_mfma_f32_16x16x32_bf16 v[32:35], v[128:131], v[184:187], v[32:35]
	v_mfma_f32_16x16x32_bf16 v[16:19], v[128:131], v[214:217], 0
	v_mfma_f32_16x16x32_bf16 v[16:19], v[124:127], v[188:191], v[16:19]
	v_mfma_f32_16x16x32_bf16 v[12:15], v[132:135], v[188:191], 0
	v_mfma_f32_16x16x32_bf16 v[12:15], v[144:147], v[214:217], v[12:15]
	v_mfma_f32_16x16x32_bf16 v[28:31], v[144:147], v[184:187], 0
	v_mfma_f32_16x16x32_bf16 v[28:31], v[132:135], v[180:183], v[28:31]
	v_mfma_f32_16x16x32_bf16 v[44:47], v[132:135], v[172:175], 0
	v_mfma_f32_16x16x32_bf16 v[44:47], v[144:147], v[176:179], v[44:47]
	v_mfma_f32_16x16x32_bf16 v[60:63], v[144:147], v[168:171], 0
	v_mfma_f32_16x16x32_bf16 v[60:63], v[132:135], v[164:167], v[60:63]
	v_mfma_f32_16x16x32_bf16 v[56:59], v[148:151], v[164:167], 0
	v_mfma_f32_16x16x32_bf16 v[56:59], v[152:155], v[168:171], v[56:59]
	v_mfma_f32_16x16x32_bf16 v[40:43], v[152:155], v[176:179], 0
	v_mfma_f32_16x16x32_bf16 v[40:43], v[148:151], v[172:175], v[40:43]
	v_mfma_f32_16x16x32_bf16 v[24:27], v[148:151], v[180:183], 0
	v_mfma_f32_16x16x32_bf16 v[24:27], v[152:155], v[184:187], v[24:27]
	v_mfma_f32_16x16x32_bf16 v[8:11], v[152:155], v[214:217], 0
	v_mfma_f32_16x16x32_bf16 v[8:11], v[148:151], v[188:191], v[8:11]
	v_mfma_f32_16x16x32_bf16 v[4:7], v[156:159], v[188:191], 0
	v_mfma_f32_16x16x32_bf16 v[4:7], v[160:163], v[214:217], v[4:7]
	v_mfma_f32_16x16x32_bf16 v[20:23], v[160:163], v[184:187], 0
	v_mfma_f32_16x16x32_bf16 v[20:23], v[156:159], v[180:183], v[20:23]
	v_mfma_f32_16x16x32_bf16 v[36:39], v[156:159], v[172:175], 0
	v_mfma_f32_16x16x32_bf16 v[36:39], v[160:163], v[176:179], v[36:39]
	v_mfma_f32_16x16x32_bf16 v[52:55], v[160:163], v[168:171], 0
	v_mfma_f32_16x16x32_bf16 v[52:55], v[156:159], v[164:167], v[52:55]
	s_setprio 0
	s_barrier
	s_add_i32 s56, 0, 0x18000
	s_add_i32 s57, 0, 0x1c000
	v_add_u32_e32 v144, s56, v240
	v_add_u32_e32 v160, s57, v240
	ds_read_b128 v[124:127], v144
	ds_read_b128 v[128:131], v144 offset:1024
	ds_read_b128 v[132:135], v144 offset:2048
	ds_read_b128 v[144:147], v144 offset:3072
	ds_read_b128 v[148:151], v160
	ds_read_b128 v[152:155], v160 offset:1024
	ds_read_b128 v[156:159], v160 offset:2048
	ds_read_b128 v[160:163], v160 offset:3072
	s_add_u32 s36, s36, 0x100000
	s_addc_u32 s37, s37, 0
	s_mov_b32 m0, s43
	v_lshl_add_u64 v[226:227], s[36:37], 0, v[208:209]
	ds_read_b128 v[164:167], v242 offset:32768
	ds_read_b128 v[168:171], v242 offset:33792
	ds_read_b128 v[172:175], v242 offset:34816
	ds_read_b128 v[176:179], v242 offset:35840
	ds_read_b128 v[180:183], v242 offset:36864
	ds_read_b128 v[184:187], v242 offset:37888
	ds_read_b128 v[188:191], v242 offset:38912
	ds_read_b128 v[214:217], v242 offset:39936
	global_load_lds_dwordx4 v[226:227], off
	v_lshl_add_u64 v[226:227], s[36:37], 0, v[206:207]
	s_mov_b32 m0, s44
	s_nop 0
	global_load_lds_dwordx4 v[226:227], off
	s_waitcnt vmcnt(8)
	s_waitcnt lgkmcnt(0)
	s_barrier
	s_setprio 1
	s_waitcnt lgkmcnt(0)
	v_mfma_f32_16x16x32_bf16 v[140:143], v[124:127], v[164:167], v[140:143]
	v_mfma_f32_16x16x32_bf16 v[140:143], v[128:131], v[168:171], v[140:143]
	v_mfma_f32_16x16x32_bf16 v[112:115], v[128:131], v[176:179], v[112:115]
	v_mfma_f32_16x16x32_bf16 v[112:115], v[124:127], v[172:175], v[112:115]
	v_mfma_f32_16x16x32_bf16 v[96:99], v[124:127], v[180:183], v[96:99]
	v_mfma_f32_16x16x32_bf16 v[96:99], v[128:131], v[184:187], v[96:99]
	v_mfma_f32_16x16x32_bf16 v[80:83], v[128:131], v[214:217], v[80:83]
	v_mfma_f32_16x16x32_bf16 v[80:83], v[124:127], v[188:191], v[80:83]
	v_mfma_f32_16x16x32_bf16 v[76:79], v[132:135], v[188:191], v[76:79]
	v_mfma_f32_16x16x32_bf16 v[76:79], v[144:147], v[214:217], v[76:79]
	v_mfma_f32_16x16x32_bf16 v[92:95], v[144:147], v[184:187], v[92:95]
	v_mfma_f32_16x16x32_bf16 v[92:95], v[132:135], v[180:183], v[92:95]
	v_mfma_f32_16x16x32_bf16 v[108:111], v[132:135], v[172:175], v[108:111]
	v_mfma_f32_16x16x32_bf16 v[108:111], v[144:147], v[176:179], v[108:111]
	v_mfma_f32_16x16x32_bf16 v[136:139], v[144:147], v[168:171], v[136:139]
	v_mfma_f32_16x16x32_bf16 v[136:139], v[132:135], v[164:167], v[136:139]
	v_mfma_f32_16x16x32_bf16 v[120:123], v[148:151], v[164:167], v[120:123]
	v_mfma_f32_16x16x32_bf16 v[120:123], v[152:155], v[168:171], v[120:123]
	v_mfma_f32_16x16x32_bf16 v[104:107], v[152:155], v[176:179], v[104:107]
	v_mfma_f32_16x16x32_bf16 v[104:107], v[148:151], v[172:175], v[104:107]
	v_mfma_f32_16x16x32_bf16 v[88:91], v[148:151], v[180:183], v[88:91]
	v_mfma_f32_16x16x32_bf16 v[88:91], v[152:155], v[184:187], v[88:91]
	v_mfma_f32_16x16x32_bf16 v[72:75], v[152:155], v[214:217], v[72:75]
	v_mfma_f32_16x16x32_bf16 v[72:75], v[148:151], v[188:191], v[72:75]
	v_mfma_f32_16x16x32_bf16 v[68:71], v[156:159], v[188:191], v[68:71]
	v_mfma_f32_16x16x32_bf16 v[68:71], v[160:163], v[214:217], v[68:71]
	v_mfma_f32_16x16x32_bf16 v[84:87], v[160:163], v[184:187], v[84:87]
	v_mfma_f32_16x16x32_bf16 v[84:87], v[156:159], v[180:183], v[84:87]
	v_mfma_f32_16x16x32_bf16 v[100:103], v[156:159], v[172:175], v[100:103]
	v_mfma_f32_16x16x32_bf16 v[100:103], v[160:163], v[176:179], v[100:103]
	v_mfma_f32_16x16x32_bf16 v[116:119], v[160:163], v[168:171], v[116:119]
	v_mfma_f32_16x16x32_bf16 v[116:119], v[156:159], v[164:167], v[116:119]
	s_setprio 0
	s_barrier
; #define PG8_STAGE(bufoff, gbase, voff) do { _Pragma("unroll") for (int _i = 0; _i < 2; ++_i) \
;         __builtin_amdgcn_global_load_lds((const unsigned*)((const char*)(gbase) + (voff)[_i]), (PG8_LAS unsigned*)(lds + (bufoff) + ldsw + _i * 8192), 16, 0, 0); } while (0)
; #define PG8_LDA(dst, b, h) do { _Pragma("unroll") for (int m = 0; m < 4; ++m) _Pragma("unroll") for (int k = 0; k < 2; ++k) dst[m][k] = *(const PG8_LAS bf16x8*)(lds + PG8_SA(b, h) + aoff + m * 2048 + k * 1024); } while (0)
; #define PG8_LDB(dst, b, h) do { _Pragma("unroll") for (int n = 0; n < 2; ++n) _Pragma("unroll") for (int k = 0; k < 2; ++k) dst[n][k] = *(const PG8_LAS bf16x8*)(lds + PG8_SB(b, h) + boff + n * 2048 + k * 1024); } while (0)
; #define PG8_WAIT_V(n) asm volatile("s_waitcnt vmcnt(" #n ")" ::: "memory")
; template <class Epi, class Sched, bool ALIGN_EPI = false, bool SP2 = false, bool I8 = false>
; __device__ __forceinline__ void gemm_phase(PG8_LAS unsigned char* lds, const Gemm g, const Sched& S, const Epi& E) {
;     ...
;             const char* a1 = cA + (size_t)(t + 1) * kstep;
;             const char* a2 = last ? nA : cA + (size_t)(t + 2) * kstep; const char* b2 = last ? nB : cB + (size_t)(t + 2) * kstep;
;             const char* a3 = a2 + kstep; const char* b3 = b2 + kstep;
;             if (last && has_next) S.a_ready(nxt);
;             if constexpr (SP2) {
;             PG8_LDB(B0, 0, 0); PG8_LDB(B1, 0, 1); PG8_SCHED; PG8_LDA(At, 0, 0); PG8_STAGE(PG8_SA(1, 1), a1 + hstep, voffA);
;             PG8_WAIT_V(8); PG8_WAIT_L(0); PG8_BAR; PG8_MMA(0, 0, At, B0); PG8_MMA(0, 1, At, B1); PG8_BAR; PG8_SCHED;
;             PG8_LDA(At, 0, 1); PG8_STAGE(PG8_SB(0, 0), b2, voffB); PG8_STAGE(PG8_SB(0, 1), b2 + hstep, voffB); PG8_STAGE(PG8_SA(0, 0), a2, voffA);
;             PG8_WAIT_V(8); PG8_WAIT_L(0); PG8_BAR; PG8_MMA(1, 0, At, B0); PG8_MMA(1, 1, At, B1); PG8_BAR; PG8_SCHED;
;             PG8_LDB(B0, 1, 0); PG8_LDB(B1, 1, 1); PG8_SCHED; PG8_LDA(At, 1, 0); PG8_STAGE(PG8_SA(0, 1), a2 + hstep, voffA);
;             PG8_WAIT_V(8); PG8_WAIT_L(0); PG8_BAR; PG8_MMA(0, 0, At, B0); PG8_MMA(0, 1, At, B1); PG8_BAR; PG8_SCHED;
;             PG8_LDA(At, 1, 1); PG8_STAGE(PG8_SB(1, 0), b3, voffB); PG8_STAGE(PG8_SB(1, 1), b3 + hstep, voffB); PG8_STAGE(PG8_SA(1, 0), a3, voffA);
;             PG8_WAIT_V(8); PG8_WAIT_L(0); PG8_BAR; PG8_MMA(1, 0, At, B0); PG8_MMA(1, 1, At, B1); PG8_BAR; PG8_SCHED;
	s_add_i32 s36, s56, s40
	v_lshl_add_u64 v[218:219], v[218:219], 0, s[84:85]
	s_mov_b32 m0, s36
	ds_read_b128 v[164:167], v242 offset:49152
	ds_read_b128 v[168:171], v242 offset:50176
	ds_read_b128 v[172:175], v242 offset:51200
	ds_read_b128 v[176:179], v242 offset:52224
	ds_read_b128 v[180:183], v242 offset:53248
	ds_read_b128 v[184:187], v242 offset:54272
	ds_read_b128 v[188:191], v242 offset:55296
	ds_read_b128 v[214:217], v242 offset:56320
	global_load_lds_dwordx4 v[218:219], off
	s_add_i32 m0, s36, 0x2000
	s_add_u32 s26, s26, 0x100080
	v_lshl_add_u64 v[218:219], v[220:221], 0, s[84:85]
	s_addc_u32 s27, s27, 0
	s_add_i32 s36, s57, s40
	global_load_lds_dwordx4 v[218:219], off
	v_lshl_add_u64 v[218:219], s[26:27], 0, v[2:3]
	s_mov_b32 m0, s36
	s_nop 0
	global_load_lds_dwordx4 v[218:219], off
	v_lshl_add_u64 v[218:219], s[26:27], 0, v[204:205]
	s_add_i32 m0, s36, 0x2000
	s_nop 0
	global_load_lds_dwordx4 v[218:219], off
	v_lshl_add_u64 v[218:219], v[222:223], 0, s[84:85]
	s_mov_b32 m0, s45
	s_nop 0
	global_load_lds_dwordx4 v[218:219], off
	v_lshl_add_u64 v[218:219], v[224:225], 0, s[84:85]
	s_mov_b32 m0, s46
	s_nop 0
	global_load_lds_dwordx4 v[218:219], off
	s_waitcnt vmcnt(8)
	s_waitcnt lgkmcnt(0)
	s_barrier
	s_setprio 1
	s_waitcnt lgkmcnt(0)
	v_mfma_f32_16x16x32_bf16 v[64:67], v[124:127], v[164:167], v[64:67]
	v_mfma_f32_16x16x32_bf16 v[64:67], v[128:131], v[168:171], v[64:67]
	v_mfma_f32_16x16x32_bf16 v[48:51], v[128:131], v[176:179], v[48:51]
	v_mfma_f32_16x16x32_bf16 v[48:51], v[124:127], v[172:175], v[48:51]
	v_mfma_f32_16x16x32_bf16 v[32:35], v[124:127], v[180:183], v[32:35]
	v_mfma_f32_16x16x32_bf16 v[32:35], v[128:131], v[184:187], v[32:35]
	v_mfma_f32_16x16x32_bf16 v[16:19], v[128:131], v[214:217], v[16:19]
	v_mfma_f32_16x16x32_bf16 v[16:19], v[124:127], v[188:191], v[16:19]
	v_mfma_f32_16x16x32_bf16 v[12:15], v[132:135], v[188:191], v[12:15]
	v_mfma_f32_16x16x32_bf16 v[12:15], v[144:147], v[214:217], v[12:15]
	v_mfma_f32_16x16x32_bf16 v[28:31], v[144:147], v[184:187], v[28:31]
	v_mfma_f32_16x16x32_bf16 v[28:31], v[132:135], v[180:183], v[28:31]
	v_mfma_f32_16x16x32_bf16 v[44:47], v[132:135], v[172:175], v[44:47]
	v_mfma_f32_16x16x32_bf16 v[44:47], v[144:147], v[176:179], v[44:47]
	v_mfma_f32_16x16x32_bf16 v[60:63], v[144:147], v[168:171], v[60:63]
	v_mfma_f32_16x16x32_bf16 v[60:63], v[132:135], v[164:167], v[60:63]
	v_mfma_f32_16x16x32_bf16 v[56:59], v[148:151], v[164:167], v[56:59]
	v_mfma_f32_16x16x32_bf16 v[56:59], v[152:155], v[168:171], v[56:59]
	v_mfma_f32_16x16x32_bf16 v[40:43], v[152:155], v[176:179], v[40:43]
	v_mfma_f32_16x16x32_bf16 v[40:43], v[148:151], v[172:175], v[40:43]
	v_mfma_f32_16x16x32_bf16 v[24:27], v[148:151], v[180:183], v[24:27]
	v_mfma_f32_16x16x32_bf16 v[24:27], v[152:155], v[184:187], v[24:27]
	v_mfma_f32_16x16x32_bf16 v[8:11], v[152:155], v[214:217], v[8:11]
	v_mfma_f32_16x16x32_bf16 v[8:11], v[148:151], v[188:191], v[8:11]
	v_mfma_f32_16x16x32_bf16 v[4:7], v[156:159], v[188:191], v[4:7]
	v_mfma_f32_16x16x32_bf16 v[4:7], v[160:163], v[214:217], v[4:7]
	v_mfma_f32_16x16x32_bf16 v[20:23], v[160:163], v[184:187], v[20:23]
	v_mfma_f32_16x16x32_bf16 v[20:23], v[156:159], v[180:183], v[20:23]
	v_mfma_f32_16x16x32_bf16 v[36:39], v[156:159], v[172:175], v[36:39]
	v_mfma_f32_16x16x32_bf16 v[36:39], v[160:163], v[176:179], v[36:39]
	v_mfma_f32_16x16x32_bf16 v[52:55], v[160:163], v[168:171], v[52:55]
	v_mfma_f32_16x16x32_bf16 v[52:55], v[156:159], v[164:167], v[52:55]
	s_setprio 0
	s_barrier
	s_add_i32 s55, s55, 2
	s_add_u32 s24, s24, 0x100
	s_addc_u32 s25, s25, 0
	s_add_u32 s53, s53, 0x100
	s_addc_u32 s54, s54, 0
	s_cmp_gt_u32 s55, 61
	s_cbranch_scc1 .Lkloop_exit_2
.LBB0_1456:
	s_add_u32 s26, s24, 0xfff00080
	s_addc_u32 s27, s25, -1
	s_add_i32 s56, 0, 0x10000
	s_cmp_eq_u32 s55, 60
	s_cselect_b32 s37, s17, s27
	s_cselect_b32 s36, s51, s26
	s_cselect_b32 s27, s19, s54
	s_cselect_b32 s26, s52, s53
	s_add_i32 s58, 0, 0x14000
	v_add_u32_e32 v144, s56, v240
	v_add_u32_e32 v160, s58, v240
	ds_read_b128 v[124:127], v144
	ds_read_b128 v[128:131], v144 offset:1024
	ds_read_b128 v[132:135], v144 offset:2048
	ds_read_b128 v[144:147], v144 offset:3072
	ds_read_b128 v[148:151], v160
	ds_read_b128 v[152:155], v160 offset:1024
	ds_read_b128 v[156:159], v160 offset:2048
	ds_read_b128 v[160:163], v160 offset:3072
	v_lshl_add_u64 v[218:219], s[24:25], 0, v[210:211]
	s_add_i32 m0, s41, 0xc000
	ds_read_b128 v[164:167], v242
	ds_read_b128 v[168:171], v242 offset:1024
	ds_read_b128 v[172:175], v242 offset:2048
	ds_read_b128 v[176:179], v242 offset:3072
	ds_read_b128 v[180:183], v242 offset:4096
	ds_read_b128 v[184:187], v242 offset:5120
	ds_read_b128 v[188:191], v242 offset:6144
	ds_read_b128 v[214:217], v242 offset:7168
	global_load_lds_dwordx4 v[218:219], off
	v_lshl_add_u64 v[218:219], s[24:25], 0, v[212:213]
	s_add_i32 m0, s41, 0xe000
	s_nop 0
	global_load_lds_dwordx4 v[218:219], off
	s_waitcnt vmcnt(8)
	s_waitcnt lgkmcnt(0)
	s_barrier
; #define PG8_STAGE(bufoff, gbase, voff) do { _Pragma("unroll") for (int _i = 0; _i < 2; ++_i) \
;         __builtin_amdgcn_global_load_lds((const unsigned*)((const char*)(gbase) + (voff)[_i]), (PG8_LAS unsigned*)(lds + (bufoff) + ldsw + _i * 8192), 16, 0, 0); } while (0)
; #define PG8_LDA(dst, b, h) do { _Pragma("unroll") for (int m = 0; m < 4; ++m) _Pragma("unroll") for (int k = 0; k < 2; ++k) dst[m][k] = *(const PG8_LAS bf16x8*)(lds + PG8_SA(b, h) + aoff + m * 2048 + k * 1024); } while (0)
; #define PG8_WAIT_V(n) asm volatile("s_waitcnt vmcnt(" #n ")" ::: "memory")
; #define PG8_WAIT_L(n) asm volatile("s_waitcnt lgkmcnt(" #n ")" ::: "memory")
; #define PG8_BAR __builtin_amdgcn_s_barrier()
; #define PG8_SCHED __builtin_amdgcn_sched_barrier(0)
; template <class Epi, class Sched, bool ALIGN_EPI = false, bool SP2 = false, bool I8 = false>
; __device__ __forceinline__ void gemm_phase(PG8_LAS unsigned char* lds, const Gemm g, const Sched& S, const Epi& E) {
;     ...
;             PG8_WAIT_V(8); PG8_WAIT_L(0); PG8_BAR; PG8_MMA(0, 0, At, B0); PG8_MMA(0, 1, At, B1); PG8_BAR; PG8_SCHED;
;             PG8_LDA(At, 0, 1); PG8_STAGE(PG8_SB(0, 0), b2, voffB); PG8_STAGE(PG8_SB(0, 1), b2 + hstep, voffB); PG8_STAGE(PG8_SA(0, 0), a2, voffA);
;             PG8_WAIT_V(8); PG8_WAIT_L(0); PG8_BAR; PG8_MMA(1, 0, At, B0); PG8_MMA(1, 1, At, B1); PG8_BAR; PG8_SCHED;
	s_setprio 1
	s_waitcnt lgkmcnt(0)
	v_mfma_f32_16x16x32_bf16 v[140:143], v[124:127], v[164:167], v[140:143]
	v_mfma_f32_16x16x32_bf16 v[140:143], v[128:131], v[168:171], v[140:143]
	v_mfma_f32_16x16x32_bf16 v[112:115], v[128:131], v[176:179], v[112:115]
	v_mfma_f32_16x16x32_bf16 v[112:115], v[124:127], v[172:175], v[112:115]
	v_mfma_f32_16x16x32_bf16 v[96:99], v[124:127], v[180:183], v[96:99]
	v_mfma_f32_16x16x32_bf16 v[96:99], v[128:131], v[184:187], v[96:99]
	v_mfma_f32_16x16x32_bf16 v[80:83], v[128:131], v[214:217], v[80:83]
	v_mfma_f32_16x16x32_bf16 v[80:83], v[124:127], v[188:191], v[80:83]
	v_mfma_f32_16x16x32_bf16 v[76:79], v[132:135], v[188:191], v[76:79]
	v_mfma_f32_16x16x32_bf16 v[76:79], v[144:147], v[214:217], v[76:79]
	v_mfma_f32_16x16x32_bf16 v[92:95], v[144:147], v[184:187], v[92:95]
	v_mfma_f32_16x16x32_bf16 v[92:95], v[132:135], v[180:183], v[92:95]
	v_mfma_f32_16x16x32_bf16 v[108:111], v[132:135], v[172:175], v[108:111]
	v_mfma_f32_16x16x32_bf16 v[108:111], v[144:147], v[176:179], v[108:111]
	v_mfma_f32_16x16x32_bf16 v[136:139], v[144:147], v[168:171], v[136:139]
	v_mfma_f32_16x16x32_bf16 v[136:139], v[132:135], v[164:167], v[136:139]
	v_mfma_f32_16x16x32_bf16 v[120:123], v[148:151], v[164:167], v[120:123]
	v_mfma_f32_16x16x32_bf16 v[120:123], v[152:155], v[168:171], v[120:123]
	v_mfma_f32_16x16x32_bf16 v[104:107], v[152:155], v[176:179], v[104:107]
	v_mfma_f32_16x16x32_bf16 v[104:107], v[148:151], v[172:175], v[104:107]
	v_mfma_f32_16x16x32_bf16 v[88:91], v[148:151], v[180:183], v[88:91]
	v_mfma_f32_16x16x32_bf16 v[88:91], v[152:155], v[184:187], v[88:91]
	v_mfma_f32_16x16x32_bf16 v[72:75], v[152:155], v[214:217], v[72:75]
	v_mfma_f32_16x16x32_bf16 v[72:75], v[148:151], v[188:191], v[72:75]
	v_mfma_f32_16x16x32_bf16 v[68:71], v[156:159], v[188:191], v[68:71]
	v_mfma_f32_16x16x32_bf16 v[68:71], v[160:163], v[214:217], v[68:71]
	v_mfma_f32_16x16x32_bf16 v[84:87], v[160:163], v[184:187], v[84:87]
	v_mfma_f32_16x16x32_bf16 v[84:87], v[156:159], v[180:183], v[84:87]
	v_mfma_f32_16x16x32_bf16 v[100:103], v[156:159], v[172:175], v[100:103]
	v_mfma_f32_16x16x32_bf16 v[100:103], v[160:163], v[176:179], v[100:103]
	v_mfma_f32_16x16x32_bf16 v[116:119], v[160:163], v[168:171], v[116:119]
	v_mfma_f32_16x16x32_bf16 v[116:119], v[156:159], v[164:167], v[116:119]
	s_setprio 0
	s_barrier
	s_add_i32 s56, s56, s40
	v_lshl_add_u64 v[218:219], s[26:27], 0, v[2:3]
	s_mov_b32 m0, s56
	ds_read_b128 v[164:167], v242 offset:16384
	ds_read_b128 v[168:171], v242 offset:17408
	ds_read_b128 v[172:175], v242 offset:18432
	ds_read_b128 v[176:179], v242 offset:19456
	ds_read_b128 v[180:183], v242 offset:20480
	ds_read_b128 v[184:187], v242 offset:21504
	ds_read_b128 v[188:191], v242 offset:22528
	ds_read_b128 v[214:217], v242 offset:23552
	global_load_lds_dwordx4 v[218:219], off
	s_add_i32 m0, s56, 0x2000
	s_add_u32 s56, s26, 0x100000
	v_lshl_add_u64 v[220:221], s[26:27], 0, v[204:205]
	s_addc_u32 s57, s27, 0
	s_add_i32 s58, s58, s40
	global_load_lds_dwordx4 v[220:221], off
	v_lshl_add_u64 v[222:223], s[56:57], 0, v[2:3]
	s_mov_b32 m0, s58
	v_lshl_add_u64 v[224:225], s[36:37], 0, v[206:207]
	global_load_lds_dwordx4 v[222:223], off
	v_lshl_add_u64 v[222:223], s[56:57], 0, v[204:205]
	s_add_i32 m0, s58, 0x2000
	s_nop 0
	global_load_lds_dwordx4 v[222:223], off
	v_lshl_add_u64 v[222:223], s[36:37], 0, v[208:209]
	s_mov_b32 m0, s41
	s_nop 0
	global_load_lds_dwordx4 v[222:223], off
	s_mov_b32 m0, s42
	s_nop 0
	global_load_lds_dwordx4 v[224:225], off
	s_waitcnt vmcnt(8)
	s_waitcnt lgkmcnt(0)
	s_barrier
	s_setprio 1
	s_waitcnt lgkmcnt(0)
	v_mfma_f32_16x16x32_bf16 v[64:67], v[124:127], v[164:167], v[64:67]
	v_mfma_f32_16x16x32_bf16 v[64:67], v[128:131], v[168:171], v[64:67]
	v_mfma_f32_16x16x32_bf16 v[48:51], v[128:131], v[176:179], v[48:51]
	v_mfma_f32_16x16x32_bf16 v[48:51], v[124:127], v[172:175], v[48:51]
	v_mfma_f32_16x16x32_bf16 v[32:35], v[124:127], v[180:183], v[32:35]
	v_mfma_f32_16x16x32_bf16 v[32:35], v[128:131], v[184:187], v[32:35]
	v_mfma_f32_16x16x32_bf16 v[16:19], v[128:131], v[214:217], v[16:19]
	v_mfma_f32_16x16x32_bf16 v[16:19], v[124:127], v[188:191], v[16:19]
	v_mfma_f32_16x16x32_bf16 v[12:15], v[132:135], v[188:191], v[12:15]
	v_mfma_f32_16x16x32_bf16 v[12:15], v[144:147], v[214:217], v[12:15]
	v_mfma_f32_16x16x32_bf16 v[28:31], v[144:147], v[184:187], v[28:31]
	v_mfma_f32_16x16x32_bf16 v[28:31], v[132:135], v[180:183], v[28:31]
	v_mfma_f32_16x16x32_bf16 v[44:47], v[132:135], v[172:175], v[44:47]
	v_mfma_f32_16x16x32_bf16 v[44:47], v[144:147], v[176:179], v[44:47]
	v_mfma_f32_16x16x32_bf16 v[60:63], v[144:147], v[168:171], v[60:63]
	v_mfma_f32_16x16x32_bf16 v[60:63], v[132:135], v[164:167], v[60:63]
	v_mfma_f32_16x16x32_bf16 v[56:59], v[148:151], v[164:167], v[56:59]
	v_mfma_f32_16x16x32_bf16 v[56:59], v[152:155], v[168:171], v[56:59]
	v_mfma_f32_16x16x32_bf16 v[40:43], v[152:155], v[176:179], v[40:43]
	v_mfma_f32_16x16x32_bf16 v[40:43], v[148:151], v[172:175], v[40:43]
	v_mfma_f32_16x16x32_bf16 v[24:27], v[148:151], v[180:183], v[24:27]
	v_mfma_f32_16x16x32_bf16 v[24:27], v[152:155], v[184:187], v[24:27]
	v_mfma_f32_16x16x32_bf16 v[8:11], v[152:155], v[214:217], v[8:11]
	v_mfma_f32_16x16x32_bf16 v[8:11], v[148:151], v[188:191], v[8:11]
	v_mfma_f32_16x16x32_bf16 v[4:7], v[156:159], v[188:191], v[4:7]
	v_mfma_f32_16x16x32_bf16 v[4:7], v[160:163], v[214:217], v[4:7]
	v_mfma_f32_16x16x32_bf16 v[20:23], v[160:163], v[184:187], v[20:23]
	v_mfma_f32_16x16x32_bf16 v[20:23], v[156:159], v[180:183], v[20:23]
	v_mfma_f32_16x16x32_bf16 v[36:39], v[156:159], v[172:175], v[36:39]
	v_mfma_f32_16x16x32_bf16 v[36:39], v[160:163], v[176:179], v[36:39]
	v_mfma_f32_16x16x32_bf16 v[52:55], v[160:163], v[168:171], v[52:55]
	v_mfma_f32_16x16x32_bf16 v[52:55], v[156:159], v[164:167], v[52:55]
	s_setprio 0
	s_barrier
; #define PG8_STAGE(bufoff, gbase, voff) do { _Pragma("unroll") for (int _i = 0; _i < 2; ++_i) \
;         __builtin_amdgcn_global_load_lds((const unsigned*)((const char*)(gbase) + (voff)[_i]), (PG8_LAS unsigned*)(lds + (bufoff) + ldsw + _i * 8192), 16, 0, 0); } while (0)
; #define PG8_LDA(dst, b, h) do { _Pragma("unroll") for (int m = 0; m < 4; ++m) _Pragma("unroll") for (int k = 0; k < 2; ++k) dst[m][k] = *(const PG8_LAS bf16x8*)(lds + PG8_SA(b, h) + aoff + m * 2048 + k * 1024); } while (0)
; #define PG8_LDB(dst, b, h) do { _Pragma("unroll") for (int n = 0; n < 2; ++n) _Pragma("unroll") for (int k = 0; k < 2; ++k) dst[n][k] = *(const PG8_LAS bf16x8*)(lds + PG8_SB(b, h) + boff + n * 2048 + k * 1024); } while (0)
; #define PG8_WAIT_V(n) asm volatile("s_waitcnt vmcnt(" #n ")" ::: "memory")
; #define PG8_WAIT_L(n) asm volatile("s_waitcnt lgkmcnt(" #n ")" ::: "memory")
; #define PG8_BAR __builtin_amdgcn_s_barrier()
; #define PG8_SCHED __builtin_amdgcn_sched_barrier(0)
; template <class Epi, class Sched, bool ALIGN_EPI = false, bool SP2 = false, bool I8 = false>
; __device__ __forceinline__ void gemm_phase(PG8_LAS unsigned char* lds, const Gemm g, const Sched& S, const Epi& E) {
;     ...
;             PG8_LDB(B0, 1, 0); PG8_LDB(B1, 1, 1); PG8_SCHED; PG8_LDA(At, 1, 0); PG8_STAGE(PG8_SA(0, 1), a2 + hstep, voffA);
;             PG8_WAIT_V(8); PG8_WAIT_L(0); PG8_BAR; PG8_MMA(0, 0, At, B0); PG8_MMA(0, 1, At, B1); PG8_BAR; PG8_SCHED;
	s_add_i32 s56, 0, 0x18000
	s_add_i32 s57, 0, 0x1c000
	v_add_u32_e32 v144, s56, v240
	v_add_u32_e32 v160, s57, v240
	ds_read_b128 v[124:127], v144
	ds_read_b128 v[128:131], v144 offset:1024
	ds_read_b128 v[132:135], v144 offset:2048
	ds_read_b128 v[144:147], v144 offset:3072
	ds_read_b128 v[148:151], v160
	ds_read_b128 v[152:155], v160 offset:1024
	ds_read_b128 v[156:159], v160 offset:2048
	ds_read_b128 v[160:163], v160 offset:3072
	s_add_u32 s36, s36, 0x100000
	s_addc_u32 s37, s37, 0
	s_mov_b32 m0, s43
	v_lshl_add_u64 v[226:227], s[36:37], 0, v[208:209]
	ds_read_b128 v[164:167], v242 offset:32768
	ds_read_b128 v[168:171], v242 offset:33792
	ds_read_b128 v[172:175], v242 offset:34816
	ds_read_b128 v[176:179], v242 offset:35840
	ds_read_b128 v[180:183], v242 offset:36864
	ds_read_b128 v[184:187], v242 offset:37888
	ds_read_b128 v[188:191], v242 offset:38912
	ds_read_b128 v[214:217], v242 offset:39936
	global_load_lds_dwordx4 v[226:227], off
	v_lshl_add_u64 v[226:227], s[36:37], 0, v[206:207]
	s_mov_b32 m0, s44
	s_nop 0
	global_load_lds_dwordx4 v[226:227], off
	s_waitcnt vmcnt(8)
	s_waitcnt lgkmcnt(0)
	s_barrier
	s_setprio 1
	s_waitcnt lgkmcnt(0)
	v_mfma_f32_16x16x32_bf16 v[140:143], v[124:127], v[164:167], v[140:143]
	v_mfma_f32_16x16x32_bf16 v[140:143], v[128:131], v[168:171], v[140:143]
	v_mfma_f32_16x16x32_bf16 v[112:115], v[128:131], v[176:179], v[112:115]
	v_mfma_f32_16x16x32_bf16 v[112:115], v[124:127], v[172:175], v[112:115]
	v_mfma_f32_16x16x32_bf16 v[96:99], v[124:127], v[180:183], v[96:99]
	v_mfma_f32_16x16x32_bf16 v[96:99], v[128:131], v[184:187], v[96:99]
	v_mfma_f32_16x16x32_bf16 v[80:83], v[128:131], v[214:217], v[80:83]
	v_mfma_f32_16x16x32_bf16 v[80:83], v[124:127], v[188:191], v[80:83]
	v_mfma_f32_16x16x32_bf16 v[76:79], v[132:135], v[188:191], v[76:79]
	v_mfma_f32_16x16x32_bf16 v[76:79], v[144:147], v[214:217], v[76:79]
	v_mfma_f32_16x16x32_bf16 v[92:95], v[144:147], v[184:187], v[92:95]
	v_mfma_f32_16x16x32_bf16 v[92:95], v[132:135], v[180:183], v[92:95]
	v_mfma_f32_16x16x32_bf16 v[108:111], v[132:135], v[172:175], v[108:111]
	v_mfma_f32_16x16x32_bf16 v[108:111], v[144:147], v[176:179], v[108:111]
	v_mfma_f32_16x16x32_bf16 v[136:139], v[144:147], v[168:171], v[136:139]
	v_mfma_f32_16x16x32_bf16 v[136:139], v[132:135], v[164:167], v[136:139]
	v_mfma_f32_16x16x32_bf16 v[120:123], v[148:151], v[164:167], v[120:123]
	v_mfma_f32_16x16x32_bf16 v[120:123], v[152:155], v[168:171], v[120:123]
	v_mfma_f32_16x16x32_bf16 v[104:107], v[152:155], v[176:179], v[104:107]
	v_mfma_f32_16x16x32_bf16 v[104:107], v[148:151], v[172:175], v[104:107]
	v_mfma_f32_16x16x32_bf16 v[88:91], v[148:151], v[180:183], v[88:91]
	v_mfma_f32_16x16x32_bf16 v[88:91], v[152:155], v[184:187], v[88:91]
	v_mfma_f32_16x16x32_bf16 v[72:75], v[152:155], v[214:217], v[72:75]
	v_mfma_f32_16x16x32_bf16 v[72:75], v[148:151], v[188:191], v[72:75]
	v_mfma_f32_16x16x32_bf16 v[68:71], v[156:159], v[188:191], v[68:71]
	v_mfma_f32_16x16x32_bf16 v[68:71], v[160:163], v[214:217], v[68:71]
	v_mfma_f32_16x16x32_bf16 v[84:87], v[160:163], v[184:187], v[84:87]
	v_mfma_f32_16x16x32_bf16 v[84:87], v[156:159], v[180:183], v[84:87]
	v_mfma_f32_16x16x32_bf16 v[100:103], v[156:159], v[172:175], v[100:103]
	v_mfma_f32_16x16x32_bf16 v[100:103], v[160:163], v[176:179], v[100:103]
	v_mfma_f32_16x16x32_bf16 v[116:119], v[160:163], v[168:171], v[116:119]
	v_mfma_f32_16x16x32_bf16 v[116:119], v[156:159], v[164:167], v[116:119]
	s_setprio 0
	s_barrier
; #define PG8_STAGE(bufoff, gbase, voff) do { _Pragma("unroll") for (int _i = 0; _i < 2; ++_i) \
;         __builtin_amdgcn_global_load_lds((const unsigned*)((const char*)(gbase) + (voff)[_i]), (PG8_LAS unsigned*)(lds + (bufoff) + ldsw + _i * 8192), 16, 0, 0); } while (0)
; #define PG8_LDA(dst, b, h) do { _Pragma("unroll") for (int m = 0; m < 4; ++m) _Pragma("unroll") for (int k = 0; k < 2; ++k) dst[m][k] = *(const PG8_LAS bf16x8*)(lds + PG8_SA(b, h) + aoff + m * 2048 + k * 1024); } while (0)
; #define PG8_WAIT_V(n) asm volatile("s_waitcnt vmcnt(" #n ")" ::: "memory")
; #define PG8_WAIT_L(n) asm volatile("s_waitcnt lgkmcnt(" #n ")" ::: "memory")
; #define PG8_BAR __builtin_amdgcn_s_barrier()
; #define PG8_SCHED __builtin_amdgcn_sched_barrier(0)
; template <class Epi, class Sched, bool ALIGN_EPI = false, bool SP2 = false, bool I8 = false>
; __device__ __forceinline__ void gemm_phase(PG8_LAS unsigned char* lds, const Gemm g, const Sched& S, const Epi& E) {
;     ...
;         for (int t = 0; t < nt; t += 2) {
;     ...
;             PG8_LDA(At, 1, 1); PG8_STAGE(PG8_SB(1, 0), b3, voffB); PG8_STAGE(PG8_SB(1, 1), b3 + hstep, voffB); PG8_STAGE(PG8_SA(1, 0), a3, voffA);
;             PG8_WAIT_V(8); PG8_WAIT_L(0); PG8_BAR; PG8_MMA(1, 0, At, B0); PG8_MMA(1, 1, At, B1); PG8_BAR; PG8_SCHED;
	s_add_i32 s36, s56, s40
	v_lshl_add_u64 v[218:219], v[218:219], 0, s[84:85]
	s_mov_b32 m0, s36
	ds_read_b128 v[164:167], v242 offset:49152
	ds_read_b128 v[168:171], v242 offset:50176
	ds_read_b128 v[172:175], v242 offset:51200
	ds_read_b128 v[176:179], v242 offset:52224
	ds_read_b128 v[180:183], v242 offset:53248
	ds_read_b128 v[184:187], v242 offset:54272
	ds_read_b128 v[188:191], v242 offset:55296
	ds_read_b128 v[214:217], v242 offset:56320
	global_load_lds_dwordx4 v[218:219], off
	s_add_i32 m0, s36, 0x2000
	s_add_u32 s26, s26, 0x100080
	v_lshl_add_u64 v[218:219], v[220:221], 0, s[84:85]
	s_addc_u32 s27, s27, 0
	s_add_i32 s36, s57, s40
	global_load_lds_dwordx4 v[218:219], off
	v_lshl_add_u64 v[218:219], s[26:27], 0, v[2:3]
	s_mov_b32 m0, s36
	s_nop 0
	global_load_lds_dwordx4 v[218:219], off
	v_lshl_add_u64 v[218:219], s[26:27], 0, v[204:205]
	s_add_i32 m0, s36, 0x2000
	s_nop 0
	global_load_lds_dwordx4 v[218:219], off
	v_lshl_add_u64 v[218:219], v[222:223], 0, s[84:85]
	s_mov_b32 m0, s45
	s_nop 0
	global_load_lds_dwordx4 v[218:219], off
	v_lshl_add_u64 v[218:219], v[224:225], 0, s[84:85]
	s_mov_b32 m0, s46
	s_nop 0
	global_load_lds_dwordx4 v[218:219], off
	s_waitcnt vmcnt(8)
	s_waitcnt lgkmcnt(0)
	s_barrier
	s_setprio 1
	s_waitcnt lgkmcnt(0)
	v_mfma_f32_16x16x32_bf16 v[64:67], v[124:127], v[164:167], v[64:67]
	v_mfma_f32_16x16x32_bf16 v[64:67], v[128:131], v[168:171], v[64:67]
	v_mfma_f32_16x16x32_bf16 v[48:51], v[128:131], v[176:179], v[48:51]
	v_mfma_f32_16x16x32_bf16 v[48:51], v[124:127], v[172:175], v[48:51]
	v_mfma_f32_16x16x32_bf16 v[32:35], v[124:127], v[180:183], v[32:35]
	v_mfma_f32_16x16x32_bf16 v[32:35], v[128:131], v[184:187], v[32:35]
	v_mfma_f32_16x16x32_bf16 v[16:19], v[128:131], v[214:217], v[16:19]
	v_mfma_f32_16x16x32_bf16 v[16:19], v[124:127], v[188:191], v[16:19]
	v_mfma_f32_16x16x32_bf16 v[12:15], v[132:135], v[188:191], v[12:15]
	v_mfma_f32_16x16x32_bf16 v[12:15], v[144:147], v[214:217], v[12:15]
	v_mfma_f32_16x16x32_bf16 v[28:31], v[144:147], v[184:187], v[28:31]
	v_mfma_f32_16x16x32_bf16 v[28:31], v[132:135], v[180:183], v[28:31]
	v_mfma_f32_16x16x32_bf16 v[44:47], v[132:135], v[172:175], v[44:47]
	v_mfma_f32_16x16x32_bf16 v[44:47], v[144:147], v[176:179], v[44:47]
	v_mfma_f32_16x16x32_bf16 v[60:63], v[144:147], v[168:171], v[60:63]
	v_mfma_f32_16x16x32_bf16 v[60:63], v[132:135], v[164:167], v[60:63]
	v_mfma_f32_16x16x32_bf16 v[56:59], v[148:151], v[164:167], v[56:59]
	v_mfma_f32_16x16x32_bf16 v[56:59], v[152:155], v[168:171], v[56:59]
	v_mfma_f32_16x16x32_bf16 v[40:43], v[152:155], v[176:179], v[40:43]
	v_mfma_f32_16x16x32_bf16 v[40:43], v[148:151], v[172:175], v[40:43]
	v_mfma_f32_16x16x32_bf16 v[24:27], v[148:151], v[180:183], v[24:27]
	v_mfma_f32_16x16x32_bf16 v[24:27], v[152:155], v[184:187], v[24:27]
	v_mfma_f32_16x16x32_bf16 v[8:11], v[152:155], v[214:217], v[8:11]
	v_mfma_f32_16x16x32_bf16 v[8:11], v[148:151], v[188:191], v[8:11]
	v_mfma_f32_16x16x32_bf16 v[4:7], v[156:159], v[188:191], v[4:7]
	v_mfma_f32_16x16x32_bf16 v[4:7], v[160:163], v[214:217], v[4:7]
	v_mfma_f32_16x16x32_bf16 v[20:23], v[160:163], v[184:187], v[20:23]
	v_mfma_f32_16x16x32_bf16 v[20:23], v[156:159], v[180:183], v[20:23]
	v_mfma_f32_16x16x32_bf16 v[36:39], v[156:159], v[172:175], v[36:39]
	v_mfma_f32_16x16x32_bf16 v[36:39], v[160:163], v[176:179], v[36:39]
	v_mfma_f32_16x16x32_bf16 v[52:55], v[160:163], v[168:171], v[52:55]
	v_mfma_f32_16x16x32_bf16 v[52:55], v[156:159], v[164:167], v[52:55]
	s_setprio 0
	s_barrier
	s_add_i32 s55, s55, 2
	s_add_u32 s24, s24, 0x100
	s_addc_u32 s25, s25, 0
	s_add_u32 s53, s53, 0x100
	s_addc_u32 s54, s54, 0
	s_cmp_gt_u32 s55, 61
	s_cbranch_scc0 .LBB0_1456

; #define PG8_STAGE(bufoff, gbase, voff) do { _Pragma("unroll") for (int _i = 0; _i < 2; ++_i) \
;         __builtin_amdgcn_global_load_lds((const unsigned*)((const char*)(gbase) + (voff)[_i]), (PG8_LAS unsigned*)(lds + (bufoff) + ldsw + _i * 8192), 16, 0, 0); } while (0)
; #define PG8_LDA(dst, b, h) do { _Pragma("unroll") for (int m = 0; m < 4; ++m) _Pragma("unroll") for (int k = 0; k < 2; ++k) dst[m][k] = *(const PG8_LAS bf16x8*)(lds + PG8_SA(b, h) + aoff + m * 2048 + k * 1024); } while (0)
; #define PG8_LDB(dst, b, h) do { _Pragma("unroll") for (int n = 0; n < 2; ++n) _Pragma("unroll") for (int k = 0; k < 2; ++k) dst[n][k] = *(const PG8_LAS bf16x8*)(lds + PG8_SB(b, h) + boff + n * 2048 + k * 1024); } while (0)
; #define PG8_WAIT_V(n) asm volatile("s_waitcnt vmcnt(" #n ")" ::: "memory")
; #define PG8_WAIT_L(n) asm volatile("s_waitcnt lgkmcnt(" #n ")" ::: "memory")
; #define PG8_BAR __builtin_amdgcn_s_barrier()
; #define PG8_SCHED __builtin_amdgcn_sched_barrier(0)
; template <class Epi, class Sched, bool ALIGN_EPI = false, bool SP2 = false, bool I8 = false>
; __device__ __forceinline__ void gemm_phase(PG8_LAS unsigned char* lds, const Gemm g, const Sched& S, const Epi& E) {
;     ...
;         const bool has_next = S.next(ui + 1, nxt);
;         const char* nA = has_next ? (const char*)g.A + (size_t)nxt.pm * tstep : cA; const char* nB = has_next ? (const char*)g.Bt + (size_t)nxt.pn * tstep : cB;
;         for (int t = 0; t < nt; t += 2) {
;             const bool last = (t == nt - 2);
;             const char* a1 = cA + (size_t)(t + 1) * kstep;
;             const char* a2 = last ? nA : cA + (size_t)(t + 2) * kstep; const char* b2 = last ? nB : cB + (size_t)(t + 2) * kstep;
;             const char* a3 = a2 + kstep; const char* b3 = b2 + kstep;
;             if (last && has_next) S.a_ready(nxt);
;             if constexpr (SP2) {
;             PG8_LDB(B0, 0, 0); PG8_LDB(B1, 0, 1); PG8_SCHED; PG8_LDA(At, 0, 0); PG8_STAGE(PG8_SA(1, 1), a1 + hstep, voffA);
;             PG8_WAIT_V(8); PG8_WAIT_L(0); PG8_BAR; PG8_MMA(0, 0, At, B0); PG8_MMA(0, 1, At, B1); PG8_BAR; PG8_SCHED;
;             PG8_LDA(At, 0, 1); PG8_STAGE(PG8_SB(0, 0), b2, voffB); PG8_STAGE(PG8_SB(0, 1), b2 + hstep, voffB); PG8_STAGE(PG8_SA(0, 0), a2, voffA);
;             PG8_WAIT_V(8); PG8_WAIT_L(0); PG8_BAR; PG8_MMA(1, 0, At, B0); PG8_MMA(1, 1, At, B1); PG8_BAR; PG8_SCHED;
.LBB0_1590:
	s_ashr_i32 s25, s24, 31
	s_lshl_b64 s[26:27], s[24:25], 20
	s_add_u32 s26, s28, s26
	s_addc_u32 s27, s42, s27
	s_and_b64 s[36:37], s[10:11], exec
	s_cselect_b32 s25, s27, s41
	s_cselect_b32 s57, s26, s40
	s_ashr_i32 s23, s22, 31
	s_lshl_b64 s[36:37], s[22:23], 20
	s_add_u32 s36, s43, s36
	s_addc_u32 s37, s46, s37
	s_and_b64 s[48:49], s[10:11], exec
	s_cselect_b32 s23, s37, s45
	s_cselect_b32 s58, s36, s44
	s_add_u32 s40, s40, 0x80080
	s_addc_u32 s41, s41, 0
	s_add_u32 s59, s44, 0x100
	s_addc_u32 s60, s45, 0
	s_mov_b32 s61, -2
	s_add_u32 s44, s40, 0xfff80080
	s_addc_u32 s45, s41, -1
	s_add_i32 s64, 0, 0x10000
	s_cmp_eq_u32 s61, 28
	s_cselect_b32 s49, s25, s45
	s_cselect_b32 s48, s57, s44
	s_cselect_b32 s45, s23, s60
	s_cselect_b32 s44, s58, s59
	s_add_i32 s67, 0, 0x14000
	v_add_u32_e32 v144, s64, v167
	v_add_u32_e32 v158, s67, v167
	ds_read_b128 v[36:39], v144
	ds_read_b128 v[44:47], v144 offset:1024
	ds_read_b128 v[140:143], v144 offset:2048
	ds_read_b128 v[144:147], v144 offset:3072
	ds_read_b128 v[160:163], v158
	ds_read_b128 v[172:175], v158 offset:1024
	ds_read_b128 v[176:179], v158 offset:2048
	ds_read_b128 v[180:183], v158 offset:3072
	v_lshl_add_u64 v[164:165], s[40:41], 0, v[154:155]
	s_add_i32 m0, s50, 0xc000
	ds_read_b128 v[184:187], v171
	ds_read_b128 v[188:191], v171 offset:1024
	ds_read_b128 v[204:207], v171 offset:2048
	ds_read_b128 v[208:211], v171 offset:3072
	ds_read_b128 v[212:215], v171 offset:4096
	ds_read_b128 v[216:219], v171 offset:5120
	ds_read_b128 v[220:223], v171 offset:6144
	ds_read_b128 v[224:227], v171 offset:7168
	global_load_lds_dwordx4 v[164:165], off
	v_lshl_add_u64 v[164:165], s[40:41], 0, v[156:157]
	s_add_i32 m0, s50, 0xe000
	s_nop 0
	global_load_lds_dwordx4 v[164:165], off
	s_waitcnt vmcnt(8)
	s_waitcnt lgkmcnt(0)
	s_barrier
	s_setprio 1
	s_waitcnt lgkmcnt(0)
	v_mfma_i32_16x16x64_i8 v[136:139], v[36:39], v[184:187], 0
	v_mfma_i32_16x16x64_i8 v[136:139], v[44:47], v[188:191], v[136:139]
	v_mfma_i32_16x16x64_i8 v[120:123], v[44:47], v[208:211], 0
	v_mfma_i32_16x16x64_i8 v[120:123], v[36:39], v[204:207], v[120:123]
	v_mfma_i32_16x16x64_i8 v[104:107], v[36:39], v[212:215], 0
	v_mfma_i32_16x16x64_i8 v[104:107], v[44:47], v[216:219], v[104:107]
	v_mfma_i32_16x16x64_i8 v[88:91], v[44:47], v[224:227], 0
	v_mfma_i32_16x16x64_i8 v[88:91], v[36:39], v[220:223], v[88:91]
	v_mfma_i32_16x16x64_i8 v[80:83], v[140:143], v[220:223], 0
	v_mfma_i32_16x16x64_i8 v[80:83], v[144:147], v[224:227], v[80:83]
	v_mfma_i32_16x16x64_i8 v[96:99], v[144:147], v[216:219], 0
	v_mfma_i32_16x16x64_i8 v[96:99], v[140:143], v[212:215], v[96:99]
	v_mfma_i32_16x16x64_i8 v[112:115], v[140:143], v[204:207], 0
	v_mfma_i32_16x16x64_i8 v[112:115], v[144:147], v[208:211], v[112:115]
	v_mfma_i32_16x16x64_i8 v[128:131], v[144:147], v[188:191], 0
	v_mfma_i32_16x16x64_i8 v[128:131], v[140:143], v[184:187], v[128:131]
	v_mfma_i32_16x16x64_i8 v[132:135], v[160:163], v[184:187], 0
	v_mfma_i32_16x16x64_i8 v[132:135], v[172:175], v[188:191], v[132:135]
	v_mfma_i32_16x16x64_i8 v[116:119], v[172:175], v[208:211], 0
	v_mfma_i32_16x16x64_i8 v[116:119], v[160:163], v[204:207], v[116:119]
	v_mfma_i32_16x16x64_i8 v[100:103], v[160:163], v[212:215], 0
	v_mfma_i32_16x16x64_i8 v[100:103], v[172:175], v[216:219], v[100:103]
	v_mfma_i32_16x16x64_i8 v[84:87], v[172:175], v[224:227], 0
	v_mfma_i32_16x16x64_i8 v[84:87], v[160:163], v[220:223], v[84:87]
	v_mfma_i32_16x16x64_i8 v[76:79], v[176:179], v[220:223], 0
	v_mfma_i32_16x16x64_i8 v[76:79], v[180:183], v[224:227], v[76:79]
	v_mfma_i32_16x16x64_i8 v[92:95], v[180:183], v[216:219], 0
	v_mfma_i32_16x16x64_i8 v[92:95], v[176:179], v[212:215], v[92:95]
	v_mfma_i32_16x16x64_i8 v[108:111], v[176:179], v[204:207], 0
	v_mfma_i32_16x16x64_i8 v[108:111], v[180:183], v[208:211], v[108:111]
	v_mfma_i32_16x16x64_i8 v[124:127], v[180:183], v[188:191], 0
	v_mfma_i32_16x16x64_i8 v[124:127], v[176:179], v[184:187], v[124:127]
	s_setprio 0
	s_barrier
	s_add_i32 s64, s64, s47
	v_lshl_add_u64 v[164:165], s[44:45], 0, v[2:3]
	s_mov_b32 m0, s64
	ds_read_b128 v[184:187], v171 offset:16384
	ds_read_b128 v[188:191], v171 offset:17408
	ds_read_b128 v[204:207], v171 offset:18432
	ds_read_b128 v[208:211], v171 offset:19456
	ds_read_b128 v[212:215], v171 offset:20480
	ds_read_b128 v[216:219], v171 offset:21504
	ds_read_b128 v[220:223], v171 offset:22528
	ds_read_b128 v[224:227], v171 offset:23552
	global_load_lds_dwordx4 v[164:165], off
	s_add_i32 m0, s64, 0x2000
	s_add_u32 s64, s44, 0x80000
	v_lshl_add_u64 v[228:229], s[44:45], 0, v[148:149]
	s_addc_u32 s65, s45, 0
	s_add_i32 s67, s67, s47
	global_load_lds_dwordx4 v[228:229], off
	v_lshl_add_u64 v[240:241], s[64:65], 0, v[2:3]
	s_mov_b32 m0, s67
	v_lshl_add_u64 v[242:243], s[48:49], 0, v[150:151]
	global_load_lds_dwordx4 v[240:241], off
	v_lshl_add_u64 v[240:241], s[64:65], 0, v[148:149]
	s_add_i32 m0, s67, 0x2000
	s_nop 0
	global_load_lds_dwordx4 v[240:241], off
	v_lshl_add_u64 v[240:241], s[48:49], 0, v[152:153]
	s_mov_b32 m0, s50
	s_nop 0
	global_load_lds_dwordx4 v[240:241], off
	s_mov_b32 m0, s51
	s_nop 0
	global_load_lds_dwordx4 v[242:243], off
	s_waitcnt vmcnt(8)
	s_waitcnt lgkmcnt(0)
	s_barrier
; #define PG8_STAGE(bufoff, gbase, voff) do { _Pragma("unroll") for (int _i = 0; _i < 2; ++_i) \
;         __builtin_amdgcn_global_load_lds((const unsigned*)((const char*)(gbase) + (voff)[_i]), (PG8_LAS unsigned*)(lds + (bufoff) + ldsw + _i * 8192), 16, 0, 0); } while (0)
; #define PG8_LDA(dst, b, h) do { _Pragma("unroll") for (int m = 0; m < 4; ++m) _Pragma("unroll") for (int k = 0; k < 2; ++k) dst[m][k] = *(const PG8_LAS bf16x8*)(lds + PG8_SA(b, h) + aoff + m * 2048 + k * 1024); } while (0)
; #define PG8_LDB(dst, b, h) do { _Pragma("unroll") for (int n = 0; n < 2; ++n) _Pragma("unroll") for (int k = 0; k < 2; ++k) dst[n][k] = *(const PG8_LAS bf16x8*)(lds + PG8_SB(b, h) + boff + n * 2048 + k * 1024); } while (0)
; #define PG8_WAIT_V(n) asm volatile("s_waitcnt vmcnt(" #n ")" ::: "memory")
; #define PG8_WAIT_L(n) asm volatile("s_waitcnt lgkmcnt(" #n ")" ::: "memory")
; #define PG8_BAR __builtin_amdgcn_s_barrier()
; #define PG8_SCHED __builtin_amdgcn_sched_barrier(0)
; template <class Epi, class Sched, bool ALIGN_EPI = false, bool SP2 = false, bool I8 = false>
; __device__ __forceinline__ void gemm_phase(PG8_LAS unsigned char* lds, const Gemm g, const Sched& S, const Epi& E) {
;     ...
;             PG8_WAIT_V(8); PG8_WAIT_L(0); PG8_BAR; PG8_MMA(1, 0, At, B0); PG8_MMA(1, 1, At, B1); PG8_BAR; PG8_SCHED;
;             PG8_LDB(B0, 1, 0); PG8_LDB(B1, 1, 1); PG8_SCHED; PG8_LDA(At, 1, 0); PG8_STAGE(PG8_SA(0, 1), a2 + hstep, voffA);
;             PG8_WAIT_V(8); PG8_WAIT_L(0); PG8_BAR; PG8_MMA(0, 0, At, B0); PG8_MMA(0, 1, At, B1); PG8_BAR; PG8_SCHED;
	s_setprio 1
	s_waitcnt lgkmcnt(0)
	v_mfma_i32_16x16x64_i8 v[72:75], v[36:39], v[184:187], 0
	v_mfma_i32_16x16x64_i8 v[72:75], v[44:47], v[188:191], v[72:75]
	v_mfma_i32_16x16x64_i8 v[56:59], v[44:47], v[208:211], 0
	v_mfma_i32_16x16x64_i8 v[56:59], v[36:39], v[204:207], v[56:59]
	v_mfma_i32_16x16x64_i8 v[32:35], v[36:39], v[212:215], 0
	v_mfma_i32_16x16x64_i8 v[32:35], v[44:47], v[216:219], v[32:35]
	v_mfma_i32_16x16x64_i8 v[16:19], v[44:47], v[224:227], 0
	v_mfma_i32_16x16x64_i8 v[16:19], v[36:39], v[220:223], v[16:19]
	v_mfma_i32_16x16x64_i8 v[8:11], v[140:143], v[220:223], 0
	v_mfma_i32_16x16x64_i8 v[8:11], v[144:147], v[224:227], v[8:11]
	v_mfma_i32_16x16x64_i8 v[24:27], v[144:147], v[216:219], 0
	v_mfma_i32_16x16x64_i8 v[24:27], v[140:143], v[212:215], v[24:27]
	v_mfma_i32_16x16x64_i8 v[48:51], v[140:143], v[204:207], 0
	v_mfma_i32_16x16x64_i8 v[48:51], v[144:147], v[208:211], v[48:51]
	v_mfma_i32_16x16x64_i8 v[64:67], v[144:147], v[188:191], 0
	v_mfma_i32_16x16x64_i8 v[64:67], v[140:143], v[184:187], v[64:67]
	v_mfma_i32_16x16x64_i8 v[36:39], v[160:163], v[184:187], 0
	v_mfma_i32_16x16x64_i8 v[36:39], v[172:175], v[188:191], v[36:39]
	v_mfma_i32_16x16x64_i8 v[52:55], v[172:175], v[208:211], 0
	v_mfma_i32_16x16x64_i8 v[52:55], v[160:163], v[204:207], v[52:55]
	v_mfma_i32_16x16x64_i8 v[28:31], v[160:163], v[212:215], 0
	v_mfma_i32_16x16x64_i8 v[28:31], v[172:175], v[216:219], v[28:31]
	v_mfma_i32_16x16x64_i8 v[12:15], v[172:175], v[224:227], 0
	v_mfma_i32_16x16x64_i8 v[12:15], v[160:163], v[220:223], v[12:15]
	v_mfma_i32_16x16x64_i8 v[4:7], v[176:179], v[220:223], 0
	v_mfma_i32_16x16x64_i8 v[4:7], v[180:183], v[224:227], v[4:7]
	v_mfma_i32_16x16x64_i8 v[20:23], v[180:183], v[216:219], 0
	v_mfma_i32_16x16x64_i8 v[20:23], v[176:179], v[212:215], v[20:23]
	v_mfma_i32_16x16x64_i8 v[40:43], v[176:179], v[204:207], 0
	v_mfma_i32_16x16x64_i8 v[40:43], v[180:183], v[208:211], v[40:43]
	v_mfma_i32_16x16x64_i8 v[44:47], v[180:183], v[188:191], 0
	v_mfma_i32_16x16x64_i8 v[44:47], v[176:179], v[184:187], v[44:47]
	s_setprio 0
	s_barrier
	s_add_i32 s64, 0, 0x18000
	s_add_i32 s65, 0, 0x1c000
	v_add_u32_e32 v144, s64, v167
	v_add_u32_e32 v158, s65, v167
	ds_read_b128 v[60:63], v144
	ds_read_b128 v[68:71], v144 offset:1024
	ds_read_b128 v[140:143], v144 offset:2048
	ds_read_b128 v[144:147], v144 offset:3072
	ds_read_b128 v[160:163], v158
	ds_read_b128 v[172:175], v158 offset:1024
	ds_read_b128 v[176:179], v158 offset:2048
	ds_read_b128 v[180:183], v158 offset:3072
	s_add_u32 s48, s48, 0x80000
	s_addc_u32 s49, s49, 0
	s_mov_b32 m0, s52
	v_lshl_add_u64 v[244:245], s[48:49], 0, v[152:153]
	ds_read_b128 v[184:187], v171 offset:32768
	ds_read_b128 v[188:191], v171 offset:33792
	ds_read_b128 v[204:207], v171 offset:34816
	ds_read_b128 v[208:211], v171 offset:35840
	ds_read_b128 v[212:215], v171 offset:36864
	ds_read_b128 v[216:219], v171 offset:37888
	ds_read_b128 v[220:223], v171 offset:38912
	ds_read_b128 v[224:227], v171 offset:39936
	global_load_lds_dwordx4 v[244:245], off
	v_lshl_add_u64 v[244:245], s[48:49], 0, v[150:151]
	s_mov_b32 m0, s53
	s_nop 0
	global_load_lds_dwordx4 v[244:245], off
	s_waitcnt vmcnt(8)
	s_waitcnt lgkmcnt(0)
	s_barrier
	s_setprio 1
	s_waitcnt lgkmcnt(0)
	v_mfma_i32_16x16x64_i8 v[136:139], v[60:63], v[184:187], v[136:139]
	v_mfma_i32_16x16x64_i8 v[136:139], v[68:71], v[188:191], v[136:139]
	v_mfma_i32_16x16x64_i8 v[120:123], v[68:71], v[208:211], v[120:123]
	v_mfma_i32_16x16x64_i8 v[120:123], v[60:63], v[204:207], v[120:123]
	v_mfma_i32_16x16x64_i8 v[104:107], v[60:63], v[212:215], v[104:107]
	v_mfma_i32_16x16x64_i8 v[104:107], v[68:71], v[216:219], v[104:107]
	v_mfma_i32_16x16x64_i8 v[88:91], v[68:71], v[224:227], v[88:91]
	v_mfma_i32_16x16x64_i8 v[88:91], v[60:63], v[220:223], v[88:91]
	v_mfma_i32_16x16x64_i8 v[80:83], v[140:143], v[220:223], v[80:83]
	v_mfma_i32_16x16x64_i8 v[80:83], v[144:147], v[224:227], v[80:83]
	v_mfma_i32_16x16x64_i8 v[96:99], v[144:147], v[216:219], v[96:99]
	v_mfma_i32_16x16x64_i8 v[96:99], v[140:143], v[212:215], v[96:99]
	v_mfma_i32_16x16x64_i8 v[112:115], v[140:143], v[204:207], v[112:115]
	v_mfma_i32_16x16x64_i8 v[112:115], v[144:147], v[208:211], v[112:115]
	v_mfma_i32_16x16x64_i8 v[128:131], v[144:147], v[188:191], v[128:131]
	v_mfma_i32_16x16x64_i8 v[128:131], v[140:143], v[184:187], v[128:131]
	v_mfma_i32_16x16x64_i8 v[132:135], v[160:163], v[184:187], v[132:135]
	v_mfma_i32_16x16x64_i8 v[132:135], v[172:175], v[188:191], v[132:135]
	v_mfma_i32_16x16x64_i8 v[116:119], v[172:175], v[208:211], v[116:119]
	v_mfma_i32_16x16x64_i8 v[116:119], v[160:163], v[204:207], v[116:119]
	v_mfma_i32_16x16x64_i8 v[100:103], v[160:163], v[212:215], v[100:103]
	v_mfma_i32_16x16x64_i8 v[100:103], v[172:175], v[216:219], v[100:103]
	v_mfma_i32_16x16x64_i8 v[84:87], v[172:175], v[224:227], v[84:87]
	v_mfma_i32_16x16x64_i8 v[84:87], v[160:163], v[220:223], v[84:87]
	v_mfma_i32_16x16x64_i8 v[76:79], v[176:179], v[220:223], v[76:79]
	v_mfma_i32_16x16x64_i8 v[76:79], v[180:183], v[224:227], v[76:79]
	v_mfma_i32_16x16x64_i8 v[92:95], v[180:183], v[216:219], v[92:95]
	v_mfma_i32_16x16x64_i8 v[92:95], v[176:179], v[212:215], v[92:95]
	v_mfma_i32_16x16x64_i8 v[108:111], v[176:179], v[204:207], v[108:111]
	v_mfma_i32_16x16x64_i8 v[108:111], v[180:183], v[208:211], v[108:111]
	v_mfma_i32_16x16x64_i8 v[124:127], v[180:183], v[188:191], v[124:127]
	v_mfma_i32_16x16x64_i8 v[124:127], v[176:179], v[184:187], v[124:127]
	s_setprio 0
	s_barrier
; #define PG8_STAGE(bufoff, gbase, voff) do { _Pragma("unroll") for (int _i = 0; _i < 2; ++_i) \
;         __builtin_amdgcn_global_load_lds((const unsigned*)((const char*)(gbase) + (voff)[_i]), (PG8_LAS unsigned*)(lds + (bufoff) + ldsw + _i * 8192), 16, 0, 0); } while (0)
; #define PG8_LDA(dst, b, h) do { _Pragma("unroll") for (int m = 0; m < 4; ++m) _Pragma("unroll") for (int k = 0; k < 2; ++k) dst[m][k] = *(const PG8_LAS bf16x8*)(lds + PG8_SA(b, h) + aoff + m * 2048 + k * 1024); } while (0)
; #define PG8_LDB(dst, b, h) do { _Pragma("unroll") for (int n = 0; n < 2; ++n) _Pragma("unroll") for (int k = 0; k < 2; ++k) dst[n][k] = *(const PG8_LAS bf16x8*)(lds + PG8_SB(b, h) + boff + n * 2048 + k * 1024); } while (0)
; #define PG8_WAIT_V(n) asm volatile("s_waitcnt vmcnt(" #n ")" ::: "memory")
; #define PG8_WAIT_L(n) asm volatile("s_waitcnt lgkmcnt(" #n ")" ::: "memory")
; #define PG8_BAR __builtin_amdgcn_s_barrier()
; #define PG8_SCHED __builtin_amdgcn_sched_barrier(0)
; template <class Epi, class Sched, bool ALIGN_EPI = false, bool SP2 = false, bool I8 = false>
; __device__ __forceinline__ void gemm_phase(PG8_LAS unsigned char* lds, const Gemm g, const Sched& S, const Epi& E) {
;     ...
;         const bool has_next = S.next(ui + 1, nxt);
;         const char* nA = has_next ? (const char*)g.A + (size_t)nxt.pm * tstep : cA; const char* nB = has_next ? (const char*)g.Bt + (size_t)nxt.pn * tstep : cB;
;         for (int t = 0; t < nt; t += 2) {
;             const bool last = (t == nt - 2);
;             const char* a1 = cA + (size_t)(t + 1) * kstep;
;             const char* a2 = last ? nA : cA + (size_t)(t + 2) * kstep; const char* b2 = last ? nB : cB + (size_t)(t + 2) * kstep;
;             const char* a3 = a2 + kstep; const char* b3 = b2 + kstep;
;             if (last && has_next) S.a_ready(nxt);
;             if constexpr (SP2) {
;             PG8_LDB(B0, 0, 0); PG8_LDB(B1, 0, 1); PG8_SCHED; PG8_LDA(At, 0, 0); PG8_STAGE(PG8_SA(1, 1), a1 + hstep, voffA);
;     ...
;             PG8_LDA(At, 1, 1); PG8_STAGE(PG8_SB(1, 0), b3, voffB); PG8_STAGE(PG8_SB(1, 1), b3 + hstep, voffB); PG8_STAGE(PG8_SA(1, 0), a3, voffA);
;             PG8_WAIT_V(8); PG8_WAIT_L(0); PG8_BAR; PG8_MMA(1, 0, At, B0); PG8_MMA(1, 1, At, B1); PG8_BAR; PG8_SCHED;
	s_add_i32 s48, s64, s47
	v_lshl_add_u64 v[164:165], v[164:165], 0, s[84:85]
	s_mov_b32 m0, s48
	ds_read_b128 v[184:187], v171 offset:49152
	ds_read_b128 v[188:191], v171 offset:50176
	ds_read_b128 v[204:207], v171 offset:51200
	ds_read_b128 v[208:211], v171 offset:52224
	ds_read_b128 v[212:215], v171 offset:53248
	ds_read_b128 v[216:219], v171 offset:54272
	ds_read_b128 v[220:223], v171 offset:55296
	ds_read_b128 v[224:227], v171 offset:56320
	global_load_lds_dwordx4 v[164:165], off
	s_add_i32 m0, s48, 0x2000
	s_add_u32 s44, s44, 0x80080
	v_lshl_add_u64 v[164:165], v[228:229], 0, s[84:85]
	s_addc_u32 s45, s45, 0
	s_add_i32 s48, s65, s47
	global_load_lds_dwordx4 v[164:165], off
	v_lshl_add_u64 v[164:165], s[44:45], 0, v[2:3]
	s_mov_b32 m0, s48
	s_nop 0
	global_load_lds_dwordx4 v[164:165], off
	v_lshl_add_u64 v[164:165], s[44:45], 0, v[148:149]
	s_add_i32 m0, s48, 0x2000
	s_nop 0
	global_load_lds_dwordx4 v[164:165], off
	v_lshl_add_u64 v[164:165], v[240:241], 0, s[84:85]
	s_mov_b32 m0, s54
	s_nop 0
	global_load_lds_dwordx4 v[164:165], off
	v_lshl_add_u64 v[164:165], v[242:243], 0, s[84:85]
	s_mov_b32 m0, s55
	s_nop 0
	global_load_lds_dwordx4 v[164:165], off
	s_waitcnt vmcnt(8)
	s_waitcnt lgkmcnt(0)
	s_barrier
	s_setprio 1
	s_waitcnt lgkmcnt(0)
	v_mfma_i32_16x16x64_i8 v[72:75], v[60:63], v[184:187], v[72:75]
	v_mfma_i32_16x16x64_i8 v[72:75], v[68:71], v[188:191], v[72:75]
	v_mfma_i32_16x16x64_i8 v[56:59], v[68:71], v[208:211], v[56:59]
	v_mfma_i32_16x16x64_i8 v[56:59], v[60:63], v[204:207], v[56:59]
	v_mfma_i32_16x16x64_i8 v[32:35], v[60:63], v[212:215], v[32:35]
	v_mfma_i32_16x16x64_i8 v[32:35], v[68:71], v[216:219], v[32:35]
	v_mfma_i32_16x16x64_i8 v[16:19], v[68:71], v[224:227], v[16:19]
	v_mfma_i32_16x16x64_i8 v[16:19], v[60:63], v[220:223], v[16:19]
	v_mfma_i32_16x16x64_i8 v[8:11], v[140:143], v[220:223], v[8:11]
	v_mfma_i32_16x16x64_i8 v[8:11], v[144:147], v[224:227], v[8:11]
	v_mfma_i32_16x16x64_i8 v[24:27], v[144:147], v[216:219], v[24:27]
	v_mfma_i32_16x16x64_i8 v[24:27], v[140:143], v[212:215], v[24:27]
	v_mfma_i32_16x16x64_i8 v[48:51], v[140:143], v[204:207], v[48:51]
	v_mfma_i32_16x16x64_i8 v[48:51], v[144:147], v[208:211], v[48:51]
	v_mfma_i32_16x16x64_i8 v[64:67], v[144:147], v[188:191], v[64:67]
	v_mfma_i32_16x16x64_i8 v[64:67], v[140:143], v[184:187], v[64:67]
	v_mfma_i32_16x16x64_i8 v[36:39], v[160:163], v[184:187], v[36:39]
	v_mfma_i32_16x16x64_i8 v[68:71], v[172:175], v[188:191], v[36:39]
	v_mfma_i32_16x16x64_i8 v[36:39], v[172:175], v[208:211], v[52:55]
	v_mfma_i32_16x16x64_i8 v[52:55], v[160:163], v[204:207], v[36:39]
	v_mfma_i32_16x16x64_i8 v[28:31], v[160:163], v[212:215], v[28:31]
	v_mfma_i32_16x16x64_i8 v[28:31], v[172:175], v[216:219], v[28:31]
	v_mfma_i32_16x16x64_i8 v[12:15], v[172:175], v[224:227], v[12:15]
	v_mfma_i32_16x16x64_i8 v[12:15], v[160:163], v[220:223], v[12:15]
	v_mfma_i32_16x16x64_i8 v[4:7], v[176:179], v[220:223], v[4:7]
	v_mfma_i32_16x16x64_i8 v[4:7], v[180:183], v[224:227], v[4:7]
	v_mfma_i32_16x16x64_i8 v[20:23], v[180:183], v[216:219], v[20:23]
	v_mfma_i32_16x16x64_i8 v[20:23], v[176:179], v[212:215], v[20:23]
	v_mfma_i32_16x16x64_i8 v[36:39], v[176:179], v[204:207], v[40:43]
	v_mfma_i32_16x16x64_i8 v[40:43], v[180:183], v[208:211], v[36:39]
	v_mfma_i32_16x16x64_i8 v[36:39], v[180:183], v[188:191], v[44:47]
	v_mfma_i32_16x16x64_i8 v[60:63], v[176:179], v[184:187], v[36:39]
	s_setprio 0
	s_barrier
	s_add_i32 s61, s61, 2
	s_add_u32 s40, s40, 0x100
	s_addc_u32 s41, s41, 0
	s_add_u32 s59, s59, 0x100
	s_addc_u32 s60, s60, 0
	s_cmp_gt_u32 s61, 29
	s_cbranch_scc1 .Lkloop_exit_3
.LBB0_1591:
	s_add_u32 s44, s40, 0xfff80080
	s_addc_u32 s45, s41, -1
	s_add_i32 s64, 0, 0x10000
	s_cmp_eq_u32 s61, 28
	s_cselect_b32 s49, s25, s45
	s_cselect_b32 s48, s57, s44
	s_cselect_b32 s45, s23, s60
	s_cselect_b32 s44, s58, s59
	s_add_i32 s67, 0, 0x14000
	v_add_u32_e32 v144, s64, v167
	v_add_u32_e32 v158, s67, v167
	ds_read_b128 v[36:39], v144
	ds_read_b128 v[44:47], v144 offset:1024
	ds_read_b128 v[140:143], v144 offset:2048
	ds_read_b128 v[144:147], v144 offset:3072
	ds_read_b128 v[160:163], v158
	ds_read_b128 v[172:175], v158 offset:1024
	ds_read_b128 v[176:179], v158 offset:2048
	ds_read_b128 v[180:183], v158 offset:3072
	v_lshl_add_u64 v[164:165], s[40:41], 0, v[154:155]
	s_add_i32 m0, s50, 0xc000
	ds_read_b128 v[184:187], v171
	ds_read_b128 v[188:191], v171 offset:1024
	ds_read_b128 v[204:207], v171 offset:2048
	ds_read_b128 v[208:211], v171 offset:3072
	ds_read_b128 v[212:215], v171 offset:4096
	ds_read_b128 v[216:219], v171 offset:5120
	ds_read_b128 v[220:223], v171 offset:6144
	ds_read_b128 v[224:227], v171 offset:7168
	global_load_lds_dwordx4 v[164:165], off
	v_lshl_add_u64 v[164:165], s[40:41], 0, v[156:157]
	s_add_i32 m0, s50, 0xe000
	s_nop 0
	global_load_lds_dwordx4 v[164:165], off
	s_waitcnt vmcnt(8)
	s_waitcnt lgkmcnt(0)
	s_barrier
; #define PG8_STAGE(bufoff, gbase, voff) do { _Pragma("unroll") for (int _i = 0; _i < 2; ++_i) \
;         __builtin_amdgcn_global_load_lds((const unsigned*)((const char*)(gbase) + (voff)[_i]), (PG8_LAS unsigned*)(lds + (bufoff) + ldsw + _i * 8192), 16, 0, 0); } while (0)
; #define PG8_LDA(dst, b, h) do { _Pragma("unroll") for (int m = 0; m < 4; ++m) _Pragma("unroll") for (int k = 0; k < 2; ++k) dst[m][k] = *(const PG8_LAS bf16x8*)(lds + PG8_SA(b, h) + aoff + m * 2048 + k * 1024); } while (0)
; #define PG8_WAIT_V(n) asm volatile("s_waitcnt vmcnt(" #n ")" ::: "memory")
; #define PG8_WAIT_L(n) asm volatile("s_waitcnt lgkmcnt(" #n ")" ::: "memory")
; #define PG8_BAR __builtin_amdgcn_s_barrier()
; #define PG8_SCHED __builtin_amdgcn_sched_barrier(0)
; template <class Epi, class Sched, bool ALIGN_EPI = false, bool SP2 = false, bool I8 = false>
; __device__ __forceinline__ void gemm_phase(PG8_LAS unsigned char* lds, const Gemm g, const Sched& S, const Epi& E) {
;     ...
;             PG8_WAIT_V(8); PG8_WAIT_L(0); PG8_BAR; PG8_MMA(0, 0, At, B0); PG8_MMA(0, 1, At, B1); PG8_BAR; PG8_SCHED;
;             PG8_LDA(At, 0, 1); PG8_STAGE(PG8_SB(0, 0), b2, voffB); PG8_STAGE(PG8_SB(0, 1), b2 + hstep, voffB); PG8_STAGE(PG8_SA(0, 0), a2, voffA);
;             PG8_WAIT_V(8); PG8_WAIT_L(0); PG8_BAR; PG8_MMA(1, 0, At, B0); PG8_MMA(1, 1, At, B1); PG8_BAR; PG8_SCHED;
	s_setprio 1
	s_waitcnt lgkmcnt(0)
	v_mfma_i32_16x16x64_i8 v[136:139], v[36:39], v[184:187], v[136:139]
	v_mfma_i32_16x16x64_i8 v[136:139], v[44:47], v[188:191], v[136:139]
	v_mfma_i32_16x16x64_i8 v[120:123], v[44:47], v[208:211], v[120:123]
	v_mfma_i32_16x16x64_i8 v[120:123], v[36:39], v[204:207], v[120:123]
	v_mfma_i32_16x16x64_i8 v[104:107], v[36:39], v[212:215], v[104:107]
	v_mfma_i32_16x16x64_i8 v[104:107], v[44:47], v[216:219], v[104:107]
	v_mfma_i32_16x16x64_i8 v[88:91], v[44:47], v[224:227], v[88:91]
	v_mfma_i32_16x16x64_i8 v[88:91], v[36:39], v[220:223], v[88:91]
	v_mfma_i32_16x16x64_i8 v[80:83], v[140:143], v[220:223], v[80:83]
	v_mfma_i32_16x16x64_i8 v[80:83], v[144:147], v[224:227], v[80:83]
	v_mfma_i32_16x16x64_i8 v[96:99], v[144:147], v[216:219], v[96:99]
	v_mfma_i32_16x16x64_i8 v[96:99], v[140:143], v[212:215], v[96:99]
	v_mfma_i32_16x16x64_i8 v[112:115], v[140:143], v[204:207], v[112:115]
	v_mfma_i32_16x16x64_i8 v[112:115], v[144:147], v[208:211], v[112:115]
	v_mfma_i32_16x16x64_i8 v[128:131], v[144:147], v[188:191], v[128:131]
	v_mfma_i32_16x16x64_i8 v[128:131], v[140:143], v[184:187], v[128:131]
	v_mfma_i32_16x16x64_i8 v[132:135], v[160:163], v[184:187], v[132:135]
	v_mfma_i32_16x16x64_i8 v[132:135], v[172:175], v[188:191], v[132:135]
	v_mfma_i32_16x16x64_i8 v[116:119], v[172:175], v[208:211], v[116:119]
	v_mfma_i32_16x16x64_i8 v[116:119], v[160:163], v[204:207], v[116:119]
	v_mfma_i32_16x16x64_i8 v[100:103], v[160:163], v[212:215], v[100:103]
	v_mfma_i32_16x16x64_i8 v[100:103], v[172:175], v[216:219], v[100:103]
	v_mfma_i32_16x16x64_i8 v[84:87], v[172:175], v[224:227], v[84:87]
	v_mfma_i32_16x16x64_i8 v[84:87], v[160:163], v[220:223], v[84:87]
	v_mfma_i32_16x16x64_i8 v[76:79], v[176:179], v[220:223], v[76:79]
	v_mfma_i32_16x16x64_i8 v[76:79], v[180:183], v[224:227], v[76:79]
	v_mfma_i32_16x16x64_i8 v[92:95], v[180:183], v[216:219], v[92:95]
	v_mfma_i32_16x16x64_i8 v[92:95], v[176:179], v[212:215], v[92:95]
	v_mfma_i32_16x16x64_i8 v[108:111], v[176:179], v[204:207], v[108:111]
	v_mfma_i32_16x16x64_i8 v[108:111], v[180:183], v[208:211], v[108:111]
	v_mfma_i32_16x16x64_i8 v[124:127], v[180:183], v[188:191], v[124:127]
	v_mfma_i32_16x16x64_i8 v[124:127], v[176:179], v[184:187], v[124:127]
	s_setprio 0
	s_barrier
	s_add_i32 s64, s64, s47
	v_lshl_add_u64 v[164:165], s[44:45], 0, v[2:3]
	s_mov_b32 m0, s64
	ds_read_b128 v[184:187], v171 offset:16384
	ds_read_b128 v[188:191], v171 offset:17408
	ds_read_b128 v[204:207], v171 offset:18432
	ds_read_b128 v[208:211], v171 offset:19456
	ds_read_b128 v[212:215], v171 offset:20480
	ds_read_b128 v[216:219], v171 offset:21504
	ds_read_b128 v[220:223], v171 offset:22528
	ds_read_b128 v[224:227], v171 offset:23552
	global_load_lds_dwordx4 v[164:165], off
	s_add_i32 m0, s64, 0x2000
	s_add_u32 s64, s44, 0x80000
	v_lshl_add_u64 v[228:229], s[44:45], 0, v[148:149]
	s_addc_u32 s65, s45, 0
	s_add_i32 s67, s67, s47
	global_load_lds_dwordx4 v[228:229], off
	v_lshl_add_u64 v[240:241], s[64:65], 0, v[2:3]
	s_mov_b32 m0, s67
	v_lshl_add_u64 v[242:243], s[48:49], 0, v[150:151]
	global_load_lds_dwordx4 v[240:241], off
	v_lshl_add_u64 v[240:241], s[64:65], 0, v[148:149]
	s_add_i32 m0, s67, 0x2000
	s_nop 0
	global_load_lds_dwordx4 v[240:241], off
	v_lshl_add_u64 v[240:241], s[48:49], 0, v[152:153]
	s_mov_b32 m0, s50
	s_nop 0
	global_load_lds_dwordx4 v[240:241], off
	s_mov_b32 m0, s51
	s_nop 0
	global_load_lds_dwordx4 v[242:243], off
	s_waitcnt vmcnt(8)
	s_waitcnt lgkmcnt(0)
	s_barrier
	s_setprio 1
	s_waitcnt lgkmcnt(0)
	v_mfma_i32_16x16x64_i8 v[72:75], v[36:39], v[184:187], v[72:75]
	v_mfma_i32_16x16x64_i8 v[72:75], v[44:47], v[188:191], v[72:75]
	v_mfma_i32_16x16x64_i8 v[56:59], v[44:47], v[208:211], v[56:59]
	v_mfma_i32_16x16x64_i8 v[56:59], v[36:39], v[204:207], v[56:59]
	v_mfma_i32_16x16x64_i8 v[32:35], v[36:39], v[212:215], v[32:35]
	v_mfma_i32_16x16x64_i8 v[32:35], v[44:47], v[216:219], v[32:35]
	v_mfma_i32_16x16x64_i8 v[16:19], v[44:47], v[224:227], v[16:19]
	v_mfma_i32_16x16x64_i8 v[16:19], v[36:39], v[220:223], v[16:19]
	v_mfma_i32_16x16x64_i8 v[8:11], v[140:143], v[220:223], v[8:11]
	v_mfma_i32_16x16x64_i8 v[8:11], v[144:147], v[224:227], v[8:11]
	v_mfma_i32_16x16x64_i8 v[24:27], v[144:147], v[216:219], v[24:27]
	v_mfma_i32_16x16x64_i8 v[24:27], v[140:143], v[212:215], v[24:27]
	v_mfma_i32_16x16x64_i8 v[48:51], v[140:143], v[204:207], v[48:51]
	v_mfma_i32_16x16x64_i8 v[48:51], v[144:147], v[208:211], v[48:51]
	v_mfma_i32_16x16x64_i8 v[64:67], v[144:147], v[188:191], v[64:67]
	v_mfma_i32_16x16x64_i8 v[64:67], v[140:143], v[184:187], v[64:67]
	v_mfma_i32_16x16x64_i8 v[36:39], v[160:163], v[184:187], v[68:71]
	v_mfma_i32_16x16x64_i8 v[36:39], v[172:175], v[188:191], v[36:39]
	v_mfma_i32_16x16x64_i8 v[52:55], v[172:175], v[208:211], v[52:55]
	v_mfma_i32_16x16x64_i8 v[52:55], v[160:163], v[204:207], v[52:55]
	v_mfma_i32_16x16x64_i8 v[28:31], v[160:163], v[212:215], v[28:31]
	v_mfma_i32_16x16x64_i8 v[28:31], v[172:175], v[216:219], v[28:31]
	v_mfma_i32_16x16x64_i8 v[12:15], v[172:175], v[224:227], v[12:15]
	v_mfma_i32_16x16x64_i8 v[12:15], v[160:163], v[220:223], v[12:15]
	v_mfma_i32_16x16x64_i8 v[4:7], v[176:179], v[220:223], v[4:7]
	v_mfma_i32_16x16x64_i8 v[4:7], v[180:183], v[224:227], v[4:7]
	v_mfma_i32_16x16x64_i8 v[20:23], v[180:183], v[216:219], v[20:23]
	v_mfma_i32_16x16x64_i8 v[20:23], v[176:179], v[212:215], v[20:23]
	v_mfma_i32_16x16x64_i8 v[40:43], v[176:179], v[204:207], v[40:43]
	v_mfma_i32_16x16x64_i8 v[40:43], v[180:183], v[208:211], v[40:43]
	v_mfma_i32_16x16x64_i8 v[44:47], v[180:183], v[188:191], v[60:63]
	v_mfma_i32_16x16x64_i8 v[44:47], v[176:179], v[184:187], v[44:47]
	s_setprio 0
	s_barrier
; #define PG8_STAGE(bufoff, gbase, voff) do { _Pragma("unroll") for (int _i = 0; _i < 2; ++_i) \
;         __builtin_amdgcn_global_load_lds((const unsigned*)((const char*)(gbase) + (voff)[_i]), (PG8_LAS unsigned*)(lds + (bufoff) + ldsw + _i * 8192), 16, 0, 0); } while (0)
; #define PG8_LDA(dst, b, h) do { _Pragma("unroll") for (int m = 0; m < 4; ++m) _Pragma("unroll") for (int k = 0; k < 2; ++k) dst[m][k] = *(const PG8_LAS bf16x8*)(lds + PG8_SA(b, h) + aoff + m * 2048 + k * 1024); } while (0)
; #define PG8_LDB(dst, b, h) do { _Pragma("unroll") for (int n = 0; n < 2; ++n) _Pragma("unroll") for (int k = 0; k < 2; ++k) dst[n][k] = *(const PG8_LAS bf16x8*)(lds + PG8_SB(b, h) + boff + n * 2048 + k * 1024); } while (0)
; #define PG8_WAIT_V(n) asm volatile("s_waitcnt vmcnt(" #n ")" ::: "memory")
; #define PG8_WAIT_L(n) asm volatile("s_waitcnt lgkmcnt(" #n ")" ::: "memory")
; #define PG8_BAR __builtin_amdgcn_s_barrier()
; #define PG8_SCHED __builtin_amdgcn_sched_barrier(0)
; template <class Epi, class Sched, bool ALIGN_EPI = false, bool SP2 = false, bool I8 = false>
; __device__ __forceinline__ void gemm_phase(PG8_LAS unsigned char* lds, const Gemm g, const Sched& S, const Epi& E) {
;     ...
;             PG8_LDB(B0, 1, 0); PG8_LDB(B1, 1, 1); PG8_SCHED; PG8_LDA(At, 1, 0); PG8_STAGE(PG8_SA(0, 1), a2 + hstep, voffA);
;             PG8_WAIT_V(8); PG8_WAIT_L(0); PG8_BAR; PG8_MMA(0, 0, At, B0); PG8_MMA(0, 1, At, B1); PG8_BAR; PG8_SCHED;
;             PG8_LDA(At, 1, 1); PG8_STAGE(PG8_SB(1, 0), b3, voffB); PG8_STAGE(PG8_SB(1, 1), b3 + hstep, voffB); PG8_STAGE(PG8_SA(1, 0), a3, voffA);
;             PG8_WAIT_V(8); PG8_WAIT_L(0); PG8_BAR; PG8_MMA(1, 0, At, B0); PG8_MMA(1, 1, At, B1); PG8_BAR; PG8_SCHED;
	s_add_i32 s64, 0, 0x18000
	s_add_i32 s65, 0, 0x1c000
	v_add_u32_e32 v144, s64, v167
	v_add_u32_e32 v158, s65, v167
	ds_read_b128 v[60:63], v144
	ds_read_b128 v[68:71], v144 offset:1024
	ds_read_b128 v[140:143], v144 offset:2048
	ds_read_b128 v[144:147], v144 offset:3072
	ds_read_b128 v[160:163], v158
	ds_read_b128 v[172:175], v158 offset:1024
	ds_read_b128 v[176:179], v158 offset:2048
	ds_read_b128 v[180:183], v158 offset:3072
	s_add_u32 s48, s48, 0x80000
	s_addc_u32 s49, s49, 0
	s_mov_b32 m0, s52
	v_lshl_add_u64 v[244:245], s[48:49], 0, v[152:153]
	ds_read_b128 v[184:187], v171 offset:32768
	ds_read_b128 v[188:191], v171 offset:33792
	ds_read_b128 v[204:207], v171 offset:34816
	ds_read_b128 v[208:211], v171 offset:35840
	ds_read_b128 v[212:215], v171 offset:36864
	ds_read_b128 v[216:219], v171 offset:37888
	ds_read_b128 v[220:223], v171 offset:38912
	ds_read_b128 v[224:227], v171 offset:39936
	global_load_lds_dwordx4 v[244:245], off
	v_lshl_add_u64 v[244:245], s[48:49], 0, v[150:151]
	s_mov_b32 m0, s53
	s_nop 0
	global_load_lds_dwordx4 v[244:245], off
	s_waitcnt vmcnt(8)
	s_waitcnt lgkmcnt(0)
	s_barrier
	s_setprio 1
	s_waitcnt lgkmcnt(0)
	v_mfma_i32_16x16x64_i8 v[136:139], v[60:63], v[184:187], v[136:139]
	v_mfma_i32_16x16x64_i8 v[136:139], v[68:71], v[188:191], v[136:139]
	v_mfma_i32_16x16x64_i8 v[120:123], v[68:71], v[208:211], v[120:123]
	v_mfma_i32_16x16x64_i8 v[120:123], v[60:63], v[204:207], v[120:123]
	v_mfma_i32_16x16x64_i8 v[104:107], v[60:63], v[212:215], v[104:107]
	v_mfma_i32_16x16x64_i8 v[104:107], v[68:71], v[216:219], v[104:107]
	v_mfma_i32_16x16x64_i8 v[88:91], v[68:71], v[224:227], v[88:91]
	v_mfma_i32_16x16x64_i8 v[88:91], v[60:63], v[220:223], v[88:91]
	v_mfma_i32_16x16x64_i8 v[80:83], v[140:143], v[220:223], v[80:83]
	v_mfma_i32_16x16x64_i8 v[80:83], v[144:147], v[224:227], v[80:83]
	v_mfma_i32_16x16x64_i8 v[96:99], v[144:147], v[216:219], v[96:99]
	v_mfma_i32_16x16x64_i8 v[96:99], v[140:143], v[212:215], v[96:99]
	v_mfma_i32_16x16x64_i8 v[112:115], v[140:143], v[204:207], v[112:115]
	v_mfma_i32_16x16x64_i8 v[112:115], v[144:147], v[208:211], v[112:115]
	v_mfma_i32_16x16x64_i8 v[128:131], v[144:147], v[188:191], v[128:131]
	v_mfma_i32_16x16x64_i8 v[128:131], v[140:143], v[184:187], v[128:131]
	v_mfma_i32_16x16x64_i8 v[132:135], v[160:163], v[184:187], v[132:135]
	v_mfma_i32_16x16x64_i8 v[132:135], v[172:175], v[188:191], v[132:135]
	v_mfma_i32_16x16x64_i8 v[116:119], v[172:175], v[208:211], v[116:119]
	v_mfma_i32_16x16x64_i8 v[116:119], v[160:163], v[204:207], v[116:119]
	v_mfma_i32_16x16x64_i8 v[100:103], v[160:163], v[212:215], v[100:103]
	v_mfma_i32_16x16x64_i8 v[100:103], v[172:175], v[216:219], v[100:103]
	v_mfma_i32_16x16x64_i8 v[84:87], v[172:175], v[224:227], v[84:87]
	v_mfma_i32_16x16x64_i8 v[84:87], v[160:163], v[220:223], v[84:87]
	v_mfma_i32_16x16x64_i8 v[76:79], v[176:179], v[220:223], v[76:79]
	v_mfma_i32_16x16x64_i8 v[76:79], v[180:183], v[224:227], v[76:79]
	v_mfma_i32_16x16x64_i8 v[92:95], v[180:183], v[216:219], v[92:95]
	v_mfma_i32_16x16x64_i8 v[92:95], v[176:179], v[212:215], v[92:95]
	v_mfma_i32_16x16x64_i8 v[108:111], v[176:179], v[204:207], v[108:111]
	v_mfma_i32_16x16x64_i8 v[108:111], v[180:183], v[208:211], v[108:111]
	v_mfma_i32_16x16x64_i8 v[124:127], v[180:183], v[188:191], v[124:127]
	v_mfma_i32_16x16x64_i8 v[124:127], v[176:179], v[184:187], v[124:127]
	s_setprio 0
	s_barrier
	s_add_i32 s48, s64, s47
	v_lshl_add_u64 v[164:165], v[164:165], 0, s[84:85]
	s_mov_b32 m0, s48
	ds_read_b128 v[184:187], v171 offset:49152
	ds_read_b128 v[188:191], v171 offset:50176
	ds_read_b128 v[204:207], v171 offset:51200
	ds_read_b128 v[208:211], v171 offset:52224
	ds_read_b128 v[212:215], v171 offset:53248
	ds_read_b128 v[216:219], v171 offset:54272
	ds_read_b128 v[220:223], v171 offset:55296
	ds_read_b128 v[224:227], v171 offset:56320
	global_load_lds_dwordx4 v[164:165], off
	s_add_i32 m0, s48, 0x2000
	s_add_u32 s44, s44, 0x80080
	v_lshl_add_u64 v[164:165], v[228:229], 0, s[84:85]
	s_addc_u32 s45, s45, 0
	s_add_i32 s48, s65, s47
	global_load_lds_dwordx4 v[164:165], off
	v_lshl_add_u64 v[164:165], s[44:45], 0, v[2:3]
	s_mov_b32 m0, s48
	s_nop 0
	global_load_lds_dwordx4 v[164:165], off
	v_lshl_add_u64 v[164:165], s[44:45], 0, v[148:149]
	s_add_i32 m0, s48, 0x2000
	s_nop 0
	global_load_lds_dwordx4 v[164:165], off
	v_lshl_add_u64 v[164:165], v[240:241], 0, s[84:85]
	s_mov_b32 m0, s54
	s_nop 0
	global_load_lds_dwordx4 v[164:165], off
	v_lshl_add_u64 v[164:165], v[242:243], 0, s[84:85]
	s_mov_b32 m0, s55
	s_nop 0
	global_load_lds_dwordx4 v[164:165], off
	s_waitcnt vmcnt(8)
	s_waitcnt lgkmcnt(0)
	s_barrier
	s_setprio 1
	s_waitcnt lgkmcnt(0)
	v_mfma_i32_16x16x64_i8 v[72:75], v[60:63], v[184:187], v[72:75]
	v_mfma_i32_16x16x64_i8 v[72:75], v[68:71], v[188:191], v[72:75]
	v_mfma_i32_16x16x64_i8 v[56:59], v[68:71], v[208:211], v[56:59]
	v_mfma_i32_16x16x64_i8 v[56:59], v[60:63], v[204:207], v[56:59]
	v_mfma_i32_16x16x64_i8 v[32:35], v[60:63], v[212:215], v[32:35]
	v_mfma_i32_16x16x64_i8 v[32:35], v[68:71], v[216:219], v[32:35]
	v_mfma_i32_16x16x64_i8 v[16:19], v[68:71], v[224:227], v[16:19]
	v_mfma_i32_16x16x64_i8 v[16:19], v[60:63], v[220:223], v[16:19]
	v_mfma_i32_16x16x64_i8 v[8:11], v[140:143], v[220:223], v[8:11]
	v_mfma_i32_16x16x64_i8 v[8:11], v[144:147], v[224:227], v[8:11]
	v_mfma_i32_16x16x64_i8 v[24:27], v[144:147], v[216:219], v[24:27]
	v_mfma_i32_16x16x64_i8 v[24:27], v[140:143], v[212:215], v[24:27]
	v_mfma_i32_16x16x64_i8 v[48:51], v[140:143], v[204:207], v[48:51]
	v_mfma_i32_16x16x64_i8 v[48:51], v[144:147], v[208:211], v[48:51]
	v_mfma_i32_16x16x64_i8 v[64:67], v[144:147], v[188:191], v[64:67]
	v_mfma_i32_16x16x64_i8 v[64:67], v[140:143], v[184:187], v[64:67]
	v_mfma_i32_16x16x64_i8 v[36:39], v[160:163], v[184:187], v[36:39]
	v_mfma_i32_16x16x64_i8 v[68:71], v[172:175], v[188:191], v[36:39]
	v_mfma_i32_16x16x64_i8 v[36:39], v[172:175], v[208:211], v[52:55]
	v_mfma_i32_16x16x64_i8 v[52:55], v[160:163], v[204:207], v[36:39]
	v_mfma_i32_16x16x64_i8 v[28:31], v[160:163], v[212:215], v[28:31]
	v_mfma_i32_16x16x64_i8 v[28:31], v[172:175], v[216:219], v[28:31]
	v_mfma_i32_16x16x64_i8 v[12:15], v[172:175], v[224:227], v[12:15]
	v_mfma_i32_16x16x64_i8 v[12:15], v[160:163], v[220:223], v[12:15]
	v_mfma_i32_16x16x64_i8 v[4:7], v[176:179], v[220:223], v[4:7]
	v_mfma_i32_16x16x64_i8 v[4:7], v[180:183], v[224:227], v[4:7]
	v_mfma_i32_16x16x64_i8 v[20:23], v[180:183], v[216:219], v[20:23]
	v_mfma_i32_16x16x64_i8 v[20:23], v[176:179], v[212:215], v[20:23]
	v_mfma_i32_16x16x64_i8 v[36:39], v[176:179], v[204:207], v[40:43]
	v_mfma_i32_16x16x64_i8 v[40:43], v[180:183], v[208:211], v[36:39]
	v_mfma_i32_16x16x64_i8 v[36:39], v[180:183], v[188:191], v[44:47]
	v_mfma_i32_16x16x64_i8 v[60:63], v[176:179], v[184:187], v[36:39]
	s_setprio 0
	s_barrier
	s_add_i32 s61, s61, 2
	s_add_u32 s40, s40, 0x100
	s_addc_u32 s41, s41, 0
	s_add_u32 s59, s59, 0x100
	s_addc_u32 s60, s60, 0
	s_cmp_gt_u32 s61, 29
	s_cbranch_scc0 .LBB0_1591

; #define PG8_STAGE(bufoff, gbase, voff) do { _Pragma("unroll") for (int _i = 0; _i < 2; ++_i) \
;         __builtin_amdgcn_global_load_lds((const unsigned*)((const char*)(gbase) + (voff)[_i]), (PG8_LAS unsigned*)(lds + (bufoff) + ldsw + _i * 8192), 16, 0, 0); } while (0)
; #define PG8_LDA(dst, b, h) do { _Pragma("unroll") for (int m = 0; m < 4; ++m) _Pragma("unroll") for (int k = 0; k < 2; ++k) dst[m][k] = *(const PG8_LAS bf16x8*)(lds + PG8_SA(b, h) + aoff + m * 2048 + k * 1024); } while (0)
; #define PG8_LDB(dst, b, h) do { _Pragma("unroll") for (int n = 0; n < 2; ++n) _Pragma("unroll") for (int k = 0; k < 2; ++k) dst[n][k] = *(const PG8_LAS bf16x8*)(lds + PG8_SB(b, h) + boff + n * 2048 + k * 1024); } while (0)
; #define PG8_SCHED __builtin_amdgcn_sched_barrier(0)
; template <class Epi, class Sched, bool ALIGN_EPI = false, bool SP2 = false, bool I8 = false>
; __device__ __forceinline__ void gemm_phase(PG8_LAS unsigned char* lds, const Gemm g, const Sched& S, const Epi& E) {
;     ...
;         const bool has_next = S.next(ui + 1, nxt);
;         const char* nA = has_next ? (const char*)g.A + (size_t)nxt.pm * tstep : cA; const char* nB = has_next ? (const char*)g.Bt + (size_t)nxt.pn * tstep : cB;
;         for (int t = 0; t < nt; t += 2) {
;             const bool last = (t == nt - 2);
;             const char* a1 = cA + (size_t)(t + 1) * kstep;
;             const char* a2 = last ? nA : cA + (size_t)(t + 2) * kstep; const char* b2 = last ? nB : cB + (size_t)(t + 2) * kstep;
;             const char* a3 = a2 + kstep; const char* b3 = b2 + kstep;
;             if (last && has_next) S.a_ready(nxt);
;             if constexpr (SP2) {
;             PG8_LDB(B0, 0, 0); PG8_LDB(B1, 0, 1); PG8_SCHED; PG8_LDA(At, 0, 0); PG8_STAGE(PG8_SA(1, 1), a1 + hstep, voffA);
;     ...
; #pragma unroll
;         for (int a = 0; a < 2; ++a)
; #pragma unroll
;             for (int b = 0; b < 2; ++b)
; #pragma unroll
;                 for (int m = 0; m < 4; ++m)
; #pragma unroll
;                     for (int n = 0; n < 2; ++n) acc[a][b][m][n] = (acc_t){0, 0, 0, 0};
.LBB0_1621:
	v_mov_b32_e32 v127, 0
	s_andn2_b64 vcc, exec, s[26:27]
	v_mov_b32_e32 v126, v127
	v_mov_b32_e32 v125, v127
	v_mov_b32_e32 v124, v127
	v_mov_b32_e32 v131, v127
	v_mov_b32_e32 v130, v127
	v_mov_b32_e32 v129, v127
	v_mov_b32_e32 v128, v127
	v_mov_b32_e32 v115, v127
	v_mov_b32_e32 v114, v127
	v_mov_b32_e32 v113, v127
	v_mov_b32_e32 v112, v127
	v_mov_b32_e32 v111, v127
	v_mov_b32_e32 v110, v127
	v_mov_b32_e32 v109, v127
	v_mov_b32_e32 v108, v127
	v_mov_b32_e32 v99, v127
	v_mov_b32_e32 v98, v127
	v_mov_b32_e32 v97, v127
	v_mov_b32_e32 v96, v127
	v_mov_b32_e32 v95, v127
	v_mov_b32_e32 v94, v127
	v_mov_b32_e32 v93, v127
	v_mov_b32_e32 v92, v127
	v_mov_b32_e32 v83, v127
	v_mov_b32_e32 v82, v127
	v_mov_b32_e32 v81, v127
	v_mov_b32_e32 v80, v127
	v_mov_b32_e32 v79, v127
	v_mov_b32_e32 v78, v127
	v_mov_b32_e32 v77, v127
	v_mov_b32_e32 v76, v127
	v_mov_b32_e32 v123, v127
	v_mov_b32_e32 v122, v127
	v_mov_b32_e32 v121, v127
	v_mov_b32_e32 v120, v127
	v_mov_b32_e32 v119, v127
	v_mov_b32_e32 v118, v127
	v_mov_b32_e32 v117, v127
	v_mov_b32_e32 v116, v127
	v_mov_b32_e32 v107, v127
	v_mov_b32_e32 v106, v127
	v_mov_b32_e32 v105, v127
	v_mov_b32_e32 v104, v127
	v_mov_b32_e32 v103, v127
	v_mov_b32_e32 v102, v127
	v_mov_b32_e32 v101, v127
	v_mov_b32_e32 v100, v127
	v_mov_b32_e32 v91, v127
	v_mov_b32_e32 v90, v127
	v_mov_b32_e32 v89, v127
	v_mov_b32_e32 v88, v127
	v_mov_b32_e32 v87, v127
	v_mov_b32_e32 v86, v127
	v_mov_b32_e32 v85, v127
	v_mov_b32_e32 v84, v127
	v_mov_b32_e32 v75, v127
	v_mov_b32_e32 v74, v127
	v_mov_b32_e32 v73, v127
	v_mov_b32_e32 v72, v127
	v_mov_b32_e32 v71, v127
	v_mov_b32_e32 v70, v127
	v_mov_b32_e32 v69, v127
	v_mov_b32_e32 v68, v127
	v_mov_b32_e32 v67, v127
	v_mov_b32_e32 v66, v127
	v_mov_b32_e32 v65, v127
	v_mov_b32_e32 v64, v127
	v_mov_b32_e32 v63, v127
	v_mov_b32_e32 v62, v127
	v_mov_b32_e32 v61, v127
	v_mov_b32_e32 v60, v127
	v_mov_b32_e32 v51, v127
	v_mov_b32_e32 v50, v127
	v_mov_b32_e32 v49, v127
	v_mov_b32_e32 v48, v127
	v_mov_b32_e32 v47, v127
	v_mov_b32_e32 v46, v127
	v_mov_b32_e32 v45, v127
	v_mov_b32_e32 v44, v127
	v_mov_b32_e32 v35, v127
	v_mov_b32_e32 v34, v127
	v_mov_b32_e32 v33, v127
	v_mov_b32_e32 v32, v127
	v_mov_b32_e32 v31, v127
	v_mov_b32_e32 v30, v127
	v_mov_b32_e32 v29, v127
	v_mov_b32_e32 v28, v127
	v_mov_b32_e32 v19, v127
	v_mov_b32_e32 v18, v127
	v_mov_b32_e32 v17, v127
	v_mov_b32_e32 v16, v127
	v_mov_b32_e32 v15, v127
	v_mov_b32_e32 v14, v127
	v_mov_b32_e32 v13, v127
	v_mov_b32_e32 v12, v127
	v_mov_b32_e32 v59, v127
	v_mov_b32_e32 v58, v127
	v_mov_b32_e32 v57, v127
	v_mov_b32_e32 v56, v127
	v_mov_b32_e32 v55, v127
	v_mov_b32_e32 v54, v127
	v_mov_b32_e32 v53, v127
	v_mov_b32_e32 v52, v127
	v_mov_b32_e32 v43, v127
	v_mov_b32_e32 v42, v127
	v_mov_b32_e32 v41, v127
	v_mov_b32_e32 v40, v127
	v_mov_b32_e32 v39, v127
	v_mov_b32_e32 v38, v127
	v_mov_b32_e32 v37, v127
	v_mov_b32_e32 v36, v127
	v_mov_b32_e32 v27, v127
	v_mov_b32_e32 v26, v127
	v_mov_b32_e32 v25, v127
	v_mov_b32_e32 v24, v127
	v_mov_b32_e32 v23, v127
	v_mov_b32_e32 v22, v127
	v_mov_b32_e32 v21, v127
	v_mov_b32_e32 v20, v127
	v_mov_b32_e32 v11, v127
	v_mov_b32_e32 v10, v127
	v_mov_b32_e32 v9, v127
	v_mov_b32_e32 v8, v127
	v_mov_b32_e32 v7, v127
	v_mov_b32_e32 v6, v127
	v_mov_b32_e32 v5, v127
	v_mov_b32_e32 v4, v127
	s_cbranch_vccnz .LBB0_1625
	s_add_u32 s44, s44, 0x80
	s_addc_u32 s45, s45, 0
	s_add_u32 s65, s48, 0x100
	s_addc_u32 s67, s49, 0
	s_mov_b32 s48, 0
	s_add_i32 s72, s48, 2
	s_add_u32 s73, s44, 0x80
	s_addc_u32 s49, s45, 0
	s_add_i32 s86, 0, 0x10000
	s_cmp_eq_u32 s57, s48
	s_cselect_b32 s49, s13, s49
	s_cselect_b32 s48, s12, s73
	s_cselect_b32 s77, s41, s67
	s_cselect_b32 s76, s40, s65
	s_add_i32 s73, 0, 0x14000
	v_add_u32_e32 v158, s86, v143
	v_add_u32_e32 v174, s73, v143
	ds_read_b128 v[146:149], v158
	ds_read_b128 v[150:153], v158 offset:1024
	ds_read_b128 v[154:157], v158 offset:2048
	ds_read_b128 v[158:161], v158 offset:3072
	ds_read_b128 v[162:165], v174
	ds_read_b128 v[166:169], v174 offset:1024
	ds_read_b128 v[170:173], v174 offset:2048
	ds_read_b128 v[174:177], v174 offset:3072
	v_lshl_add_u64 v[190:191], s[44:45], 0, v[138:139]
	s_add_i32 m0, s47, 0xc000
	ds_read_b128 v[178:181], v145
	ds_read_b128 v[182:185], v145 offset:1024
	ds_read_b128 v[186:189], v145 offset:2048
	ds_read_b128 v[204:207], v145 offset:3072
	ds_read_b128 v[208:211], v145 offset:4096
	ds_read_b128 v[212:215], v145 offset:5120
	ds_read_b128 v[216:219], v145 offset:6144
	ds_read_b128 v[220:223], v145 offset:7168
	global_load_lds_dwordx4 v[190:191], off
	v_lshl_add_u64 v[190:191], s[44:45], 0, v[140:141]
	s_add_i32 m0, s47, 0xe000
	s_nop 0
	global_load_lds_dwordx4 v[190:191], off
	s_waitcnt vmcnt(8)
	s_waitcnt lgkmcnt(0)
	s_barrier
; #define PG8_STAGE(bufoff, gbase, voff) do { _Pragma("unroll") for (int _i = 0; _i < 2; ++_i) \
;         __builtin_amdgcn_global_load_lds((const unsigned*)((const char*)(gbase) + (voff)[_i]), (PG8_LAS unsigned*)(lds + (bufoff) + ldsw + _i * 8192), 16, 0, 0); } while (0)
; #define PG8_LDA(dst, b, h) do { _Pragma("unroll") for (int m = 0; m < 4; ++m) _Pragma("unroll") for (int k = 0; k < 2; ++k) dst[m][k] = *(const PG8_LAS bf16x8*)(lds + PG8_SA(b, h) + aoff + m * 2048 + k * 1024); } while (0)
; #define PG8_WAIT_V(n) asm volatile("s_waitcnt vmcnt(" #n ")" ::: "memory")
; #define PG8_WAIT_L(n) asm volatile("s_waitcnt lgkmcnt(" #n ")" ::: "memory")
; #define PG8_BAR __builtin_amdgcn_s_barrier()
; #define PG8_SCHED __builtin_amdgcn_sched_barrier(0)
; template <class Epi, class Sched, bool ALIGN_EPI = false, bool SP2 = false, bool I8 = false>
; __device__ __forceinline__ void gemm_phase(PG8_LAS unsigned char* lds, const Gemm g, const Sched& S, const Epi& E) {
;     ...
;             PG8_WAIT_V(8); PG8_WAIT_L(0); PG8_BAR; PG8_MMA(0, 0, At, B0); PG8_MMA(0, 1, At, B1); PG8_BAR; PG8_SCHED;
;             PG8_LDA(At, 0, 1); PG8_STAGE(PG8_SB(0, 0), b2, voffB); PG8_STAGE(PG8_SB(0, 1), b2 + hstep, voffB); PG8_STAGE(PG8_SA(0, 0), a2, voffA);
;             PG8_WAIT_V(8); PG8_WAIT_L(0); PG8_BAR; PG8_MMA(1, 0, At, B0); PG8_MMA(1, 1, At, B1); PG8_BAR; PG8_SCHED;
	s_setprio 1
	s_waitcnt lgkmcnt(0)
	v_mfma_f32_16x16x32_bf16 v[124:127], v[146:149], v[178:181], 0
	v_mfma_f32_16x16x32_bf16 v[124:127], v[150:153], v[182:185], v[124:127]
	v_mfma_f32_16x16x32_bf16 v[112:115], v[150:153], v[204:207], 0
	v_mfma_f32_16x16x32_bf16 v[112:115], v[146:149], v[186:189], v[112:115]
	v_mfma_f32_16x16x32_bf16 v[96:99], v[146:149], v[208:211], 0
	v_mfma_f32_16x16x32_bf16 v[96:99], v[150:153], v[212:215], v[96:99]
	v_mfma_f32_16x16x32_bf16 v[80:83], v[150:153], v[220:223], 0
	v_mfma_f32_16x16x32_bf16 v[80:83], v[146:149], v[216:219], v[80:83]
	v_mfma_f32_16x16x32_bf16 v[76:79], v[154:157], v[216:219], 0
	v_mfma_f32_16x16x32_bf16 v[76:79], v[158:161], v[220:223], v[76:79]
	v_mfma_f32_16x16x32_bf16 v[92:95], v[158:161], v[212:215], 0
	v_mfma_f32_16x16x32_bf16 v[92:95], v[154:157], v[208:211], v[92:95]
	v_mfma_f32_16x16x32_bf16 v[108:111], v[154:157], v[186:189], 0
	v_mfma_f32_16x16x32_bf16 v[108:111], v[158:161], v[204:207], v[108:111]
	v_mfma_f32_16x16x32_bf16 v[128:131], v[158:161], v[182:185], 0
	v_mfma_f32_16x16x32_bf16 v[128:131], v[154:157], v[178:181], v[128:131]
	v_mfma_f32_16x16x32_bf16 v[120:123], v[162:165], v[178:181], 0
	v_mfma_f32_16x16x32_bf16 v[120:123], v[166:169], v[182:185], v[120:123]
	v_mfma_f32_16x16x32_bf16 v[104:107], v[166:169], v[204:207], 0
	v_mfma_f32_16x16x32_bf16 v[104:107], v[162:165], v[186:189], v[104:107]
	v_mfma_f32_16x16x32_bf16 v[88:91], v[162:165], v[208:211], 0
	v_mfma_f32_16x16x32_bf16 v[88:91], v[166:169], v[212:215], v[88:91]
	v_mfma_f32_16x16x32_bf16 v[72:75], v[166:169], v[220:223], 0
	v_mfma_f32_16x16x32_bf16 v[72:75], v[162:165], v[216:219], v[72:75]
	v_mfma_f32_16x16x32_bf16 v[68:71], v[170:173], v[216:219], 0
	v_mfma_f32_16x16x32_bf16 v[68:71], v[174:177], v[220:223], v[68:71]
	v_mfma_f32_16x16x32_bf16 v[84:87], v[174:177], v[212:215], 0
	v_mfma_f32_16x16x32_bf16 v[84:87], v[170:173], v[208:211], v[84:87]
	v_mfma_f32_16x16x32_bf16 v[100:103], v[170:173], v[186:189], 0
	v_mfma_f32_16x16x32_bf16 v[100:103], v[174:177], v[204:207], v[100:103]
	v_mfma_f32_16x16x32_bf16 v[116:119], v[174:177], v[182:185], 0
	v_mfma_f32_16x16x32_bf16 v[116:119], v[170:173], v[178:181], v[116:119]
	s_setprio 0
	s_barrier
	s_add_i32 s86, s86, s28
	v_lshl_add_u64 v[190:191], s[76:77], 0, v[2:3]
	s_mov_b32 m0, s86
	ds_read_b128 v[178:181], v145 offset:16384
	ds_read_b128 v[182:185], v145 offset:17408
	ds_read_b128 v[186:189], v145 offset:18432
	ds_read_b128 v[204:207], v145 offset:19456
	ds_read_b128 v[208:211], v145 offset:20480
	ds_read_b128 v[212:215], v145 offset:21504
	ds_read_b128 v[216:219], v145 offset:22528
	ds_read_b128 v[220:223], v145 offset:23552
	global_load_lds_dwordx4 v[190:191], off
	s_add_i32 m0, s86, 0x2000
	v_lshl_add_u64 v[224:225], s[76:77], 0, v[136:137]
	s_add_u32 s76, s76, s18
	s_addc_u32 s77, s77, s19
	s_add_i32 s73, s73, s28
	global_load_lds_dwordx4 v[224:225], off
	v_lshl_add_u64 v[226:227], s[76:77], 0, v[2:3]
	s_mov_b32 m0, s73
	v_lshl_add_u64 v[228:229], s[76:77], 0, v[136:137]
	global_load_lds_dwordx4 v[226:227], off
	s_add_i32 m0, s73, 0x2000
	v_lshl_add_u64 v[240:241], s[48:49], 0, v[132:133]
	global_load_lds_dwordx4 v[228:229], off
	s_mov_b32 m0, s47
	v_lshl_add_u64 v[242:243], s[48:49], 0, v[134:135]
	global_load_lds_dwordx4 v[240:241], off
	s_mov_b32 m0, s50
	s_nop 0
	global_load_lds_dwordx4 v[242:243], off
	s_waitcnt vmcnt(8)
	s_waitcnt lgkmcnt(0)
	s_barrier
	s_setprio 1
	s_waitcnt lgkmcnt(0)
	v_mfma_f32_16x16x32_bf16 v[64:67], v[146:149], v[178:181], 0
	v_mfma_f32_16x16x32_bf16 v[64:67], v[150:153], v[182:185], v[64:67]
	v_mfma_f32_16x16x32_bf16 v[48:51], v[150:153], v[204:207], 0
	v_mfma_f32_16x16x32_bf16 v[48:51], v[146:149], v[186:189], v[48:51]
	v_mfma_f32_16x16x32_bf16 v[32:35], v[146:149], v[208:211], 0
	v_mfma_f32_16x16x32_bf16 v[32:35], v[150:153], v[212:215], v[32:35]
	v_mfma_f32_16x16x32_bf16 v[16:19], v[150:153], v[220:223], 0
	v_mfma_f32_16x16x32_bf16 v[16:19], v[146:149], v[216:219], v[16:19]
	v_mfma_f32_16x16x32_bf16 v[12:15], v[154:157], v[216:219], 0
	v_mfma_f32_16x16x32_bf16 v[12:15], v[158:161], v[220:223], v[12:15]
	v_mfma_f32_16x16x32_bf16 v[28:31], v[158:161], v[212:215], 0
	v_mfma_f32_16x16x32_bf16 v[28:31], v[154:157], v[208:211], v[28:31]
	v_mfma_f32_16x16x32_bf16 v[44:47], v[154:157], v[186:189], 0
	v_mfma_f32_16x16x32_bf16 v[44:47], v[158:161], v[204:207], v[44:47]
	v_mfma_f32_16x16x32_bf16 v[60:63], v[158:161], v[182:185], 0
	v_mfma_f32_16x16x32_bf16 v[60:63], v[154:157], v[178:181], v[60:63]
	v_mfma_f32_16x16x32_bf16 v[56:59], v[162:165], v[178:181], 0
	v_mfma_f32_16x16x32_bf16 v[56:59], v[166:169], v[182:185], v[56:59]
	v_mfma_f32_16x16x32_bf16 v[40:43], v[166:169], v[204:207], 0
	v_mfma_f32_16x16x32_bf16 v[40:43], v[162:165], v[186:189], v[40:43]
	v_mfma_f32_16x16x32_bf16 v[24:27], v[162:165], v[208:211], 0
	v_mfma_f32_16x16x32_bf16 v[24:27], v[166:169], v[212:215], v[24:27]
	v_mfma_f32_16x16x32_bf16 v[8:11], v[166:169], v[220:223], 0
	v_mfma_f32_16x16x32_bf16 v[8:11], v[162:165], v[216:219], v[8:11]
	v_mfma_f32_16x16x32_bf16 v[4:7], v[170:173], v[216:219], 0
	v_mfma_f32_16x16x32_bf16 v[4:7], v[174:177], v[220:223], v[4:7]
	v_mfma_f32_16x16x32_bf16 v[20:23], v[174:177], v[212:215], 0
	v_mfma_f32_16x16x32_bf16 v[20:23], v[170:173], v[208:211], v[20:23]
	v_mfma_f32_16x16x32_bf16 v[36:39], v[170:173], v[186:189], 0
	v_mfma_f32_16x16x32_bf16 v[36:39], v[174:177], v[204:207], v[36:39]
	v_mfma_f32_16x16x32_bf16 v[52:55], v[174:177], v[182:185], 0
	v_mfma_f32_16x16x32_bf16 v[52:55], v[170:173], v[178:181], v[52:55]
	s_setprio 0
	s_barrier
; #define PG8_STAGE(bufoff, gbase, voff) do { _Pragma("unroll") for (int _i = 0; _i < 2; ++_i) \
;         __builtin_amdgcn_global_load_lds((const unsigned*)((const char*)(gbase) + (voff)[_i]), (PG8_LAS unsigned*)(lds + (bufoff) + ldsw + _i * 8192), 16, 0, 0); } while (0)
; #define PG8_LDA(dst, b, h) do { _Pragma("unroll") for (int m = 0; m < 4; ++m) _Pragma("unroll") for (int k = 0; k < 2; ++k) dst[m][k] = *(const PG8_LAS bf16x8*)(lds + PG8_SA(b, h) + aoff + m * 2048 + k * 1024); } while (0)
; #define PG8_LDB(dst, b, h) do { _Pragma("unroll") for (int n = 0; n < 2; ++n) _Pragma("unroll") for (int k = 0; k < 2; ++k) dst[n][k] = *(const PG8_LAS bf16x8*)(lds + PG8_SB(b, h) + boff + n * 2048 + k * 1024); } while (0)
; #define PG8_WAIT_V(n) asm volatile("s_waitcnt vmcnt(" #n ")" ::: "memory")
; #define PG8_WAIT_L(n) asm volatile("s_waitcnt lgkmcnt(" #n ")" ::: "memory")
; #define PG8_BAR __builtin_amdgcn_s_barrier()
; #define PG8_SCHED __builtin_amdgcn_sched_barrier(0)
; template <class Epi, class Sched, bool ALIGN_EPI = false, bool SP2 = false, bool I8 = false>
; __device__ __forceinline__ void gemm_phase(PG8_LAS unsigned char* lds, const Gemm g, const Sched& S, const Epi& E) {
;     ...
;             PG8_LDB(B0, 1, 0); PG8_LDB(B1, 1, 1); PG8_SCHED; PG8_LDA(At, 1, 0); PG8_STAGE(PG8_SA(0, 1), a2 + hstep, voffA);
;             PG8_WAIT_V(8); PG8_WAIT_L(0); PG8_BAR; PG8_MMA(0, 0, At, B0); PG8_MMA(0, 1, At, B1); PG8_BAR; PG8_SCHED;
;             PG8_LDA(At, 1, 1); PG8_STAGE(PG8_SB(1, 0), b3, voffB); PG8_STAGE(PG8_SB(1, 1), b3 + hstep, voffB); PG8_STAGE(PG8_SA(1, 0), a3, voffA);
;             PG8_WAIT_V(8); PG8_WAIT_L(0); PG8_BAR; PG8_MMA(1, 0, At, B0); PG8_MMA(1, 1, At, B1); PG8_BAR; PG8_SCHED;
	s_add_i32 s73, 0, 0x18000
	s_add_i32 s76, 0, 0x1c000
	v_add_u32_e32 v158, s73, v143
	v_add_u32_e32 v174, s76, v143
	ds_read_b128 v[146:149], v158
	ds_read_b128 v[150:153], v158 offset:1024
	ds_read_b128 v[154:157], v158 offset:2048
	ds_read_b128 v[158:161], v158 offset:3072
	ds_read_b128 v[162:165], v174
	ds_read_b128 v[166:169], v174 offset:1024
	ds_read_b128 v[170:173], v174 offset:2048
	ds_read_b128 v[174:177], v174 offset:3072
	s_add_u32 s48, s48, s18
	s_addc_u32 s49, s49, s19
	s_mov_b32 m0, s51
	v_lshl_add_u64 v[244:245], s[48:49], 0, v[132:133]
	ds_read_b128 v[178:181], v145 offset:32768
	ds_read_b128 v[182:185], v145 offset:33792
	ds_read_b128 v[186:189], v145 offset:34816
	ds_read_b128 v[204:207], v145 offset:35840
	ds_read_b128 v[208:211], v145 offset:36864
	ds_read_b128 v[212:215], v145 offset:37888
	ds_read_b128 v[216:219], v145 offset:38912
	ds_read_b128 v[220:223], v145 offset:39936
	global_load_lds_dwordx4 v[244:245], off
	v_lshl_add_u64 v[244:245], s[48:49], 0, v[134:135]
	s_mov_b32 m0, s52
	s_nop 0
	global_load_lds_dwordx4 v[244:245], off
	s_waitcnt vmcnt(8)
	s_waitcnt lgkmcnt(0)
	s_barrier
	s_setprio 1
	s_waitcnt lgkmcnt(0)
	v_mfma_f32_16x16x32_bf16 v[124:127], v[146:149], v[178:181], v[124:127]
	v_mfma_f32_16x16x32_bf16 v[124:127], v[150:153], v[182:185], v[124:127]
	v_mfma_f32_16x16x32_bf16 v[112:115], v[150:153], v[204:207], v[112:115]
	v_mfma_f32_16x16x32_bf16 v[112:115], v[146:149], v[186:189], v[112:115]
	v_mfma_f32_16x16x32_bf16 v[96:99], v[146:149], v[208:211], v[96:99]
	v_mfma_f32_16x16x32_bf16 v[96:99], v[150:153], v[212:215], v[96:99]
	v_mfma_f32_16x16x32_bf16 v[80:83], v[150:153], v[220:223], v[80:83]
	v_mfma_f32_16x16x32_bf16 v[80:83], v[146:149], v[216:219], v[80:83]
	v_mfma_f32_16x16x32_bf16 v[76:79], v[154:157], v[216:219], v[76:79]
	v_mfma_f32_16x16x32_bf16 v[76:79], v[158:161], v[220:223], v[76:79]
	v_mfma_f32_16x16x32_bf16 v[92:95], v[158:161], v[212:215], v[92:95]
	v_mfma_f32_16x16x32_bf16 v[92:95], v[154:157], v[208:211], v[92:95]
	v_mfma_f32_16x16x32_bf16 v[108:111], v[154:157], v[186:189], v[108:111]
	v_mfma_f32_16x16x32_bf16 v[108:111], v[158:161], v[204:207], v[108:111]
	v_mfma_f32_16x16x32_bf16 v[128:131], v[158:161], v[182:185], v[128:131]
	v_mfma_f32_16x16x32_bf16 v[128:131], v[154:157], v[178:181], v[128:131]
	v_mfma_f32_16x16x32_bf16 v[120:123], v[162:165], v[178:181], v[120:123]
	v_mfma_f32_16x16x32_bf16 v[120:123], v[166:169], v[182:185], v[120:123]
	v_mfma_f32_16x16x32_bf16 v[104:107], v[166:169], v[204:207], v[104:107]
	v_mfma_f32_16x16x32_bf16 v[104:107], v[162:165], v[186:189], v[104:107]
	v_mfma_f32_16x16x32_bf16 v[88:91], v[162:165], v[208:211], v[88:91]
	v_mfma_f32_16x16x32_bf16 v[88:91], v[166:169], v[212:215], v[88:91]
	v_mfma_f32_16x16x32_bf16 v[72:75], v[166:169], v[220:223], v[72:75]
	v_mfma_f32_16x16x32_bf16 v[72:75], v[162:165], v[216:219], v[72:75]
	v_mfma_f32_16x16x32_bf16 v[68:71], v[170:173], v[216:219], v[68:71]
	v_mfma_f32_16x16x32_bf16 v[68:71], v[174:177], v[220:223], v[68:71]
	v_mfma_f32_16x16x32_bf16 v[84:87], v[174:177], v[212:215], v[84:87]
	v_mfma_f32_16x16x32_bf16 v[84:87], v[170:173], v[208:211], v[84:87]
	v_mfma_f32_16x16x32_bf16 v[100:103], v[170:173], v[186:189], v[100:103]
	v_mfma_f32_16x16x32_bf16 v[100:103], v[174:177], v[204:207], v[100:103]
	v_mfma_f32_16x16x32_bf16 v[116:119], v[174:177], v[182:185], v[116:119]
	v_mfma_f32_16x16x32_bf16 v[116:119], v[170:173], v[178:181], v[116:119]
	s_setprio 0
	s_barrier
	s_add_i32 s48, s73, s28
	v_lshl_add_u64 v[190:191], v[190:191], 0, s[84:85]
	s_mov_b32 m0, s48
	ds_read_b128 v[178:181], v145 offset:49152
	ds_read_b128 v[182:185], v145 offset:50176
	ds_read_b128 v[186:189], v145 offset:51200
	ds_read_b128 v[204:207], v145 offset:52224
	ds_read_b128 v[208:211], v145 offset:53248
	ds_read_b128 v[212:215], v145 offset:54272
	ds_read_b128 v[216:219], v145 offset:55296
	ds_read_b128 v[220:223], v145 offset:56320
	global_load_lds_dwordx4 v[190:191], off
	v_lshl_add_u64 v[190:191], v[224:225], 0, s[84:85]
	s_add_i32 m0, s48, 0x2000
	s_add_i32 s48, s76, s28
	global_load_lds_dwordx4 v[190:191], off
	v_lshl_add_u64 v[190:191], v[226:227], 0, s[84:85]
	s_mov_b32 m0, s48
	s_nop 0
	global_load_lds_dwordx4 v[190:191], off
	v_lshl_add_u64 v[190:191], v[228:229], 0, s[84:85]
	s_add_i32 m0, s48, 0x2000
	s_nop 0
	global_load_lds_dwordx4 v[190:191], off
	v_lshl_add_u64 v[190:191], v[240:241], 0, s[84:85]
	s_mov_b32 m0, s55
	s_nop 0
	global_load_lds_dwordx4 v[190:191], off
	v_lshl_add_u64 v[190:191], v[242:243], 0, s[84:85]
	s_mov_b32 m0, s56
	s_nop 0
	global_load_lds_dwordx4 v[190:191], off
	s_waitcnt vmcnt(8)
	s_waitcnt lgkmcnt(0)
	s_barrier
; #define PG8_STAGE(bufoff, gbase, voff) do { _Pragma("unroll") for (int _i = 0; _i < 2; ++_i) \
;         __builtin_amdgcn_global_load_lds((const unsigned*)((const char*)(gbase) + (voff)[_i]), (PG8_LAS unsigned*)(lds + (bufoff) + ldsw + _i * 8192), 16, 0, 0); } while (0)
; #define PG8_LDA(dst, b, h) do { _Pragma("unroll") for (int m = 0; m < 4; ++m) _Pragma("unroll") for (int k = 0; k < 2; ++k) dst[m][k] = *(const PG8_LAS bf16x8*)(lds + PG8_SA(b, h) + aoff + m * 2048 + k * 1024); } while (0)
; template <class Epi, class Sched, bool ALIGN_EPI = false, bool SP2 = false, bool I8 = false>
; __device__ __forceinline__ void gemm_phase(PG8_LAS unsigned char* lds, const Gemm g, const Sched& S, const Epi& E) {
;     ...
;         const bool has_next = S.next(ui + 1, nxt);
;         const char* nA = has_next ? (const char*)g.A + (size_t)nxt.pm * tstep : cA; const char* nB = has_next ? (const char*)g.Bt + (size_t)nxt.pn * tstep : cB;
;         for (int t = 0; t < nt; t += 2) {
;             const bool last = (t == nt - 2);
;             const char* a1 = cA + (size_t)(t + 1) * kstep;
;             const char* a2 = last ? nA : cA + (size_t)(t + 2) * kstep; const char* b2 = last ? nB : cB + (size_t)(t + 2) * kstep;
;             const char* a3 = a2 + kstep; const char* b3 = b2 + kstep;
;             if (last && has_next) S.a_ready(nxt);
;             if constexpr (SP2) {
;             PG8_LDB(B0, 0, 0); PG8_LDB(B1, 0, 1); PG8_SCHED; PG8_LDA(At, 0, 0); PG8_STAGE(PG8_SA(1, 1), a1 + hstep, voffA);
;             PG8_WAIT_V(8); PG8_WAIT_L(0); PG8_BAR; PG8_MMA(0, 0, At, B0); PG8_MMA(0, 1, At, B1); PG8_BAR; PG8_SCHED;
;             PG8_LDA(At, 0, 1); PG8_STAGE(PG8_SB(0, 0), b2, voffB); PG8_STAGE(PG8_SB(0, 1), b2 + hstep, voffB); PG8_STAGE(PG8_SA(0, 0), a2, voffA);
;             PG8_WAIT_V(8); PG8_WAIT_L(0); PG8_BAR; PG8_MMA(1, 0, At, B0); PG8_MMA(1, 1, At, B1); PG8_BAR; PG8_SCHED;
;             PG8_LDB(B0, 1, 0); PG8_LDB(B1, 1, 1); PG8_SCHED; PG8_LDA(At, 1, 0); PG8_STAGE(PG8_SA(0, 1), a2 + hstep, voffA);
;             PG8_WAIT_V(8); PG8_WAIT_L(0); PG8_BAR; PG8_MMA(0, 0, At, B0); PG8_MMA(0, 1, At, B1); PG8_BAR; PG8_SCHED;
;             PG8_LDA(At, 1, 1); PG8_STAGE(PG8_SB(1, 0), b3, voffB); PG8_STAGE(PG8_SB(1, 1), b3 + hstep, voffB); PG8_STAGE(PG8_SA(1, 0), a3, voffA);
;             PG8_WAIT_V(8); PG8_WAIT_L(0); PG8_BAR; PG8_MMA(1, 0, At, B0); PG8_MMA(1, 1, At, B1); PG8_BAR; PG8_SCHED;
	s_setprio 1
	s_waitcnt lgkmcnt(0)
	v_mfma_f32_16x16x32_bf16 v[64:67], v[146:149], v[178:181], v[64:67]
	v_mfma_f32_16x16x32_bf16 v[64:67], v[150:153], v[182:185], v[64:67]
	v_mfma_f32_16x16x32_bf16 v[48:51], v[150:153], v[204:207], v[48:51]
	v_mfma_f32_16x16x32_bf16 v[48:51], v[146:149], v[186:189], v[48:51]
	v_mfma_f32_16x16x32_bf16 v[32:35], v[146:149], v[208:211], v[32:35]
	v_mfma_f32_16x16x32_bf16 v[32:35], v[150:153], v[212:215], v[32:35]
	v_mfma_f32_16x16x32_bf16 v[16:19], v[150:153], v[220:223], v[16:19]
	v_mfma_f32_16x16x32_bf16 v[16:19], v[146:149], v[216:219], v[16:19]
	v_mfma_f32_16x16x32_bf16 v[12:15], v[154:157], v[216:219], v[12:15]
	v_mfma_f32_16x16x32_bf16 v[12:15], v[158:161], v[220:223], v[12:15]
	v_mfma_f32_16x16x32_bf16 v[28:31], v[158:161], v[212:215], v[28:31]
	v_mfma_f32_16x16x32_bf16 v[28:31], v[154:157], v[208:211], v[28:31]
	v_mfma_f32_16x16x32_bf16 v[44:47], v[154:157], v[186:189], v[44:47]
	v_mfma_f32_16x16x32_bf16 v[44:47], v[158:161], v[204:207], v[44:47]
	v_mfma_f32_16x16x32_bf16 v[60:63], v[158:161], v[182:185], v[60:63]
	v_mfma_f32_16x16x32_bf16 v[60:63], v[154:157], v[178:181], v[60:63]
	v_mfma_f32_16x16x32_bf16 v[56:59], v[162:165], v[178:181], v[56:59]
	v_mfma_f32_16x16x32_bf16 v[56:59], v[166:169], v[182:185], v[56:59]
	v_mfma_f32_16x16x32_bf16 v[40:43], v[166:169], v[204:207], v[40:43]
	v_mfma_f32_16x16x32_bf16 v[40:43], v[162:165], v[186:189], v[40:43]
	v_mfma_f32_16x16x32_bf16 v[24:27], v[162:165], v[208:211], v[24:27]
	v_mfma_f32_16x16x32_bf16 v[24:27], v[166:169], v[212:215], v[24:27]
	v_mfma_f32_16x16x32_bf16 v[8:11], v[166:169], v[220:223], v[8:11]
	v_mfma_f32_16x16x32_bf16 v[8:11], v[162:165], v[216:219], v[8:11]
	v_mfma_f32_16x16x32_bf16 v[4:7], v[170:173], v[216:219], v[4:7]
	v_mfma_f32_16x16x32_bf16 v[4:7], v[174:177], v[220:223], v[4:7]
	v_mfma_f32_16x16x32_bf16 v[20:23], v[174:177], v[212:215], v[20:23]
	v_mfma_f32_16x16x32_bf16 v[20:23], v[170:173], v[208:211], v[20:23]
	v_mfma_f32_16x16x32_bf16 v[36:39], v[170:173], v[186:189], v[36:39]
	v_mfma_f32_16x16x32_bf16 v[36:39], v[174:177], v[204:207], v[36:39]
	v_mfma_f32_16x16x32_bf16 v[52:55], v[174:177], v[182:185], v[52:55]
	v_mfma_f32_16x16x32_bf16 v[52:55], v[170:173], v[178:181], v[52:55]
	s_setprio 0
	s_barrier
	s_add_u32 s44, s44, 0x100
	s_addc_u32 s45, s45, 0
	s_add_u32 s65, s65, 0x100
	s_addc_u32 s67, s67, 0
	s_cmp_ge_i32 s72, s53
	s_mov_b32 s48, s72
	s_cbranch_scc1 .Lkloop_exit_4
.LBB0_1623:
	s_add_i32 s72, s48, 2
	s_add_u32 s73, s44, 0x80
	s_addc_u32 s49, s45, 0
	s_add_i32 s86, 0, 0x10000
	s_cmp_eq_u32 s57, s48
	s_cselect_b32 s49, s13, s49
	s_cselect_b32 s48, s12, s73
	s_cselect_b32 s77, s41, s67
	s_cselect_b32 s76, s40, s65
	s_add_i32 s73, 0, 0x14000
	v_add_u32_e32 v158, s86, v143
	v_add_u32_e32 v174, s73, v143
	ds_read_b128 v[146:149], v158
	ds_read_b128 v[150:153], v158 offset:1024
	ds_read_b128 v[154:157], v158 offset:2048
	ds_read_b128 v[158:161], v158 offset:3072
	ds_read_b128 v[162:165], v174
	ds_read_b128 v[166:169], v174 offset:1024
	ds_read_b128 v[170:173], v174 offset:2048
	ds_read_b128 v[174:177], v174 offset:3072
	v_lshl_add_u64 v[190:191], s[44:45], 0, v[138:139]
	s_add_i32 m0, s47, 0xc000
	ds_read_b128 v[178:181], v145
	ds_read_b128 v[182:185], v145 offset:1024
	ds_read_b128 v[186:189], v145 offset:2048
	ds_read_b128 v[204:207], v145 offset:3072
	ds_read_b128 v[208:211], v145 offset:4096
	ds_read_b128 v[212:215], v145 offset:5120
	ds_read_b128 v[216:219], v145 offset:6144
	ds_read_b128 v[220:223], v145 offset:7168
	global_load_lds_dwordx4 v[190:191], off
	v_lshl_add_u64 v[190:191], s[44:45], 0, v[140:141]
	s_add_i32 m0, s47, 0xe000
	s_nop 0
	global_load_lds_dwordx4 v[190:191], off
	s_waitcnt vmcnt(8)
	s_waitcnt lgkmcnt(0)
	s_barrier
	s_setprio 1
	s_waitcnt lgkmcnt(0)
	v_mfma_f32_16x16x32_bf16 v[124:127], v[146:149], v[178:181], v[124:127]
	v_mfma_f32_16x16x32_bf16 v[124:127], v[150:153], v[182:185], v[124:127]
	v_mfma_f32_16x16x32_bf16 v[112:115], v[150:153], v[204:207], v[112:115]
	v_mfma_f32_16x16x32_bf16 v[112:115], v[146:149], v[186:189], v[112:115]
	v_mfma_f32_16x16x32_bf16 v[96:99], v[146:149], v[208:211], v[96:99]
	v_mfma_f32_16x16x32_bf16 v[96:99], v[150:153], v[212:215], v[96:99]
	v_mfma_f32_16x16x32_bf16 v[80:83], v[150:153], v[220:223], v[80:83]
	v_mfma_f32_16x16x32_bf16 v[80:83], v[146:149], v[216:219], v[80:83]
	v_mfma_f32_16x16x32_bf16 v[76:79], v[154:157], v[216:219], v[76:79]
	v_mfma_f32_16x16x32_bf16 v[76:79], v[158:161], v[220:223], v[76:79]
	v_mfma_f32_16x16x32_bf16 v[92:95], v[158:161], v[212:215], v[92:95]
	v_mfma_f32_16x16x32_bf16 v[92:95], v[154:157], v[208:211], v[92:95]
	v_mfma_f32_16x16x32_bf16 v[108:111], v[154:157], v[186:189], v[108:111]
	v_mfma_f32_16x16x32_bf16 v[108:111], v[158:161], v[204:207], v[108:111]
	v_mfma_f32_16x16x32_bf16 v[128:131], v[158:161], v[182:185], v[128:131]
	v_mfma_f32_16x16x32_bf16 v[128:131], v[154:157], v[178:181], v[128:131]
	v_mfma_f32_16x16x32_bf16 v[120:123], v[162:165], v[178:181], v[120:123]
	v_mfma_f32_16x16x32_bf16 v[120:123], v[166:169], v[182:185], v[120:123]
	v_mfma_f32_16x16x32_bf16 v[104:107], v[166:169], v[204:207], v[104:107]
	v_mfma_f32_16x16x32_bf16 v[104:107], v[162:165], v[186:189], v[104:107]
	v_mfma_f32_16x16x32_bf16 v[88:91], v[162:165], v[208:211], v[88:91]
	v_mfma_f32_16x16x32_bf16 v[88:91], v[166:169], v[212:215], v[88:91]
	v_mfma_f32_16x16x32_bf16 v[72:75], v[166:169], v[220:223], v[72:75]
	v_mfma_f32_16x16x32_bf16 v[72:75], v[162:165], v[216:219], v[72:75]
	v_mfma_f32_16x16x32_bf16 v[68:71], v[170:173], v[216:219], v[68:71]
	v_mfma_f32_16x16x32_bf16 v[68:71], v[174:177], v[220:223], v[68:71]
	v_mfma_f32_16x16x32_bf16 v[84:87], v[174:177], v[212:215], v[84:87]
	v_mfma_f32_16x16x32_bf16 v[84:87], v[170:173], v[208:211], v[84:87]
	v_mfma_f32_16x16x32_bf16 v[100:103], v[170:173], v[186:189], v[100:103]
	v_mfma_f32_16x16x32_bf16 v[100:103], v[174:177], v[204:207], v[100:103]
	v_mfma_f32_16x16x32_bf16 v[116:119], v[174:177], v[182:185], v[116:119]
	v_mfma_f32_16x16x32_bf16 v[116:119], v[170:173], v[178:181], v[116:119]
	s_setprio 0
	s_barrier
; #define PG8_STAGE(bufoff, gbase, voff) do { _Pragma("unroll") for (int _i = 0; _i < 2; ++_i) \
;         __builtin_amdgcn_global_load_lds((const unsigned*)((const char*)(gbase) + (voff)[_i]), (PG8_LAS unsigned*)(lds + (bufoff) + ldsw + _i * 8192), 16, 0, 0); } while (0)
; #define PG8_LDA(dst, b, h) do { _Pragma("unroll") for (int m = 0; m < 4; ++m) _Pragma("unroll") for (int k = 0; k < 2; ++k) dst[m][k] = *(const PG8_LAS bf16x8*)(lds + PG8_SA(b, h) + aoff + m * 2048 + k * 1024); } while (0)
; #define PG8_LDB(dst, b, h) do { _Pragma("unroll") for (int n = 0; n < 2; ++n) _Pragma("unroll") for (int k = 0; k < 2; ++k) dst[n][k] = *(const PG8_LAS bf16x8*)(lds + PG8_SB(b, h) + boff + n * 2048 + k * 1024); } while (0)
; #define PG8_WAIT_V(n) asm volatile("s_waitcnt vmcnt(" #n ")" ::: "memory")
; #define PG8_WAIT_L(n) asm volatile("s_waitcnt lgkmcnt(" #n ")" ::: "memory")
; #define PG8_BAR __builtin_amdgcn_s_barrier()
; #define PG8_SCHED __builtin_amdgcn_sched_barrier(0)
; template <class Epi, class Sched, bool ALIGN_EPI = false, bool SP2 = false, bool I8 = false>
; __device__ __forceinline__ void gemm_phase(PG8_LAS unsigned char* lds, const Gemm g, const Sched& S, const Epi& E) {
;     ...
;             PG8_LDA(At, 0, 1); PG8_STAGE(PG8_SB(0, 0), b2, voffB); PG8_STAGE(PG8_SB(0, 1), b2 + hstep, voffB); PG8_STAGE(PG8_SA(0, 0), a2, voffA);
;             PG8_WAIT_V(8); PG8_WAIT_L(0); PG8_BAR; PG8_MMA(1, 0, At, B0); PG8_MMA(1, 1, At, B1); PG8_BAR; PG8_SCHED;
;             PG8_LDB(B0, 1, 0); PG8_LDB(B1, 1, 1); PG8_SCHED; PG8_LDA(At, 1, 0); PG8_STAGE(PG8_SA(0, 1), a2 + hstep, voffA);
;             PG8_WAIT_V(8); PG8_WAIT_L(0); PG8_BAR; PG8_MMA(0, 0, At, B0); PG8_MMA(0, 1, At, B1); PG8_BAR; PG8_SCHED;
;             PG8_LDA(At, 1, 1); PG8_STAGE(PG8_SB(1, 0), b3, voffB); PG8_STAGE(PG8_SB(1, 1), b3 + hstep, voffB); PG8_STAGE(PG8_SA(1, 0), a3, voffA);
	s_add_i32 s86, s86, s28
	v_lshl_add_u64 v[190:191], s[76:77], 0, v[2:3]
	s_mov_b32 m0, s86
	ds_read_b128 v[178:181], v145 offset:16384
	ds_read_b128 v[182:185], v145 offset:17408
	ds_read_b128 v[186:189], v145 offset:18432
	ds_read_b128 v[204:207], v145 offset:19456
	ds_read_b128 v[208:211], v145 offset:20480
	ds_read_b128 v[212:215], v145 offset:21504
	ds_read_b128 v[216:219], v145 offset:22528
	ds_read_b128 v[220:223], v145 offset:23552
	global_load_lds_dwordx4 v[190:191], off
	s_add_i32 m0, s86, 0x2000
	v_lshl_add_u64 v[224:225], s[76:77], 0, v[136:137]
	s_add_u32 s76, s76, s18
	s_addc_u32 s77, s77, s19
	s_add_i32 s73, s73, s28
	global_load_lds_dwordx4 v[224:225], off
	v_lshl_add_u64 v[226:227], s[76:77], 0, v[2:3]
	s_mov_b32 m0, s73
	v_lshl_add_u64 v[228:229], s[76:77], 0, v[136:137]
	global_load_lds_dwordx4 v[226:227], off
	s_add_i32 m0, s73, 0x2000
	v_lshl_add_u64 v[240:241], s[48:49], 0, v[132:133]
	global_load_lds_dwordx4 v[228:229], off
	s_mov_b32 m0, s47
	v_lshl_add_u64 v[242:243], s[48:49], 0, v[134:135]
	global_load_lds_dwordx4 v[240:241], off
	s_mov_b32 m0, s50
	s_nop 0
	global_load_lds_dwordx4 v[242:243], off
	s_waitcnt vmcnt(8)
	s_waitcnt lgkmcnt(0)
	s_barrier
	s_setprio 1
	s_waitcnt lgkmcnt(0)
	v_mfma_f32_16x16x32_bf16 v[64:67], v[146:149], v[178:181], v[64:67]
	v_mfma_f32_16x16x32_bf16 v[64:67], v[150:153], v[182:185], v[64:67]
	v_mfma_f32_16x16x32_bf16 v[48:51], v[150:153], v[204:207], v[48:51]
	v_mfma_f32_16x16x32_bf16 v[48:51], v[146:149], v[186:189], v[48:51]
	v_mfma_f32_16x16x32_bf16 v[32:35], v[146:149], v[208:211], v[32:35]
	v_mfma_f32_16x16x32_bf16 v[32:35], v[150:153], v[212:215], v[32:35]
	v_mfma_f32_16x16x32_bf16 v[16:19], v[150:153], v[220:223], v[16:19]
	v_mfma_f32_16x16x32_bf16 v[16:19], v[146:149], v[216:219], v[16:19]
	v_mfma_f32_16x16x32_bf16 v[12:15], v[154:157], v[216:219], v[12:15]
	v_mfma_f32_16x16x32_bf16 v[12:15], v[158:161], v[220:223], v[12:15]
	v_mfma_f32_16x16x32_bf16 v[28:31], v[158:161], v[212:215], v[28:31]
	v_mfma_f32_16x16x32_bf16 v[28:31], v[154:157], v[208:211], v[28:31]
	v_mfma_f32_16x16x32_bf16 v[44:47], v[154:157], v[186:189], v[44:47]
	v_mfma_f32_16x16x32_bf16 v[44:47], v[158:161], v[204:207], v[44:47]
	v_mfma_f32_16x16x32_bf16 v[60:63], v[158:161], v[182:185], v[60:63]
	v_mfma_f32_16x16x32_bf16 v[60:63], v[154:157], v[178:181], v[60:63]
	v_mfma_f32_16x16x32_bf16 v[56:59], v[162:165], v[178:181], v[56:59]
	v_mfma_f32_16x16x32_bf16 v[56:59], v[166:169], v[182:185], v[56:59]
	v_mfma_f32_16x16x32_bf16 v[40:43], v[166:169], v[204:207], v[40:43]
	v_mfma_f32_16x16x32_bf16 v[40:43], v[162:165], v[186:189], v[40:43]
	v_mfma_f32_16x16x32_bf16 v[24:27], v[162:165], v[208:211], v[24:27]
	v_mfma_f32_16x16x32_bf16 v[24:27], v[166:169], v[212:215], v[24:27]
	v_mfma_f32_16x16x32_bf16 v[8:11], v[166:169], v[220:223], v[8:11]
	v_mfma_f32_16x16x32_bf16 v[8:11], v[162:165], v[216:219], v[8:11]
	v_mfma_f32_16x16x32_bf16 v[4:7], v[170:173], v[216:219], v[4:7]
	v_mfma_f32_16x16x32_bf16 v[4:7], v[174:177], v[220:223], v[4:7]
	v_mfma_f32_16x16x32_bf16 v[20:23], v[174:177], v[212:215], v[20:23]
	v_mfma_f32_16x16x32_bf16 v[20:23], v[170:173], v[208:211], v[20:23]
	v_mfma_f32_16x16x32_bf16 v[36:39], v[170:173], v[186:189], v[36:39]
	v_mfma_f32_16x16x32_bf16 v[36:39], v[174:177], v[204:207], v[36:39]
	v_mfma_f32_16x16x32_bf16 v[52:55], v[174:177], v[182:185], v[52:55]
	v_mfma_f32_16x16x32_bf16 v[52:55], v[170:173], v[178:181], v[52:55]
	s_setprio 0
	s_barrier
	s_add_i32 s73, 0, 0x18000
	s_add_i32 s76, 0, 0x1c000
	v_add_u32_e32 v158, s73, v143
	v_add_u32_e32 v174, s76, v143
	ds_read_b128 v[146:149], v158
	ds_read_b128 v[150:153], v158 offset:1024
	ds_read_b128 v[154:157], v158 offset:2048
	ds_read_b128 v[158:161], v158 offset:3072
	ds_read_b128 v[162:165], v174
	ds_read_b128 v[166:169], v174 offset:1024
	ds_read_b128 v[170:173], v174 offset:2048
	ds_read_b128 v[174:177], v174 offset:3072
	s_add_u32 s48, s48, s18
	s_addc_u32 s49, s49, s19
	s_mov_b32 m0, s51
	v_lshl_add_u64 v[244:245], s[48:49], 0, v[132:133]
	ds_read_b128 v[178:181], v145 offset:32768
	ds_read_b128 v[182:185], v145 offset:33792
	ds_read_b128 v[186:189], v145 offset:34816
	ds_read_b128 v[204:207], v145 offset:35840
	ds_read_b128 v[208:211], v145 offset:36864
	ds_read_b128 v[212:215], v145 offset:37888
	ds_read_b128 v[216:219], v145 offset:38912
	ds_read_b128 v[220:223], v145 offset:39936
	global_load_lds_dwordx4 v[244:245], off
	v_lshl_add_u64 v[244:245], s[48:49], 0, v[134:135]
	s_mov_b32 m0, s52
	s_nop 0
	global_load_lds_dwordx4 v[244:245], off
	s_waitcnt vmcnt(8)
	s_waitcnt lgkmcnt(0)
	s_barrier
; #define PG8_STAGE(bufoff, gbase, voff) do { _Pragma("unroll") for (int _i = 0; _i < 2; ++_i) \
;         __builtin_amdgcn_global_load_lds((const unsigned*)((const char*)(gbase) + (voff)[_i]), (PG8_LAS unsigned*)(lds + (bufoff) + ldsw + _i * 8192), 16, 0, 0); } while (0)
; #define PG8_LDA(dst, b, h) do { _Pragma("unroll") for (int m = 0; m < 4; ++m) _Pragma("unroll") for (int k = 0; k < 2; ++k) dst[m][k] = *(const PG8_LAS bf16x8*)(lds + PG8_SA(b, h) + aoff + m * 2048 + k * 1024); } while (0)
; #define PG8_WAIT_V(n) asm volatile("s_waitcnt vmcnt(" #n ")" ::: "memory")
; #define PG8_WAIT_L(n) asm volatile("s_waitcnt lgkmcnt(" #n ")" ::: "memory")
; #define PG8_BAR __builtin_amdgcn_s_barrier()
; #define PG8_SCHED __builtin_amdgcn_sched_barrier(0)
; template <class Epi, class Sched, bool ALIGN_EPI = false, bool SP2 = false, bool I8 = false>
; __device__ __forceinline__ void gemm_phase(PG8_LAS unsigned char* lds, const Gemm g, const Sched& S, const Epi& E) {
;     ...
;         for (int t = 0; t < nt; t += 2) {
;     ...
;             PG8_WAIT_V(8); PG8_WAIT_L(0); PG8_BAR; PG8_MMA(0, 0, At, B0); PG8_MMA(0, 1, At, B1); PG8_BAR; PG8_SCHED;
;             PG8_LDA(At, 1, 1); PG8_STAGE(PG8_SB(1, 0), b3, voffB); PG8_STAGE(PG8_SB(1, 1), b3 + hstep, voffB); PG8_STAGE(PG8_SA(1, 0), a3, voffA);
;             PG8_WAIT_V(8); PG8_WAIT_L(0); PG8_BAR; PG8_MMA(1, 0, At, B0); PG8_MMA(1, 1, At, B1); PG8_BAR; PG8_SCHED;
	s_setprio 1
	s_waitcnt lgkmcnt(0)
	v_mfma_f32_16x16x32_bf16 v[124:127], v[146:149], v[178:181], v[124:127]
	v_mfma_f32_16x16x32_bf16 v[124:127], v[150:153], v[182:185], v[124:127]
	v_mfma_f32_16x16x32_bf16 v[112:115], v[150:153], v[204:207], v[112:115]
	v_mfma_f32_16x16x32_bf16 v[112:115], v[146:149], v[186:189], v[112:115]
	v_mfma_f32_16x16x32_bf16 v[96:99], v[146:149], v[208:211], v[96:99]
	v_mfma_f32_16x16x32_bf16 v[96:99], v[150:153], v[212:215], v[96:99]
	v_mfma_f32_16x16x32_bf16 v[80:83], v[150:153], v[220:223], v[80:83]
	v_mfma_f32_16x16x32_bf16 v[80:83], v[146:149], v[216:219], v[80:83]
	v_mfma_f32_16x16x32_bf16 v[76:79], v[154:157], v[216:219], v[76:79]
	v_mfma_f32_16x16x32_bf16 v[76:79], v[158:161], v[220:223], v[76:79]
	v_mfma_f32_16x16x32_bf16 v[92:95], v[158:161], v[212:215], v[92:95]
	v_mfma_f32_16x16x32_bf16 v[92:95], v[154:157], v[208:211], v[92:95]
	v_mfma_f32_16x16x32_bf16 v[108:111], v[154:157], v[186:189], v[108:111]
	v_mfma_f32_16x16x32_bf16 v[108:111], v[158:161], v[204:207], v[108:111]
	v_mfma_f32_16x16x32_bf16 v[128:131], v[158:161], v[182:185], v[128:131]
	v_mfma_f32_16x16x32_bf16 v[128:131], v[154:157], v[178:181], v[128:131]
	v_mfma_f32_16x16x32_bf16 v[120:123], v[162:165], v[178:181], v[120:123]
	v_mfma_f32_16x16x32_bf16 v[120:123], v[166:169], v[182:185], v[120:123]
	v_mfma_f32_16x16x32_bf16 v[104:107], v[166:169], v[204:207], v[104:107]
	v_mfma_f32_16x16x32_bf16 v[104:107], v[162:165], v[186:189], v[104:107]
	v_mfma_f32_16x16x32_bf16 v[88:91], v[162:165], v[208:211], v[88:91]
	v_mfma_f32_16x16x32_bf16 v[88:91], v[166:169], v[212:215], v[88:91]
	v_mfma_f32_16x16x32_bf16 v[72:75], v[166:169], v[220:223], v[72:75]
	v_mfma_f32_16x16x32_bf16 v[72:75], v[162:165], v[216:219], v[72:75]
	v_mfma_f32_16x16x32_bf16 v[68:71], v[170:173], v[216:219], v[68:71]
	v_mfma_f32_16x16x32_bf16 v[68:71], v[174:177], v[220:223], v[68:71]
	v_mfma_f32_16x16x32_bf16 v[84:87], v[174:177], v[212:215], v[84:87]
	v_mfma_f32_16x16x32_bf16 v[84:87], v[170:173], v[208:211], v[84:87]
	v_mfma_f32_16x16x32_bf16 v[100:103], v[170:173], v[186:189], v[100:103]
	v_mfma_f32_16x16x32_bf16 v[100:103], v[174:177], v[204:207], v[100:103]
	v_mfma_f32_16x16x32_bf16 v[116:119], v[174:177], v[182:185], v[116:119]
	v_mfma_f32_16x16x32_bf16 v[116:119], v[170:173], v[178:181], v[116:119]
	s_setprio 0
	s_barrier
	s_add_i32 s48, s73, s28
	v_lshl_add_u64 v[190:191], v[190:191], 0, s[84:85]
	s_mov_b32 m0, s48
	ds_read_b128 v[178:181], v145 offset:49152
	ds_read_b128 v[182:185], v145 offset:50176
	ds_read_b128 v[186:189], v145 offset:51200
	ds_read_b128 v[204:207], v145 offset:52224
	ds_read_b128 v[208:211], v145 offset:53248
	ds_read_b128 v[212:215], v145 offset:54272
	ds_read_b128 v[216:219], v145 offset:55296
	ds_read_b128 v[220:223], v145 offset:56320
	global_load_lds_dwordx4 v[190:191], off
	v_lshl_add_u64 v[190:191], v[224:225], 0, s[84:85]
	s_add_i32 m0, s48, 0x2000
	s_add_i32 s48, s76, s28
	global_load_lds_dwordx4 v[190:191], off
	v_lshl_add_u64 v[190:191], v[226:227], 0, s[84:85]
	s_mov_b32 m0, s48
	s_nop 0
	global_load_lds_dwordx4 v[190:191], off
	v_lshl_add_u64 v[190:191], v[228:229], 0, s[84:85]
	s_add_i32 m0, s48, 0x2000
	s_nop 0
	global_load_lds_dwordx4 v[190:191], off
	v_lshl_add_u64 v[190:191], v[240:241], 0, s[84:85]
	s_mov_b32 m0, s55
	s_nop 0
	global_load_lds_dwordx4 v[190:191], off
	v_lshl_add_u64 v[190:191], v[242:243], 0, s[84:85]
	s_mov_b32 m0, s56
	s_nop 0
	global_load_lds_dwordx4 v[190:191], off
	s_waitcnt vmcnt(8)
	s_waitcnt lgkmcnt(0)
	s_barrier
	s_setprio 1
	s_waitcnt lgkmcnt(0)
	v_mfma_f32_16x16x32_bf16 v[64:67], v[146:149], v[178:181], v[64:67]
	v_mfma_f32_16x16x32_bf16 v[64:67], v[150:153], v[182:185], v[64:67]
	v_mfma_f32_16x16x32_bf16 v[48:51], v[150:153], v[204:207], v[48:51]
	v_mfma_f32_16x16x32_bf16 v[48:51], v[146:149], v[186:189], v[48:51]
	v_mfma_f32_16x16x32_bf16 v[32:35], v[146:149], v[208:211], v[32:35]
	v_mfma_f32_16x16x32_bf16 v[32:35], v[150:153], v[212:215], v[32:35]
	v_mfma_f32_16x16x32_bf16 v[16:19], v[150:153], v[220:223], v[16:19]
	v_mfma_f32_16x16x32_bf16 v[16:19], v[146:149], v[216:219], v[16:19]
	v_mfma_f32_16x16x32_bf16 v[12:15], v[154:157], v[216:219], v[12:15]
	v_mfma_f32_16x16x32_bf16 v[12:15], v[158:161], v[220:223], v[12:15]
	v_mfma_f32_16x16x32_bf16 v[28:31], v[158:161], v[212:215], v[28:31]
	v_mfma_f32_16x16x32_bf16 v[28:31], v[154:157], v[208:211], v[28:31]
	v_mfma_f32_16x16x32_bf16 v[44:47], v[154:157], v[186:189], v[44:47]
	v_mfma_f32_16x16x32_bf16 v[44:47], v[158:161], v[204:207], v[44:47]
	v_mfma_f32_16x16x32_bf16 v[60:63], v[158:161], v[182:185], v[60:63]
	v_mfma_f32_16x16x32_bf16 v[60:63], v[154:157], v[178:181], v[60:63]
	v_mfma_f32_16x16x32_bf16 v[56:59], v[162:165], v[178:181], v[56:59]
	v_mfma_f32_16x16x32_bf16 v[56:59], v[166:169], v[182:185], v[56:59]
	v_mfma_f32_16x16x32_bf16 v[40:43], v[166:169], v[204:207], v[40:43]
	v_mfma_f32_16x16x32_bf16 v[40:43], v[162:165], v[186:189], v[40:43]
	v_mfma_f32_16x16x32_bf16 v[24:27], v[162:165], v[208:211], v[24:27]
	v_mfma_f32_16x16x32_bf16 v[24:27], v[166:169], v[212:215], v[24:27]
	v_mfma_f32_16x16x32_bf16 v[8:11], v[166:169], v[220:223], v[8:11]
	v_mfma_f32_16x16x32_bf16 v[8:11], v[162:165], v[216:219], v[8:11]
	v_mfma_f32_16x16x32_bf16 v[4:7], v[170:173], v[216:219], v[4:7]
	v_mfma_f32_16x16x32_bf16 v[4:7], v[174:177], v[220:223], v[4:7]
	v_mfma_f32_16x16x32_bf16 v[20:23], v[174:177], v[212:215], v[20:23]
	v_mfma_f32_16x16x32_bf16 v[20:23], v[170:173], v[208:211], v[20:23]
	v_mfma_f32_16x16x32_bf16 v[36:39], v[170:173], v[186:189], v[36:39]
	v_mfma_f32_16x16x32_bf16 v[36:39], v[174:177], v[204:207], v[36:39]
	v_mfma_f32_16x16x32_bf16 v[52:55], v[174:177], v[182:185], v[52:55]
	v_mfma_f32_16x16x32_bf16 v[52:55], v[170:173], v[178:181], v[52:55]
	s_setprio 0
	s_barrier
	s_add_u32 s44, s44, 0x100
	s_addc_u32 s45, s45, 0
	s_add_u32 s65, s65, 0x100
	s_addc_u32 s67, s67, 0
	s_cmp_ge_i32 s72, s53
	s_mov_b32 s48, s72
	s_cbranch_scc0 .LBB0_1623

; #define PG8_STAGE(bufoff, gbase, voff) do { _Pragma("unroll") for (int _i = 0; _i < 2; ++_i) \
;         __builtin_amdgcn_global_load_lds((const unsigned*)((const char*)(gbase) + (voff)[_i]), (PG8_LAS unsigned*)(lds + (bufoff) + ldsw + _i * 8192), 16, 0, 0); } while (0)
; #define PG8_LDA(dst, b, h) do { _Pragma("unroll") for (int m = 0; m < 4; ++m) _Pragma("unroll") for (int k = 0; k < 2; ++k) dst[m][k] = *(const PG8_LAS bf16x8*)(lds + PG8_SA(b, h) + aoff + m * 2048 + k * 1024); } while (0)
; #define PG8_LDB(dst, b, h) do { _Pragma("unroll") for (int n = 0; n < 2; ++n) _Pragma("unroll") for (int k = 0; k < 2; ++k) dst[n][k] = *(const PG8_LAS bf16x8*)(lds + PG8_SB(b, h) + boff + n * 2048 + k * 1024); } while (0)
; #define PG8_WAIT_V(n) asm volatile("s_waitcnt vmcnt(" #n ")" ::: "memory")
; #define PG8_WAIT_L(n) asm volatile("s_waitcnt lgkmcnt(" #n ")" ::: "memory")
; #define PG8_BAR __builtin_amdgcn_s_barrier()
; #define PG8_SCHED __builtin_amdgcn_sched_barrier(0)
; template <class Epi, class Sched, bool ALIGN_EPI = false, bool SP2 = false, bool I8 = false>
; __device__ __forceinline__ void gemm_phase(PG8_LAS unsigned char* lds, const Gemm g, const Sched& S, const Epi& E) {
;     ...
;         const bool has_next = S.next(ui + 1, nxt);
;         const char* nA = has_next ? (const char*)g.A + (size_t)nxt.pm * tstep : cA; const char* nB = has_next ? (const char*)g.Bt + (size_t)nxt.pn * tstep : cB;
;         for (int t = 0; t < nt; t += 2) {
;             const bool last = (t == nt - 2);
;             const char* a1 = cA + (size_t)(t + 1) * kstep;
;             const char* a2 = last ? nA : cA + (size_t)(t + 2) * kstep; const char* b2 = last ? nB : cB + (size_t)(t + 2) * kstep;
;             const char* a3 = a2 + kstep; const char* b3 = b2 + kstep;
;             if (last && has_next) S.a_ready(nxt);
;             if constexpr (SP2) {
;             PG8_LDB(B0, 0, 0); PG8_LDB(B1, 0, 1); PG8_SCHED; PG8_LDA(At, 0, 0); PG8_STAGE(PG8_SA(1, 1), a1 + hstep, voffA);
;             PG8_WAIT_V(8); PG8_WAIT_L(0); PG8_BAR; PG8_MMA(0, 0, At, B0); PG8_MMA(0, 1, At, B1); PG8_BAR; PG8_SCHED;
;             PG8_LDA(At, 0, 1); PG8_STAGE(PG8_SB(0, 0), b2, voffB); PG8_STAGE(PG8_SB(0, 1), b2 + hstep, voffB); PG8_STAGE(PG8_SA(0, 0), a2, voffA);
;             PG8_WAIT_V(8); PG8_WAIT_L(0); PG8_BAR; PG8_MMA(1, 0, At, B0); PG8_MMA(1, 1, At, B1); PG8_BAR; PG8_SCHED;
.LBB0_1699:
	s_add_u32 s53, s24, 0x100
	s_addc_u32 s54, s25, 0
	s_mov_b32 s55, -2
	s_add_u32 s24, s22, 0x100
	s_addc_u32 s25, s23, 0
	s_add_i32 s56, 0, 0x10000
	s_cmpk_eq_i32 s55, 0xa8
	s_cselect_b32 s37, s13, s25
	s_cselect_b32 s36, s12, s24
	s_cselect_b32 s27, s21, s54
	s_cselect_b32 s26, s20, s53
	s_add_i32 s57, 0, 0x14000
	v_add_u32_e32 v144, s56, v240
	v_add_u32_e32 v160, s57, v240
	ds_read_b128 v[124:127], v144
	ds_read_b128 v[128:131], v144 offset:1024
	ds_read_b128 v[132:135], v144 offset:2048
	ds_read_b128 v[144:147], v144 offset:3072
	ds_read_b128 v[148:151], v160
	ds_read_b128 v[152:155], v160 offset:1024
	ds_read_b128 v[156:159], v160 offset:2048
	ds_read_b128 v[160:163], v160 offset:3072
	v_lshl_add_u64 v[218:219], s[22:23], 0, v[210:211]
	s_add_i32 m0, s42, 0xc000
	ds_read_b128 v[164:167], v242
	ds_read_b128 v[168:171], v242 offset:1024
	ds_read_b128 v[172:175], v242 offset:2048
	ds_read_b128 v[176:179], v242 offset:3072
	ds_read_b128 v[180:183], v242 offset:4096
	ds_read_b128 v[184:187], v242 offset:5120
	ds_read_b128 v[188:191], v242 offset:6144
	ds_read_b128 v[214:217], v242 offset:7168
	global_load_lds_dwordx4 v[218:219], off
	v_lshl_add_u64 v[218:219], s[22:23], 0, v[212:213]
	s_add_i32 m0, s42, 0xe000
	s_nop 0
	global_load_lds_dwordx4 v[218:219], off
	s_waitcnt vmcnt(8)
	s_waitcnt lgkmcnt(0)
	s_barrier
	s_setprio 1
	s_waitcnt lgkmcnt(0)
	v_mfma_f32_16x16x32_bf16 v[140:143], v[124:127], v[164:167], 0
	v_mfma_f32_16x16x32_bf16 v[140:143], v[128:131], v[168:171], v[140:143]
	v_mfma_f32_16x16x32_bf16 v[112:115], v[128:131], v[176:179], 0
	v_mfma_f32_16x16x32_bf16 v[112:115], v[124:127], v[172:175], v[112:115]
	v_mfma_f32_16x16x32_bf16 v[96:99], v[124:127], v[180:183], 0
	v_mfma_f32_16x16x32_bf16 v[96:99], v[128:131], v[184:187], v[96:99]
	v_mfma_f32_16x16x32_bf16 v[80:83], v[128:131], v[214:217], 0
	v_mfma_f32_16x16x32_bf16 v[80:83], v[124:127], v[188:191], v[80:83]
	v_mfma_f32_16x16x32_bf16 v[76:79], v[132:135], v[188:191], 0
	v_mfma_f32_16x16x32_bf16 v[76:79], v[144:147], v[214:217], v[76:79]
	v_mfma_f32_16x16x32_bf16 v[92:95], v[144:147], v[184:187], 0
	v_mfma_f32_16x16x32_bf16 v[92:95], v[132:135], v[180:183], v[92:95]
	v_mfma_f32_16x16x32_bf16 v[108:111], v[132:135], v[172:175], 0
	v_mfma_f32_16x16x32_bf16 v[108:111], v[144:147], v[176:179], v[108:111]
	v_mfma_f32_16x16x32_bf16 v[136:139], v[144:147], v[168:171], 0
	v_mfma_f32_16x16x32_bf16 v[136:139], v[132:135], v[164:167], v[136:139]
	v_mfma_f32_16x16x32_bf16 v[120:123], v[148:151], v[164:167], 0
	v_mfma_f32_16x16x32_bf16 v[120:123], v[152:155], v[168:171], v[120:123]
	v_mfma_f32_16x16x32_bf16 v[104:107], v[152:155], v[176:179], 0
	v_mfma_f32_16x16x32_bf16 v[104:107], v[148:151], v[172:175], v[104:107]
	v_mfma_f32_16x16x32_bf16 v[88:91], v[148:151], v[180:183], 0
	v_mfma_f32_16x16x32_bf16 v[88:91], v[152:155], v[184:187], v[88:91]
	v_mfma_f32_16x16x32_bf16 v[72:75], v[152:155], v[214:217], 0
	v_mfma_f32_16x16x32_bf16 v[72:75], v[148:151], v[188:191], v[72:75]
	v_mfma_f32_16x16x32_bf16 v[68:71], v[156:159], v[188:191], 0
	v_mfma_f32_16x16x32_bf16 v[68:71], v[160:163], v[214:217], v[68:71]
	v_mfma_f32_16x16x32_bf16 v[84:87], v[160:163], v[184:187], 0
	v_mfma_f32_16x16x32_bf16 v[84:87], v[156:159], v[180:183], v[84:87]
	v_mfma_f32_16x16x32_bf16 v[100:103], v[156:159], v[172:175], 0
	v_mfma_f32_16x16x32_bf16 v[100:103], v[160:163], v[176:179], v[100:103]
	v_mfma_f32_16x16x32_bf16 v[116:119], v[160:163], v[168:171], 0
	v_mfma_f32_16x16x32_bf16 v[116:119], v[156:159], v[164:167], v[116:119]
	s_setprio 0
	s_barrier
	s_add_i32 s22, s56, s41
	v_lshl_add_u64 v[218:219], s[26:27], 0, v[2:3]
	s_mov_b32 m0, s22
	ds_read_b128 v[164:167], v242 offset:16384
	ds_read_b128 v[168:171], v242 offset:17408
	ds_read_b128 v[172:175], v242 offset:18432
	ds_read_b128 v[176:179], v242 offset:19456
	ds_read_b128 v[180:183], v242 offset:20480
	ds_read_b128 v[184:187], v242 offset:21504
	ds_read_b128 v[188:191], v242 offset:22528
	ds_read_b128 v[214:217], v242 offset:23552
	global_load_lds_dwordx4 v[218:219], off
	s_add_i32 m0, s22, 0x2000
	s_add_u32 s22, s26, 0x2b0000
	v_lshl_add_u64 v[220:221], s[26:27], 0, v[204:205]
	s_addc_u32 s23, s27, 0
	s_add_i32 s56, s57, s41
	global_load_lds_dwordx4 v[220:221], off
	v_lshl_add_u64 v[222:223], s[22:23], 0, v[2:3]
	s_mov_b32 m0, s56
	v_lshl_add_u64 v[224:225], s[36:37], 0, v[206:207]
	global_load_lds_dwordx4 v[222:223], off
	v_lshl_add_u64 v[222:223], s[22:23], 0, v[204:205]
	s_add_i32 m0, s56, 0x2000
	s_nop 0
	global_load_lds_dwordx4 v[222:223], off
	v_lshl_add_u64 v[222:223], s[36:37], 0, v[208:209]
	s_mov_b32 m0, s42
	s_nop 0
	global_load_lds_dwordx4 v[222:223], off
	s_mov_b32 m0, s43
	s_nop 0
	global_load_lds_dwordx4 v[224:225], off
	s_waitcnt vmcnt(8)
	s_waitcnt lgkmcnt(0)
	s_barrier
; #define PG8_STAGE(bufoff, gbase, voff) do { _Pragma("unroll") for (int _i = 0; _i < 2; ++_i) \
;         __builtin_amdgcn_global_load_lds((const unsigned*)((const char*)(gbase) + (voff)[_i]), (PG8_LAS unsigned*)(lds + (bufoff) + ldsw + _i * 8192), 16, 0, 0); } while (0)
; #define PG8_LDA(dst, b, h) do { _Pragma("unroll") for (int m = 0; m < 4; ++m) _Pragma("unroll") for (int k = 0; k < 2; ++k) dst[m][k] = *(const PG8_LAS bf16x8*)(lds + PG8_SA(b, h) + aoff + m * 2048 + k * 1024); } while (0)
; #define PG8_LDB(dst, b, h) do { _Pragma("unroll") for (int n = 0; n < 2; ++n) _Pragma("unroll") for (int k = 0; k < 2; ++k) dst[n][k] = *(const PG8_LAS bf16x8*)(lds + PG8_SB(b, h) + boff + n * 2048 + k * 1024); } while (0)
; #define PG8_WAIT_V(n) asm volatile("s_waitcnt vmcnt(" #n ")" ::: "memory")
; #define PG8_WAIT_L(n) asm volatile("s_waitcnt lgkmcnt(" #n ")" ::: "memory")
; #define PG8_BAR __builtin_amdgcn_s_barrier()
; #define PG8_SCHED __builtin_amdgcn_sched_barrier(0)
; template <class Epi, class Sched, bool ALIGN_EPI = false, bool SP2 = false, bool I8 = false>
; __device__ __forceinline__ void gemm_phase(PG8_LAS unsigned char* lds, const Gemm g, const Sched& S, const Epi& E) {
;     ...
;             PG8_WAIT_V(8); PG8_WAIT_L(0); PG8_BAR; PG8_MMA(1, 0, At, B0); PG8_MMA(1, 1, At, B1); PG8_BAR; PG8_SCHED;
;             PG8_LDB(B0, 1, 0); PG8_LDB(B1, 1, 1); PG8_SCHED; PG8_LDA(At, 1, 0); PG8_STAGE(PG8_SA(0, 1), a2 + hstep, voffA);
;             PG8_WAIT_V(8); PG8_WAIT_L(0); PG8_BAR; PG8_MMA(0, 0, At, B0); PG8_MMA(0, 1, At, B1); PG8_BAR; PG8_SCHED;
	s_setprio 1
	s_waitcnt lgkmcnt(0)
	v_mfma_f32_16x16x32_bf16 v[64:67], v[124:127], v[164:167], 0
	v_mfma_f32_16x16x32_bf16 v[64:67], v[128:131], v[168:171], v[64:67]
	v_mfma_f32_16x16x32_bf16 v[48:51], v[128:131], v[176:179], 0
	v_mfma_f32_16x16x32_bf16 v[48:51], v[124:127], v[172:175], v[48:51]
	v_mfma_f32_16x16x32_bf16 v[32:35], v[124:127], v[180:183], 0
	v_mfma_f32_16x16x32_bf16 v[32:35], v[128:131], v[184:187], v[32:35]
	v_mfma_f32_16x16x32_bf16 v[16:19], v[128:131], v[214:217], 0
	v_mfma_f32_16x16x32_bf16 v[16:19], v[124:127], v[188:191], v[16:19]
	v_mfma_f32_16x16x32_bf16 v[12:15], v[132:135], v[188:191], 0
	v_mfma_f32_16x16x32_bf16 v[12:15], v[144:147], v[214:217], v[12:15]
	v_mfma_f32_16x16x32_bf16 v[28:31], v[144:147], v[184:187], 0
	v_mfma_f32_16x16x32_bf16 v[28:31], v[132:135], v[180:183], v[28:31]
	v_mfma_f32_16x16x32_bf16 v[44:47], v[132:135], v[172:175], 0
	v_mfma_f32_16x16x32_bf16 v[44:47], v[144:147], v[176:179], v[44:47]
	v_mfma_f32_16x16x32_bf16 v[60:63], v[144:147], v[168:171], 0
	v_mfma_f32_16x16x32_bf16 v[60:63], v[132:135], v[164:167], v[60:63]
	v_mfma_f32_16x16x32_bf16 v[56:59], v[148:151], v[164:167], 0
	v_mfma_f32_16x16x32_bf16 v[56:59], v[152:155], v[168:171], v[56:59]
	v_mfma_f32_16x16x32_bf16 v[40:43], v[152:155], v[176:179], 0
	v_mfma_f32_16x16x32_bf16 v[40:43], v[148:151], v[172:175], v[40:43]
	v_mfma_f32_16x16x32_bf16 v[24:27], v[148:151], v[180:183], 0
	v_mfma_f32_16x16x32_bf16 v[24:27], v[152:155], v[184:187], v[24:27]
	v_mfma_f32_16x16x32_bf16 v[8:11], v[152:155], v[214:217], 0
	v_mfma_f32_16x16x32_bf16 v[8:11], v[148:151], v[188:191], v[8:11]
	v_mfma_f32_16x16x32_bf16 v[4:7], v[156:159], v[188:191], 0
	v_mfma_f32_16x16x32_bf16 v[4:7], v[160:163], v[214:217], v[4:7]
	v_mfma_f32_16x16x32_bf16 v[20:23], v[160:163], v[184:187], 0
	v_mfma_f32_16x16x32_bf16 v[20:23], v[156:159], v[180:183], v[20:23]
	v_mfma_f32_16x16x32_bf16 v[36:39], v[156:159], v[172:175], 0
	v_mfma_f32_16x16x32_bf16 v[36:39], v[160:163], v[176:179], v[36:39]
	v_mfma_f32_16x16x32_bf16 v[52:55], v[160:163], v[168:171], 0
	v_mfma_f32_16x16x32_bf16 v[52:55], v[156:159], v[164:167], v[52:55]
	s_setprio 0
	s_barrier
	s_add_i32 s56, 0, 0x18000
	s_add_i32 s57, 0, 0x1c000
	v_add_u32_e32 v144, s56, v240
	v_add_u32_e32 v160, s57, v240
	ds_read_b128 v[124:127], v144
	ds_read_b128 v[128:131], v144 offset:1024
	ds_read_b128 v[132:135], v144 offset:2048
	ds_read_b128 v[144:147], v144 offset:3072
	ds_read_b128 v[148:151], v160
	ds_read_b128 v[152:155], v160 offset:1024
	ds_read_b128 v[156:159], v160 offset:2048
	ds_read_b128 v[160:163], v160 offset:3072
	s_add_u32 s22, s36, 0x2b0000
	s_addc_u32 s23, s37, 0
	s_mov_b32 m0, s44
	v_lshl_add_u64 v[226:227], s[22:23], 0, v[208:209]
	ds_read_b128 v[164:167], v242 offset:32768
	ds_read_b128 v[168:171], v242 offset:33792
	ds_read_b128 v[172:175], v242 offset:34816
	ds_read_b128 v[176:179], v242 offset:35840
	ds_read_b128 v[180:183], v242 offset:36864
	ds_read_b128 v[184:187], v242 offset:37888
	ds_read_b128 v[188:191], v242 offset:38912
	ds_read_b128 v[214:217], v242 offset:39936
	global_load_lds_dwordx4 v[226:227], off
	v_lshl_add_u64 v[226:227], s[22:23], 0, v[206:207]
	s_mov_b32 m0, s45
	s_nop 0
	global_load_lds_dwordx4 v[226:227], off
	s_waitcnt vmcnt(8)
	s_waitcnt lgkmcnt(0)
	s_barrier
	s_setprio 1
	s_waitcnt lgkmcnt(0)
	v_mfma_f32_16x16x32_bf16 v[140:143], v[124:127], v[164:167], v[140:143]
	v_mfma_f32_16x16x32_bf16 v[140:143], v[128:131], v[168:171], v[140:143]
	v_mfma_f32_16x16x32_bf16 v[112:115], v[128:131], v[176:179], v[112:115]
	v_mfma_f32_16x16x32_bf16 v[112:115], v[124:127], v[172:175], v[112:115]
	v_mfma_f32_16x16x32_bf16 v[96:99], v[124:127], v[180:183], v[96:99]
	v_mfma_f32_16x16x32_bf16 v[96:99], v[128:131], v[184:187], v[96:99]
	v_mfma_f32_16x16x32_bf16 v[80:83], v[128:131], v[214:217], v[80:83]
	v_mfma_f32_16x16x32_bf16 v[80:83], v[124:127], v[188:191], v[80:83]
	v_mfma_f32_16x16x32_bf16 v[76:79], v[132:135], v[188:191], v[76:79]
	v_mfma_f32_16x16x32_bf16 v[76:79], v[144:147], v[214:217], v[76:79]
	v_mfma_f32_16x16x32_bf16 v[92:95], v[144:147], v[184:187], v[92:95]
	v_mfma_f32_16x16x32_bf16 v[92:95], v[132:135], v[180:183], v[92:95]
	v_mfma_f32_16x16x32_bf16 v[108:111], v[132:135], v[172:175], v[108:111]
	v_mfma_f32_16x16x32_bf16 v[108:111], v[144:147], v[176:179], v[108:111]
	v_mfma_f32_16x16x32_bf16 v[136:139], v[144:147], v[168:171], v[136:139]
	v_mfma_f32_16x16x32_bf16 v[136:139], v[132:135], v[164:167], v[136:139]
	v_mfma_f32_16x16x32_bf16 v[120:123], v[148:151], v[164:167], v[120:123]
	v_mfma_f32_16x16x32_bf16 v[120:123], v[152:155], v[168:171], v[120:123]
	v_mfma_f32_16x16x32_bf16 v[104:107], v[152:155], v[176:179], v[104:107]
	v_mfma_f32_16x16x32_bf16 v[104:107], v[148:151], v[172:175], v[104:107]
	v_mfma_f32_16x16x32_bf16 v[88:91], v[148:151], v[180:183], v[88:91]
	v_mfma_f32_16x16x32_bf16 v[88:91], v[152:155], v[184:187], v[88:91]
	v_mfma_f32_16x16x32_bf16 v[72:75], v[152:155], v[214:217], v[72:75]
	v_mfma_f32_16x16x32_bf16 v[72:75], v[148:151], v[188:191], v[72:75]
	v_mfma_f32_16x16x32_bf16 v[68:71], v[156:159], v[188:191], v[68:71]
	v_mfma_f32_16x16x32_bf16 v[68:71], v[160:163], v[214:217], v[68:71]
	v_mfma_f32_16x16x32_bf16 v[84:87], v[160:163], v[184:187], v[84:87]
	v_mfma_f32_16x16x32_bf16 v[84:87], v[156:159], v[180:183], v[84:87]
	v_mfma_f32_16x16x32_bf16 v[100:103], v[156:159], v[172:175], v[100:103]
	v_mfma_f32_16x16x32_bf16 v[100:103], v[160:163], v[176:179], v[100:103]
	v_mfma_f32_16x16x32_bf16 v[116:119], v[160:163], v[168:171], v[116:119]
	v_mfma_f32_16x16x32_bf16 v[116:119], v[156:159], v[164:167], v[116:119]
	s_setprio 0
	s_barrier
; #define PG8_STAGE(bufoff, gbase, voff) do { _Pragma("unroll") for (int _i = 0; _i < 2; ++_i) \
;         __builtin_amdgcn_global_load_lds((const unsigned*)((const char*)(gbase) + (voff)[_i]), (PG8_LAS unsigned*)(lds + (bufoff) + ldsw + _i * 8192), 16, 0, 0); } while (0)
; #define PG8_LDA(dst, b, h) do { _Pragma("unroll") for (int m = 0; m < 4; ++m) _Pragma("unroll") for (int k = 0; k < 2; ++k) dst[m][k] = *(const PG8_LAS bf16x8*)(lds + PG8_SA(b, h) + aoff + m * 2048 + k * 1024); } while (0)
; template <class Epi, class Sched, bool ALIGN_EPI = false, bool SP2 = false, bool I8 = false>
; __device__ __forceinline__ void gemm_phase(PG8_LAS unsigned char* lds, const Gemm g, const Sched& S, const Epi& E) {
;     ...
;         const bool has_next = S.next(ui + 1, nxt);
;         const char* nA = has_next ? (const char*)g.A + (size_t)nxt.pm * tstep : cA; const char* nB = has_next ? (const char*)g.Bt + (size_t)nxt.pn * tstep : cB;
;         for (int t = 0; t < nt; t += 2) {
;             const bool last = (t == nt - 2);
;             const char* a1 = cA + (size_t)(t + 1) * kstep;
;             const char* a2 = last ? nA : cA + (size_t)(t + 2) * kstep; const char* b2 = last ? nB : cB + (size_t)(t + 2) * kstep;
;             const char* a3 = a2 + kstep; const char* b3 = b2 + kstep;
;             if (last && has_next) S.a_ready(nxt);
;             if constexpr (SP2) {
;             PG8_LDB(B0, 0, 0); PG8_LDB(B1, 0, 1); PG8_SCHED; PG8_LDA(At, 0, 0); PG8_STAGE(PG8_SA(1, 1), a1 + hstep, voffA);
;             PG8_WAIT_V(8); PG8_WAIT_L(0); PG8_BAR; PG8_MMA(0, 0, At, B0); PG8_MMA(0, 1, At, B1); PG8_BAR; PG8_SCHED;
;             PG8_LDA(At, 0, 1); PG8_STAGE(PG8_SB(0, 0), b2, voffB); PG8_STAGE(PG8_SB(0, 1), b2 + hstep, voffB); PG8_STAGE(PG8_SA(0, 0), a2, voffA);
;             PG8_WAIT_V(8); PG8_WAIT_L(0); PG8_BAR; PG8_MMA(1, 0, At, B0); PG8_MMA(1, 1, At, B1); PG8_BAR; PG8_SCHED;
;             PG8_LDB(B0, 1, 0); PG8_LDB(B1, 1, 1); PG8_SCHED; PG8_LDA(At, 1, 0); PG8_STAGE(PG8_SA(0, 1), a2 + hstep, voffA);
;             PG8_WAIT_V(8); PG8_WAIT_L(0); PG8_BAR; PG8_MMA(0, 0, At, B0); PG8_MMA(0, 1, At, B1); PG8_BAR; PG8_SCHED;
;             PG8_LDA(At, 1, 1); PG8_STAGE(PG8_SB(1, 0), b3, voffB); PG8_STAGE(PG8_SB(1, 1), b3 + hstep, voffB); PG8_STAGE(PG8_SA(1, 0), a3, voffA);
;             PG8_WAIT_V(8); PG8_WAIT_L(0); PG8_BAR; PG8_MMA(1, 0, At, B0); PG8_MMA(1, 1, At, B1); PG8_BAR; PG8_SCHED;
	s_add_i32 s22, s56, s41
	v_lshl_add_u64 v[218:219], v[218:219], 0, s[84:85]
	s_mov_b32 m0, s22
	ds_read_b128 v[164:167], v242 offset:49152
	ds_read_b128 v[168:171], v242 offset:50176
	ds_read_b128 v[172:175], v242 offset:51200
	ds_read_b128 v[176:179], v242 offset:52224
	ds_read_b128 v[180:183], v242 offset:53248
	ds_read_b128 v[184:187], v242 offset:54272
	ds_read_b128 v[188:191], v242 offset:55296
	ds_read_b128 v[214:217], v242 offset:56320
	global_load_lds_dwordx4 v[218:219], off
	s_add_i32 m0, s22, 0x2000
	s_add_u32 s22, s26, 0x2b0080
	v_lshl_add_u64 v[218:219], v[220:221], 0, s[84:85]
	s_addc_u32 s23, s27, 0
	s_add_i32 s26, s57, s41
	global_load_lds_dwordx4 v[218:219], off
	v_lshl_add_u64 v[218:219], s[22:23], 0, v[2:3]
	s_mov_b32 m0, s26
	s_nop 0
	global_load_lds_dwordx4 v[218:219], off
	v_lshl_add_u64 v[218:219], s[22:23], 0, v[204:205]
	s_add_i32 m0, s26, 0x2000
	s_nop 0
	global_load_lds_dwordx4 v[218:219], off
	v_lshl_add_u64 v[218:219], v[222:223], 0, s[84:85]
	s_mov_b32 m0, s46
	s_nop 0
	global_load_lds_dwordx4 v[218:219], off
	v_lshl_add_u64 v[218:219], v[224:225], 0, s[84:85]
	s_mov_b32 m0, s47
	s_nop 0
	global_load_lds_dwordx4 v[218:219], off
	s_waitcnt vmcnt(8)
	s_waitcnt lgkmcnt(0)
	s_barrier
	s_setprio 1
	s_waitcnt lgkmcnt(0)
	v_mfma_f32_16x16x32_bf16 v[64:67], v[124:127], v[164:167], v[64:67]
	v_mfma_f32_16x16x32_bf16 v[64:67], v[128:131], v[168:171], v[64:67]
	v_mfma_f32_16x16x32_bf16 v[48:51], v[128:131], v[176:179], v[48:51]
	v_mfma_f32_16x16x32_bf16 v[48:51], v[124:127], v[172:175], v[48:51]
	v_mfma_f32_16x16x32_bf16 v[32:35], v[124:127], v[180:183], v[32:35]
	v_mfma_f32_16x16x32_bf16 v[32:35], v[128:131], v[184:187], v[32:35]
	v_mfma_f32_16x16x32_bf16 v[16:19], v[128:131], v[214:217], v[16:19]
	v_mfma_f32_16x16x32_bf16 v[16:19], v[124:127], v[188:191], v[16:19]
	v_mfma_f32_16x16x32_bf16 v[12:15], v[132:135], v[188:191], v[12:15]
	v_mfma_f32_16x16x32_bf16 v[12:15], v[144:147], v[214:217], v[12:15]
	v_mfma_f32_16x16x32_bf16 v[28:31], v[144:147], v[184:187], v[28:31]
	v_mfma_f32_16x16x32_bf16 v[28:31], v[132:135], v[180:183], v[28:31]
	v_mfma_f32_16x16x32_bf16 v[44:47], v[132:135], v[172:175], v[44:47]
	v_mfma_f32_16x16x32_bf16 v[44:47], v[144:147], v[176:179], v[44:47]
	v_mfma_f32_16x16x32_bf16 v[60:63], v[144:147], v[168:171], v[60:63]
	v_mfma_f32_16x16x32_bf16 v[60:63], v[132:135], v[164:167], v[60:63]
	v_mfma_f32_16x16x32_bf16 v[56:59], v[148:151], v[164:167], v[56:59]
	v_mfma_f32_16x16x32_bf16 v[56:59], v[152:155], v[168:171], v[56:59]
	v_mfma_f32_16x16x32_bf16 v[40:43], v[152:155], v[176:179], v[40:43]
	v_mfma_f32_16x16x32_bf16 v[40:43], v[148:151], v[172:175], v[40:43]
	v_mfma_f32_16x16x32_bf16 v[24:27], v[148:151], v[180:183], v[24:27]
	v_mfma_f32_16x16x32_bf16 v[24:27], v[152:155], v[184:187], v[24:27]
	v_mfma_f32_16x16x32_bf16 v[8:11], v[152:155], v[214:217], v[8:11]
	v_mfma_f32_16x16x32_bf16 v[8:11], v[148:151], v[188:191], v[8:11]
	v_mfma_f32_16x16x32_bf16 v[4:7], v[156:159], v[188:191], v[4:7]
	v_mfma_f32_16x16x32_bf16 v[4:7], v[160:163], v[214:217], v[4:7]
	v_mfma_f32_16x16x32_bf16 v[20:23], v[160:163], v[184:187], v[20:23]
	v_mfma_f32_16x16x32_bf16 v[20:23], v[156:159], v[180:183], v[20:23]
	v_mfma_f32_16x16x32_bf16 v[36:39], v[156:159], v[172:175], v[36:39]
	v_mfma_f32_16x16x32_bf16 v[36:39], v[160:163], v[176:179], v[36:39]
	v_mfma_f32_16x16x32_bf16 v[52:55], v[160:163], v[168:171], v[52:55]
	v_mfma_f32_16x16x32_bf16 v[52:55], v[156:159], v[164:167], v[52:55]
	s_setprio 0
	s_barrier
	s_add_i32 s55, s55, 2
	s_add_u32 s53, s53, 0x100
	s_addc_u32 s54, s54, 0
	s_cmpk_gt_u32 s55, 0xa9
	s_mov_b64 s[22:23], s[24:25]
	s_cbranch_scc1 .Lkloop_exit_5
.LBB0_1700:
	s_add_u32 s24, s22, 0x100
	s_addc_u32 s25, s23, 0
	s_add_i32 s56, 0, 0x10000
	s_cmpk_eq_i32 s55, 0xa8
	s_cselect_b32 s37, s13, s25
	s_cselect_b32 s36, s12, s24
	s_cselect_b32 s27, s21, s54
	s_cselect_b32 s26, s20, s53
	s_add_i32 s57, 0, 0x14000
	v_add_u32_e32 v144, s56, v240
	v_add_u32_e32 v160, s57, v240
	ds_read_b128 v[124:127], v144
	ds_read_b128 v[128:131], v144 offset:1024
	ds_read_b128 v[132:135], v144 offset:2048
	ds_read_b128 v[144:147], v144 offset:3072
	ds_read_b128 v[148:151], v160
	ds_read_b128 v[152:155], v160 offset:1024
	ds_read_b128 v[156:159], v160 offset:2048
	ds_read_b128 v[160:163], v160 offset:3072
	v_lshl_add_u64 v[218:219], s[22:23], 0, v[210:211]
	s_add_i32 m0, s42, 0xc000
	ds_read_b128 v[164:167], v242
	ds_read_b128 v[168:171], v242 offset:1024
	ds_read_b128 v[172:175], v242 offset:2048
	ds_read_b128 v[176:179], v242 offset:3072
	ds_read_b128 v[180:183], v242 offset:4096
	ds_read_b128 v[184:187], v242 offset:5120
	ds_read_b128 v[188:191], v242 offset:6144
	ds_read_b128 v[214:217], v242 offset:7168
	global_load_lds_dwordx4 v[218:219], off
	v_lshl_add_u64 v[218:219], s[22:23], 0, v[212:213]
	s_add_i32 m0, s42, 0xe000
	s_nop 0
	global_load_lds_dwordx4 v[218:219], off
	s_waitcnt vmcnt(8)
	s_waitcnt lgkmcnt(0)
	s_barrier
; #define PG8_STAGE(bufoff, gbase, voff) do { _Pragma("unroll") for (int _i = 0; _i < 2; ++_i) \
;         __builtin_amdgcn_global_load_lds((const unsigned*)((const char*)(gbase) + (voff)[_i]), (PG8_LAS unsigned*)(lds + (bufoff) + ldsw + _i * 8192), 16, 0, 0); } while (0)
; #define PG8_LDA(dst, b, h) do { _Pragma("unroll") for (int m = 0; m < 4; ++m) _Pragma("unroll") for (int k = 0; k < 2; ++k) dst[m][k] = *(const PG8_LAS bf16x8*)(lds + PG8_SA(b, h) + aoff + m * 2048 + k * 1024); } while (0)
; #define PG8_WAIT_V(n) asm volatile("s_waitcnt vmcnt(" #n ")" ::: "memory")
; #define PG8_WAIT_L(n) asm volatile("s_waitcnt lgkmcnt(" #n ")" ::: "memory")
; #define PG8_BAR __builtin_amdgcn_s_barrier()
; #define PG8_SCHED __builtin_amdgcn_sched_barrier(0)
; template <class Epi, class Sched, bool ALIGN_EPI = false, bool SP2 = false, bool I8 = false>
; __device__ __forceinline__ void gemm_phase(PG8_LAS unsigned char* lds, const Gemm g, const Sched& S, const Epi& E) {
;     ...
;             PG8_WAIT_V(8); PG8_WAIT_L(0); PG8_BAR; PG8_MMA(0, 0, At, B0); PG8_MMA(0, 1, At, B1); PG8_BAR; PG8_SCHED;
;             PG8_LDA(At, 0, 1); PG8_STAGE(PG8_SB(0, 0), b2, voffB); PG8_STAGE(PG8_SB(0, 1), b2 + hstep, voffB); PG8_STAGE(PG8_SA(0, 0), a2, voffA);
;             PG8_WAIT_V(8); PG8_WAIT_L(0); PG8_BAR; PG8_MMA(1, 0, At, B0); PG8_MMA(1, 1, At, B1); PG8_BAR; PG8_SCHED;
	s_setprio 1
	s_waitcnt lgkmcnt(0)
	v_mfma_f32_16x16x32_bf16 v[140:143], v[124:127], v[164:167], v[140:143]
	v_mfma_f32_16x16x32_bf16 v[140:143], v[128:131], v[168:171], v[140:143]
	v_mfma_f32_16x16x32_bf16 v[112:115], v[128:131], v[176:179], v[112:115]
	v_mfma_f32_16x16x32_bf16 v[112:115], v[124:127], v[172:175], v[112:115]
	v_mfma_f32_16x16x32_bf16 v[96:99], v[124:127], v[180:183], v[96:99]
	v_mfma_f32_16x16x32_bf16 v[96:99], v[128:131], v[184:187], v[96:99]
	v_mfma_f32_16x16x32_bf16 v[80:83], v[128:131], v[214:217], v[80:83]
	v_mfma_f32_16x16x32_bf16 v[80:83], v[124:127], v[188:191], v[80:83]
	v_mfma_f32_16x16x32_bf16 v[76:79], v[132:135], v[188:191], v[76:79]
	v_mfma_f32_16x16x32_bf16 v[76:79], v[144:147], v[214:217], v[76:79]
	v_mfma_f32_16x16x32_bf16 v[92:95], v[144:147], v[184:187], v[92:95]
	v_mfma_f32_16x16x32_bf16 v[92:95], v[132:135], v[180:183], v[92:95]
	v_mfma_f32_16x16x32_bf16 v[108:111], v[132:135], v[172:175], v[108:111]
	v_mfma_f32_16x16x32_bf16 v[108:111], v[144:147], v[176:179], v[108:111]
	v_mfma_f32_16x16x32_bf16 v[136:139], v[144:147], v[168:171], v[136:139]
	v_mfma_f32_16x16x32_bf16 v[136:139], v[132:135], v[164:167], v[136:139]
	v_mfma_f32_16x16x32_bf16 v[120:123], v[148:151], v[164:167], v[120:123]
	v_mfma_f32_16x16x32_bf16 v[120:123], v[152:155], v[168:171], v[120:123]
	v_mfma_f32_16x16x32_bf16 v[104:107], v[152:155], v[176:179], v[104:107]
	v_mfma_f32_16x16x32_bf16 v[104:107], v[148:151], v[172:175], v[104:107]
	v_mfma_f32_16x16x32_bf16 v[88:91], v[148:151], v[180:183], v[88:91]
	v_mfma_f32_16x16x32_bf16 v[88:91], v[152:155], v[184:187], v[88:91]
	v_mfma_f32_16x16x32_bf16 v[72:75], v[152:155], v[214:217], v[72:75]
	v_mfma_f32_16x16x32_bf16 v[72:75], v[148:151], v[188:191], v[72:75]
	v_mfma_f32_16x16x32_bf16 v[68:71], v[156:159], v[188:191], v[68:71]
	v_mfma_f32_16x16x32_bf16 v[68:71], v[160:163], v[214:217], v[68:71]
	v_mfma_f32_16x16x32_bf16 v[84:87], v[160:163], v[184:187], v[84:87]
	v_mfma_f32_16x16x32_bf16 v[84:87], v[156:159], v[180:183], v[84:87]
	v_mfma_f32_16x16x32_bf16 v[100:103], v[156:159], v[172:175], v[100:103]
	v_mfma_f32_16x16x32_bf16 v[100:103], v[160:163], v[176:179], v[100:103]
	v_mfma_f32_16x16x32_bf16 v[116:119], v[160:163], v[168:171], v[116:119]
	v_mfma_f32_16x16x32_bf16 v[116:119], v[156:159], v[164:167], v[116:119]
	s_setprio 0
	s_barrier
	s_add_i32 s22, s56, s41
	v_lshl_add_u64 v[218:219], s[26:27], 0, v[2:3]
	s_mov_b32 m0, s22
	ds_read_b128 v[164:167], v242 offset:16384
	ds_read_b128 v[168:171], v242 offset:17408
	ds_read_b128 v[172:175], v242 offset:18432
	ds_read_b128 v[176:179], v242 offset:19456
	ds_read_b128 v[180:183], v242 offset:20480
	ds_read_b128 v[184:187], v242 offset:21504
	ds_read_b128 v[188:191], v242 offset:22528
	ds_read_b128 v[214:217], v242 offset:23552
	global_load_lds_dwordx4 v[218:219], off
	s_add_i32 m0, s22, 0x2000
	s_add_u32 s22, s26, 0x2b0000
	v_lshl_add_u64 v[220:221], s[26:27], 0, v[204:205]
	s_addc_u32 s23, s27, 0
	s_add_i32 s56, s57, s41
	global_load_lds_dwordx4 v[220:221], off
	v_lshl_add_u64 v[222:223], s[22:23], 0, v[2:3]
	s_mov_b32 m0, s56
	v_lshl_add_u64 v[224:225], s[36:37], 0, v[206:207]
	global_load_lds_dwordx4 v[222:223], off
	v_lshl_add_u64 v[222:223], s[22:23], 0, v[204:205]
	s_add_i32 m0, s56, 0x2000
	s_nop 0
	global_load_lds_dwordx4 v[222:223], off
	v_lshl_add_u64 v[222:223], s[36:37], 0, v[208:209]
	s_mov_b32 m0, s42
	s_nop 0
	global_load_lds_dwordx4 v[222:223], off
	s_mov_b32 m0, s43
	s_nop 0
	global_load_lds_dwordx4 v[224:225], off
	s_waitcnt vmcnt(8)
	s_waitcnt lgkmcnt(0)
	s_barrier
	s_setprio 1
	s_waitcnt lgkmcnt(0)
	v_mfma_f32_16x16x32_bf16 v[64:67], v[124:127], v[164:167], v[64:67]
	v_mfma_f32_16x16x32_bf16 v[64:67], v[128:131], v[168:171], v[64:67]
	v_mfma_f32_16x16x32_bf16 v[48:51], v[128:131], v[176:179], v[48:51]
	v_mfma_f32_16x16x32_bf16 v[48:51], v[124:127], v[172:175], v[48:51]
	v_mfma_f32_16x16x32_bf16 v[32:35], v[124:127], v[180:183], v[32:35]
	v_mfma_f32_16x16x32_bf16 v[32:35], v[128:131], v[184:187], v[32:35]
	v_mfma_f32_16x16x32_bf16 v[16:19], v[128:131], v[214:217], v[16:19]
	v_mfma_f32_16x16x32_bf16 v[16:19], v[124:127], v[188:191], v[16:19]
	v_mfma_f32_16x16x32_bf16 v[12:15], v[132:135], v[188:191], v[12:15]
	v_mfma_f32_16x16x32_bf16 v[12:15], v[144:147], v[214:217], v[12:15]
	v_mfma_f32_16x16x32_bf16 v[28:31], v[144:147], v[184:187], v[28:31]
	v_mfma_f32_16x16x32_bf16 v[28:31], v[132:135], v[180:183], v[28:31]
	v_mfma_f32_16x16x32_bf16 v[44:47], v[132:135], v[172:175], v[44:47]
	v_mfma_f32_16x16x32_bf16 v[44:47], v[144:147], v[176:179], v[44:47]
	v_mfma_f32_16x16x32_bf16 v[60:63], v[144:147], v[168:171], v[60:63]
	v_mfma_f32_16x16x32_bf16 v[60:63], v[132:135], v[164:167], v[60:63]
	v_mfma_f32_16x16x32_bf16 v[56:59], v[148:151], v[164:167], v[56:59]
	v_mfma_f32_16x16x32_bf16 v[56:59], v[152:155], v[168:171], v[56:59]
	v_mfma_f32_16x16x32_bf16 v[40:43], v[152:155], v[176:179], v[40:43]
	v_mfma_f32_16x16x32_bf16 v[40:43], v[148:151], v[172:175], v[40:43]
	v_mfma_f32_16x16x32_bf16 v[24:27], v[148:151], v[180:183], v[24:27]
	v_mfma_f32_16x16x32_bf16 v[24:27], v[152:155], v[184:187], v[24:27]
	v_mfma_f32_16x16x32_bf16 v[8:11], v[152:155], v[214:217], v[8:11]
	v_mfma_f32_16x16x32_bf16 v[8:11], v[148:151], v[188:191], v[8:11]
	v_mfma_f32_16x16x32_bf16 v[4:7], v[156:159], v[188:191], v[4:7]
	v_mfma_f32_16x16x32_bf16 v[4:7], v[160:163], v[214:217], v[4:7]
	v_mfma_f32_16x16x32_bf16 v[20:23], v[160:163], v[184:187], v[20:23]
	v_mfma_f32_16x16x32_bf16 v[20:23], v[156:159], v[180:183], v[20:23]
	v_mfma_f32_16x16x32_bf16 v[36:39], v[156:159], v[172:175], v[36:39]
	v_mfma_f32_16x16x32_bf16 v[36:39], v[160:163], v[176:179], v[36:39]
	v_mfma_f32_16x16x32_bf16 v[52:55], v[160:163], v[168:171], v[52:55]
	v_mfma_f32_16x16x32_bf16 v[52:55], v[156:159], v[164:167], v[52:55]
	s_setprio 0
	s_barrier
; #define PG8_STAGE(bufoff, gbase, voff) do { _Pragma("unroll") for (int _i = 0; _i < 2; ++_i) \
;         __builtin_amdgcn_global_load_lds((const unsigned*)((const char*)(gbase) + (voff)[_i]), (PG8_LAS unsigned*)(lds + (bufoff) + ldsw + _i * 8192), 16, 0, 0); } while (0)
; #define PG8_LDA(dst, b, h) do { _Pragma("unroll") for (int m = 0; m < 4; ++m) _Pragma("unroll") for (int k = 0; k < 2; ++k) dst[m][k] = *(const PG8_LAS bf16x8*)(lds + PG8_SA(b, h) + aoff + m * 2048 + k * 1024); } while (0)
; #define PG8_LDB(dst, b, h) do { _Pragma("unroll") for (int n = 0; n < 2; ++n) _Pragma("unroll") for (int k = 0; k < 2; ++k) dst[n][k] = *(const PG8_LAS bf16x8*)(lds + PG8_SB(b, h) + boff + n * 2048 + k * 1024); } while (0)
; #define PG8_WAIT_V(n) asm volatile("s_waitcnt vmcnt(" #n ")" ::: "memory")
; #define PG8_WAIT_L(n) asm volatile("s_waitcnt lgkmcnt(" #n ")" ::: "memory")
; #define PG8_BAR __builtin_amdgcn_s_barrier()
; #define PG8_SCHED __builtin_amdgcn_sched_barrier(0)
; template <class Epi, class Sched, bool ALIGN_EPI = false, bool SP2 = false, bool I8 = false>
; __device__ __forceinline__ void gemm_phase(PG8_LAS unsigned char* lds, const Gemm g, const Sched& S, const Epi& E) {
;     ...
;             PG8_LDB(B0, 1, 0); PG8_LDB(B1, 1, 1); PG8_SCHED; PG8_LDA(At, 1, 0); PG8_STAGE(PG8_SA(0, 1), a2 + hstep, voffA);
;             PG8_WAIT_V(8); PG8_WAIT_L(0); PG8_BAR; PG8_MMA(0, 0, At, B0); PG8_MMA(0, 1, At, B1); PG8_BAR; PG8_SCHED;
	s_add_i32 s56, 0, 0x18000
	s_add_i32 s57, 0, 0x1c000
	v_add_u32_e32 v144, s56, v240
	v_add_u32_e32 v160, s57, v240
	ds_read_b128 v[124:127], v144
	ds_read_b128 v[128:131], v144 offset:1024
	ds_read_b128 v[132:135], v144 offset:2048
	ds_read_b128 v[144:147], v144 offset:3072
	ds_read_b128 v[148:151], v160
	ds_read_b128 v[152:155], v160 offset:1024
	ds_read_b128 v[156:159], v160 offset:2048
	ds_read_b128 v[160:163], v160 offset:3072
	s_add_u32 s22, s36, 0x2b0000
	s_addc_u32 s23, s37, 0
	s_mov_b32 m0, s44
	v_lshl_add_u64 v[226:227], s[22:23], 0, v[208:209]
	ds_read_b128 v[164:167], v242 offset:32768
	ds_read_b128 v[168:171], v242 offset:33792
	ds_read_b128 v[172:175], v242 offset:34816
	ds_read_b128 v[176:179], v242 offset:35840
	ds_read_b128 v[180:183], v242 offset:36864
	ds_read_b128 v[184:187], v242 offset:37888
	ds_read_b128 v[188:191], v242 offset:38912
	ds_read_b128 v[214:217], v242 offset:39936
	global_load_lds_dwordx4 v[226:227], off
	v_lshl_add_u64 v[226:227], s[22:23], 0, v[206:207]
	s_mov_b32 m0, s45
	s_nop 0
	global_load_lds_dwordx4 v[226:227], off
	s_waitcnt vmcnt(8)
	s_waitcnt lgkmcnt(0)
	s_barrier
	s_setprio 1
	s_waitcnt lgkmcnt(0)
	v_mfma_f32_16x16x32_bf16 v[140:143], v[124:127], v[164:167], v[140:143]
	v_mfma_f32_16x16x32_bf16 v[140:143], v[128:131], v[168:171], v[140:143]
	v_mfma_f32_16x16x32_bf16 v[112:115], v[128:131], v[176:179], v[112:115]
	v_mfma_f32_16x16x32_bf16 v[112:115], v[124:127], v[172:175], v[112:115]
	v_mfma_f32_16x16x32_bf16 v[96:99], v[124:127], v[180:183], v[96:99]
	v_mfma_f32_16x16x32_bf16 v[96:99], v[128:131], v[184:187], v[96:99]
	v_mfma_f32_16x16x32_bf16 v[80:83], v[128:131], v[214:217], v[80:83]
	v_mfma_f32_16x16x32_bf16 v[80:83], v[124:127], v[188:191], v[80:83]
	v_mfma_f32_16x16x32_bf16 v[76:79], v[132:135], v[188:191], v[76:79]
	v_mfma_f32_16x16x32_bf16 v[76:79], v[144:147], v[214:217], v[76:79]
	v_mfma_f32_16x16x32_bf16 v[92:95], v[144:147], v[184:187], v[92:95]
	v_mfma_f32_16x16x32_bf16 v[92:95], v[132:135], v[180:183], v[92:95]
	v_mfma_f32_16x16x32_bf16 v[108:111], v[132:135], v[172:175], v[108:111]
	v_mfma_f32_16x16x32_bf16 v[108:111], v[144:147], v[176:179], v[108:111]
	v_mfma_f32_16x16x32_bf16 v[136:139], v[144:147], v[168:171], v[136:139]
	v_mfma_f32_16x16x32_bf16 v[136:139], v[132:135], v[164:167], v[136:139]
	v_mfma_f32_16x16x32_bf16 v[120:123], v[148:151], v[164:167], v[120:123]
	v_mfma_f32_16x16x32_bf16 v[120:123], v[152:155], v[168:171], v[120:123]
	v_mfma_f32_16x16x32_bf16 v[104:107], v[152:155], v[176:179], v[104:107]
	v_mfma_f32_16x16x32_bf16 v[104:107], v[148:151], v[172:175], v[104:107]
	v_mfma_f32_16x16x32_bf16 v[88:91], v[148:151], v[180:183], v[88:91]
	v_mfma_f32_16x16x32_bf16 v[88:91], v[152:155], v[184:187], v[88:91]
	v_mfma_f32_16x16x32_bf16 v[72:75], v[152:155], v[214:217], v[72:75]
	v_mfma_f32_16x16x32_bf16 v[72:75], v[148:151], v[188:191], v[72:75]
	v_mfma_f32_16x16x32_bf16 v[68:71], v[156:159], v[188:191], v[68:71]
	v_mfma_f32_16x16x32_bf16 v[68:71], v[160:163], v[214:217], v[68:71]
	v_mfma_f32_16x16x32_bf16 v[84:87], v[160:163], v[184:187], v[84:87]
	v_mfma_f32_16x16x32_bf16 v[84:87], v[156:159], v[180:183], v[84:87]
	v_mfma_f32_16x16x32_bf16 v[100:103], v[156:159], v[172:175], v[100:103]
	v_mfma_f32_16x16x32_bf16 v[100:103], v[160:163], v[176:179], v[100:103]
	v_mfma_f32_16x16x32_bf16 v[116:119], v[160:163], v[168:171], v[116:119]
	v_mfma_f32_16x16x32_bf16 v[116:119], v[156:159], v[164:167], v[116:119]
	s_setprio 0
	s_barrier
; #define PG8_STAGE(bufoff, gbase, voff) do { _Pragma("unroll") for (int _i = 0; _i < 2; ++_i) \
;         __builtin_amdgcn_global_load_lds((const unsigned*)((const char*)(gbase) + (voff)[_i]), (PG8_LAS unsigned*)(lds + (bufoff) + ldsw + _i * 8192), 16, 0, 0); } while (0)
; #define PG8_LDA(dst, b, h) do { _Pragma("unroll") for (int m = 0; m < 4; ++m) _Pragma("unroll") for (int k = 0; k < 2; ++k) dst[m][k] = *(const PG8_LAS bf16x8*)(lds + PG8_SA(b, h) + aoff + m * 2048 + k * 1024); } while (0)
; #define PG8_WAIT_V(n) asm volatile("s_waitcnt vmcnt(" #n ")" ::: "memory")
; #define PG8_WAIT_L(n) asm volatile("s_waitcnt lgkmcnt(" #n ")" ::: "memory")
; #define PG8_BAR __builtin_amdgcn_s_barrier()
; #define PG8_SCHED __builtin_amdgcn_sched_barrier(0)
; template <class Epi, class Sched, bool ALIGN_EPI = false, bool SP2 = false, bool I8 = false>
; __device__ __forceinline__ void gemm_phase(PG8_LAS unsigned char* lds, const Gemm g, const Sched& S, const Epi& E) {
;     ...
;         for (int t = 0; t < nt; t += 2) {
;     ...
;             PG8_LDA(At, 1, 1); PG8_STAGE(PG8_SB(1, 0), b3, voffB); PG8_STAGE(PG8_SB(1, 1), b3 + hstep, voffB); PG8_STAGE(PG8_SA(1, 0), a3, voffA);
;             PG8_WAIT_V(8); PG8_WAIT_L(0); PG8_BAR; PG8_MMA(1, 0, At, B0); PG8_MMA(1, 1, At, B1); PG8_BAR; PG8_SCHED;
	s_add_i32 s22, s56, s41
	v_lshl_add_u64 v[218:219], v[218:219], 0, s[84:85]
	s_mov_b32 m0, s22
	ds_read_b128 v[164:167], v242 offset:49152
	ds_read_b128 v[168:171], v242 offset:50176
	ds_read_b128 v[172:175], v242 offset:51200
	ds_read_b128 v[176:179], v242 offset:52224
	ds_read_b128 v[180:183], v242 offset:53248
	ds_read_b128 v[184:187], v242 offset:54272
	ds_read_b128 v[188:191], v242 offset:55296
	ds_read_b128 v[214:217], v242 offset:56320
	global_load_lds_dwordx4 v[218:219], off
	s_add_i32 m0, s22, 0x2000
	s_add_u32 s22, s26, 0x2b0080
	v_lshl_add_u64 v[218:219], v[220:221], 0, s[84:85]
	s_addc_u32 s23, s27, 0
	s_add_i32 s26, s57, s41
	global_load_lds_dwordx4 v[218:219], off
	v_lshl_add_u64 v[218:219], s[22:23], 0, v[2:3]
	s_mov_b32 m0, s26
	s_nop 0
	global_load_lds_dwordx4 v[218:219], off
	v_lshl_add_u64 v[218:219], s[22:23], 0, v[204:205]
	s_add_i32 m0, s26, 0x2000
	s_nop 0
	global_load_lds_dwordx4 v[218:219], off
	v_lshl_add_u64 v[218:219], v[222:223], 0, s[84:85]
	s_mov_b32 m0, s46
	s_nop 0
	global_load_lds_dwordx4 v[218:219], off
	v_lshl_add_u64 v[218:219], v[224:225], 0, s[84:85]
	s_mov_b32 m0, s47
	s_nop 0
	global_load_lds_dwordx4 v[218:219], off
	s_waitcnt vmcnt(8)
	s_waitcnt lgkmcnt(0)
	s_barrier
	s_setprio 1
	s_waitcnt lgkmcnt(0)
	v_mfma_f32_16x16x32_bf16 v[64:67], v[124:127], v[164:167], v[64:67]
	v_mfma_f32_16x16x32_bf16 v[64:67], v[128:131], v[168:171], v[64:67]
	v_mfma_f32_16x16x32_bf16 v[48:51], v[128:131], v[176:179], v[48:51]
	v_mfma_f32_16x16x32_bf16 v[48:51], v[124:127], v[172:175], v[48:51]
	v_mfma_f32_16x16x32_bf16 v[32:35], v[124:127], v[180:183], v[32:35]
	v_mfma_f32_16x16x32_bf16 v[32:35], v[128:131], v[184:187], v[32:35]
	v_mfma_f32_16x16x32_bf16 v[16:19], v[128:131], v[214:217], v[16:19]
	v_mfma_f32_16x16x32_bf16 v[16:19], v[124:127], v[188:191], v[16:19]
	v_mfma_f32_16x16x32_bf16 v[12:15], v[132:135], v[188:191], v[12:15]
	v_mfma_f32_16x16x32_bf16 v[12:15], v[144:147], v[214:217], v[12:15]
	v_mfma_f32_16x16x32_bf16 v[28:31], v[144:147], v[184:187], v[28:31]
	v_mfma_f32_16x16x32_bf16 v[28:31], v[132:135], v[180:183], v[28:31]
	v_mfma_f32_16x16x32_bf16 v[44:47], v[132:135], v[172:175], v[44:47]
	v_mfma_f32_16x16x32_bf16 v[44:47], v[144:147], v[176:179], v[44:47]
	v_mfma_f32_16x16x32_bf16 v[60:63], v[144:147], v[168:171], v[60:63]
	v_mfma_f32_16x16x32_bf16 v[60:63], v[132:135], v[164:167], v[60:63]
	v_mfma_f32_16x16x32_bf16 v[56:59], v[148:151], v[164:167], v[56:59]
	v_mfma_f32_16x16x32_bf16 v[56:59], v[152:155], v[168:171], v[56:59]
	v_mfma_f32_16x16x32_bf16 v[40:43], v[152:155], v[176:179], v[40:43]
	v_mfma_f32_16x16x32_bf16 v[40:43], v[148:151], v[172:175], v[40:43]
	v_mfma_f32_16x16x32_bf16 v[24:27], v[148:151], v[180:183], v[24:27]
	v_mfma_f32_16x16x32_bf16 v[24:27], v[152:155], v[184:187], v[24:27]
	v_mfma_f32_16x16x32_bf16 v[8:11], v[152:155], v[214:217], v[8:11]
	v_mfma_f32_16x16x32_bf16 v[8:11], v[148:151], v[188:191], v[8:11]
	v_mfma_f32_16x16x32_bf16 v[4:7], v[156:159], v[188:191], v[4:7]
	v_mfma_f32_16x16x32_bf16 v[4:7], v[160:163], v[214:217], v[4:7]
	v_mfma_f32_16x16x32_bf16 v[20:23], v[160:163], v[184:187], v[20:23]
	v_mfma_f32_16x16x32_bf16 v[20:23], v[156:159], v[180:183], v[20:23]
	v_mfma_f32_16x16x32_bf16 v[36:39], v[156:159], v[172:175], v[36:39]
	v_mfma_f32_16x16x32_bf16 v[36:39], v[160:163], v[176:179], v[36:39]
	v_mfma_f32_16x16x32_bf16 v[52:55], v[160:163], v[168:171], v[52:55]
	v_mfma_f32_16x16x32_bf16 v[52:55], v[156:159], v[164:167], v[52:55]
	s_setprio 0
	s_barrier
	s_add_i32 s55, s55, 2
	s_add_u32 s53, s53, 0x100
	s_addc_u32 s54, s54, 0
	s_cmpk_gt_u32 s55, 0xa9
	s_mov_b64 s[22:23], s[24:25]
	s_cbranch_scc0 .LBB0_1700

; #define PG8_STAGE(bufoff, gbase, voff) do { _Pragma("unroll") for (int _i = 0; _i < 2; ++_i) \
;         __builtin_amdgcn_global_load_lds((const unsigned*)((const char*)(gbase) + (voff)[_i]), (PG8_LAS unsigned*)(lds + (bufoff) + ldsw + _i * 8192), 16, 0, 0); } while (0)
; #define PG8_LDA(dst, b, h) do { _Pragma("unroll") for (int m = 0; m < 4; ++m) _Pragma("unroll") for (int k = 0; k < 2; ++k) dst[m][k] = *(const PG8_LAS bf16x8*)(lds + PG8_SA(b, h) + aoff + m * 2048 + k * 1024); } while (0)
; #define PG8_LDB(dst, b, h) do { _Pragma("unroll") for (int n = 0; n < 2; ++n) _Pragma("unroll") for (int k = 0; k < 2; ++k) dst[n][k] = *(const PG8_LAS bf16x8*)(lds + PG8_SB(b, h) + boff + n * 2048 + k * 1024); } while (0)
; #define PG8_WAIT_V(n) asm volatile("s_waitcnt vmcnt(" #n ")" ::: "memory")
; #define PG8_WAIT_L(n) asm volatile("s_waitcnt lgkmcnt(" #n ")" ::: "memory")
; #define PG8_BAR __builtin_amdgcn_s_barrier()
; #define PG8_SCHED __builtin_amdgcn_sched_barrier(0)
; template <class Epi, class Sched, bool ALIGN_EPI = false, bool SP2 = false, bool I8 = false>
; __device__ __forceinline__ void gemm_phase(PG8_LAS unsigned char* lds, const Gemm g, const Sched& S, const Epi& E) {
;     ...
;         const char* nA = has_next ? (const char*)g.A + (size_t)nxt.pm * tstep : cA; const char* nB = has_next ? (const char*)g.Bt + (size_t)nxt.pn * tstep : cB;
;         for (int t = 0; t < nt; t += 2) {
;             const bool last = (t == nt - 2);
;             const char* a1 = cA + (size_t)(t + 1) * kstep;
;             const char* a2 = last ? nA : cA + (size_t)(t + 2) * kstep; const char* b2 = last ? nB : cB + (size_t)(t + 2) * kstep;
;             const char* a3 = a2 + kstep; const char* b3 = b2 + kstep;
;             if (last && has_next) S.a_ready(nxt);
;             if constexpr (SP2) {
;             PG8_LDB(B0, 0, 0); PG8_LDB(B1, 0, 1); PG8_SCHED; PG8_LDA(At, 0, 0); PG8_STAGE(PG8_SA(1, 1), a1 + hstep, voffA);
;             PG8_WAIT_V(8); PG8_WAIT_L(0); PG8_BAR; PG8_MMA(0, 0, At, B0); PG8_MMA(0, 1, At, B1); PG8_BAR; PG8_SCHED;
;             PG8_LDA(At, 0, 1); PG8_STAGE(PG8_SB(0, 0), b2, voffB); PG8_STAGE(PG8_SB(0, 1), b2 + hstep, voffB); PG8_STAGE(PG8_SA(0, 0), a2, voffA);
;             PG8_WAIT_V(8); PG8_WAIT_L(0); PG8_BAR; PG8_MMA(1, 0, At, B0); PG8_MMA(1, 1, At, B1); PG8_BAR; PG8_SCHED;
.LBB0_1842:
	s_ashr_i32 s45, s44, 31
	s_lshl_b64 s[34:35], s[44:45], 20
	s_add_u32 s50, s47, s34
	s_addc_u32 s51, s52, s35
	s_and_b64 s[34:35], s[8:9], exec
	s_cselect_b32 s11, s51, s55
	s_cselect_b32 s13, s50, s54
	s_ashr_i32 s49, s48, 31
	s_lshl_b64 s[34:35], s[48:49], 20
	s_add_u32 s56, s53, s34
	s_addc_u32 s57, s64, s35
	s_and_b64 s[34:35], s[8:9], exec
	s_cselect_b32 s34, s57, s59
	s_cselect_b32 s35, s56, s58
	s_add_u32 s54, s54, 0x80080
	s_addc_u32 s55, s55, 0
	s_add_u32 s45, s58, 0x100
	s_addc_u32 s49, s59, 0
	s_mov_b32 s86, -2
	s_waitcnt lgkmcnt(0)
	s_add_u32 s58, s54, 0xfff80080
	s_addc_u32 s59, s55, -1
	s_add_i32 s87, 0, 0x10000
	s_cmp_eq_u32 s86, 28
	s_cselect_b32 s61, s11, s59
	s_cselect_b32 s60, s13, s58
	s_cselect_b32 s59, s34, s49
	s_cselect_b32 s58, s35, s45
	s_add_i32 vcc_lo, 0, 0x14000
	v_add_u32_e32 v40, s87, v217
	v_add_u32_e32 v160, vcc_lo, v217
	ds_read_b128 v[28:31], v40
	ds_read_b128 v[32:35], v40 offset:1024
	ds_read_b128 v[36:39], v40 offset:2048
	ds_read_b128 v[40:43], v40 offset:3072
	ds_read_b128 v[140:143], v160
	ds_read_b128 v[144:147], v160 offset:1024
	ds_read_b128 v[156:159], v160 offset:2048
	ds_read_b128 v[160:163], v160 offset:3072
	v_lshl_add_u64 v[190:191], s[54:55], 0, v[186:187]
	s_add_i32 m0, s65, 0xc000
	ds_read_b128 v[164:167], v219
	ds_read_b128 v[168:171], v219 offset:1024
	ds_read_b128 v[172:175], v219 offset:2048
	ds_read_b128 v[176:179], v219 offset:3072
	ds_read_b128 v[204:207], v219 offset:4096
	ds_read_b128 v[208:211], v219 offset:5120
	ds_read_b128 v[212:215], v219 offset:6144
	ds_read_b128 v[220:223], v219 offset:7168
	global_load_lds_dwordx4 v[190:191], off
	v_lshl_add_u64 v[190:191], s[54:55], 0, v[188:189]
	s_add_i32 m0, s65, 0xe000
	s_nop 0
	global_load_lds_dwordx4 v[190:191], off
	s_waitcnt vmcnt(8)
	s_waitcnt lgkmcnt(0)
	s_barrier
	s_setprio 1
	s_waitcnt lgkmcnt(0)
	v_mfma_i32_16x16x64_i8 v[152:155], v[28:31], v[164:167], 0
	v_mfma_i32_16x16x64_i8 v[152:155], v[32:35], v[168:171], v[152:155]
	v_mfma_i32_16x16x64_i8 v[128:131], v[32:35], v[176:179], 0
	v_mfma_i32_16x16x64_i8 v[128:131], v[28:31], v[172:175], v[128:131]
	v_mfma_i32_16x16x64_i8 v[112:115], v[28:31], v[204:207], 0
	v_mfma_i32_16x16x64_i8 v[112:115], v[32:35], v[208:211], v[112:115]
	v_mfma_i32_16x16x64_i8 v[96:99], v[32:35], v[220:223], 0
	v_mfma_i32_16x16x64_i8 v[96:99], v[28:31], v[212:215], v[96:99]
	v_mfma_i32_16x16x64_i8 v[92:95], v[36:39], v[212:215], 0
	v_mfma_i32_16x16x64_i8 v[92:95], v[40:43], v[220:223], v[92:95]
	v_mfma_i32_16x16x64_i8 v[108:111], v[40:43], v[208:211], 0
	v_mfma_i32_16x16x64_i8 v[108:111], v[36:39], v[204:207], v[108:111]
	v_mfma_i32_16x16x64_i8 v[124:127], v[36:39], v[172:175], 0
	v_mfma_i32_16x16x64_i8 v[124:127], v[40:43], v[176:179], v[124:127]
	v_mfma_i32_16x16x64_i8 v[148:151], v[40:43], v[168:171], 0
	v_mfma_i32_16x16x64_i8 v[148:151], v[36:39], v[164:167], v[148:151]
	v_mfma_i32_16x16x64_i8 v[136:139], v[140:143], v[164:167], 0
	v_mfma_i32_16x16x64_i8 v[136:139], v[144:147], v[168:171], v[136:139]
	v_mfma_i32_16x16x64_i8 v[120:123], v[144:147], v[176:179], 0
	v_mfma_i32_16x16x64_i8 v[120:123], v[140:143], v[172:175], v[120:123]
	v_mfma_i32_16x16x64_i8 v[104:107], v[140:143], v[204:207], 0
	v_mfma_i32_16x16x64_i8 v[104:107], v[144:147], v[208:211], v[104:107]
	v_mfma_i32_16x16x64_i8 v[88:91], v[144:147], v[220:223], 0
	v_mfma_i32_16x16x64_i8 v[88:91], v[140:143], v[212:215], v[88:91]
	v_mfma_i32_16x16x64_i8 v[84:87], v[156:159], v[212:215], 0
	v_mfma_i32_16x16x64_i8 v[84:87], v[160:163], v[220:223], v[84:87]
	v_mfma_i32_16x16x64_i8 v[100:103], v[160:163], v[208:211], 0
	v_mfma_i32_16x16x64_i8 v[100:103], v[156:159], v[204:207], v[100:103]
	v_mfma_i32_16x16x64_i8 v[116:119], v[156:159], v[172:175], 0
	v_mfma_i32_16x16x64_i8 v[116:119], v[160:163], v[176:179], v[116:119]
	v_mfma_i32_16x16x64_i8 v[132:135], v[160:163], v[168:171], 0
	v_mfma_i32_16x16x64_i8 v[132:135], v[156:159], v[164:167], v[132:135]
	s_setprio 0
	s_barrier
	s_add_i32 s87, s87, s46
	v_lshl_add_u64 v[190:191], s[58:59], 0, v[2:3]
	s_mov_b32 m0, s87
	ds_read_b128 v[164:167], v219 offset:16384
	ds_read_b128 v[168:171], v219 offset:17408
	ds_read_b128 v[172:175], v219 offset:18432
	ds_read_b128 v[176:179], v219 offset:19456
	ds_read_b128 v[204:207], v219 offset:20480
	ds_read_b128 v[208:211], v219 offset:21504
	ds_read_b128 v[212:215], v219 offset:22528
	ds_read_b128 v[220:223], v219 offset:23552
	global_load_lds_dwordx4 v[190:191], off
	s_add_i32 m0, s87, 0x2000
	s_add_u32 s96, s58, 0x80000
	v_lshl_add_u64 v[224:225], s[58:59], 0, v[184:185]
	s_addc_u32 s97, s59, 0
	s_add_i32 s87, vcc_lo, s46
	global_load_lds_dwordx4 v[224:225], off
	v_lshl_add_u64 v[226:227], s[96:97], 0, v[2:3]
	s_mov_b32 m0, s87
	v_lshl_add_u64 v[228:229], s[60:61], 0, v[182:183]
	global_load_lds_dwordx4 v[226:227], off
	v_lshl_add_u64 v[226:227], s[96:97], 0, v[184:185]
	s_add_i32 m0, s87, 0x2000
	s_nop 0
	global_load_lds_dwordx4 v[226:227], off
	v_lshl_add_u64 v[226:227], s[60:61], 0, v[180:181]
	s_mov_b32 m0, s65
	s_nop 0
	global_load_lds_dwordx4 v[226:227], off
	s_mov_b32 m0, s67
	s_nop 0
	global_load_lds_dwordx4 v[228:229], off
	s_waitcnt vmcnt(8)
	s_waitcnt lgkmcnt(0)
	s_barrier
; #define PG8_STAGE(bufoff, gbase, voff) do { _Pragma("unroll") for (int _i = 0; _i < 2; ++_i) \
;         __builtin_amdgcn_global_load_lds((const unsigned*)((const char*)(gbase) + (voff)[_i]), (PG8_LAS unsigned*)(lds + (bufoff) + ldsw + _i * 8192), 16, 0, 0); } while (0)
; #define PG8_LDA(dst, b, h) do { _Pragma("unroll") for (int m = 0; m < 4; ++m) _Pragma("unroll") for (int k = 0; k < 2; ++k) dst[m][k] = *(const PG8_LAS bf16x8*)(lds + PG8_SA(b, h) + aoff + m * 2048 + k * 1024); } while (0)
; #define PG8_LDB(dst, b, h) do { _Pragma("unroll") for (int n = 0; n < 2; ++n) _Pragma("unroll") for (int k = 0; k < 2; ++k) dst[n][k] = *(const PG8_LAS bf16x8*)(lds + PG8_SB(b, h) + boff + n * 2048 + k * 1024); } while (0)
; #define PG8_WAIT_V(n) asm volatile("s_waitcnt vmcnt(" #n ")" ::: "memory")
; #define PG8_WAIT_L(n) asm volatile("s_waitcnt lgkmcnt(" #n ")" ::: "memory")
; #define PG8_BAR __builtin_amdgcn_s_barrier()
; #define PG8_SCHED __builtin_amdgcn_sched_barrier(0)
; template <class Epi, class Sched, bool ALIGN_EPI = false, bool SP2 = false, bool I8 = false>
; __device__ __forceinline__ void gemm_phase(PG8_LAS unsigned char* lds, const Gemm g, const Sched& S, const Epi& E) {
;     ...
;             PG8_WAIT_V(8); PG8_WAIT_L(0); PG8_BAR; PG8_MMA(1, 0, At, B0); PG8_MMA(1, 1, At, B1); PG8_BAR; PG8_SCHED;
;             PG8_LDB(B0, 1, 0); PG8_LDB(B1, 1, 1); PG8_SCHED; PG8_LDA(At, 1, 0); PG8_STAGE(PG8_SA(0, 1), a2 + hstep, voffA);
;             PG8_WAIT_V(8); PG8_WAIT_L(0); PG8_BAR; PG8_MMA(0, 0, At, B0); PG8_MMA(0, 1, At, B1); PG8_BAR; PG8_SCHED;
	s_setprio 1
	s_waitcnt lgkmcnt(0)
	v_mfma_i32_16x16x64_i8 v[80:83], v[28:31], v[164:167], 0
	v_mfma_i32_16x16x64_i8 v[80:83], v[32:35], v[168:171], v[80:83]
	v_mfma_i32_16x16x64_i8 v[64:67], v[32:35], v[176:179], 0
	v_mfma_i32_16x16x64_i8 v[64:67], v[28:31], v[172:175], v[64:67]
	v_mfma_i32_16x16x64_i8 v[48:51], v[28:31], v[204:207], 0
	v_mfma_i32_16x16x64_i8 v[48:51], v[32:35], v[208:211], v[48:51]
	v_mfma_i32_16x16x64_i8 v[16:19], v[32:35], v[220:223], 0
	v_mfma_i32_16x16x64_i8 v[16:19], v[28:31], v[212:215], v[16:19]
	v_mfma_i32_16x16x64_i8 v[12:15], v[36:39], v[212:215], 0
	v_mfma_i32_16x16x64_i8 v[12:15], v[40:43], v[220:223], v[12:15]
	v_mfma_i32_16x16x64_i8 v[44:47], v[40:43], v[208:211], 0
	v_mfma_i32_16x16x64_i8 v[44:47], v[36:39], v[204:207], v[44:47]
	v_mfma_i32_16x16x64_i8 v[60:63], v[36:39], v[172:175], 0
	v_mfma_i32_16x16x64_i8 v[60:63], v[40:43], v[176:179], v[60:63]
	v_mfma_i32_16x16x64_i8 v[76:79], v[40:43], v[168:171], 0
	v_mfma_i32_16x16x64_i8 v[76:79], v[36:39], v[164:167], v[76:79]
	v_mfma_i32_16x16x64_i8 v[28:31], v[140:143], v[164:167], 0
	v_mfma_i32_16x16x64_i8 v[28:31], v[144:147], v[168:171], v[28:31]
	v_mfma_i32_16x16x64_i8 v[36:39], v[144:147], v[176:179], 0
	v_mfma_i32_16x16x64_i8 v[36:39], v[140:143], v[172:175], v[36:39]
	v_mfma_i32_16x16x64_i8 v[24:27], v[140:143], v[204:207], 0
	v_mfma_i32_16x16x64_i8 v[24:27], v[144:147], v[208:211], v[24:27]
	v_mfma_i32_16x16x64_i8 v[8:11], v[144:147], v[220:223], 0
	v_mfma_i32_16x16x64_i8 v[8:11], v[140:143], v[212:215], v[8:11]
	v_mfma_i32_16x16x64_i8 v[4:7], v[156:159], v[212:215], 0
	v_mfma_i32_16x16x64_i8 v[4:7], v[160:163], v[220:223], v[4:7]
	v_mfma_i32_16x16x64_i8 v[20:23], v[160:163], v[208:211], 0
	v_mfma_i32_16x16x64_i8 v[20:23], v[156:159], v[204:207], v[20:23]
	v_mfma_i32_16x16x64_i8 v[40:43], v[156:159], v[172:175], 0
	v_mfma_i32_16x16x64_i8 v[40:43], v[160:163], v[176:179], v[40:43]
	v_mfma_i32_16x16x64_i8 v[32:35], v[160:163], v[168:171], 0
	v_mfma_i32_16x16x64_i8 v[32:35], v[156:159], v[164:167], v[32:35]
	s_setprio 0
	s_barrier
	s_add_i32 s87, 0, 0x18000
	s_add_i32 s96, 0, 0x1c000
	v_add_u32_e32 v72, s87, v217
	v_add_u32_e32 v160, s96, v217
	ds_read_b128 v[52:55], v72
	ds_read_b128 v[56:59], v72 offset:1024
	ds_read_b128 v[68:71], v72 offset:2048
	ds_read_b128 v[72:75], v72 offset:3072
	ds_read_b128 v[140:143], v160
	ds_read_b128 v[144:147], v160 offset:1024
	ds_read_b128 v[156:159], v160 offset:2048
	ds_read_b128 v[160:163], v160 offset:3072
	s_add_u32 s60, s60, 0x80000
	s_addc_u32 s61, s61, 0
	s_mov_b32 m0, s72
	v_lshl_add_u64 v[240:241], s[60:61], 0, v[180:181]
	ds_read_b128 v[164:167], v219 offset:32768
	ds_read_b128 v[168:171], v219 offset:33792
	ds_read_b128 v[172:175], v219 offset:34816
	ds_read_b128 v[176:179], v219 offset:35840
	ds_read_b128 v[204:207], v219 offset:36864
	ds_read_b128 v[208:211], v219 offset:37888
	ds_read_b128 v[212:215], v219 offset:38912
	ds_read_b128 v[220:223], v219 offset:39936
	global_load_lds_dwordx4 v[240:241], off
	v_lshl_add_u64 v[240:241], s[60:61], 0, v[182:183]
	s_mov_b32 m0, s73
	s_nop 0
	global_load_lds_dwordx4 v[240:241], off
	s_waitcnt vmcnt(8)
	s_waitcnt lgkmcnt(0)
	s_barrier
	s_setprio 1
	s_waitcnt lgkmcnt(0)
	v_mfma_i32_16x16x64_i8 v[152:155], v[52:55], v[164:167], v[152:155]
	v_mfma_i32_16x16x64_i8 v[152:155], v[56:59], v[168:171], v[152:155]
	v_mfma_i32_16x16x64_i8 v[128:131], v[56:59], v[176:179], v[128:131]
	v_mfma_i32_16x16x64_i8 v[128:131], v[52:55], v[172:175], v[128:131]
	v_mfma_i32_16x16x64_i8 v[112:115], v[52:55], v[204:207], v[112:115]
	v_mfma_i32_16x16x64_i8 v[112:115], v[56:59], v[208:211], v[112:115]
	v_mfma_i32_16x16x64_i8 v[96:99], v[56:59], v[220:223], v[96:99]
	v_mfma_i32_16x16x64_i8 v[96:99], v[52:55], v[212:215], v[96:99]
	v_mfma_i32_16x16x64_i8 v[92:95], v[68:71], v[212:215], v[92:95]
	v_mfma_i32_16x16x64_i8 v[92:95], v[72:75], v[220:223], v[92:95]
	v_mfma_i32_16x16x64_i8 v[108:111], v[72:75], v[208:211], v[108:111]
	v_mfma_i32_16x16x64_i8 v[108:111], v[68:71], v[204:207], v[108:111]
	v_mfma_i32_16x16x64_i8 v[124:127], v[68:71], v[172:175], v[124:127]
	v_mfma_i32_16x16x64_i8 v[124:127], v[72:75], v[176:179], v[124:127]
	v_mfma_i32_16x16x64_i8 v[148:151], v[72:75], v[168:171], v[148:151]
	v_mfma_i32_16x16x64_i8 v[148:151], v[68:71], v[164:167], v[148:151]
	v_mfma_i32_16x16x64_i8 v[136:139], v[140:143], v[164:167], v[136:139]
	v_mfma_i32_16x16x64_i8 v[136:139], v[144:147], v[168:171], v[136:139]
	v_mfma_i32_16x16x64_i8 v[120:123], v[144:147], v[176:179], v[120:123]
	v_mfma_i32_16x16x64_i8 v[120:123], v[140:143], v[172:175], v[120:123]
	v_mfma_i32_16x16x64_i8 v[104:107], v[140:143], v[204:207], v[104:107]
	v_mfma_i32_16x16x64_i8 v[104:107], v[144:147], v[208:211], v[104:107]
	v_mfma_i32_16x16x64_i8 v[88:91], v[144:147], v[220:223], v[88:91]
	v_mfma_i32_16x16x64_i8 v[88:91], v[140:143], v[212:215], v[88:91]
	v_mfma_i32_16x16x64_i8 v[84:87], v[156:159], v[212:215], v[84:87]
	v_mfma_i32_16x16x64_i8 v[84:87], v[160:163], v[220:223], v[84:87]
	v_mfma_i32_16x16x64_i8 v[100:103], v[160:163], v[208:211], v[100:103]
	v_mfma_i32_16x16x64_i8 v[100:103], v[156:159], v[204:207], v[100:103]
	v_mfma_i32_16x16x64_i8 v[116:119], v[156:159], v[172:175], v[116:119]
	v_mfma_i32_16x16x64_i8 v[116:119], v[160:163], v[176:179], v[116:119]
	v_mfma_i32_16x16x64_i8 v[132:135], v[160:163], v[168:171], v[132:135]
	v_mfma_i32_16x16x64_i8 v[132:135], v[156:159], v[164:167], v[132:135]
	s_setprio 0
	s_barrier
; #define PG8_STAGE(bufoff, gbase, voff) do { _Pragma("unroll") for (int _i = 0; _i < 2; ++_i) \
;         __builtin_amdgcn_global_load_lds((const unsigned*)((const char*)(gbase) + (voff)[_i]), (PG8_LAS unsigned*)(lds + (bufoff) + ldsw + _i * 8192), 16, 0, 0); } while (0)
; #define PG8_LDA(dst, b, h) do { _Pragma("unroll") for (int m = 0; m < 4; ++m) _Pragma("unroll") for (int k = 0; k < 2; ++k) dst[m][k] = *(const PG8_LAS bf16x8*)(lds + PG8_SA(b, h) + aoff + m * 2048 + k * 1024); } while (0)
; #define PG8_WAIT_V(n) asm volatile("s_waitcnt vmcnt(" #n ")" ::: "memory")
; #define PG8_WAIT_L(n) asm volatile("s_waitcnt lgkmcnt(" #n ")" ::: "memory")
; #define PG8_BAR __builtin_amdgcn_s_barrier()
; template <class Epi, class Sched, bool ALIGN_EPI = false, bool SP2 = false, bool I8 = false>
; __device__ __forceinline__ void gemm_phase(PG8_LAS unsigned char* lds, const Gemm g, const Sched& S, const Epi& E) {
;     ...
;         for (int t = 0; t < nt; t += 2) {
;             const bool last = (t == nt - 2);
;             const char* a1 = cA + (size_t)(t + 1) * kstep;
;             const char* a2 = last ? nA : cA + (size_t)(t + 2) * kstep; const char* b2 = last ? nB : cB + (size_t)(t + 2) * kstep;
;             const char* a3 = a2 + kstep; const char* b3 = b2 + kstep;
;             if (last && has_next) S.a_ready(nxt);
;             if constexpr (SP2) {
;             PG8_LDB(B0, 0, 0); PG8_LDB(B1, 0, 1); PG8_SCHED; PG8_LDA(At, 0, 0); PG8_STAGE(PG8_SA(1, 1), a1 + hstep, voffA);
;             PG8_WAIT_V(8); PG8_WAIT_L(0); PG8_BAR; PG8_MMA(0, 0, At, B0); PG8_MMA(0, 1, At, B1); PG8_BAR; PG8_SCHED;
;             PG8_LDA(At, 0, 1); PG8_STAGE(PG8_SB(0, 0), b2, voffB); PG8_STAGE(PG8_SB(0, 1), b2 + hstep, voffB); PG8_STAGE(PG8_SA(0, 0), a2, voffA);
;             PG8_WAIT_V(8); PG8_WAIT_L(0); PG8_BAR; PG8_MMA(1, 0, At, B0); PG8_MMA(1, 1, At, B1); PG8_BAR; PG8_SCHED;
;             PG8_LDB(B0, 1, 0); PG8_LDB(B1, 1, 1); PG8_SCHED; PG8_LDA(At, 1, 0); PG8_STAGE(PG8_SA(0, 1), a2 + hstep, voffA);
;             PG8_WAIT_V(8); PG8_WAIT_L(0); PG8_BAR; PG8_MMA(0, 0, At, B0); PG8_MMA(0, 1, At, B1); PG8_BAR; PG8_SCHED;
;             PG8_LDA(At, 1, 1); PG8_STAGE(PG8_SB(1, 0), b3, voffB); PG8_STAGE(PG8_SB(1, 1), b3 + hstep, voffB); PG8_STAGE(PG8_SA(1, 0), a3, voffA);
;             PG8_WAIT_V(8); PG8_WAIT_L(0); PG8_BAR; PG8_MMA(1, 0, At, B0); PG8_MMA(1, 1, At, B1); PG8_BAR; PG8_SCHED;
	s_add_i32 s60, s87, s46
	v_lshl_add_u64 v[190:191], v[190:191], 0, s[84:85]
	s_mov_b32 m0, s60
	ds_read_b128 v[164:167], v219 offset:49152
	ds_read_b128 v[168:171], v219 offset:50176
	ds_read_b128 v[172:175], v219 offset:51200
	ds_read_b128 v[176:179], v219 offset:52224
	ds_read_b128 v[204:207], v219 offset:53248
	ds_read_b128 v[208:211], v219 offset:54272
	ds_read_b128 v[212:215], v219 offset:55296
	ds_read_b128 v[220:223], v219 offset:56320
	global_load_lds_dwordx4 v[190:191], off
	s_add_i32 m0, s60, 0x2000
	s_add_u32 s58, s58, 0x80080
	v_lshl_add_u64 v[190:191], v[224:225], 0, s[84:85]
	s_addc_u32 s59, s59, 0
	s_add_i32 s60, s96, s46
	global_load_lds_dwordx4 v[190:191], off
	v_lshl_add_u64 v[190:191], s[58:59], 0, v[2:3]
	s_mov_b32 m0, s60
	s_nop 0
	global_load_lds_dwordx4 v[190:191], off
	v_lshl_add_u64 v[190:191], s[58:59], 0, v[184:185]
	s_add_i32 m0, s60, 0x2000
	s_nop 0
	global_load_lds_dwordx4 v[190:191], off
	v_lshl_add_u64 v[190:191], v[226:227], 0, s[84:85]
	s_mov_b32 m0, s28
	s_nop 0
	global_load_lds_dwordx4 v[190:191], off
	v_lshl_add_u64 v[190:191], v[228:229], 0, s[84:85]
	s_mov_b32 m0, s77
	s_nop 0
	global_load_lds_dwordx4 v[190:191], off
	s_waitcnt vmcnt(8)
	s_waitcnt lgkmcnt(0)
	s_barrier
	s_setprio 1
	s_waitcnt lgkmcnt(0)
	v_mfma_i32_16x16x64_i8 v[80:83], v[52:55], v[164:167], v[80:83]
	v_mfma_i32_16x16x64_i8 v[80:83], v[56:59], v[168:171], v[80:83]
	v_mfma_i32_16x16x64_i8 v[64:67], v[56:59], v[176:179], v[64:67]
	v_mfma_i32_16x16x64_i8 v[64:67], v[52:55], v[172:175], v[64:67]
	v_mfma_i32_16x16x64_i8 v[48:51], v[52:55], v[204:207], v[48:51]
	v_mfma_i32_16x16x64_i8 v[48:51], v[56:59], v[208:211], v[48:51]
	v_mfma_i32_16x16x64_i8 v[16:19], v[56:59], v[220:223], v[16:19]
	v_mfma_i32_16x16x64_i8 v[16:19], v[52:55], v[212:215], v[16:19]
	v_mfma_i32_16x16x64_i8 v[12:15], v[68:71], v[212:215], v[12:15]
	v_mfma_i32_16x16x64_i8 v[12:15], v[72:75], v[220:223], v[12:15]
	v_mfma_i32_16x16x64_i8 v[44:47], v[72:75], v[208:211], v[44:47]
	v_mfma_i32_16x16x64_i8 v[44:47], v[68:71], v[204:207], v[44:47]
	v_mfma_i32_16x16x64_i8 v[60:63], v[68:71], v[172:175], v[60:63]
	v_mfma_i32_16x16x64_i8 v[60:63], v[72:75], v[176:179], v[60:63]
	v_mfma_i32_16x16x64_i8 v[76:79], v[72:75], v[168:171], v[76:79]
	v_mfma_i32_16x16x64_i8 v[76:79], v[68:71], v[164:167], v[76:79]
	v_mfma_i32_16x16x64_i8 v[28:31], v[140:143], v[164:167], v[28:31]
	v_mfma_i32_16x16x64_i8 v[72:75], v[144:147], v[168:171], v[28:31]
	v_mfma_i32_16x16x64_i8 v[28:31], v[144:147], v[176:179], v[36:39]
	v_mfma_i32_16x16x64_i8 v[56:59], v[140:143], v[172:175], v[28:31]
	v_mfma_i32_16x16x64_i8 v[24:27], v[140:143], v[204:207], v[24:27]
	v_mfma_i32_16x16x64_i8 v[24:27], v[144:147], v[208:211], v[24:27]
	v_mfma_i32_16x16x64_i8 v[8:11], v[144:147], v[220:223], v[8:11]
	v_mfma_i32_16x16x64_i8 v[8:11], v[140:143], v[212:215], v[8:11]
	v_mfma_i32_16x16x64_i8 v[4:7], v[156:159], v[212:215], v[4:7]
	v_mfma_i32_16x16x64_i8 v[4:7], v[160:163], v[220:223], v[4:7]
	v_mfma_i32_16x16x64_i8 v[20:23], v[160:163], v[208:211], v[20:23]
	v_mfma_i32_16x16x64_i8 v[20:23], v[156:159], v[204:207], v[20:23]
	v_mfma_i32_16x16x64_i8 v[28:31], v[156:159], v[172:175], v[40:43]
	v_mfma_i32_16x16x64_i8 v[52:55], v[160:163], v[176:179], v[28:31]
	v_mfma_i32_16x16x64_i8 v[28:31], v[160:163], v[168:171], v[32:35]
	v_mfma_i32_16x16x64_i8 v[68:71], v[156:159], v[164:167], v[28:31]
	s_setprio 0
	s_barrier
	s_add_i32 s86, s86, 2
	s_add_u32 s54, s54, 0x100
	s_addc_u32 s55, s55, 0
	s_add_u32 s45, s45, 0x100
	s_addc_u32 s49, s49, 0
	s_cmp_gt_u32 s86, 29
	s_cbranch_scc1 .Lkloop_exit_6
.LBB0_1843:
	s_add_u32 s58, s54, 0xfff80080
	s_addc_u32 s59, s55, -1
	s_add_i32 s87, 0, 0x10000
	s_cmp_eq_u32 s86, 28
	s_cselect_b32 s61, s11, s59
	s_cselect_b32 s60, s13, s58
	s_cselect_b32 s59, s34, s49
	s_cselect_b32 s58, s35, s45
	s_add_i32 vcc_lo, 0, 0x14000
	v_add_u32_e32 v40, s87, v217
	v_add_u32_e32 v160, vcc_lo, v217
	ds_read_b128 v[28:31], v40
	ds_read_b128 v[32:35], v40 offset:1024
	ds_read_b128 v[36:39], v40 offset:2048
	ds_read_b128 v[40:43], v40 offset:3072
	ds_read_b128 v[140:143], v160
	ds_read_b128 v[144:147], v160 offset:1024
	ds_read_b128 v[156:159], v160 offset:2048
	ds_read_b128 v[160:163], v160 offset:3072
	v_lshl_add_u64 v[190:191], s[54:55], 0, v[186:187]
	s_add_i32 m0, s65, 0xc000
	ds_read_b128 v[164:167], v219
	ds_read_b128 v[168:171], v219 offset:1024
	ds_read_b128 v[172:175], v219 offset:2048
	ds_read_b128 v[176:179], v219 offset:3072
	ds_read_b128 v[204:207], v219 offset:4096
	ds_read_b128 v[208:211], v219 offset:5120
	ds_read_b128 v[212:215], v219 offset:6144
	ds_read_b128 v[220:223], v219 offset:7168
	global_load_lds_dwordx4 v[190:191], off
	v_lshl_add_u64 v[190:191], s[54:55], 0, v[188:189]
	s_add_i32 m0, s65, 0xe000
	s_nop 0
	global_load_lds_dwordx4 v[190:191], off
	s_waitcnt vmcnt(8)
	s_waitcnt lgkmcnt(0)
	s_barrier
; #define PG8_STAGE(bufoff, gbase, voff) do { _Pragma("unroll") for (int _i = 0; _i < 2; ++_i) \
;         __builtin_amdgcn_global_load_lds((const unsigned*)((const char*)(gbase) + (voff)[_i]), (PG8_LAS unsigned*)(lds + (bufoff) + ldsw + _i * 8192), 16, 0, 0); } while (0)
; #define PG8_LDA(dst, b, h) do { _Pragma("unroll") for (int m = 0; m < 4; ++m) _Pragma("unroll") for (int k = 0; k < 2; ++k) dst[m][k] = *(const PG8_LAS bf16x8*)(lds + PG8_SA(b, h) + aoff + m * 2048 + k * 1024); } while (0)
; #define PG8_LDB(dst, b, h) do { _Pragma("unroll") for (int n = 0; n < 2; ++n) _Pragma("unroll") for (int k = 0; k < 2; ++k) dst[n][k] = *(const PG8_LAS bf16x8*)(lds + PG8_SB(b, h) + boff + n * 2048 + k * 1024); } while (0)
; #define PG8_WAIT_V(n) asm volatile("s_waitcnt vmcnt(" #n ")" ::: "memory")
; #define PG8_WAIT_L(n) asm volatile("s_waitcnt lgkmcnt(" #n ")" ::: "memory")
; #define PG8_BAR __builtin_amdgcn_s_barrier()
; #define PG8_SCHED __builtin_amdgcn_sched_barrier(0)
; template <class Epi, class Sched, bool ALIGN_EPI = false, bool SP2 = false, bool I8 = false>
; __device__ __forceinline__ void gemm_phase(PG8_LAS unsigned char* lds, const Gemm g, const Sched& S, const Epi& E) {
;     ...
;             PG8_LDB(B0, 0, 0); PG8_LDB(B1, 0, 1); PG8_SCHED; PG8_LDA(At, 0, 0); PG8_STAGE(PG8_SA(1, 1), a1 + hstep, voffA);
;             PG8_WAIT_V(8); PG8_WAIT_L(0); PG8_BAR; PG8_MMA(0, 0, At, B0); PG8_MMA(0, 1, At, B1); PG8_BAR; PG8_SCHED;
;             PG8_LDA(At, 0, 1); PG8_STAGE(PG8_SB(0, 0), b2, voffB); PG8_STAGE(PG8_SB(0, 1), b2 + hstep, voffB); PG8_STAGE(PG8_SA(0, 0), a2, voffA);
;             PG8_WAIT_V(8); PG8_WAIT_L(0); PG8_BAR; PG8_MMA(1, 0, At, B0); PG8_MMA(1, 1, At, B1); PG8_BAR; PG8_SCHED;
	s_setprio 1
	s_waitcnt lgkmcnt(0)
	v_mfma_i32_16x16x64_i8 v[152:155], v[28:31], v[164:167], v[152:155]
	v_mfma_i32_16x16x64_i8 v[152:155], v[32:35], v[168:171], v[152:155]
	v_mfma_i32_16x16x64_i8 v[128:131], v[32:35], v[176:179], v[128:131]
	v_mfma_i32_16x16x64_i8 v[128:131], v[28:31], v[172:175], v[128:131]
	v_mfma_i32_16x16x64_i8 v[112:115], v[28:31], v[204:207], v[112:115]
	v_mfma_i32_16x16x64_i8 v[112:115], v[32:35], v[208:211], v[112:115]
	v_mfma_i32_16x16x64_i8 v[96:99], v[32:35], v[220:223], v[96:99]
	v_mfma_i32_16x16x64_i8 v[96:99], v[28:31], v[212:215], v[96:99]
	v_mfma_i32_16x16x64_i8 v[92:95], v[36:39], v[212:215], v[92:95]
	v_mfma_i32_16x16x64_i8 v[92:95], v[40:43], v[220:223], v[92:95]
	v_mfma_i32_16x16x64_i8 v[108:111], v[40:43], v[208:211], v[108:111]
	v_mfma_i32_16x16x64_i8 v[108:111], v[36:39], v[204:207], v[108:111]
	v_mfma_i32_16x16x64_i8 v[124:127], v[36:39], v[172:175], v[124:127]
	v_mfma_i32_16x16x64_i8 v[124:127], v[40:43], v[176:179], v[124:127]
	v_mfma_i32_16x16x64_i8 v[148:151], v[40:43], v[168:171], v[148:151]
	v_mfma_i32_16x16x64_i8 v[148:151], v[36:39], v[164:167], v[148:151]
	v_mfma_i32_16x16x64_i8 v[136:139], v[140:143], v[164:167], v[136:139]
	v_mfma_i32_16x16x64_i8 v[136:139], v[144:147], v[168:171], v[136:139]
	v_mfma_i32_16x16x64_i8 v[120:123], v[144:147], v[176:179], v[120:123]
	v_mfma_i32_16x16x64_i8 v[120:123], v[140:143], v[172:175], v[120:123]
	v_mfma_i32_16x16x64_i8 v[104:107], v[140:143], v[204:207], v[104:107]
	v_mfma_i32_16x16x64_i8 v[104:107], v[144:147], v[208:211], v[104:107]
	v_mfma_i32_16x16x64_i8 v[88:91], v[144:147], v[220:223], v[88:91]
	v_mfma_i32_16x16x64_i8 v[88:91], v[140:143], v[212:215], v[88:91]
	v_mfma_i32_16x16x64_i8 v[84:87], v[156:159], v[212:215], v[84:87]
	v_mfma_i32_16x16x64_i8 v[84:87], v[160:163], v[220:223], v[84:87]
	v_mfma_i32_16x16x64_i8 v[100:103], v[160:163], v[208:211], v[100:103]
	v_mfma_i32_16x16x64_i8 v[100:103], v[156:159], v[204:207], v[100:103]
	v_mfma_i32_16x16x64_i8 v[116:119], v[156:159], v[172:175], v[116:119]
	v_mfma_i32_16x16x64_i8 v[116:119], v[160:163], v[176:179], v[116:119]
	v_mfma_i32_16x16x64_i8 v[132:135], v[160:163], v[168:171], v[132:135]
	v_mfma_i32_16x16x64_i8 v[132:135], v[156:159], v[164:167], v[132:135]
	s_setprio 0
	s_barrier
	s_add_i32 s87, s87, s46
	v_lshl_add_u64 v[190:191], s[58:59], 0, v[2:3]
	s_mov_b32 m0, s87
	ds_read_b128 v[164:167], v219 offset:16384
	ds_read_b128 v[168:171], v219 offset:17408
	ds_read_b128 v[172:175], v219 offset:18432
	ds_read_b128 v[176:179], v219 offset:19456
	ds_read_b128 v[204:207], v219 offset:20480
	ds_read_b128 v[208:211], v219 offset:21504
	ds_read_b128 v[212:215], v219 offset:22528
	ds_read_b128 v[220:223], v219 offset:23552
	global_load_lds_dwordx4 v[190:191], off
	s_add_i32 m0, s87, 0x2000
	s_add_u32 s96, s58, 0x80000
	v_lshl_add_u64 v[224:225], s[58:59], 0, v[184:185]
	s_addc_u32 s97, s59, 0
	s_add_i32 s87, vcc_lo, s46
	global_load_lds_dwordx4 v[224:225], off
	v_lshl_add_u64 v[226:227], s[96:97], 0, v[2:3]
	s_mov_b32 m0, s87
	v_lshl_add_u64 v[228:229], s[60:61], 0, v[182:183]
	global_load_lds_dwordx4 v[226:227], off
	v_lshl_add_u64 v[226:227], s[96:97], 0, v[184:185]
	s_add_i32 m0, s87, 0x2000
	s_nop 0
	global_load_lds_dwordx4 v[226:227], off
	v_lshl_add_u64 v[226:227], s[60:61], 0, v[180:181]
	s_mov_b32 m0, s65
	s_nop 0
	global_load_lds_dwordx4 v[226:227], off
	s_mov_b32 m0, s67
	s_nop 0
	global_load_lds_dwordx4 v[228:229], off
	s_waitcnt vmcnt(8)
	s_waitcnt lgkmcnt(0)
	s_barrier
	s_setprio 1
	s_waitcnt lgkmcnt(0)
	v_mfma_i32_16x16x64_i8 v[80:83], v[28:31], v[164:167], v[80:83]
	v_mfma_i32_16x16x64_i8 v[80:83], v[32:35], v[168:171], v[80:83]
	v_mfma_i32_16x16x64_i8 v[64:67], v[32:35], v[176:179], v[64:67]
	v_mfma_i32_16x16x64_i8 v[64:67], v[28:31], v[172:175], v[64:67]
	v_mfma_i32_16x16x64_i8 v[48:51], v[28:31], v[204:207], v[48:51]
	v_mfma_i32_16x16x64_i8 v[48:51], v[32:35], v[208:211], v[48:51]
	v_mfma_i32_16x16x64_i8 v[16:19], v[32:35], v[220:223], v[16:19]
	v_mfma_i32_16x16x64_i8 v[16:19], v[28:31], v[212:215], v[16:19]
	v_mfma_i32_16x16x64_i8 v[12:15], v[36:39], v[212:215], v[12:15]
	v_mfma_i32_16x16x64_i8 v[12:15], v[40:43], v[220:223], v[12:15]
	v_mfma_i32_16x16x64_i8 v[44:47], v[40:43], v[208:211], v[44:47]
	v_mfma_i32_16x16x64_i8 v[44:47], v[36:39], v[204:207], v[44:47]
	v_mfma_i32_16x16x64_i8 v[60:63], v[36:39], v[172:175], v[60:63]
	v_mfma_i32_16x16x64_i8 v[60:63], v[40:43], v[176:179], v[60:63]
	v_mfma_i32_16x16x64_i8 v[76:79], v[40:43], v[168:171], v[76:79]
	v_mfma_i32_16x16x64_i8 v[76:79], v[36:39], v[164:167], v[76:79]
	v_mfma_i32_16x16x64_i8 v[28:31], v[140:143], v[164:167], v[72:75]
	v_mfma_i32_16x16x64_i8 v[28:31], v[144:147], v[168:171], v[28:31]
	v_mfma_i32_16x16x64_i8 v[36:39], v[144:147], v[176:179], v[56:59]
	v_mfma_i32_16x16x64_i8 v[36:39], v[140:143], v[172:175], v[36:39]
	v_mfma_i32_16x16x64_i8 v[24:27], v[140:143], v[204:207], v[24:27]
	v_mfma_i32_16x16x64_i8 v[24:27], v[144:147], v[208:211], v[24:27]
	v_mfma_i32_16x16x64_i8 v[8:11], v[144:147], v[220:223], v[8:11]
	v_mfma_i32_16x16x64_i8 v[8:11], v[140:143], v[212:215], v[8:11]
	v_mfma_i32_16x16x64_i8 v[4:7], v[156:159], v[212:215], v[4:7]
	v_mfma_i32_16x16x64_i8 v[4:7], v[160:163], v[220:223], v[4:7]
	v_mfma_i32_16x16x64_i8 v[20:23], v[160:163], v[208:211], v[20:23]
	v_mfma_i32_16x16x64_i8 v[20:23], v[156:159], v[204:207], v[20:23]
	v_mfma_i32_16x16x64_i8 v[40:43], v[156:159], v[172:175], v[52:55]
	v_mfma_i32_16x16x64_i8 v[40:43], v[160:163], v[176:179], v[40:43]
	v_mfma_i32_16x16x64_i8 v[32:35], v[160:163], v[168:171], v[68:71]
	v_mfma_i32_16x16x64_i8 v[32:35], v[156:159], v[164:167], v[32:35]
	s_setprio 0
	s_barrier
; #define PG8_STAGE(bufoff, gbase, voff) do { _Pragma("unroll") for (int _i = 0; _i < 2; ++_i) \
;         __builtin_amdgcn_global_load_lds((const unsigned*)((const char*)(gbase) + (voff)[_i]), (PG8_LAS unsigned*)(lds + (bufoff) + ldsw + _i * 8192), 16, 0, 0); } while (0)
; #define PG8_LDA(dst, b, h) do { _Pragma("unroll") for (int m = 0; m < 4; ++m) _Pragma("unroll") for (int k = 0; k < 2; ++k) dst[m][k] = *(const PG8_LAS bf16x8*)(lds + PG8_SA(b, h) + aoff + m * 2048 + k * 1024); } while (0)
; #define PG8_LDB(dst, b, h) do { _Pragma("unroll") for (int n = 0; n < 2; ++n) _Pragma("unroll") for (int k = 0; k < 2; ++k) dst[n][k] = *(const PG8_LAS bf16x8*)(lds + PG8_SB(b, h) + boff + n * 2048 + k * 1024); } while (0)
; #define PG8_WAIT_V(n) asm volatile("s_waitcnt vmcnt(" #n ")" ::: "memory")
; #define PG8_WAIT_L(n) asm volatile("s_waitcnt lgkmcnt(" #n ")" ::: "memory")
; #define PG8_BAR __builtin_amdgcn_s_barrier()
; #define PG8_SCHED __builtin_amdgcn_sched_barrier(0)
; template <class Epi, class Sched, bool ALIGN_EPI = false, bool SP2 = false, bool I8 = false>
; __device__ __forceinline__ void gemm_phase(PG8_LAS unsigned char* lds, const Gemm g, const Sched& S, const Epi& E) {
;     ...
;             PG8_LDB(B0, 1, 0); PG8_LDB(B1, 1, 1); PG8_SCHED; PG8_LDA(At, 1, 0); PG8_STAGE(PG8_SA(0, 1), a2 + hstep, voffA);
;             PG8_WAIT_V(8); PG8_WAIT_L(0); PG8_BAR; PG8_MMA(0, 0, At, B0); PG8_MMA(0, 1, At, B1); PG8_BAR; PG8_SCHED;
;             PG8_LDA(At, 1, 1); PG8_STAGE(PG8_SB(1, 0), b3, voffB); PG8_STAGE(PG8_SB(1, 1), b3 + hstep, voffB); PG8_STAGE(PG8_SA(1, 0), a3, voffA);
;             PG8_WAIT_V(8); PG8_WAIT_L(0); PG8_BAR; PG8_MMA(1, 0, At, B0); PG8_MMA(1, 1, At, B1); PG8_BAR; PG8_SCHED;
	s_add_i32 s87, 0, 0x18000
	s_add_i32 s96, 0, 0x1c000
	v_add_u32_e32 v72, s87, v217
	v_add_u32_e32 v160, s96, v217
	ds_read_b128 v[52:55], v72
	ds_read_b128 v[56:59], v72 offset:1024
	ds_read_b128 v[68:71], v72 offset:2048
	ds_read_b128 v[72:75], v72 offset:3072
	ds_read_b128 v[140:143], v160
	ds_read_b128 v[144:147], v160 offset:1024
	ds_read_b128 v[156:159], v160 offset:2048
	ds_read_b128 v[160:163], v160 offset:3072
	s_add_u32 s60, s60, 0x80000
	s_addc_u32 s61, s61, 0
	s_mov_b32 m0, s72
	v_lshl_add_u64 v[240:241], s[60:61], 0, v[180:181]
	ds_read_b128 v[164:167], v219 offset:32768
	ds_read_b128 v[168:171], v219 offset:33792
	ds_read_b128 v[172:175], v219 offset:34816
	ds_read_b128 v[176:179], v219 offset:35840
	ds_read_b128 v[204:207], v219 offset:36864
	ds_read_b128 v[208:211], v219 offset:37888
	ds_read_b128 v[212:215], v219 offset:38912
	ds_read_b128 v[220:223], v219 offset:39936
	global_load_lds_dwordx4 v[240:241], off
	v_lshl_add_u64 v[240:241], s[60:61], 0, v[182:183]
	s_mov_b32 m0, s73
	s_nop 0
	global_load_lds_dwordx4 v[240:241], off
	s_waitcnt vmcnt(8)
	s_waitcnt lgkmcnt(0)
	s_barrier
	s_setprio 1
	s_waitcnt lgkmcnt(0)
	v_mfma_i32_16x16x64_i8 v[152:155], v[52:55], v[164:167], v[152:155]
	v_mfma_i32_16x16x64_i8 v[152:155], v[56:59], v[168:171], v[152:155]
	v_mfma_i32_16x16x64_i8 v[128:131], v[56:59], v[176:179], v[128:131]
	v_mfma_i32_16x16x64_i8 v[128:131], v[52:55], v[172:175], v[128:131]
	v_mfma_i32_16x16x64_i8 v[112:115], v[52:55], v[204:207], v[112:115]
	v_mfma_i32_16x16x64_i8 v[112:115], v[56:59], v[208:211], v[112:115]
	v_mfma_i32_16x16x64_i8 v[96:99], v[56:59], v[220:223], v[96:99]
	v_mfma_i32_16x16x64_i8 v[96:99], v[52:55], v[212:215], v[96:99]
	v_mfma_i32_16x16x64_i8 v[92:95], v[68:71], v[212:215], v[92:95]
	v_mfma_i32_16x16x64_i8 v[92:95], v[72:75], v[220:223], v[92:95]
	v_mfma_i32_16x16x64_i8 v[108:111], v[72:75], v[208:211], v[108:111]
	v_mfma_i32_16x16x64_i8 v[108:111], v[68:71], v[204:207], v[108:111]
	v_mfma_i32_16x16x64_i8 v[124:127], v[68:71], v[172:175], v[124:127]
	v_mfma_i32_16x16x64_i8 v[124:127], v[72:75], v[176:179], v[124:127]
	v_mfma_i32_16x16x64_i8 v[148:151], v[72:75], v[168:171], v[148:151]
	v_mfma_i32_16x16x64_i8 v[148:151], v[68:71], v[164:167], v[148:151]
	v_mfma_i32_16x16x64_i8 v[136:139], v[140:143], v[164:167], v[136:139]
	v_mfma_i32_16x16x64_i8 v[136:139], v[144:147], v[168:171], v[136:139]
	v_mfma_i32_16x16x64_i8 v[120:123], v[144:147], v[176:179], v[120:123]
	v_mfma_i32_16x16x64_i8 v[120:123], v[140:143], v[172:175], v[120:123]
	v_mfma_i32_16x16x64_i8 v[104:107], v[140:143], v[204:207], v[104:107]
	v_mfma_i32_16x16x64_i8 v[104:107], v[144:147], v[208:211], v[104:107]
	v_mfma_i32_16x16x64_i8 v[88:91], v[144:147], v[220:223], v[88:91]
	v_mfma_i32_16x16x64_i8 v[88:91], v[140:143], v[212:215], v[88:91]
	v_mfma_i32_16x16x64_i8 v[84:87], v[156:159], v[212:215], v[84:87]
	v_mfma_i32_16x16x64_i8 v[84:87], v[160:163], v[220:223], v[84:87]
	v_mfma_i32_16x16x64_i8 v[100:103], v[160:163], v[208:211], v[100:103]
	v_mfma_i32_16x16x64_i8 v[100:103], v[156:159], v[204:207], v[100:103]
	v_mfma_i32_16x16x64_i8 v[116:119], v[156:159], v[172:175], v[116:119]
	v_mfma_i32_16x16x64_i8 v[116:119], v[160:163], v[176:179], v[116:119]
	v_mfma_i32_16x16x64_i8 v[132:135], v[160:163], v[168:171], v[132:135]
	v_mfma_i32_16x16x64_i8 v[132:135], v[156:159], v[164:167], v[132:135]
	s_setprio 0
	s_barrier
	s_add_i32 s60, s87, s46
	v_lshl_add_u64 v[190:191], v[190:191], 0, s[84:85]
	s_mov_b32 m0, s60
	ds_read_b128 v[164:167], v219 offset:49152
	ds_read_b128 v[168:171], v219 offset:50176
	ds_read_b128 v[172:175], v219 offset:51200
	ds_read_b128 v[176:179], v219 offset:52224
	ds_read_b128 v[204:207], v219 offset:53248
	ds_read_b128 v[208:211], v219 offset:54272
	ds_read_b128 v[212:215], v219 offset:55296
	ds_read_b128 v[220:223], v219 offset:56320
	global_load_lds_dwordx4 v[190:191], off
	s_add_i32 m0, s60, 0x2000
	s_add_u32 s58, s58, 0x80080
	v_lshl_add_u64 v[190:191], v[224:225], 0, s[84:85]
	s_addc_u32 s59, s59, 0
	s_add_i32 s60, s96, s46
	global_load_lds_dwordx4 v[190:191], off
	v_lshl_add_u64 v[190:191], s[58:59], 0, v[2:3]
	s_mov_b32 m0, s60
	s_nop 0
	global_load_lds_dwordx4 v[190:191], off
	v_lshl_add_u64 v[190:191], s[58:59], 0, v[184:185]
	s_add_i32 m0, s60, 0x2000
	s_nop 0
	global_load_lds_dwordx4 v[190:191], off
	v_lshl_add_u64 v[190:191], v[226:227], 0, s[84:85]
	s_mov_b32 m0, s28
	s_nop 0
	global_load_lds_dwordx4 v[190:191], off
	v_lshl_add_u64 v[190:191], v[228:229], 0, s[84:85]
	s_mov_b32 m0, s77
	s_nop 0
	global_load_lds_dwordx4 v[190:191], off
	s_waitcnt vmcnt(8)
	s_waitcnt lgkmcnt(0)
	s_barrier
	s_setprio 1
	s_waitcnt lgkmcnt(0)
	v_mfma_i32_16x16x64_i8 v[80:83], v[52:55], v[164:167], v[80:83]
	v_mfma_i32_16x16x64_i8 v[80:83], v[56:59], v[168:171], v[80:83]
	v_mfma_i32_16x16x64_i8 v[64:67], v[56:59], v[176:179], v[64:67]
	v_mfma_i32_16x16x64_i8 v[64:67], v[52:55], v[172:175], v[64:67]
	v_mfma_i32_16x16x64_i8 v[48:51], v[52:55], v[204:207], v[48:51]
	v_mfma_i32_16x16x64_i8 v[48:51], v[56:59], v[208:211], v[48:51]
	v_mfma_i32_16x16x64_i8 v[16:19], v[56:59], v[220:223], v[16:19]
	v_mfma_i32_16x16x64_i8 v[16:19], v[52:55], v[212:215], v[16:19]
	v_mfma_i32_16x16x64_i8 v[12:15], v[68:71], v[212:215], v[12:15]
	v_mfma_i32_16x16x64_i8 v[12:15], v[72:75], v[220:223], v[12:15]
	v_mfma_i32_16x16x64_i8 v[44:47], v[72:75], v[208:211], v[44:47]
	v_mfma_i32_16x16x64_i8 v[44:47], v[68:71], v[204:207], v[44:47]
	v_mfma_i32_16x16x64_i8 v[60:63], v[68:71], v[172:175], v[60:63]
	v_mfma_i32_16x16x64_i8 v[60:63], v[72:75], v[176:179], v[60:63]
	v_mfma_i32_16x16x64_i8 v[76:79], v[72:75], v[168:171], v[76:79]
	v_mfma_i32_16x16x64_i8 v[76:79], v[68:71], v[164:167], v[76:79]
	v_mfma_i32_16x16x64_i8 v[28:31], v[140:143], v[164:167], v[28:31]
	v_mfma_i32_16x16x64_i8 v[72:75], v[144:147], v[168:171], v[28:31]
	v_mfma_i32_16x16x64_i8 v[28:31], v[144:147], v[176:179], v[36:39]
	v_mfma_i32_16x16x64_i8 v[56:59], v[140:143], v[172:175], v[28:31]
	v_mfma_i32_16x16x64_i8 v[24:27], v[140:143], v[204:207], v[24:27]
	v_mfma_i32_16x16x64_i8 v[24:27], v[144:147], v[208:211], v[24:27]
	v_mfma_i32_16x16x64_i8 v[8:11], v[144:147], v[220:223], v[8:11]
	v_mfma_i32_16x16x64_i8 v[8:11], v[140:143], v[212:215], v[8:11]
	v_mfma_i32_16x16x64_i8 v[4:7], v[156:159], v[212:215], v[4:7]
	v_mfma_i32_16x16x64_i8 v[4:7], v[160:163], v[220:223], v[4:7]
	v_mfma_i32_16x16x64_i8 v[20:23], v[160:163], v[208:211], v[20:23]
	v_mfma_i32_16x16x64_i8 v[20:23], v[156:159], v[204:207], v[20:23]
	v_mfma_i32_16x16x64_i8 v[28:31], v[156:159], v[172:175], v[40:43]
	v_mfma_i32_16x16x64_i8 v[52:55], v[160:163], v[176:179], v[28:31]
	v_mfma_i32_16x16x64_i8 v[28:31], v[160:163], v[168:171], v[32:35]
	v_mfma_i32_16x16x64_i8 v[68:71], v[156:159], v[164:167], v[28:31]
	s_setprio 0
	s_barrier
	s_add_i32 s86, s86, 2
	s_add_u32 s54, s54, 0x100
	s_addc_u32 s55, s55, 0
	s_add_u32 s45, s45, 0x100
	s_addc_u32 s49, s49, 0
	s_cmp_gt_u32 s86, 29
	s_cbranch_scc0 .LBB0_1843
